# non-temporal policy on the D stores of the two pool phases; on top of v57
# baseline (speedup 1.0000x reference)
.LBB0_239:
	v_readlane_b32 s24, v251, 49
	v_readlane_b32 s25, v251, 50
	v_readlane_b32 s12, v252, 34
	v_readlane_b32 s13, v252, 35
	v_lshl_add_u64 v[30:31], v[28:29], 0, s[24:25]
	v_readlane_b32 s24, v252, 9
	v_readlane_b32 s25, v252, 10
	v_readlane_b32 s1, v252, 1
	v_readlane_b32 s18, v254, 17
	v_lshl_add_u64 v[34:35], v[28:29], 0, s[24:25]
	v_readlane_b32 s24, v252, 13
	v_readlane_b32 s25, v252, 14
	v_mov_b32_e32 v1, s1
	v_readlane_b32 s1, v252, 3
	v_lshl_add_u64 v[36:37], v[28:29], 0, s[24:25]
	v_readlane_b32 s24, v252, 17
	v_readlane_b32 s25, v252, 18
	s_lshl_b32 s8, s1, 1
	v_readlane_b32 s1, v252, 7
	v_lshl_add_u64 v[38:39], v[28:29], 0, s[24:25]
	global_load_dwordx2 v[104:105], v[30:31], off
	global_load_dwordx2 v[106:107], v[34:35], off
	global_load_dwordx2 v[80:81], v[36:37], off
	global_load_dwordx2 v[72:73], v[38:39], off
	v_readlane_b32 s24, v252, 21
	v_readlane_b32 s25, v252, 22
	v_readlane_b32 s19, v254, 18
	s_mov_b32 s28, s4
	v_lshl_add_u64 v[30:31], v[28:29], 0, s[24:25]
	v_readlane_b32 s24, v252, 25
	v_readlane_b32 s25, v252, 26
	s_mov_b32 s83, s52
	s_mov_b32 s36, s39
	v_lshl_add_u64 v[34:35], v[28:29], 0, s[24:25]
	v_readlane_b32 s24, v252, 28
	v_readlane_b32 s25, v252, 29
	s_mov_b32 s80, s30
	s_mov_b32 s82, s29
	v_lshl_add_u64 v[36:37], v[28:29], 0, s[24:25]
	v_readlane_b32 s24, v252, 31
	v_readlane_b32 s25, v252, 32
	s_nop 1
	v_lshl_add_u64 v[38:39], v[28:29], 0, s[24:25]
	global_load_dwordx2 v[74:75], v[30:31], off
	global_load_dwordx2 v[68:69], v[34:35], off
	global_load_dwordx2 v[62:63], v[36:37], off
	global_load_dwordx2 v[52:53], v[38:39], off
	v_lshl_add_u64 v[30:31], v[28:29], 0, s[12:13]
	v_readlane_b32 s12, v252, 37
	v_readlane_b32 s13, v252, 38
	v_readlane_b32 s24, v252, 51
	v_readlane_b32 s25, v252, 52
	v_lshl_add_u64 v[34:35], v[28:29], 0, s[12:13]
	v_readlane_b32 s12, v252, 40
	v_readlane_b32 s13, v252, 41
	s_nop 1
	v_lshl_add_u64 v[36:37], v[28:29], 0, s[12:13]
	v_readlane_b32 s12, v252, 43
	v_readlane_b32 s13, v252, 44
	s_nop 1
	v_lshl_add_u64 v[38:39], v[28:29], 0, s[12:13]
	global_load_dwordx2 v[58:59], v[30:31], off
	global_load_dwordx2 v[50:51], v[34:35], off
	global_load_dwordx2 v[46:47], v[36:37], off
	s_nop 0
	global_load_dwordx2 v[38:39], v[38:39], off
	v_readlane_b32 s12, v251, 37
	v_readlane_b32 s13, v251, 38
	s_nop 1
	v_lshl_add_u64 v[30:31], v[28:29], 0, s[12:13]
	v_readlane_b32 s12, v254, 1
	v_readlane_b32 s13, v254, 2
	s_nop 1
	v_lshl_add_u64 v[34:35], v[28:29], 0, s[12:13]
	v_readlane_b32 s12, v254, 3
	v_readlane_b32 s13, v254, 4
	s_nop 1
	v_lshl_add_u64 v[54:55], v[28:29], 0, s[12:13]
	v_readlane_b32 s12, v254, 5
	v_readlane_b32 s13, v254, 6
	s_nop 1
	v_lshl_add_u64 v[60:61], v[28:29], 0, s[12:13]
	global_load_dwordx2 v[42:43], v[30:31], off
	global_load_dwordx2 v[36:37], v[34:35], off
	s_nop 0
	global_load_dwordx2 v[34:35], v[54:55], off
	global_load_dwordx2 v[30:31], v[60:61], off
	v_pk_add_f32 v[54:55], v[90:91], 0 op_sel_hi:[1,0]
	ds_read_b128 v[82:85], v1
	ds_read_b128 v[92:95], v1 offset:16
	ds_read_b128 v[96:99], v1 offset:32
	ds_read_b128 v[100:103], v1 offset:48
	v_pk_add_f32 v[54:55], v[86:87], v[54:55]
	s_waitcnt lgkmcnt(3)
	v_pk_mul_f32 v[108:109], v[26:27], v[82:83] op_sel_hi:[1,0]
	v_pk_add_f32 v[54:55], v[76:77], v[54:55]
	v_pk_mul_f32 v[110:111], v[26:27], v[82:83] op_sel:[0,1]
	v_pk_add_f32 v[54:55], v[66:67], v[54:55]
	s_waitcnt lgkmcnt(0)
	v_pk_mul_f32 v[70:71], v[26:27], v[100:101] op_sel_hi:[1,0]
	v_pk_add_f32 v[54:55], v[56:57], v[54:55]
	v_pk_mul_f32 v[64:65], v[26:27], v[100:101] op_sel:[0,1]
	v_pk_add_f32 v[54:55], v[48:49], v[54:55]
	v_pk_mul_f32 v[112:113], v[26:27], v[84:85] op_sel_hi:[1,0]
	v_pk_add_f32 v[54:55], v[44:45], v[54:55]
	v_mov_b32_e32 v82, v85
	v_pk_add_f32 v[100:101], v[40:41], v[54:55]
	v_pk_mul_f32 v[88:89], v[26:27], v[96:97] op_sel_hi:[1,0]
	v_pk_mul_f32 v[84:85], v[26:27], v[96:97] op_sel:[0,1]
	v_mov_b32_e32 v96, v99
	s_waitcnt vmcnt(15)
	v_pk_fma_f32 v[100:101], v[104:105], v[108:109], v[100:101]
	v_pk_mul_f32 v[78:79], v[26:27], v[98:99] op_sel_hi:[1,0]
	v_pk_mul_f32 v[60:61], v[26:27], v[102:103] op_sel_hi:[1,0]
	v_mov_b32_e32 v98, v103
	v_pk_mul_f32 v[102:103], v[26:27], v[82:83] op_sel_hi:[1,0]
	v_pk_mul_f32 v[82:83], v[26:27], v[96:97] op_sel_hi:[1,0]
	v_pk_mul_f32 v[96:97], v[104:105], v[108:109]
	v_pk_add_f32 v[90:91], v[100:101], v[90:91] neg_lo:[0,1] neg_hi:[0,1]
	v_pk_mul_f32 v[54:55], v[26:27], v[98:99] op_sel_hi:[1,0]
	v_pk_fma_f32 v[96:97], v[4:5], v[90:91], v[96:97] neg_lo:[0,0,1] neg_hi:[0,0,1]
	s_waitcnt vmcnt(14)
	v_pk_fma_f32 v[90:91], v[106:107], v[110:111], v[90:91]
	v_pk_mul_f32 v[98:99], v[106:107], v[110:111]
	v_pk_add_f32 v[86:87], v[90:91], v[86:87] neg_lo:[0,1] neg_hi:[0,1]
	s_waitcnt vmcnt(13)
	v_pk_mul_f32 v[118:119], v[80:81], v[112:113]
	v_pk_fma_f32 v[90:91], v[6:7], v[86:87], v[98:99] neg_lo:[0,0,1] neg_hi:[0,0,1]
	v_pk_fma_f32 v[86:87], v[80:81], v[112:113], v[86:87]
	v_pk_mul_f32 v[114:115], v[26:27], v[92:93] op_sel_hi:[1,0]
	v_pk_add_f32 v[76:77], v[86:87], v[76:77] neg_lo:[0,1] neg_hi:[0,1]
	s_waitcnt vmcnt(12)
	v_pk_mul_f32 v[120:121], v[72:73], v[102:103]
	v_pk_fma_f32 v[86:87], v[8:9], v[76:77], v[118:119] neg_lo:[0,0,1] neg_hi:[0,0,1]
	v_pk_fma_f32 v[76:77], v[72:73], v[102:103], v[76:77]
	v_pk_mul_f32 v[92:93], v[26:27], v[92:93] op_sel:[0,1]
	v_pk_add_f32 v[66:67], v[76:77], v[66:67] neg_lo:[0,1] neg_hi:[0,1]
	s_waitcnt vmcnt(11)
	v_pk_mul_f32 v[122:123], v[74:75], v[114:115]
	v_pk_fma_f32 v[76:77], v[10:11], v[66:67], v[120:121] neg_lo:[0,0,1] neg_hi:[0,0,1]
	v_pk_fma_f32 v[66:67], v[74:75], v[114:115], v[66:67]
	v_cvt_pk_bf16_f32 v100, v96, v97
	v_lshl_add_u64 v[96:97], v[24:25], 0, s[8:9]
	v_pk_add_f32 v[56:57], v[66:67], v[56:57] neg_lo:[0,1] neg_hi:[0,1]
	s_lshl_b32 s8, s1, 1
	v_readlane_b32 s1, v252, 11
	v_pk_fma_f32 v[66:67], v[12:13], v[56:57], v[122:123] neg_lo:[0,0,1] neg_hi:[0,0,1]
	s_waitcnt vmcnt(10)
	v_pk_fma_f32 v[56:57], v[68:69], v[92:93], v[56:57]
	v_pk_mul_f32 v[116:117], v[26:27], v[94:95] op_sel_hi:[1,0]
	v_pk_mul_f32 v[124:125], v[68:69], v[92:93]
	global_store_dword v[96:97], v100, off nt
	v_cvt_pk_bf16_f32 v96, v90, v91
	v_lshl_add_u64 v[90:91], v[24:25], 0, s[8:9]
	s_lshl_b32 s8, s1, 1
	v_readlane_b32 s1, v252, 15
	v_pk_add_f32 v[48:49], v[56:57], v[48:49] neg_lo:[0,1] neg_hi:[0,1]
	v_mov_b32_e32 v94, v95
	global_store_dword v[90:91], v96, off nt
	v_cvt_pk_bf16_f32 v90, v86, v87
	v_lshl_add_u64 v[86:87], v[24:25], 0, s[8:9]
	s_lshl_b32 s8, s1, 1
	v_readlane_b32 s1, v252, 19
	v_pk_fma_f32 v[56:57], v[14:15], v[48:49], v[124:125] neg_lo:[0,0,1] neg_hi:[0,0,1]
	s_waitcnt vmcnt(11)
	v_pk_fma_f32 v[48:49], v[62:63], v[116:117], v[48:49]
	v_pk_mul_f32 v[94:95], v[26:27], v[94:95] op_sel_hi:[1,0]
	v_pk_mul_f32 v[126:127], v[62:63], v[116:117]
	global_store_dword v[86:87], v90, off nt
	v_cvt_pk_bf16_f32 v86, v76, v77
	v_lshl_add_u64 v[76:77], v[24:25], 0, s[8:9]
	s_lshl_b32 s8, s1, 1
	v_readlane_b32 s1, v252, 23
	v_pk_add_f32 v[44:45], v[48:49], v[44:45] neg_lo:[0,1] neg_hi:[0,1]
	global_store_dword v[76:77], v86, off nt
	v_cvt_pk_bf16_f32 v76, v66, v67
	v_lshl_add_u64 v[66:67], v[24:25], 0, s[8:9]
	s_lshl_b32 s8, s1, 1
	v_pk_fma_f32 v[48:49], v[16:17], v[44:45], v[126:127] neg_lo:[0,0,1] neg_hi:[0,0,1]
	v_readlane_b32 s1, v252, 27
	s_waitcnt vmcnt(12)
	v_pk_fma_f32 v[44:45], v[52:53], v[94:95], v[44:45]
	v_pk_mul_f32 v[128:129], v[52:53], v[94:95]
	global_store_dword v[66:67], v76, off nt
	v_cvt_pk_bf16_f32 v66, v56, v57
	v_lshl_add_u64 v[56:57], v[24:25], 0, s[8:9]
	s_lshl_b32 s8, s1, 1
	v_pk_add_f32 v[40:41], v[44:45], v[40:41] neg_lo:[0,1] neg_hi:[0,1]
	s_mov_b32 s12, 0x3e000000
	v_readlane_b32 s1, v252, 30
	global_store_dword v[56:57], v66, off nt
	v_cvt_pk_bf16_f32 v56, v48, v49
	v_lshl_add_u64 v[48:49], v[24:25], 0, s[8:9]
	v_pk_fma_f32 v[44:45], v[40:41], s[12:13], v[128:129] op_sel_hi:[1,0,1] neg_lo:[0,0,1] neg_hi:[0,0,1]
	s_lshl_b32 s8, s1, 1
	s_waitcnt vmcnt(13)
	v_pk_fma_f32 v[40:41], v[58:59], v[88:89], v[40:41]
	v_pk_mul_f32 v[130:131], v[58:59], v[88:89]
	global_store_dword v[48:49], v56, off nt
	v_cvt_pk_bf16_f32 v48, v44, v45
	v_lshl_add_u64 v[44:45], v[24:25], 0, s[8:9]
	v_pk_fma_f32 v[40:41], v[104:105], v[108:109], v[40:41] neg_lo:[1,0,0] neg_hi:[1,0,0]
	v_readlane_b32 s1, v252, 33
	global_store_dword v[44:45], v48, off nt
	v_pk_fma_f32 v[44:45], v[40:41], s[12:13], v[130:131] op_sel_hi:[1,0,1] neg_lo:[0,0,1] neg_hi:[0,0,1]
	s_lshl_b32 s8, s1, 1
	s_waitcnt vmcnt(14)
	v_pk_fma_f32 v[40:41], v[50:51], v[84:85], v[40:41]
	v_pk_mul_f32 v[132:133], v[50:51], v[84:85]
	v_cvt_pk_bf16_f32 v48, v44, v45
	v_lshl_add_u64 v[44:45], v[24:25], 0, s[8:9]
	v_pk_fma_f32 v[40:41], v[106:107], v[110:111], v[40:41] neg_lo:[1,0,0] neg_hi:[1,0,0]
	v_readlane_b32 s1, v252, 36
	global_store_dword v[44:45], v48, off nt
	v_pk_fma_f32 v[44:45], v[40:41], s[12:13], v[132:133] op_sel_hi:[1,0,1] neg_lo:[0,0,1] neg_hi:[0,0,1]
	s_lshl_b32 s8, s1, 1
	s_waitcnt vmcnt(14)
	v_pk_fma_f32 v[40:41], v[46:47], v[78:79], v[40:41]
	v_pk_mul_f32 v[134:135], v[46:47], v[78:79]
	v_cvt_pk_bf16_f32 v48, v44, v45
	v_lshl_add_u64 v[44:45], v[24:25], 0, s[8:9]
	v_pk_fma_f32 v[40:41], v[80:81], v[112:113], v[40:41] neg_lo:[1,0,0] neg_hi:[1,0,0]
	v_readlane_b32 s1, v252, 39
	global_store_dword v[44:45], v48, off nt
	v_pk_fma_f32 v[44:45], v[40:41], s[12:13], v[134:135] op_sel_hi:[1,0,1] neg_lo:[0,0,1] neg_hi:[0,0,1]
	s_lshl_b32 s8, s1, 1
	s_waitcnt vmcnt(14)
	v_pk_fma_f32 v[40:41], v[38:39], v[82:83], v[40:41]
	v_pk_mul_f32 v[136:137], v[38:39], v[82:83]
	v_cvt_pk_bf16_f32 v48, v44, v45
	v_lshl_add_u64 v[44:45], v[24:25], 0, s[8:9]
	v_pk_fma_f32 v[40:41], v[72:73], v[102:103], v[40:41] neg_lo:[1,0,0] neg_hi:[1,0,0]
	v_readlane_b32 s1, v252, 42
	global_store_dword v[44:45], v48, off nt
	v_pk_fma_f32 v[44:45], v[40:41], s[12:13], v[136:137] op_sel_hi:[1,0,1] neg_lo:[0,0,1] neg_hi:[0,0,1]
	s_lshl_b32 s8, s1, 1
	s_waitcnt vmcnt(14)
	v_pk_fma_f32 v[40:41], v[42:43], v[70:71], v[40:41]
	v_pk_mul_f32 v[138:139], v[42:43], v[70:71]
	v_cvt_pk_bf16_f32 v48, v44, v45
	v_lshl_add_u64 v[44:45], v[24:25], 0, s[8:9]
	v_pk_fma_f32 v[40:41], v[74:75], v[114:115], v[40:41] neg_lo:[1,0,0] neg_hi:[1,0,0]
	v_readlane_b32 s1, v252, 45
	global_store_dword v[44:45], v48, off nt
	v_pk_fma_f32 v[44:45], v[40:41], s[12:13], v[138:139] op_sel_hi:[1,0,1] neg_lo:[0,0,1] neg_hi:[0,0,1]
	s_lshl_b32 s8, s1, 1
	s_waitcnt vmcnt(14)
	v_pk_fma_f32 v[40:41], v[36:37], v[64:65], v[40:41]
	v_pk_mul_f32 v[140:141], v[36:37], v[64:65]
	v_cvt_pk_bf16_f32 v48, v44, v45
	v_lshl_add_u64 v[44:45], v[24:25], 0, s[8:9]
	v_pk_fma_f32 v[40:41], v[68:69], v[92:93], v[40:41] neg_lo:[1,0,0] neg_hi:[1,0,0]
	v_readlane_b32 s1, v252, 47
	global_store_dword v[44:45], v48, off nt
	v_pk_fma_f32 v[44:45], v[40:41], s[12:13], v[140:141] op_sel_hi:[1,0,1] neg_lo:[0,0,1] neg_hi:[0,0,1]
	s_lshl_b32 s8, s1, 1
	s_waitcnt vmcnt(14)
	v_pk_fma_f32 v[40:41], v[34:35], v[60:61], v[40:41]
	v_pk_mul_f32 v[142:143], v[34:35], v[60:61]
	v_cvt_pk_bf16_f32 v48, v44, v45
	v_lshl_add_u64 v[44:45], v[24:25], 0, s[8:9]
	v_pk_fma_f32 v[40:41], v[62:63], v[116:117], v[40:41] neg_lo:[1,0,0] neg_hi:[1,0,0]
	global_store_dword v[44:45], v48, off nt
	v_pk_fma_f32 v[44:45], v[40:41], s[12:13], v[142:143] op_sel_hi:[1,0,1] neg_lo:[0,0,1] neg_hi:[0,0,1]
	v_readlane_b32 s1, v252, 48
	s_waitcnt vmcnt(14)
	v_pk_fma_f32 v[40:41], v[30:31], v[54:55], v[40:41]
	v_pk_mul_f32 v[144:145], v[30:31], v[54:55]
	s_lshl_b32 s8, s1, 1
	v_pk_fma_f32 v[108:109], v[52:53], v[94:95], v[40:41] neg_lo:[1,0,0] neg_hi:[1,0,0]
	v_readlane_b32 s1, v252, 49
	v_cvt_pk_bf16_f32 v48, v44, v45
	v_lshl_add_u64 v[44:45], v[24:25], 0, s[8:9]
	v_pk_fma_f32 v[40:41], v[108:109], s[12:13], v[144:145] op_sel_hi:[1,0,1] neg_lo:[0,0,1] neg_hi:[0,0,1]
	s_lshl_b32 s8, s1, 1
	global_store_dword v[44:45], v48, off nt
	v_cvt_pk_bf16_f32 v44, v40, v41
	v_lshl_add_u64 v[40:41], v[24:25], 0, s[8:9]
	global_store_dword v[40:41], v44, off nt
	v_lshl_add_u64 v[40:41], v[28:29], 0, s[24:25]
	v_readlane_b32 s24, v252, 54
	global_load_dwordx2 v[110:111], v[40:41], off
	v_readlane_b32 s25, v252, 55
	v_readlane_b32 s1, v252, 50
	s_lshl_b32 s8, s1, 1
	v_lshl_add_u64 v[40:41], v[28:29], 0, s[24:25]
	v_readlane_b32 s24, v252, 56
	global_load_dwordx2 v[112:113], v[40:41], off
	v_readlane_b32 s25, v252, 57
	v_readlane_b32 s1, v252, 53
	s_nop 0
	v_lshl_add_u64 v[40:41], v[28:29], 0, s[24:25]
	v_readlane_b32 s24, v252, 59
	global_load_dwordx2 v[114:115], v[40:41], off
	v_readlane_b32 s25, v252, 60
	s_nop 1
	v_lshl_add_u64 v[40:41], v[28:29], 0, s[24:25]
	v_readlane_b32 s24, v252, 62
	global_load_dwordx2 v[116:117], v[40:41], off
	v_readlane_b32 s25, v252, 63
	s_nop 1
	v_lshl_add_u64 v[40:41], v[28:29], 0, s[24:25]
	v_readlane_b32 s24, v253, 1
	global_load_dwordx2 v[118:119], v[40:41], off
	v_readlane_b32 s25, v253, 2
	s_nop 1
	v_lshl_add_u64 v[40:41], v[28:29], 0, s[24:25]
	v_readlane_b32 s24, v253, 4
	global_load_dwordx2 v[120:121], v[40:41], off
	v_readlane_b32 s25, v253, 5
	s_nop 1
	v_lshl_add_u64 v[40:41], v[28:29], 0, s[24:25]
	v_readlane_b32 s24, v253, 7
	global_load_dwordx2 v[98:99], v[40:41], off
	v_readlane_b32 s25, v253, 8
	s_nop 1
	v_lshl_add_u64 v[40:41], v[28:29], 0, s[24:25]
	v_readlane_b32 s24, v253, 10
	global_load_dwordx2 v[96:97], v[40:41], off
	v_readlane_b32 s25, v253, 11
	s_nop 1
	v_lshl_add_u64 v[40:41], v[28:29], 0, s[24:25]
	v_readlane_b32 s24, v253, 13
	global_load_dwordx2 v[72:73], v[40:41], off
	v_readlane_b32 s25, v253, 14
	s_nop 1
	v_lshl_add_u64 v[40:41], v[28:29], 0, s[24:25]
	v_readlane_b32 s24, v254, 7
	global_load_dwordx2 v[68:69], v[40:41], off
	v_readlane_b32 s25, v254, 8
	s_nop 1
	v_lshl_add_u64 v[40:41], v[28:29], 0, s[24:25]
	v_readlane_b32 s24, v254, 9
	global_load_dwordx2 v[62:63], v[40:41], off
	v_readlane_b32 s25, v254, 10
	s_nop 1
	v_lshl_add_u64 v[40:41], v[28:29], 0, s[24:25]
	v_readlane_b32 s24, v254, 11
	global_load_dwordx2 v[56:57], v[40:41], off
	v_readlane_b32 s25, v254, 12
	s_nop 1
	v_lshl_add_u64 v[40:41], v[28:29], 0, s[24:25]
	v_readlane_b32 s24, v254, 13
	global_load_dwordx2 v[52:53], v[40:41], off
	v_readlane_b32 s25, v254, 14
	s_nop 1
	v_lshl_add_u64 v[40:41], v[28:29], 0, s[24:25]
	v_readlane_b32 s24, v254, 15
	global_load_dwordx2 v[48:49], v[40:41], off
	v_readlane_b32 s25, v254, 16
	s_nop 1
	v_lshl_add_u64 v[40:41], v[28:29], 0, s[24:25]
	global_load_dwordx2 v[44:45], v[40:41], off
	v_lshl_add_u64 v[40:41], v[28:29], 0, s[18:19]
	global_load_dwordx2 v[40:41], v[40:41], off
	ds_read_b128 v[74:77], v1 offset:64
	ds_read_b128 v[90:93], v1 offset:80
	ds_read_b128 v[100:103], v1 offset:96
	ds_read_b128 v[104:107], v1 offset:112
	v_readlane_b32 s18, v254, 19
	s_waitcnt lgkmcnt(3)
	v_pk_mul_f32 v[122:123], v[26:27], v[74:75] op_sel_hi:[1,0]
	v_pk_mul_f32 v[126:127], v[26:27], v[74:75] op_sel:[0,1]
	s_waitcnt vmcnt(15)
	v_pk_fma_f32 v[108:109], v[110:111], v[122:123], v[108:109]
	v_pk_mul_f32 v[124:125], v[110:111], v[122:123]
	v_pk_fma_f32 v[58:59], v[58:59], v[88:89], v[108:109] neg_lo:[1,0,0] neg_hi:[1,0,0]
	s_waitcnt vmcnt(14)
	v_pk_mul_f32 v[128:129], v[112:113], v[126:127]
	v_pk_fma_f32 v[88:89], v[58:59], s[12:13], v[124:125] op_sel_hi:[1,0,1] neg_lo:[0,0,1] neg_hi:[0,0,1]
	v_pk_fma_f32 v[58:59], v[112:113], v[126:127], v[58:59]
	v_pk_mul_f32 v[130:131], v[26:27], v[76:77] op_sel_hi:[1,0]
	v_pk_fma_f32 v[50:51], v[50:51], v[84:85], v[58:59] neg_lo:[1,0,0] neg_hi:[1,0,0]
	v_mov_b32_e32 v66, v77
	v_pk_fma_f32 v[58:59], v[50:51], s[12:13], v[128:129] op_sel_hi:[1,0,1] neg_lo:[0,0,1] neg_hi:[0,0,1]
	s_waitcnt vmcnt(13)
	v_pk_fma_f32 v[50:51], v[114:115], v[130:131], v[50:51]
	v_pk_mul_f32 v[132:133], v[114:115], v[130:131]
	v_pk_mul_f32 v[134:135], v[26:27], v[66:67] op_sel_hi:[1,0]
	v_pk_fma_f32 v[46:47], v[46:47], v[78:79], v[50:51] neg_lo:[1,0,0] neg_hi:[1,0,0]
	s_waitcnt vmcnt(12)
	v_pk_mul_f32 v[136:137], v[116:117], v[134:135]
	v_pk_fma_f32 v[50:51], v[46:47], s[12:13], v[132:133] op_sel_hi:[1,0,1] neg_lo:[0,0,1] neg_hi:[0,0,1]
	v_pk_fma_f32 v[46:47], v[116:117], v[134:135], v[46:47]
	s_waitcnt lgkmcnt(2)
	v_pk_mul_f32 v[138:139], v[26:27], v[90:91] op_sel_hi:[1,0]
	v_pk_fma_f32 v[38:39], v[38:39], v[82:83], v[46:47] neg_lo:[1,0,0] neg_hi:[1,0,0]
	s_waitcnt vmcnt(11)
	v_pk_mul_f32 v[140:141], v[118:119], v[138:139]
	v_pk_fma_f32 v[46:47], v[38:39], s[12:13], v[136:137] op_sel_hi:[1,0,1] neg_lo:[0,0,1] neg_hi:[0,0,1]
	v_pk_fma_f32 v[38:39], v[118:119], v[138:139], v[38:39]
	v_pk_mul_f32 v[142:143], v[26:27], v[90:91] op_sel:[0,1]
	v_pk_fma_f32 v[38:39], v[42:43], v[70:71], v[38:39] neg_lo:[1,0,0] neg_hi:[1,0,0]
	v_cvt_pk_bf16_f32 v108, v88, v89
	v_lshl_add_u64 v[88:89], v[24:25], 0, s[8:9]
	s_lshl_b32 s8, s1, 1
	v_pk_fma_f32 v[42:43], v[38:39], s[12:13], v[140:141] op_sel_hi:[1,0,1] neg_lo:[0,0,1] neg_hi:[0,0,1]
	s_waitcnt vmcnt(10)
	v_pk_fma_f32 v[38:39], v[120:121], v[142:143], v[38:39]
	v_pk_mul_f32 v[144:145], v[120:121], v[142:143]
	v_pk_mul_f32 v[146:147], v[26:27], v[92:93] op_sel_hi:[1,0]
	global_store_dword v[88:89], v108, off nt
	v_cvt_pk_bf16_f32 v84, v58, v59
	v_lshl_add_u64 v[58:59], v[24:25], 0, s[8:9]
	s_mov_b32 s1, s7
	s_lshl_b32 s8, s7, 1
	v_readlane_b32 s7, v252, 58
	v_pk_fma_f32 v[36:37], v[36:37], v[64:65], v[38:39] neg_lo:[1,0,0] neg_hi:[1,0,0]
	v_mov_b32_e32 v66, v93
	global_store_dword v[58:59], v84, off nt
	v_cvt_pk_bf16_f32 v58, v50, v51
	v_lshl_add_u64 v[50:51], v[24:25], 0, s[8:9]
	s_lshl_b32 s8, s7, 1
	v_readlane_b32 s7, v252, 61
	v_pk_fma_f32 v[38:39], v[36:37], s[12:13], v[144:145] op_sel_hi:[1,0,1] neg_lo:[0,0,1] neg_hi:[0,0,1]
	s_waitcnt vmcnt(11)
	v_pk_fma_f32 v[36:37], v[98:99], v[146:147], v[36:37]
	v_pk_mul_f32 v[148:149], v[98:99], v[146:147]
	v_pk_mul_f32 v[150:151], v[26:27], v[66:67] op_sel_hi:[1,0]
	global_store_dword v[50:51], v58, off nt
	v_cvt_pk_bf16_f32 v50, v46, v47
	v_lshl_add_u64 v[46:47], v[24:25], 0, s[8:9]
	s_lshl_b32 s8, s7, 1
	v_readlane_b32 s7, v253, 0
	v_pk_fma_f32 v[34:35], v[34:35], v[60:61], v[36:37] neg_lo:[1,0,0] neg_hi:[1,0,0]
	global_store_dword v[46:47], v50, off nt
	v_cvt_pk_bf16_f32 v46, v42, v43
	v_lshl_add_u64 v[42:43], v[24:25], 0, s[8:9]
	s_lshl_b32 s8, s7, 1
	v_pk_fma_f32 v[36:37], v[34:35], s[12:13], v[148:149] op_sel_hi:[1,0,1] neg_lo:[0,0,1] neg_hi:[0,0,1]
	v_readlane_b32 s7, v253, 3
	s_waitcnt vmcnt(12)
	v_pk_fma_f32 v[34:35], v[96:97], v[150:151], v[34:35]
	v_pk_mul_f32 v[152:153], v[96:97], v[150:151]
	s_waitcnt lgkmcnt(1)
	v_pk_mul_f32 v[94:95], v[26:27], v[100:101] op_sel_hi:[1,0]
	global_store_dword v[42:43], v46, off nt
	v_cvt_pk_bf16_f32 v42, v38, v39
	v_lshl_add_u64 v[38:39], v[24:25], 0, s[8:9]
	s_lshl_b32 s8, s7, 1
	v_pk_fma_f32 v[30:31], v[30:31], v[54:55], v[34:35] neg_lo:[1,0,0] neg_hi:[1,0,0]
	v_readlane_b32 s7, v253, 6
	global_store_dword v[38:39], v42, off nt
	v_cvt_pk_bf16_f32 v38, v36, v37
	v_lshl_add_u64 v[36:37], v[24:25], 0, s[8:9]
	v_pk_fma_f32 v[34:35], v[30:31], s[12:13], v[152:153] op_sel_hi:[1,0,1] neg_lo:[0,0,1] neg_hi:[0,0,1]
	s_lshl_b32 s8, s7, 1
	s_waitcnt vmcnt(13)
	v_pk_fma_f32 v[30:31], v[72:73], v[94:95], v[30:31]
	v_pk_mul_f32 v[154:155], v[72:73], v[94:95]
	v_pk_mul_f32 v[92:93], v[26:27], v[100:101] op_sel:[0,1]
	global_store_dword v[36:37], v38, off nt
	v_cvt_pk_bf16_f32 v36, v34, v35
	v_lshl_add_u64 v[34:35], v[24:25], 0, s[8:9]
	v_pk_fma_f32 v[30:31], v[110:111], v[122:123], v[30:31] neg_lo:[1,0,0] neg_hi:[1,0,0]
	v_readlane_b32 s7, v253, 9
	global_store_dword v[34:35], v36, off nt
	v_pk_fma_f32 v[34:35], v[30:31], s[12:13], v[154:155] op_sel_hi:[1,0,1] neg_lo:[0,0,1] neg_hi:[0,0,1]
	s_lshl_b32 s8, s7, 1
	s_waitcnt vmcnt(14)
	v_pk_fma_f32 v[30:31], v[68:69], v[92:93], v[30:31]
	v_pk_mul_f32 v[100:101], v[68:69], v[92:93]
	v_pk_mul_f32 v[90:91], v[26:27], v[102:103] op_sel_hi:[1,0]
	v_cvt_pk_bf16_f32 v36, v34, v35
	v_lshl_add_u64 v[34:35], v[24:25], 0, s[8:9]
	v_pk_fma_f32 v[30:31], v[112:113], v[126:127], v[30:31] neg_lo:[1,0,0] neg_hi:[1,0,0]
	v_readlane_b32 s7, v253, 12
	v_mov_b32_e32 v66, v103
	global_store_dword v[34:35], v36, off nt
	v_pk_fma_f32 v[34:35], v[30:31], s[12:13], v[100:101] op_sel_hi:[1,0,1] neg_lo:[0,0,1] neg_hi:[0,0,1]
	s_lshl_b32 s8, s7, 1
	s_waitcnt vmcnt(14)
	v_pk_fma_f32 v[30:31], v[62:63], v[90:91], v[30:31]
	v_pk_mul_f32 v[156:157], v[62:63], v[90:91]
	v_pk_mul_f32 v[86:87], v[26:27], v[66:67] op_sel_hi:[1,0]
	v_cvt_pk_bf16_f32 v36, v34, v35
	v_lshl_add_u64 v[34:35], v[24:25], 0, s[8:9]
	v_pk_fma_f32 v[30:31], v[114:115], v[130:131], v[30:31] neg_lo:[1,0,0] neg_hi:[1,0,0]
	v_readlane_b32 s7, v253, 15
	global_store_dword v[34:35], v36, off nt
	v_pk_fma_f32 v[34:35], v[30:31], s[12:13], v[156:157] op_sel_hi:[1,0,1] neg_lo:[0,0,1] neg_hi:[0,0,1]
	s_lshl_b32 s8, s7, 1
	s_waitcnt vmcnt(14)
	v_pk_fma_f32 v[30:31], v[56:57], v[86:87], v[30:31]
	v_pk_mul_f32 v[102:103], v[56:57], v[86:87]
	s_waitcnt lgkmcnt(0)
	v_pk_mul_f32 v[80:81], v[26:27], v[104:105] op_sel_hi:[1,0]
	v_cvt_pk_bf16_f32 v36, v34, v35
	v_lshl_add_u64 v[34:35], v[24:25], 0, s[8:9]
	v_pk_fma_f32 v[30:31], v[116:117], v[134:135], v[30:31] neg_lo:[1,0,0] neg_hi:[1,0,0]
	v_readlane_b32 s7, v253, 16
	global_store_dword v[34:35], v36, off nt
	v_pk_fma_f32 v[34:35], v[30:31], s[12:13], v[102:103] op_sel_hi:[1,0,1] neg_lo:[0,0,1] neg_hi:[0,0,1]
	s_lshl_b32 s8, s7, 1
	s_waitcnt vmcnt(14)
	v_pk_fma_f32 v[30:31], v[52:53], v[80:81], v[30:31]
	v_pk_mul_f32 v[158:159], v[52:53], v[80:81]
	v_pk_mul_f32 v[76:77], v[26:27], v[104:105] op_sel:[0,1]
	v_cvt_pk_bf16_f32 v36, v34, v35
	v_lshl_add_u64 v[34:35], v[24:25], 0, s[8:9]
	v_pk_fma_f32 v[30:31], v[118:119], v[138:139], v[30:31] neg_lo:[1,0,0] neg_hi:[1,0,0]
	v_readlane_b32 s7, v253, 17
	global_store_dword v[34:35], v36, off nt
	v_pk_fma_f32 v[34:35], v[30:31], s[12:13], v[158:159] op_sel_hi:[1,0,1] neg_lo:[0,0,1] neg_hi:[0,0,1]
	s_lshl_b32 s8, s7, 1
	s_waitcnt vmcnt(14)
	v_pk_fma_f32 v[30:31], v[48:49], v[76:77], v[30:31]
	v_pk_mul_f32 v[104:105], v[48:49], v[76:77]
	v_pk_mul_f32 v[74:75], v[26:27], v[106:107] op_sel_hi:[1,0]
	v_cvt_pk_bf16_f32 v36, v34, v35
	v_lshl_add_u64 v[34:35], v[24:25], 0, s[8:9]
	v_pk_fma_f32 v[30:31], v[120:121], v[142:143], v[30:31] neg_lo:[1,0,0] neg_hi:[1,0,0]
	v_mov_b32_e32 v66, v107
	global_store_dword v[34:35], v36, off nt
	v_pk_fma_f32 v[34:35], v[30:31], s[12:13], v[104:105] op_sel_hi:[1,0,1] neg_lo:[0,0,1] neg_hi:[0,0,1]
	s_lshl_b32 s8, s15, 1
	s_waitcnt vmcnt(14)
	v_pk_fma_f32 v[30:31], v[44:45], v[74:75], v[30:31]
	v_pk_mul_f32 v[160:161], v[44:45], v[74:75]
	v_pk_mul_f32 v[66:67], v[26:27], v[66:67] op_sel_hi:[1,0]
	v_cvt_pk_bf16_f32 v36, v34, v35
	v_lshl_add_u64 v[34:35], v[24:25], 0, s[8:9]
	v_pk_fma_f32 v[30:31], v[98:99], v[146:147], v[30:31] neg_lo:[1,0,0] neg_hi:[1,0,0]
	global_store_dword v[34:35], v36, off nt
	v_pk_fma_f32 v[34:35], v[30:31], s[12:13], v[160:161] op_sel_hi:[1,0,1] neg_lo:[0,0,1] neg_hi:[0,0,1]
	v_readlane_b32 s7, v253, 19
	s_waitcnt vmcnt(14)
	v_pk_fma_f32 v[30:31], v[40:41], v[66:67], v[30:31]
	v_pk_mul_f32 v[106:107], v[40:41], v[66:67]
	s_lshl_b32 s8, s7, 1
	v_pk_fma_f32 v[112:113], v[96:97], v[150:151], v[30:31] neg_lo:[1,0,0] neg_hi:[1,0,0]
	v_cvt_pk_bf16_f32 v36, v34, v35
	v_lshl_add_u64 v[34:35], v[24:25], 0, s[8:9]
	v_pk_fma_f32 v[30:31], v[112:113], s[12:13], v[106:107] op_sel_hi:[1,0,1] neg_lo:[0,0,1] neg_hi:[0,0,1]
	s_lshl_b32 s8, s4, 1
	global_store_dword v[34:35], v36, off nt
	v_cvt_pk_bf16_f32 v34, v30, v31
	v_lshl_add_u64 v[30:31], v[24:25], 0, s[8:9]
	v_readlane_b32 s19, v254, 20
	global_store_dword v[30:31], v34, off nt
	v_readlane_b32 s4, v254, 49
	v_lshl_add_u64 v[30:31], v[28:29], 0, s[18:19]
	v_readlane_b32 s18, v254, 21
	global_load_dwordx2 v[114:115], v[30:31], off
	v_readlane_b32 s19, v254, 22
	v_readlane_b32 s5, v254, 50
	v_readlane_b32 s7, v253, 20
	v_lshl_add_u64 v[30:31], v[28:29], 0, s[18:19]
	v_readlane_b32 s18, v254, 23
	global_load_dwordx2 v[116:117], v[30:31], off
	v_readlane_b32 s19, v254, 24
	s_lshl_b32 s8, s7, 1
	v_readlane_b32 s7, v253, 22
	v_lshl_add_u64 v[30:31], v[28:29], 0, s[18:19]
	v_readlane_b32 s18, v254, 25
	global_load_dwordx2 v[118:119], v[30:31], off
	v_readlane_b32 s19, v254, 26
	s_mov_b64 s[24:25], -1
	s_nop 0
	v_lshl_add_u64 v[30:31], v[28:29], 0, s[18:19]
	v_readlane_b32 s18, v254, 27
	global_load_dwordx2 v[120:121], v[30:31], off
	v_readlane_b32 s19, v254, 28
	s_nop 1
	v_lshl_add_u64 v[30:31], v[28:29], 0, s[18:19]
	v_readlane_b32 s18, v254, 29
	global_load_dwordx2 v[122:123], v[30:31], off
	v_readlane_b32 s19, v254, 30
	s_nop 1
	v_lshl_add_u64 v[30:31], v[28:29], 0, s[18:19]
	v_readlane_b32 s18, v254, 31
	global_load_dwordx2 v[124:125], v[30:31], off
	v_readlane_b32 s19, v254, 32
	s_nop 1
	v_lshl_add_u64 v[30:31], v[28:29], 0, s[18:19]
	v_readlane_b32 s18, v254, 33
	global_load_dwordx2 v[98:99], v[30:31], off
	v_readlane_b32 s19, v254, 34
	s_nop 1
	v_lshl_add_u64 v[30:31], v[28:29], 0, s[18:19]
	v_readlane_b32 s18, v254, 35
	global_load_dwordx2 v[96:97], v[30:31], off
	v_readlane_b32 s19, v254, 36
	s_nop 1
	v_lshl_add_u64 v[30:31], v[28:29], 0, s[18:19]
	v_readlane_b32 s18, v254, 37
	global_load_dwordx2 v[58:59], v[30:31], off
	v_readlane_b32 s19, v254, 38
	s_nop 1
	v_lshl_add_u64 v[30:31], v[28:29], 0, s[18:19]
	v_readlane_b32 s18, v254, 39
	global_load_dwordx2 v[54:55], v[30:31], off
	v_readlane_b32 s19, v254, 40
	s_nop 1
	v_lshl_add_u64 v[30:31], v[28:29], 0, s[18:19]
	v_readlane_b32 s18, v254, 41
	global_load_dwordx2 v[46:47], v[30:31], off
	v_readlane_b32 s19, v254, 42
	s_nop 1
	v_lshl_add_u64 v[30:31], v[28:29], 0, s[18:19]
	v_readlane_b32 s18, v254, 43
	global_load_dwordx2 v[42:43], v[30:31], off
	v_readlane_b32 s19, v254, 44
	s_nop 1
	v_lshl_add_u64 v[30:31], v[28:29], 0, s[18:19]
	v_readlane_b32 s18, v254, 45
	global_load_dwordx2 v[38:39], v[30:31], off
	v_readlane_b32 s19, v254, 46
	s_nop 1
	v_lshl_add_u64 v[30:31], v[28:29], 0, s[18:19]
	v_readlane_b32 s18, v254, 47
	global_load_dwordx2 v[36:37], v[30:31], off
	v_readlane_b32 s19, v254, 48
	s_nop 1
	v_lshl_add_u64 v[30:31], v[28:29], 0, s[18:19]
	global_load_dwordx2 v[34:35], v[30:31], off
	v_lshl_add_u64 v[30:31], v[28:29], 0, s[4:5]
	global_load_dwordx2 v[30:31], v[30:31], off
	ds_read_b128 v[82:85], v1 offset:128
	ds_read_b128 v[100:103], v1 offset:144
	ds_read_b128 v[104:107], v1 offset:160
	ds_read_b128 v[108:111], v1 offset:176
	s_mov_b64 s[18:19], s[48:49]
	s_waitcnt lgkmcnt(3)
	v_pk_mul_f32 v[126:127], v[26:27], v[82:83] op_sel_hi:[1,0]
	v_pk_mul_f32 v[130:131], v[26:27], v[82:83] op_sel:[0,1]
	s_waitcnt vmcnt(15)
	v_pk_fma_f32 v[112:113], v[114:115], v[126:127], v[112:113]
	v_pk_mul_f32 v[128:129], v[114:115], v[126:127]
	v_pk_fma_f32 v[72:73], v[72:73], v[94:95], v[112:113] neg_lo:[1,0,0] neg_hi:[1,0,0]
	s_waitcnt vmcnt(14)
	v_pk_mul_f32 v[132:133], v[116:117], v[130:131]
	v_pk_fma_f32 v[94:95], v[72:73], s[12:13], v[128:129] op_sel_hi:[1,0,1] neg_lo:[0,0,1] neg_hi:[0,0,1]
	v_pk_fma_f32 v[72:73], v[116:117], v[130:131], v[72:73]
	v_pk_mul_f32 v[134:135], v[26:27], v[84:85] op_sel_hi:[1,0]
	v_pk_fma_f32 v[68:69], v[68:69], v[92:93], v[72:73] neg_lo:[1,0,0] neg_hi:[1,0,0]
	v_mov_b32_e32 v50, v85
	v_pk_fma_f32 v[72:73], v[68:69], s[12:13], v[132:133] op_sel_hi:[1,0,1] neg_lo:[0,0,1] neg_hi:[0,0,1]
	s_waitcnt vmcnt(13)
	v_pk_fma_f32 v[68:69], v[118:119], v[134:135], v[68:69]
	v_pk_mul_f32 v[136:137], v[118:119], v[134:135]
	v_pk_mul_f32 v[138:139], v[26:27], v[50:51] op_sel_hi:[1,0]
	v_pk_fma_f32 v[62:63], v[62:63], v[90:91], v[68:69] neg_lo:[1,0,0] neg_hi:[1,0,0]
	s_waitcnt vmcnt(12)
	v_pk_mul_f32 v[140:141], v[120:121], v[138:139]
	v_pk_fma_f32 v[68:69], v[62:63], s[12:13], v[136:137] op_sel_hi:[1,0,1] neg_lo:[0,0,1] neg_hi:[0,0,1]
	v_pk_fma_f32 v[62:63], v[120:121], v[138:139], v[62:63]
	s_waitcnt lgkmcnt(2)
	v_pk_mul_f32 v[142:143], v[26:27], v[100:101] op_sel_hi:[1,0]
	v_pk_fma_f32 v[56:57], v[56:57], v[86:87], v[62:63] neg_lo:[1,0,0] neg_hi:[1,0,0]
	s_waitcnt vmcnt(11)
	v_pk_mul_f32 v[144:145], v[122:123], v[142:143]
	v_pk_fma_f32 v[62:63], v[56:57], s[12:13], v[140:141] op_sel_hi:[1,0,1] neg_lo:[0,0,1] neg_hi:[0,0,1]
	v_pk_fma_f32 v[56:57], v[122:123], v[142:143], v[56:57]
	v_pk_mul_f32 v[100:101], v[26:27], v[100:101] op_sel:[0,1]
	v_pk_fma_f32 v[52:53], v[52:53], v[80:81], v[56:57] neg_lo:[1,0,0] neg_hi:[1,0,0]
	v_cvt_pk_bf16_f32 v112, v94, v95
	v_lshl_add_u64 v[94:95], v[24:25], 0, s[8:9]
	s_lshl_b32 s8, s29, 1
	v_pk_fma_f32 v[56:57], v[52:53], s[12:13], v[144:145] op_sel_hi:[1,0,1] neg_lo:[0,0,1] neg_hi:[0,0,1]
	s_waitcnt vmcnt(10)
	v_pk_fma_f32 v[52:53], v[124:125], v[100:101], v[52:53]
	v_pk_mul_f32 v[146:147], v[124:125], v[100:101]
	v_pk_mul_f32 v[148:149], v[26:27], v[102:103] op_sel_hi:[1,0]
	global_store_dword v[94:95], v112, off nt
	v_cvt_pk_bf16_f32 v92, v72, v73
	v_lshl_add_u64 v[72:73], v[24:25], 0, s[8:9]
	s_lshl_b32 s8, s7, 1
	v_pk_fma_f32 v[48:49], v[48:49], v[76:77], v[52:53] neg_lo:[1,0,0] neg_hi:[1,0,0]
	v_mov_b32_e32 v50, v103
	global_store_dword v[72:73], v92, off nt
	v_cvt_pk_bf16_f32 v72, v68, v69
	v_lshl_add_u64 v[68:69], v[24:25], 0, s[8:9]
	s_lshl_b32 s8, s30, 1
	v_readlane_b32 s7, v253, 24
	v_pk_fma_f32 v[52:53], v[48:49], s[12:13], v[146:147] op_sel_hi:[1,0,1] neg_lo:[0,0,1] neg_hi:[0,0,1]
	s_waitcnt vmcnt(11)
	v_pk_fma_f32 v[48:49], v[98:99], v[148:149], v[48:49]
	v_pk_mul_f32 v[150:151], v[98:99], v[148:149]
	v_pk_mul_f32 v[102:103], v[26:27], v[50:51] op_sel_hi:[1,0]
	global_store_dword v[68:69], v72, off nt
	v_cvt_pk_bf16_f32 v68, v62, v63
	v_lshl_add_u64 v[62:63], v[24:25], 0, s[8:9]
	s_lshl_b32 s8, s7, 1
	v_pk_fma_f32 v[44:45], v[44:45], v[74:75], v[48:49] neg_lo:[1,0,0] neg_hi:[1,0,0]
	global_store_dword v[62:63], v68, off nt
	v_cvt_pk_bf16_f32 v62, v56, v57
	v_lshl_add_u64 v[56:57], v[24:25], 0, s[8:9]
	s_lshl_b32 s8, s79, 1
	v_pk_fma_f32 v[48:49], v[44:45], s[12:13], v[150:151] op_sel_hi:[1,0,1] neg_lo:[0,0,1] neg_hi:[0,0,1]
	s_waitcnt vmcnt(12)
	v_pk_fma_f32 v[44:45], v[96:97], v[102:103], v[44:45]
	v_pk_mul_f32 v[152:153], v[96:97], v[102:103]
	s_waitcnt lgkmcnt(1)
	v_pk_mul_f32 v[88:89], v[26:27], v[104:105] op_sel_hi:[1,0]
	global_store_dword v[56:57], v62, off nt
	v_cvt_pk_bf16_f32 v56, v52, v53
	v_lshl_add_u64 v[52:53], v[24:25], 0, s[8:9]
	s_lshl_b32 s8, s85, 1
	v_pk_fma_f32 v[40:41], v[40:41], v[66:67], v[44:45] neg_lo:[1,0,0] neg_hi:[1,0,0]
	v_readlane_b32 s7, v253, 25
	global_store_dword v[52:53], v56, off nt
	v_cvt_pk_bf16_f32 v52, v48, v49
	v_lshl_add_u64 v[48:49], v[24:25], 0, s[8:9]
	v_pk_fma_f32 v[44:45], v[40:41], s[12:13], v[152:153] op_sel_hi:[1,0,1] neg_lo:[0,0,1] neg_hi:[0,0,1]
	s_lshl_b32 s8, s7, 1
	s_waitcnt vmcnt(13)
	v_pk_fma_f32 v[40:41], v[58:59], v[88:89], v[40:41]
	v_pk_mul_f32 v[154:155], v[58:59], v[88:89]
	v_pk_mul_f32 v[84:85], v[26:27], v[104:105] op_sel:[0,1]
	global_store_dword v[48:49], v52, off nt
	v_cvt_pk_bf16_f32 v48, v44, v45
	v_lshl_add_u64 v[44:45], v[24:25], 0, s[8:9]
	v_pk_fma_f32 v[40:41], v[114:115], v[126:127], v[40:41] neg_lo:[1,0,0] neg_hi:[1,0,0]
	v_readlane_b32 s7, v253, 26
	global_store_dword v[44:45], v48, off nt
	v_pk_fma_f32 v[44:45], v[40:41], s[12:13], v[154:155] op_sel_hi:[1,0,1] neg_lo:[0,0,1] neg_hi:[0,0,1]
	s_lshl_b32 s8, s7, 1
	s_waitcnt vmcnt(14)
	v_pk_fma_f32 v[40:41], v[54:55], v[84:85], v[40:41]
	v_pk_mul_f32 v[104:105], v[54:55], v[84:85]
	v_pk_mul_f32 v[82:83], v[26:27], v[106:107] op_sel_hi:[1,0]
	v_cvt_pk_bf16_f32 v48, v44, v45
	v_lshl_add_u64 v[44:45], v[24:25], 0, s[8:9]
	v_pk_fma_f32 v[40:41], v[116:117], v[130:131], v[40:41] neg_lo:[1,0,0] neg_hi:[1,0,0]
	v_mov_b32_e32 v50, v107
	global_store_dword v[44:45], v48, off nt
	v_pk_fma_f32 v[44:45], v[40:41], s[12:13], v[104:105] op_sel_hi:[1,0,1] neg_lo:[0,0,1] neg_hi:[0,0,1]
	s_lshl_b32 s8, s84, 1
	s_waitcnt vmcnt(14)
	v_pk_fma_f32 v[40:41], v[46:47], v[82:83], v[40:41]
	v_pk_mul_f32 v[156:157], v[46:47], v[82:83]
	v_pk_mul_f32 v[78:79], v[26:27], v[50:51] op_sel_hi:[1,0]
	v_cvt_pk_bf16_f32 v48, v44, v45
	v_lshl_add_u64 v[44:45], v[24:25], 0, s[8:9]
	v_pk_fma_f32 v[40:41], v[118:119], v[134:135], v[40:41] neg_lo:[1,0,0] neg_hi:[1,0,0]
	v_readlane_b32 s7, v253, 28
	global_store_dword v[44:45], v48, off nt
	v_pk_fma_f32 v[44:45], v[40:41], s[12:13], v[156:157] op_sel_hi:[1,0,1] neg_lo:[0,0,1] neg_hi:[0,0,1]
	s_lshl_b32 s8, s7, 1
	s_waitcnt vmcnt(14)
	v_pk_fma_f32 v[40:41], v[42:43], v[78:79], v[40:41]
	v_pk_mul_f32 v[106:107], v[42:43], v[78:79]
	s_waitcnt lgkmcnt(0)
	v_pk_mul_f32 v[70:71], v[26:27], v[108:109] op_sel_hi:[1,0]
	v_cvt_pk_bf16_f32 v48, v44, v45
	v_lshl_add_u64 v[44:45], v[24:25], 0, s[8:9]
	v_pk_fma_f32 v[40:41], v[120:121], v[138:139], v[40:41] neg_lo:[1,0,0] neg_hi:[1,0,0]
	v_readlane_b32 s7, v253, 29
	global_store_dword v[44:45], v48, off nt
	v_pk_fma_f32 v[44:45], v[40:41], s[12:13], v[106:107] op_sel_hi:[1,0,1] neg_lo:[0,0,1] neg_hi:[0,0,1]
	s_lshl_b32 s8, s7, 1
	s_waitcnt vmcnt(14)
	v_pk_fma_f32 v[40:41], v[38:39], v[70:71], v[40:41]
	v_pk_mul_f32 v[158:159], v[38:39], v[70:71]
	v_pk_mul_f32 v[64:65], v[26:27], v[108:109] op_sel:[0,1]
	v_cvt_pk_bf16_f32 v48, v44, v45
	v_lshl_add_u64 v[44:45], v[24:25], 0, s[8:9]
	v_pk_fma_f32 v[40:41], v[122:123], v[142:143], v[40:41] neg_lo:[1,0,0] neg_hi:[1,0,0]
	v_readlane_b32 s7, v253, 30
	global_store_dword v[44:45], v48, off nt
	v_pk_fma_f32 v[44:45], v[40:41], s[12:13], v[158:159] op_sel_hi:[1,0,1] neg_lo:[0,0,1] neg_hi:[0,0,1]
	s_lshl_b32 s8, s7, 1
	s_waitcnt vmcnt(14)
	v_pk_fma_f32 v[40:41], v[36:37], v[64:65], v[40:41]
	v_pk_mul_f32 v[108:109], v[36:37], v[64:65]
	v_pk_mul_f32 v[60:61], v[26:27], v[110:111] op_sel_hi:[1,0]
	v_cvt_pk_bf16_f32 v48, v44, v45
	v_lshl_add_u64 v[44:45], v[24:25], 0, s[8:9]
	v_pk_fma_f32 v[40:41], v[124:125], v[100:101], v[40:41] neg_lo:[1,0,0] neg_hi:[1,0,0]
	v_readlane_b32 s7, v253, 31
	v_mov_b32_e32 v50, v111
	global_store_dword v[44:45], v48, off nt
	v_pk_fma_f32 v[44:45], v[40:41], s[12:13], v[108:109] op_sel_hi:[1,0,1] neg_lo:[0,0,1] neg_hi:[0,0,1]
	s_lshl_b32 s8, s7, 1
	s_waitcnt vmcnt(14)
	v_pk_fma_f32 v[40:41], v[34:35], v[60:61], v[40:41]
	v_pk_mul_f32 v[160:161], v[34:35], v[60:61]
	v_pk_mul_f32 v[50:51], v[26:27], v[50:51] op_sel_hi:[1,0]
	v_cvt_pk_bf16_f32 v48, v44, v45
	v_lshl_add_u64 v[44:45], v[24:25], 0, s[8:9]
	v_pk_fma_f32 v[40:41], v[98:99], v[148:149], v[40:41] neg_lo:[1,0,0] neg_hi:[1,0,0]
	v_readlane_b32 s7, v253, 33
	global_store_dword v[44:45], v48, off nt
	v_pk_fma_f32 v[44:45], v[40:41], s[12:13], v[160:161] op_sel_hi:[1,0,1] neg_lo:[0,0,1] neg_hi:[0,0,1]
	s_lshl_b32 s8, s7, 1
	s_waitcnt vmcnt(14)
	v_pk_fma_f32 v[40:41], v[30:31], v[50:51], v[40:41]
	v_pk_mul_f32 v[110:111], v[30:31], v[50:51]
	v_cvt_pk_bf16_f32 v48, v44, v45
	v_lshl_add_u64 v[44:45], v[24:25], 0, s[8:9]
	v_pk_fma_f32 v[40:41], v[96:97], v[102:103], v[40:41] neg_lo:[1,0,0] neg_hi:[1,0,0]
	v_readlane_b32 s7, v253, 34
	global_store_dword v[44:45], v48, off nt
	v_pk_fma_f32 v[44:45], v[40:41], s[12:13], v[110:111] op_sel_hi:[1,0,1] neg_lo:[0,0,1] neg_hi:[0,0,1]
	s_lshl_b32 s8, s7, 1
	v_cvt_pk_bf16_f32 v48, v44, v45
	v_lshl_add_u64 v[44:45], v[24:25], 0, s[8:9]
	global_store_dword v[44:45], v48, off nt
	v_lshl_add_u64 v[44:45], v[28:29], 0, s[42:43]
	global_load_dwordx2 v[44:45], v[44:45], off
	v_lshl_add_u64 v[48:49], v[28:29], 0, s[20:21]
	global_load_dwordx2 v[48:49], v[48:49], off
	v_lshl_add_u64 v[52:53], v[28:29], 0, s[16:17]
	global_load_dwordx2 v[52:53], v[52:53], off
	v_lshl_add_u64 v[56:57], v[28:29], 0, s[44:45]
	global_load_dwordx2 v[56:57], v[56:57], off
	v_lshl_add_u64 v[62:63], v[28:29], 0, s[18:19]
	global_load_dwordx2 v[62:63], v[62:63], off
	v_lshl_add_u64 v[66:67], v[28:29], 0, s[94:95]
	global_load_dwordx2 v[76:77], v[66:67], off
	v_lshl_add_u64 v[66:67], v[28:29], 0, s[92:93]
	global_load_dwordx2 v[80:81], v[66:67], off
	v_lshl_add_u64 v[66:67], v[28:29], 0, s[86:87]
	global_load_dwordx2 v[86:87], v[66:67], off
	v_lshl_add_u64 v[66:67], v[28:29], 0, s[74:75]
	global_load_dwordx2 v[98:99], v[66:67], off
	v_lshl_add_u64 v[66:67], v[28:29], 0, s[76:77]
	global_load_dwordx2 v[100:101], v[66:67], off
	v_lshl_add_u64 v[66:67], v[28:29], 0, s[72:73]
	global_load_dwordx2 v[102:103], v[66:67], off
	v_lshl_add_u64 v[66:67], v[28:29], 0, s[66:67]
	global_load_dwordx2 v[104:105], v[66:67], off
	v_lshl_add_u64 v[66:67], v[28:29], 0, s[88:89]
	global_load_dwordx2 v[106:107], v[66:67], off
	v_lshl_add_u64 v[66:67], v[28:29], 0, s[68:69]
	global_load_dwordx2 v[108:109], v[66:67], off
	v_lshl_add_u64 v[66:67], v[28:29], 0, s[22:23]
	global_load_dwordx2 v[110:111], v[66:67], off
	v_lshl_add_u64 v[66:67], v[28:29], 0, s[96:97]
	global_load_dwordx2 v[112:113], v[66:67], off
	ds_read_b128 v[66:69], v1 offset:192
	ds_read_b128 v[72:75], v1 offset:208
	ds_read_b128 v[90:93], v1 offset:224
	ds_read_b128 v[94:97], v1 offset:240
	s_lshl_b32 s8, s39, 1
	s_waitcnt lgkmcnt(3)
	v_pk_mul_f32 v[114:115], v[26:27], v[66:67] op_sel_hi:[1,0]
	v_pk_mul_f32 v[66:67], v[26:27], v[66:67] op_sel:[0,1]
	v_pk_mul_f32 v[120:121], v[26:27], v[68:69] op_sel_hi:[1,0]
	v_mov_b32_e32 v68, v69
	v_pk_mul_f32 v[68:69], v[26:27], v[68:69] op_sel_hi:[1,0]
	s_waitcnt lgkmcnt(2)
	v_pk_mul_f32 v[126:127], v[26:27], v[72:73] op_sel_hi:[1,0]
	v_pk_mul_f32 v[72:73], v[26:27], v[72:73] op_sel:[0,1]
	v_readlane_b32 s7, v253, 36
	v_pk_mul_f32 v[132:133], v[26:27], v[74:75] op_sel_hi:[1,0]
	v_mov_b32_e32 v74, v75
	v_pk_mul_f32 v[74:75], v[26:27], v[74:75] op_sel_hi:[1,0]
	s_waitcnt lgkmcnt(1)
	v_pk_mul_f32 v[138:139], v[26:27], v[90:91] op_sel_hi:[1,0]
	v_pk_mul_f32 v[90:91], v[26:27], v[90:91] op_sel:[0,1]
	v_pk_mul_f32 v[144:145], v[26:27], v[92:93] op_sel_hi:[1,0]
	v_mov_b32_e32 v92, v93
	v_pk_mul_f32 v[92:93], v[26:27], v[92:93] op_sel_hi:[1,0]
	s_waitcnt lgkmcnt(0)
	v_pk_mul_f32 v[150:151], v[26:27], v[94:95] op_sel_hi:[1,0]
	v_pk_mul_f32 v[94:95], v[26:27], v[94:95] op_sel:[0,1]
	v_pk_mul_f32 v[156:157], v[26:27], v[96:97] op_sel_hi:[1,0]
	v_mov_b32_e32 v96, v97
	v_pk_mul_f32 v[96:97], v[26:27], v[96:97] op_sel_hi:[1,0]
	s_mov_b32 s4, s28
	s_mov_b32 s5, s1
	s_mov_b64 s[28:29], 0
	s_waitcnt vmcnt(15)
	v_pk_fma_f32 v[40:41], v[44:45], v[114:115], v[40:41]
	v_pk_mul_f32 v[116:117], v[44:45], v[114:115]
	v_pk_fma_f32 v[40:41], v[58:59], v[88:89], v[40:41] neg_lo:[1,0,0] neg_hi:[1,0,0]
	s_waitcnt vmcnt(14)
	v_pk_mul_f32 v[118:119], v[48:49], v[66:67]
	v_pk_fma_f32 v[58:59], v[40:41], s[12:13], v[116:117] op_sel_hi:[1,0,1] neg_lo:[0,0,1] neg_hi:[0,0,1]
	v_pk_fma_f32 v[40:41], v[48:49], v[66:67], v[40:41]
	s_waitcnt vmcnt(13)
	v_pk_mul_f32 v[122:123], v[52:53], v[120:121]
	v_pk_fma_f32 v[40:41], v[54:55], v[84:85], v[40:41] neg_lo:[1,0,0] neg_hi:[1,0,0]
	s_waitcnt vmcnt(12)
	v_pk_mul_f32 v[124:125], v[56:57], v[68:69]
	v_pk_fma_f32 v[54:55], v[40:41], s[12:13], v[118:119] op_sel_hi:[1,0,1] neg_lo:[0,0,1] neg_hi:[0,0,1]
	v_pk_fma_f32 v[40:41], v[52:53], v[120:121], v[40:41]
	s_waitcnt vmcnt(11)
	v_pk_mul_f32 v[128:129], v[62:63], v[126:127]
	v_pk_fma_f32 v[40:41], v[46:47], v[82:83], v[40:41] neg_lo:[1,0,0] neg_hi:[1,0,0]
	v_cvt_pk_bf16_f32 v1, v58, v59
	v_lshl_add_u64 v[58:59], v[24:25], 0, s[8:9]
	v_pk_fma_f32 v[46:47], v[40:41], s[12:13], v[122:123] op_sel_hi:[1,0,1] neg_lo:[0,0,1] neg_hi:[0,0,1]
	v_pk_fma_f32 v[40:41], v[56:57], v[68:69], v[40:41]
	s_lshl_b32 s8, s81, 1
	v_pk_fma_f32 v[40:41], v[42:43], v[78:79], v[40:41] neg_lo:[1,0,0] neg_hi:[1,0,0]
	s_waitcnt vmcnt(10)
	v_pk_mul_f32 v[130:131], v[76:77], v[72:73]
	v_pk_fma_f32 v[42:43], v[40:41], s[12:13], v[124:125] op_sel_hi:[1,0,1] neg_lo:[0,0,1] neg_hi:[0,0,1]
	v_pk_fma_f32 v[40:41], v[62:63], v[126:127], v[40:41]
	global_store_dword v[58:59], v1, off nt
	v_pk_fma_f32 v[38:39], v[38:39], v[70:71], v[40:41] neg_lo:[1,0,0] neg_hi:[1,0,0]
	v_cvt_pk_bf16_f32 v1, v54, v55
	v_lshl_add_u64 v[54:55], v[24:25], 0, s[8:9]
	v_pk_fma_f32 v[40:41], v[38:39], s[12:13], v[128:129] op_sel_hi:[1,0,1] neg_lo:[0,0,1] neg_hi:[0,0,1]
	v_pk_fma_f32 v[38:39], v[76:77], v[72:73], v[38:39]
	s_lshl_b32 s8, s7, 1
	v_readlane_b32 s7, v253, 37
	v_pk_fma_f32 v[36:37], v[36:37], v[64:65], v[38:39] neg_lo:[1,0,0] neg_hi:[1,0,0]
	global_store_dword v[54:55], v1, off nt
	v_cvt_pk_bf16_f32 v1, v46, v47
	v_lshl_add_u64 v[46:47], v[24:25], 0, s[8:9]
	s_lshl_b32 s8, s7, 1
	v_readlane_b32 s7, v253, 38
	v_pk_fma_f32 v[38:39], v[36:37], s[12:13], v[130:131] op_sel_hi:[1,0,1] neg_lo:[0,0,1] neg_hi:[0,0,1]
	s_waitcnt vmcnt(11)
	v_pk_fma_f32 v[36:37], v[80:81], v[132:133], v[36:37]
	v_pk_mul_f32 v[134:135], v[80:81], v[132:133]
	global_store_dword v[46:47], v1, off nt
	v_cvt_pk_bf16_f32 v1, v42, v43
	v_lshl_add_u64 v[42:43], v[24:25], 0, s[8:9]
	s_lshl_b32 s8, s7, 1
	v_readlane_b32 s7, v253, 41
	v_pk_fma_f32 v[34:35], v[34:35], v[60:61], v[36:37] neg_lo:[1,0,0] neg_hi:[1,0,0]
	global_store_dword v[42:43], v1, off nt
	v_cvt_pk_bf16_f32 v1, v40, v41
	v_lshl_add_u64 v[40:41], v[24:25], 0, s[8:9]
	s_lshl_b32 s8, s7, 1
	v_pk_fma_f32 v[36:37], v[34:35], s[12:13], v[134:135] op_sel_hi:[1,0,1] neg_lo:[0,0,1] neg_hi:[0,0,1]
	s_waitcnt vmcnt(12)
	v_pk_fma_f32 v[34:35], v[86:87], v[74:75], v[34:35]
	v_pk_mul_f32 v[136:137], v[86:87], v[74:75]
	global_store_dword v[40:41], v1, off nt
	v_cvt_pk_bf16_f32 v1, v38, v39
	v_lshl_add_u64 v[38:39], v[24:25], 0, s[8:9]
	s_lshl_b32 s8, s34, 1
	v_pk_fma_f32 v[30:31], v[30:31], v[50:51], v[34:35] neg_lo:[1,0,0] neg_hi:[1,0,0]
	v_readlane_b32 s7, v253, 42
	global_store_dword v[38:39], v1, off nt
	v_cvt_pk_bf16_f32 v1, v36, v37
	v_lshl_add_u64 v[36:37], v[24:25], 0, s[8:9]
	v_pk_fma_f32 v[34:35], v[30:31], s[12:13], v[136:137] op_sel_hi:[1,0,1] neg_lo:[0,0,1] neg_hi:[0,0,1]
	s_lshl_b32 s8, s7, 1
	s_waitcnt vmcnt(13)
	v_pk_fma_f32 v[30:31], v[98:99], v[138:139], v[30:31]
	v_pk_mul_f32 v[140:141], v[98:99], v[138:139]
	global_store_dword v[36:37], v1, off nt
	v_cvt_pk_bf16_f32 v1, v34, v35
	v_lshl_add_u64 v[34:35], v[24:25], 0, s[8:9]
	v_pk_fma_f32 v[30:31], v[44:45], v[114:115], v[30:31] neg_lo:[1,0,0] neg_hi:[1,0,0]
	global_store_dword v[34:35], v1, off nt
	v_pk_fma_f32 v[34:35], v[30:31], s[12:13], v[140:141] op_sel_hi:[1,0,1] neg_lo:[0,0,1] neg_hi:[0,0,1]
	s_lshl_b32 s8, s35, 1
	s_waitcnt vmcnt(14)
	v_pk_fma_f32 v[30:31], v[100:101], v[90:91], v[30:31]
	v_pk_mul_f32 v[142:143], v[100:101], v[90:91]
	v_cvt_pk_bf16_f32 v1, v34, v35
	v_lshl_add_u64 v[34:35], v[24:25], 0, s[8:9]
	v_pk_fma_f32 v[30:31], v[48:49], v[66:67], v[30:31] neg_lo:[1,0,0] neg_hi:[1,0,0]
	global_store_dword v[34:35], v1, off nt
	v_pk_fma_f32 v[34:35], v[30:31], s[12:13], v[142:143] op_sel_hi:[1,0,1] neg_lo:[0,0,1] neg_hi:[0,0,1]
	s_lshl_b32 s8, s90, 1
	s_waitcnt vmcnt(14)
	v_pk_fma_f32 v[30:31], v[102:103], v[144:145], v[30:31]
	v_pk_mul_f32 v[146:147], v[102:103], v[144:145]
	v_cvt_pk_bf16_f32 v1, v34, v35
	v_lshl_add_u64 v[34:35], v[24:25], 0, s[8:9]
	v_pk_fma_f32 v[30:31], v[52:53], v[120:121], v[30:31] neg_lo:[1,0,0] neg_hi:[1,0,0]
	v_readlane_b32 s7, v253, 43
	global_store_dword v[34:35], v1, off nt
	v_pk_fma_f32 v[34:35], v[30:31], s[12:13], v[146:147] op_sel_hi:[1,0,1] neg_lo:[0,0,1] neg_hi:[0,0,1]
	s_lshl_b32 s8, s7, 1
	s_waitcnt vmcnt(14)
	v_pk_fma_f32 v[30:31], v[104:105], v[92:93], v[30:31]
	v_pk_mul_f32 v[148:149], v[104:105], v[92:93]
	v_cvt_pk_bf16_f32 v1, v34, v35
	v_lshl_add_u64 v[34:35], v[24:25], 0, s[8:9]
	v_pk_fma_f32 v[30:31], v[56:57], v[68:69], v[30:31] neg_lo:[1,0,0] neg_hi:[1,0,0]
	global_store_dword v[34:35], v1, off nt
	v_pk_fma_f32 v[34:35], v[30:31], s[12:13], v[148:149] op_sel_hi:[1,0,1] neg_lo:[0,0,1] neg_hi:[0,0,1]
	s_lshl_b32 s8, s52, 1
	s_waitcnt vmcnt(14)
	v_pk_fma_f32 v[30:31], v[106:107], v[150:151], v[30:31]
	v_pk_mul_f32 v[152:153], v[106:107], v[150:151]
	v_cvt_pk_bf16_f32 v1, v34, v35
	v_lshl_add_u64 v[34:35], v[24:25], 0, s[8:9]
	v_pk_fma_f32 v[30:31], v[62:63], v[126:127], v[30:31] neg_lo:[1,0,0] neg_hi:[1,0,0]
	global_store_dword v[34:35], v1, off nt
	v_pk_fma_f32 v[34:35], v[30:31], s[12:13], v[152:153] op_sel_hi:[1,0,1] neg_lo:[0,0,1] neg_hi:[0,0,1]
	s_lshl_b32 s8, s91, 1
	s_waitcnt vmcnt(14)
	v_pk_fma_f32 v[30:31], v[108:109], v[94:95], v[30:31]
	v_pk_mul_f32 v[154:155], v[108:109], v[94:95]
	v_cvt_pk_bf16_f32 v1, v34, v35
	v_lshl_add_u64 v[34:35], v[24:25], 0, s[8:9]
	v_pk_fma_f32 v[30:31], v[76:77], v[72:73], v[30:31] neg_lo:[1,0,0] neg_hi:[1,0,0]
	global_store_dword v[34:35], v1, off nt
	v_pk_fma_f32 v[34:35], v[30:31], s[12:13], v[154:155] op_sel_hi:[1,0,1] neg_lo:[0,0,1] neg_hi:[0,0,1]
	s_lshl_b32 s8, s64, 1
	s_waitcnt vmcnt(14)
	v_pk_fma_f32 v[30:31], v[110:111], v[156:157], v[30:31]
	v_pk_mul_f32 v[158:159], v[110:111], v[156:157]
	v_cvt_pk_bf16_f32 v1, v34, v35
	v_lshl_add_u64 v[34:35], v[24:25], 0, s[8:9]
	v_pk_fma_f32 v[30:31], v[80:81], v[132:133], v[30:31] neg_lo:[1,0,0] neg_hi:[1,0,0]
	global_store_dword v[34:35], v1, off nt
	v_pk_fma_f32 v[34:35], v[30:31], s[12:13], v[158:159] op_sel_hi:[1,0,1] neg_lo:[0,0,1] neg_hi:[0,0,1]
	s_lshl_b32 s8, s65, 1
	s_waitcnt vmcnt(14)
	v_pk_fma_f32 v[30:31], v[112:113], v[96:97], v[30:31]
	v_pk_mul_f32 v[160:161], v[112:113], v[96:97]
	v_cvt_pk_bf16_f32 v1, v34, v35
	v_lshl_add_u64 v[34:35], v[24:25], 0, s[8:9]
	v_pk_fma_f32 v[30:31], v[86:87], v[74:75], v[30:31] neg_lo:[1,0,0] neg_hi:[1,0,0]
	global_store_dword v[34:35], v1, off nt
	v_pk_fma_f32 v[30:31], v[30:31], s[12:13], v[160:161] op_sel_hi:[1,0,1] neg_lo:[0,0,1] neg_hi:[0,0,1]
	s_nop 0
	v_cvt_pk_bf16_f32 v163, v30, v31
	s_branch .LBB0_241

.LBB0_244:
	v_readlane_b32 s2, v251, 49
	v_readlane_b32 s3, v251, 50
	v_readlane_b32 s1, v252, 1
	s_mov_b64 s[24:25], -1
	v_lshl_add_u64 v[30:31], v[28:29], 0, s[2:3]
	v_readlane_b32 s2, v252, 9
	v_readlane_b32 s3, v252, 10
	v_mov_b32_e32 v1, s1
	v_readlane_b32 s1, v252, 3
	v_lshl_add_u64 v[34:35], v[28:29], 0, s[2:3]
	v_readlane_b32 s2, v252, 13
	v_readlane_b32 s3, v252, 14
	s_lshl_b32 s8, s1, 1
	v_readlane_b32 s1, v252, 7
	v_lshl_add_u64 v[36:37], v[28:29], 0, s[2:3]
	v_readlane_b32 s2, v252, 17
	v_readlane_b32 s3, v252, 18
	v_lshl_add_u64 v[92:93], v[24:25], 0, s[8:9]
	s_lshl_b32 s8, s1, 1
	v_lshl_add_u64 v[38:39], v[28:29], 0, s[2:3]
	global_load_dwordx2 v[80:81], v[30:31], off
	global_load_dwordx2 v[82:83], v[34:35], off
	global_load_dwordx2 v[84:85], v[36:37], off
	global_load_dwordx2 v[86:87], v[38:39], off
	v_readlane_b32 s2, v252, 21
	v_readlane_b32 s3, v252, 22
	v_readlane_b32 s1, v252, 11
	s_nop 0
	v_lshl_add_u64 v[30:31], v[28:29], 0, s[2:3]
	v_readlane_b32 s2, v252, 25
	v_readlane_b32 s3, v252, 26
	s_nop 1
	v_lshl_add_u64 v[34:35], v[28:29], 0, s[2:3]
	v_readlane_b32 s2, v252, 28
	v_readlane_b32 s3, v252, 29
	s_nop 1
	v_lshl_add_u64 v[36:37], v[28:29], 0, s[2:3]
	v_readlane_b32 s2, v252, 31
	v_readlane_b32 s3, v252, 32
	s_nop 1
	v_lshl_add_u64 v[38:39], v[28:29], 0, s[2:3]
	global_load_dwordx2 v[88:89], v[30:31], off
	global_load_dwordx2 v[90:91], v[34:35], off
	global_load_dwordx2 v[60:61], v[36:37], off
	global_load_dwordx2 v[46:47], v[38:39], off
	v_readlane_b32 s2, v252, 34
	v_readlane_b32 s3, v252, 35
	s_nop 1
	v_lshl_add_u64 v[30:31], v[28:29], 0, s[2:3]
	v_readlane_b32 s2, v252, 37
	v_readlane_b32 s3, v252, 38
	s_nop 1
	v_lshl_add_u64 v[34:35], v[28:29], 0, s[2:3]
	v_readlane_b32 s2, v252, 40
	v_readlane_b32 s3, v252, 41
	s_nop 1
	v_lshl_add_u64 v[36:37], v[28:29], 0, s[2:3]
	v_readlane_b32 s2, v252, 43
	v_readlane_b32 s3, v252, 44
	s_nop 1
	v_lshl_add_u64 v[38:39], v[28:29], 0, s[2:3]
	global_load_dwordx2 v[52:53], v[30:31], off
	global_load_dwordx2 v[44:45], v[34:35], off
	global_load_dwordx2 v[42:43], v[36:37], off
	global_load_dwordx2 v[40:41], v[38:39], off
	v_readlane_b32 s2, v251, 37
	v_readlane_b32 s3, v251, 38
	s_nop 1
	v_lshl_add_u64 v[30:31], v[28:29], 0, s[2:3]
	v_readlane_b32 s2, v254, 1
	v_readlane_b32 s3, v254, 2
	s_nop 1
	v_lshl_add_u64 v[34:35], v[28:29], 0, s[2:3]
	v_readlane_b32 s2, v254, 3
	v_readlane_b32 s3, v254, 4
	s_nop 1
	v_lshl_add_u64 v[48:49], v[28:29], 0, s[2:3]
	v_readlane_b32 s2, v254, 5
	v_readlane_b32 s3, v254, 6
	s_nop 1
	v_lshl_add_u64 v[50:51], v[28:29], 0, s[2:3]
	global_load_dwordx2 v[38:39], v[30:31], off
	global_load_dwordx2 v[36:37], v[34:35], off
	s_nop 0
	global_load_dwordx2 v[34:35], v[48:49], off
	global_load_dwordx2 v[30:31], v[50:51], off
	v_pk_add_f32 v[48:49], v[66:67], 0 op_sel_hi:[1,0]
	v_readlane_b32 s2, v252, 51
	v_pk_add_f32 v[54:55], v[64:65], v[48:49]
	ds_read_b128 v[48:51], v1
	ds_read_b128 v[68:71], v1 offset:16
	ds_read_b128 v[72:75], v1 offset:32
	ds_read_b128 v[76:79], v1 offset:48
	v_pk_add_f32 v[54:55], v[62:63], v[54:55]
	s_waitcnt lgkmcnt(3)
	v_pk_mul_f32 v[96:97], v[26:27], v[48:49] op_sel_hi:[1,0]
	v_pk_add_f32 v[94:95], v[56:57], v[54:55]
	v_pk_mul_f32 v[98:99], v[26:27], v[48:49] op_sel:[0,1]
	v_mov_b32_e32 v48, v51
	s_waitcnt lgkmcnt(0)
	v_pk_mul_f32 v[58:59], v[26:27], v[76:77] op_sel_hi:[1,0]
	v_pk_mul_f32 v[54:55], v[26:27], v[76:77] op_sel:[0,1]
	v_mov_b32_e32 v76, v79
	v_pk_mul_f32 v[100:101], v[26:27], v[50:51] op_sel_hi:[1,0]
	s_waitcnt vmcnt(15)
	v_pk_fma_f32 v[94:95], v[80:81], v[96:97], v[94:95]
	v_pk_mul_f32 v[50:51], v[26:27], v[78:79] op_sel_hi:[1,0]
	v_pk_mul_f32 v[78:79], v[26:27], v[48:49] op_sel_hi:[1,0]
	v_pk_mul_f32 v[48:49], v[26:27], v[76:77] op_sel_hi:[1,0]
	v_pk_mul_f32 v[76:77], v[80:81], v[96:97]
	v_pk_add_f32 v[66:67], v[94:95], v[66:67] neg_lo:[0,1] neg_hi:[0,1]
	s_waitcnt vmcnt(14)
	v_pk_mul_f32 v[110:111], v[82:83], v[98:99]
	v_pk_fma_f32 v[76:77], v[18:19], v[66:67], v[76:77] neg_lo:[0,0,1] neg_hi:[0,0,1]
	v_pk_fma_f32 v[66:67], v[82:83], v[98:99], v[66:67]
	s_waitcnt vmcnt(13)
	v_pk_mul_f32 v[112:113], v[84:85], v[100:101]
	v_pk_add_f32 v[64:65], v[66:67], v[64:65] neg_lo:[0,1] neg_hi:[0,1]
	v_cvt_pk_bf16_f32 v76, v76, v77
	v_pk_mul_f32 v[102:103], v[26:27], v[68:69] op_sel_hi:[1,0]
	v_pk_fma_f32 v[66:67], v[20:21], v[64:65], v[110:111] neg_lo:[0,0,1] neg_hi:[0,0,1]
	v_pk_fma_f32 v[64:65], v[84:85], v[100:101], v[64:65]
	s_waitcnt vmcnt(12)
	v_pk_mul_f32 v[114:115], v[86:87], v[78:79]
	v_pk_add_f32 v[62:63], v[64:65], v[62:63] neg_lo:[0,1] neg_hi:[0,1]
	global_store_dword v[92:93], v76, off nt
	v_pk_fma_f32 v[64:65], v[22:23], v[62:63], v[112:113] neg_lo:[0,0,1] neg_hi:[0,0,1]
	v_pk_fma_f32 v[62:63], v[86:87], v[78:79], v[62:63]
	v_cvt_pk_bf16_f32 v76, v66, v67
	v_lshl_add_u64 v[66:67], v[24:25], 0, s[8:9]
	s_lshl_b32 s8, s1, 1
	v_pk_add_f32 v[56:57], v[62:63], v[56:57] neg_lo:[0,1] neg_hi:[0,1]
	v_readlane_b32 s1, v252, 15
	global_store_dword v[66:67], v76, off nt
	v_cvt_pk_bf16_f32 v66, v64, v65
	v_lshl_add_u64 v[64:65], v[24:25], 0, s[8:9]
	v_pk_fma_f32 v[62:63], v[56:57], s[14:15], v[114:115] op_sel_hi:[1,0,1] neg_lo:[0,0,1] neg_hi:[0,0,1]
	s_lshl_b32 s8, s1, 1
	s_waitcnt vmcnt(13)
	v_pk_fma_f32 v[56:57], v[88:89], v[102:103], v[56:57]
	v_pk_mul_f32 v[68:69], v[26:27], v[68:69] op_sel:[0,1]
	v_pk_mul_f32 v[116:117], v[88:89], v[102:103]
	global_store_dword v[64:65], v66, off nt
	v_cvt_pk_bf16_f32 v64, v62, v63
	v_lshl_add_u64 v[62:63], v[24:25], 0, s[8:9]
	v_pk_fma_f32 v[56:57], v[80:81], v[96:97], v[56:57] neg_lo:[1,0,0] neg_hi:[1,0,0]
	v_readlane_b32 s1, v252, 19
	global_store_dword v[62:63], v64, off nt
	v_pk_fma_f32 v[62:63], v[56:57], s[14:15], v[116:117] op_sel_hi:[1,0,1] neg_lo:[0,0,1] neg_hi:[0,0,1]
	s_lshl_b32 s8, s1, 1
	s_waitcnt vmcnt(14)
	v_pk_fma_f32 v[56:57], v[90:91], v[68:69], v[56:57]
	v_pk_mul_f32 v[104:105], v[26:27], v[70:71] op_sel_hi:[1,0]
	v_pk_mul_f32 v[118:119], v[90:91], v[68:69]
	v_cvt_pk_bf16_f32 v64, v62, v63
	v_lshl_add_u64 v[62:63], v[24:25], 0, s[8:9]
	v_pk_fma_f32 v[56:57], v[82:83], v[98:99], v[56:57] neg_lo:[1,0,0] neg_hi:[1,0,0]
	v_readlane_b32 s1, v252, 23
	v_mov_b32_e32 v70, v71
	global_store_dword v[62:63], v64, off nt
	v_pk_fma_f32 v[62:63], v[56:57], s[14:15], v[118:119] op_sel_hi:[1,0,1] neg_lo:[0,0,1] neg_hi:[0,0,1]
	s_lshl_b32 s8, s1, 1
	s_waitcnt vmcnt(14)
	v_pk_fma_f32 v[56:57], v[60:61], v[104:105], v[56:57]
	v_pk_mul_f32 v[70:71], v[26:27], v[70:71] op_sel_hi:[1,0]
	v_pk_mul_f32 v[120:121], v[60:61], v[104:105]
	v_cvt_pk_bf16_f32 v64, v62, v63
	v_lshl_add_u64 v[62:63], v[24:25], 0, s[8:9]
	v_pk_fma_f32 v[56:57], v[84:85], v[100:101], v[56:57] neg_lo:[1,0,0] neg_hi:[1,0,0]
	v_readlane_b32 s1, v252, 27
	global_store_dword v[62:63], v64, off nt
	v_pk_fma_f32 v[62:63], v[56:57], s[14:15], v[120:121] op_sel_hi:[1,0,1] neg_lo:[0,0,1] neg_hi:[0,0,1]
	s_lshl_b32 s8, s1, 1
	s_waitcnt vmcnt(14)
	v_pk_fma_f32 v[56:57], v[46:47], v[70:71], v[56:57]
	v_pk_mul_f32 v[106:107], v[26:27], v[72:73] op_sel_hi:[1,0]
	v_pk_mul_f32 v[122:123], v[46:47], v[70:71]
	v_cvt_pk_bf16_f32 v64, v62, v63
	v_lshl_add_u64 v[62:63], v[24:25], 0, s[8:9]
	v_pk_fma_f32 v[56:57], v[86:87], v[78:79], v[56:57] neg_lo:[1,0,0] neg_hi:[1,0,0]
	v_readlane_b32 s1, v252, 30
	global_store_dword v[62:63], v64, off nt
	v_pk_fma_f32 v[62:63], v[56:57], s[14:15], v[122:123] op_sel_hi:[1,0,1] neg_lo:[0,0,1] neg_hi:[0,0,1]
	s_lshl_b32 s8, s1, 1
	s_waitcnt vmcnt(14)
	v_pk_fma_f32 v[56:57], v[52:53], v[106:107], v[56:57]
	v_pk_mul_f32 v[72:73], v[26:27], v[72:73] op_sel:[0,1]
	v_pk_mul_f32 v[124:125], v[52:53], v[106:107]
	v_cvt_pk_bf16_f32 v64, v62, v63
	v_lshl_add_u64 v[62:63], v[24:25], 0, s[8:9]
	v_pk_fma_f32 v[56:57], v[88:89], v[102:103], v[56:57] neg_lo:[1,0,0] neg_hi:[1,0,0]
	v_readlane_b32 s1, v252, 33
	global_store_dword v[62:63], v64, off nt
	v_pk_fma_f32 v[62:63], v[56:57], s[14:15], v[124:125] op_sel_hi:[1,0,1] neg_lo:[0,0,1] neg_hi:[0,0,1]
	s_lshl_b32 s8, s1, 1
	s_waitcnt vmcnt(14)
	v_pk_fma_f32 v[56:57], v[44:45], v[72:73], v[56:57]
	v_pk_mul_f32 v[108:109], v[26:27], v[74:75] op_sel_hi:[1,0]
	v_pk_mul_f32 v[126:127], v[44:45], v[72:73]
	v_cvt_pk_bf16_f32 v64, v62, v63
	v_lshl_add_u64 v[62:63], v[24:25], 0, s[8:9]
	v_pk_fma_f32 v[56:57], v[90:91], v[68:69], v[56:57] neg_lo:[1,0,0] neg_hi:[1,0,0]
	v_mov_b32_e32 v74, v75
	global_store_dword v[62:63], v64, off nt
	v_pk_fma_f32 v[62:63], v[56:57], s[14:15], v[126:127] op_sel_hi:[1,0,1] neg_lo:[0,0,1] neg_hi:[0,0,1]
	s_waitcnt vmcnt(14)
	v_pk_fma_f32 v[56:57], v[42:43], v[108:109], v[56:57]
	v_pk_mul_f32 v[74:75], v[26:27], v[74:75] op_sel_hi:[1,0]
	v_pk_mul_f32 v[128:129], v[42:43], v[108:109]
	v_pk_fma_f32 v[56:57], v[60:61], v[104:105], v[56:57] neg_lo:[1,0,0] neg_hi:[1,0,0]
	s_waitcnt vmcnt(13)
	v_pk_mul_f32 v[130:131], v[40:41], v[74:75]
	v_pk_fma_f32 v[60:61], v[56:57], s[14:15], v[128:129] op_sel_hi:[1,0,1] neg_lo:[0,0,1] neg_hi:[0,0,1]
	v_pk_fma_f32 v[56:57], v[40:41], v[74:75], v[56:57]
	s_waitcnt vmcnt(12)
	v_pk_mul_f32 v[132:133], v[38:39], v[58:59]
	v_pk_fma_f32 v[46:47], v[46:47], v[70:71], v[56:57] neg_lo:[1,0,0] neg_hi:[1,0,0]
	v_readlane_b32 s1, v252, 36
	v_pk_fma_f32 v[56:57], v[46:47], s[14:15], v[130:131] op_sel_hi:[1,0,1] neg_lo:[0,0,1] neg_hi:[0,0,1]
	v_pk_fma_f32 v[46:47], v[38:39], v[58:59], v[46:47]
	s_lshl_b32 s8, s1, 1
	v_pk_fma_f32 v[46:47], v[52:53], v[106:107], v[46:47] neg_lo:[1,0,0] neg_hi:[1,0,0]
	v_readlane_b32 s1, v252, 39
	v_pk_fma_f32 v[52:53], v[46:47], s[14:15], v[132:133] op_sel_hi:[1,0,1] neg_lo:[0,0,1] neg_hi:[0,0,1]
	s_waitcnt vmcnt(11)
	v_pk_fma_f32 v[46:47], v[36:37], v[54:55], v[46:47]
	v_pk_mul_f32 v[134:135], v[36:37], v[54:55]
	v_cvt_pk_bf16_f32 v64, v62, v63
	v_lshl_add_u64 v[62:63], v[24:25], 0, s[8:9]
	s_lshl_b32 s8, s1, 1
	v_readlane_b32 s1, v252, 42
	v_pk_fma_f32 v[44:45], v[44:45], v[72:73], v[46:47] neg_lo:[1,0,0] neg_hi:[1,0,0]
	global_store_dword v[62:63], v64, off nt
	v_cvt_pk_bf16_f32 v62, v60, v61
	v_lshl_add_u64 v[60:61], v[24:25], 0, s[8:9]
	s_lshl_b32 s8, s1, 1
	v_readlane_b32 s1, v252, 45
	v_pk_fma_f32 v[46:47], v[44:45], s[14:15], v[134:135] op_sel_hi:[1,0,1] neg_lo:[0,0,1] neg_hi:[0,0,1]
	s_waitcnt vmcnt(11)
	v_pk_fma_f32 v[44:45], v[34:35], v[50:51], v[44:45]
	v_pk_mul_f32 v[136:137], v[34:35], v[50:51]
	global_store_dword v[60:61], v62, off nt
	v_cvt_pk_bf16_f32 v60, v56, v57
	v_lshl_add_u64 v[56:57], v[24:25], 0, s[8:9]
	s_lshl_b32 s8, s1, 1
	v_readlane_b32 s1, v252, 47
	v_pk_fma_f32 v[42:43], v[42:43], v[108:109], v[44:45] neg_lo:[1,0,0] neg_hi:[1,0,0]
	global_store_dword v[56:57], v60, off nt
	v_cvt_pk_bf16_f32 v56, v52, v53
	v_lshl_add_u64 v[52:53], v[24:25], 0, s[8:9]
	s_lshl_b32 s8, s1, 1
	v_pk_fma_f32 v[44:45], v[42:43], s[14:15], v[136:137] op_sel_hi:[1,0,1] neg_lo:[0,0,1] neg_hi:[0,0,1]
	v_readlane_b32 s1, v252, 48
	s_waitcnt vmcnt(12)
	v_pk_fma_f32 v[42:43], v[30:31], v[48:49], v[42:43]
	v_pk_mul_f32 v[138:139], v[30:31], v[48:49]
	global_store_dword v[52:53], v56, off nt
	v_cvt_pk_bf16_f32 v52, v46, v47
	v_lshl_add_u64 v[46:47], v[24:25], 0, s[8:9]
	s_lshl_b32 s8, s1, 1
	v_pk_fma_f32 v[76:77], v[40:41], v[74:75], v[42:43] neg_lo:[1,0,0] neg_hi:[1,0,0]
	v_readlane_b32 s1, v252, 49
	global_store_dword v[46:47], v52, off nt
	v_cvt_pk_bf16_f32 v46, v44, v45
	v_lshl_add_u64 v[44:45], v[24:25], 0, s[8:9]
	v_pk_fma_f32 v[40:41], v[76:77], s[14:15], v[138:139] op_sel_hi:[1,0,1] neg_lo:[0,0,1] neg_hi:[0,0,1]
	s_lshl_b32 s8, s1, 1
	global_store_dword v[44:45], v46, off nt
	v_cvt_pk_bf16_f32 v42, v40, v41
	v_lshl_add_u64 v[40:41], v[24:25], 0, s[8:9]
	v_readlane_b32 s3, v252, 52
	global_store_dword v[40:41], v42, off nt
	v_readlane_b32 s1, v252, 50
	v_lshl_add_u64 v[40:41], v[28:29], 0, s[2:3]
	v_readlane_b32 s2, v252, 54
	global_load_dwordx2 v[78:79], v[40:41], off
	v_readlane_b32 s3, v252, 55
	s_lshl_b32 s8, s1, 1
	v_readlane_b32 s1, v252, 53
	v_lshl_add_u64 v[40:41], v[28:29], 0, s[2:3]
	v_readlane_b32 s2, v252, 56
	global_load_dwordx2 v[80:81], v[40:41], off
	v_readlane_b32 s3, v252, 57
	s_nop 1
	v_lshl_add_u64 v[40:41], v[28:29], 0, s[2:3]
	v_readlane_b32 s2, v252, 59
	global_load_dwordx2 v[82:83], v[40:41], off
	v_readlane_b32 s3, v252, 60
	s_nop 1
	v_lshl_add_u64 v[40:41], v[28:29], 0, s[2:3]
	v_readlane_b32 s2, v252, 62
	global_load_dwordx2 v[84:85], v[40:41], off
	v_readlane_b32 s3, v252, 63
	s_nop 1
	v_lshl_add_u64 v[40:41], v[28:29], 0, s[2:3]
	v_readlane_b32 s2, v253, 1
	global_load_dwordx2 v[86:87], v[40:41], off
	v_readlane_b32 s3, v253, 2
	s_nop 1
	v_lshl_add_u64 v[40:41], v[28:29], 0, s[2:3]
	v_readlane_b32 s2, v253, 4
	global_load_dwordx2 v[88:89], v[40:41], off
	v_readlane_b32 s3, v253, 5
	s_nop 1
	v_lshl_add_u64 v[40:41], v[28:29], 0, s[2:3]
	v_readlane_b32 s2, v253, 7
	global_load_dwordx2 v[90:91], v[40:41], off
	v_readlane_b32 s3, v253, 8
	s_nop 1
	v_lshl_add_u64 v[40:41], v[28:29], 0, s[2:3]
	v_readlane_b32 s2, v253, 10
	global_load_dwordx2 v[92:93], v[40:41], off
	v_readlane_b32 s3, v253, 11
	s_nop 1
	v_lshl_add_u64 v[40:41], v[28:29], 0, s[2:3]
	v_readlane_b32 s2, v253, 13
	global_load_dwordx2 v[94:95], v[40:41], off
	v_readlane_b32 s3, v253, 14
	s_nop 1
	v_lshl_add_u64 v[40:41], v[28:29], 0, s[2:3]
	v_readlane_b32 s2, v254, 7
	global_load_dwordx2 v[96:97], v[40:41], off
	v_readlane_b32 s3, v254, 8
	s_nop 1
	v_lshl_add_u64 v[40:41], v[28:29], 0, s[2:3]
	v_readlane_b32 s2, v254, 9
	global_load_dwordx2 v[98:99], v[40:41], off
	v_readlane_b32 s3, v254, 10
	s_nop 1
	v_lshl_add_u64 v[40:41], v[28:29], 0, s[2:3]
	v_readlane_b32 s2, v254, 11
	global_load_dwordx2 v[100:101], v[40:41], off
	v_readlane_b32 s3, v254, 12
	s_nop 1
	v_lshl_add_u64 v[40:41], v[28:29], 0, s[2:3]
	v_readlane_b32 s2, v254, 13
	global_load_dwordx2 v[46:47], v[40:41], off
	v_readlane_b32 s3, v254, 14
	s_nop 1
	v_lshl_add_u64 v[40:41], v[28:29], 0, s[2:3]
	v_readlane_b32 s2, v254, 15
	global_load_dwordx2 v[44:45], v[40:41], off
	v_readlane_b32 s3, v254, 16
	s_nop 1
	v_lshl_add_u64 v[40:41], v[28:29], 0, s[2:3]
	v_readlane_b32 s2, v254, 17
	global_load_dwordx2 v[42:43], v[40:41], off
	v_readlane_b32 s3, v254, 18
	s_nop 1
	v_lshl_add_u64 v[40:41], v[28:29], 0, s[2:3]
	global_load_dwordx2 v[40:41], v[40:41], off
	ds_read_b128 v[60:63], v1 offset:64
	ds_read_b128 v[64:67], v1 offset:80
	ds_read_b128 v[68:71], v1 offset:96
	ds_read_b128 v[72:75], v1 offset:112
	v_readlane_b32 s2, v254, 19
	s_waitcnt lgkmcnt(3)
	v_pk_mul_f32 v[102:103], v[26:27], v[60:61] op_sel_hi:[1,0]
	v_pk_mul_f32 v[106:107], v[26:27], v[60:61] op_sel:[0,1]
	s_waitcnt vmcnt(15)
	v_pk_fma_f32 v[76:77], v[78:79], v[102:103], v[76:77]
	v_pk_mul_f32 v[104:105], v[78:79], v[102:103]
	v_pk_fma_f32 v[38:39], v[38:39], v[58:59], v[76:77] neg_lo:[1,0,0] neg_hi:[1,0,0]
	s_waitcnt vmcnt(14)
	v_pk_mul_f32 v[108:109], v[80:81], v[106:107]
	v_pk_fma_f32 v[58:59], v[38:39], s[14:15], v[104:105] op_sel_hi:[1,0,1] neg_lo:[0,0,1] neg_hi:[0,0,1]
	v_pk_fma_f32 v[38:39], v[80:81], v[106:107], v[38:39]
	v_pk_mul_f32 v[110:111], v[26:27], v[62:63] op_sel_hi:[1,0]
	v_pk_fma_f32 v[36:37], v[36:37], v[54:55], v[38:39] neg_lo:[1,0,0] neg_hi:[1,0,0]
	v_mov_b32_e32 v52, v63
	v_pk_fma_f32 v[38:39], v[36:37], s[14:15], v[108:109] op_sel_hi:[1,0,1] neg_lo:[0,0,1] neg_hi:[0,0,1]
	s_waitcnt vmcnt(13)
	v_pk_fma_f32 v[36:37], v[82:83], v[110:111], v[36:37]
	v_pk_mul_f32 v[112:113], v[82:83], v[110:111]
	v_pk_mul_f32 v[114:115], v[26:27], v[52:53] op_sel_hi:[1,0]
	v_pk_fma_f32 v[34:35], v[34:35], v[50:51], v[36:37] neg_lo:[1,0,0] neg_hi:[1,0,0]
	v_cvt_pk_bf16_f32 v76, v58, v59
	v_lshl_add_u64 v[58:59], v[24:25], 0, s[8:9]
	s_lshl_b32 s8, s1, 1
	v_pk_fma_f32 v[36:37], v[34:35], s[14:15], v[112:113] op_sel_hi:[1,0,1] neg_lo:[0,0,1] neg_hi:[0,0,1]
	s_waitcnt vmcnt(12)
	v_pk_fma_f32 v[34:35], v[84:85], v[114:115], v[34:35]
	v_pk_mul_f32 v[116:117], v[84:85], v[114:115]
	s_waitcnt lgkmcnt(2)
	v_pk_mul_f32 v[118:119], v[26:27], v[64:65] op_sel_hi:[1,0]
	global_store_dword v[58:59], v76, off nt
	v_cvt_pk_bf16_f32 v54, v38, v39
	v_lshl_add_u64 v[38:39], v[24:25], 0, s[8:9]
	s_lshl_b32 s8, s5, 1
	v_pk_fma_f32 v[30:31], v[30:31], v[48:49], v[34:35] neg_lo:[1,0,0] neg_hi:[1,0,0]
	v_readlane_b32 s1, v252, 58
	global_store_dword v[38:39], v54, off nt
	v_cvt_pk_bf16_f32 v38, v36, v37
	v_lshl_add_u64 v[36:37], v[24:25], 0, s[8:9]
	v_pk_fma_f32 v[34:35], v[30:31], s[14:15], v[116:117] op_sel_hi:[1,0,1] neg_lo:[0,0,1] neg_hi:[0,0,1]
	s_lshl_b32 s8, s1, 1
	s_waitcnt vmcnt(13)
	v_pk_fma_f32 v[30:31], v[86:87], v[118:119], v[30:31]
	v_pk_mul_f32 v[120:121], v[86:87], v[118:119]
	v_pk_mul_f32 v[64:65], v[26:27], v[64:65] op_sel:[0,1]
	global_store_dword v[36:37], v38, off nt
	v_cvt_pk_bf16_f32 v36, v34, v35
	v_lshl_add_u64 v[34:35], v[24:25], 0, s[8:9]
	v_pk_fma_f32 v[30:31], v[78:79], v[102:103], v[30:31] neg_lo:[1,0,0] neg_hi:[1,0,0]
	v_readlane_b32 s1, v252, 61
	global_store_dword v[34:35], v36, off nt
	v_pk_fma_f32 v[34:35], v[30:31], s[14:15], v[120:121] op_sel_hi:[1,0,1] neg_lo:[0,0,1] neg_hi:[0,0,1]
	s_lshl_b32 s8, s1, 1
	s_waitcnt vmcnt(14)
	v_pk_fma_f32 v[30:31], v[88:89], v[64:65], v[30:31]
	v_pk_mul_f32 v[122:123], v[88:89], v[64:65]
	v_pk_mul_f32 v[124:125], v[26:27], v[66:67] op_sel_hi:[1,0]
	v_cvt_pk_bf16_f32 v36, v34, v35
	v_lshl_add_u64 v[34:35], v[24:25], 0, s[8:9]
	v_pk_fma_f32 v[30:31], v[80:81], v[106:107], v[30:31] neg_lo:[1,0,0] neg_hi:[1,0,0]
	v_readlane_b32 s1, v253, 0
	v_mov_b32_e32 v52, v67
	global_store_dword v[34:35], v36, off nt
	v_pk_fma_f32 v[34:35], v[30:31], s[14:15], v[122:123] op_sel_hi:[1,0,1] neg_lo:[0,0,1] neg_hi:[0,0,1]
	s_lshl_b32 s8, s1, 1
	s_waitcnt vmcnt(14)
	v_pk_fma_f32 v[30:31], v[90:91], v[124:125], v[30:31]
	v_pk_mul_f32 v[126:127], v[90:91], v[124:125]
	v_pk_mul_f32 v[66:67], v[26:27], v[52:53] op_sel_hi:[1,0]
	v_cvt_pk_bf16_f32 v36, v34, v35
	v_lshl_add_u64 v[34:35], v[24:25], 0, s[8:9]
	v_pk_fma_f32 v[30:31], v[82:83], v[110:111], v[30:31] neg_lo:[1,0,0] neg_hi:[1,0,0]
	v_readlane_b32 s1, v253, 3
	global_store_dword v[34:35], v36, off nt
	v_pk_fma_f32 v[34:35], v[30:31], s[14:15], v[126:127] op_sel_hi:[1,0,1] neg_lo:[0,0,1] neg_hi:[0,0,1]
	s_lshl_b32 s8, s1, 1
	s_waitcnt vmcnt(14)
	v_pk_fma_f32 v[30:31], v[92:93], v[66:67], v[30:31]
	v_pk_mul_f32 v[128:129], v[92:93], v[66:67]
	s_waitcnt lgkmcnt(1)
	v_pk_mul_f32 v[130:131], v[26:27], v[68:69] op_sel_hi:[1,0]
	v_cvt_pk_bf16_f32 v36, v34, v35
	v_lshl_add_u64 v[34:35], v[24:25], 0, s[8:9]
	v_pk_fma_f32 v[30:31], v[84:85], v[114:115], v[30:31] neg_lo:[1,0,0] neg_hi:[1,0,0]
	v_readlane_b32 s1, v253, 6
	global_store_dword v[34:35], v36, off nt
	v_pk_fma_f32 v[34:35], v[30:31], s[14:15], v[128:129] op_sel_hi:[1,0,1] neg_lo:[0,0,1] neg_hi:[0,0,1]
	s_lshl_b32 s8, s1, 1
	s_waitcnt vmcnt(14)
	v_pk_fma_f32 v[30:31], v[94:95], v[130:131], v[30:31]
	v_pk_mul_f32 v[132:133], v[94:95], v[130:131]
	v_pk_mul_f32 v[68:69], v[26:27], v[68:69] op_sel:[0,1]
	v_cvt_pk_bf16_f32 v36, v34, v35
	v_lshl_add_u64 v[34:35], v[24:25], 0, s[8:9]
	v_pk_fma_f32 v[30:31], v[86:87], v[118:119], v[30:31] neg_lo:[1,0,0] neg_hi:[1,0,0]
	v_readlane_b32 s1, v253, 9
	global_store_dword v[34:35], v36, off nt
	v_pk_fma_f32 v[34:35], v[30:31], s[14:15], v[132:133] op_sel_hi:[1,0,1] neg_lo:[0,0,1] neg_hi:[0,0,1]
	s_lshl_b32 s8, s1, 1
	s_waitcnt vmcnt(14)
	v_pk_fma_f32 v[30:31], v[96:97], v[68:69], v[30:31]
	v_pk_mul_f32 v[134:135], v[96:97], v[68:69]
	v_pk_mul_f32 v[136:137], v[26:27], v[70:71] op_sel_hi:[1,0]
	v_cvt_pk_bf16_f32 v36, v34, v35
	v_lshl_add_u64 v[34:35], v[24:25], 0, s[8:9]
	v_pk_fma_f32 v[30:31], v[88:89], v[64:65], v[30:31] neg_lo:[1,0,0] neg_hi:[1,0,0]
	v_readlane_b32 s1, v253, 12
	v_mov_b32_e32 v52, v71
	global_store_dword v[34:35], v36, off nt
	v_pk_fma_f32 v[34:35], v[30:31], s[14:15], v[134:135] op_sel_hi:[1,0,1] neg_lo:[0,0,1] neg_hi:[0,0,1]
	s_lshl_b32 s8, s1, 1
	s_waitcnt vmcnt(14)
	v_pk_fma_f32 v[30:31], v[98:99], v[136:137], v[30:31]
	v_pk_mul_f32 v[138:139], v[98:99], v[136:137]
	v_pk_mul_f32 v[70:71], v[26:27], v[52:53] op_sel_hi:[1,0]
	v_cvt_pk_bf16_f32 v36, v34, v35
	v_lshl_add_u64 v[34:35], v[24:25], 0, s[8:9]
	v_pk_fma_f32 v[30:31], v[90:91], v[124:125], v[30:31] neg_lo:[1,0,0] neg_hi:[1,0,0]
	v_readlane_b32 s1, v253, 15
	global_store_dword v[34:35], v36, off nt
	v_pk_fma_f32 v[34:35], v[30:31], s[14:15], v[138:139] op_sel_hi:[1,0,1] neg_lo:[0,0,1] neg_hi:[0,0,1]
	s_lshl_b32 s8, s1, 1
	s_waitcnt vmcnt(14)
	v_pk_fma_f32 v[30:31], v[100:101], v[70:71], v[30:31]
	v_pk_mul_f32 v[140:141], v[100:101], v[70:71]
	s_waitcnt lgkmcnt(0)
	v_pk_mul_f32 v[62:63], v[26:27], v[72:73] op_sel_hi:[1,0]
	v_cvt_pk_bf16_f32 v36, v34, v35
	v_lshl_add_u64 v[34:35], v[24:25], 0, s[8:9]
	v_pk_fma_f32 v[30:31], v[92:93], v[66:67], v[30:31] neg_lo:[1,0,0] neg_hi:[1,0,0]
	v_readlane_b32 s1, v253, 16
	global_store_dword v[34:35], v36, off nt
	v_pk_fma_f32 v[34:35], v[30:31], s[14:15], v[140:141] op_sel_hi:[1,0,1] neg_lo:[0,0,1] neg_hi:[0,0,1]
	s_lshl_b32 s8, s1, 1
	s_waitcnt vmcnt(14)
	v_pk_fma_f32 v[30:31], v[46:47], v[62:63], v[30:31]
	v_pk_mul_f32 v[142:143], v[46:47], v[62:63]
	v_pk_mul_f32 v[60:61], v[26:27], v[72:73] op_sel:[0,1]
	v_cvt_pk_bf16_f32 v36, v34, v35
	v_lshl_add_u64 v[34:35], v[24:25], 0, s[8:9]
	v_pk_fma_f32 v[30:31], v[94:95], v[130:131], v[30:31] neg_lo:[1,0,0] neg_hi:[1,0,0]
	v_readlane_b32 s1, v253, 17
	global_store_dword v[34:35], v36, off nt
	v_pk_fma_f32 v[34:35], v[30:31], s[14:15], v[142:143] op_sel_hi:[1,0,1] neg_lo:[0,0,1] neg_hi:[0,0,1]
	s_lshl_b32 s8, s1, 1
	s_waitcnt vmcnt(14)
	v_pk_fma_f32 v[30:31], v[44:45], v[60:61], v[30:31]
	v_pk_mul_f32 v[72:73], v[44:45], v[60:61]
	v_pk_mul_f32 v[56:57], v[26:27], v[74:75] op_sel_hi:[1,0]
	v_cvt_pk_bf16_f32 v36, v34, v35
	v_lshl_add_u64 v[34:35], v[24:25], 0, s[8:9]
	v_pk_fma_f32 v[30:31], v[96:97], v[68:69], v[30:31] neg_lo:[1,0,0] neg_hi:[1,0,0]
	v_readlane_b32 s1, v253, 18
	v_mov_b32_e32 v52, v75
	global_store_dword v[34:35], v36, off nt
	v_pk_fma_f32 v[34:35], v[30:31], s[14:15], v[72:73] op_sel_hi:[1,0,1] neg_lo:[0,0,1] neg_hi:[0,0,1]
	s_lshl_b32 s8, s1, 1
	s_waitcnt vmcnt(14)
	v_pk_fma_f32 v[30:31], v[42:43], v[56:57], v[30:31]
	v_pk_mul_f32 v[144:145], v[42:43], v[56:57]
	v_pk_mul_f32 v[52:53], v[26:27], v[52:53] op_sel_hi:[1,0]
	v_cvt_pk_bf16_f32 v36, v34, v35
	v_lshl_add_u64 v[34:35], v[24:25], 0, s[8:9]
	v_pk_fma_f32 v[30:31], v[98:99], v[136:137], v[30:31] neg_lo:[1,0,0] neg_hi:[1,0,0]
	global_store_dword v[34:35], v36, off nt
	v_pk_fma_f32 v[34:35], v[30:31], s[14:15], v[144:145] op_sel_hi:[1,0,1] neg_lo:[0,0,1] neg_hi:[0,0,1]
	v_readlane_b32 s1, v253, 19
	s_waitcnt vmcnt(14)
	v_pk_fma_f32 v[30:31], v[40:41], v[52:53], v[30:31]
	v_pk_mul_f32 v[74:75], v[40:41], v[52:53]
	s_lshl_b32 s8, s1, 1
	v_pk_fma_f32 v[76:77], v[100:101], v[70:71], v[30:31] neg_lo:[1,0,0] neg_hi:[1,0,0]
	v_cvt_pk_bf16_f32 v36, v34, v35
	v_lshl_add_u64 v[34:35], v[24:25], 0, s[8:9]
	v_pk_fma_f32 v[30:31], v[76:77], s[14:15], v[74:75] op_sel_hi:[1,0,1] neg_lo:[0,0,1] neg_hi:[0,0,1]
	s_lshl_b32 s8, s4, 1
	global_store_dword v[34:35], v36, off nt
	v_cvt_pk_bf16_f32 v34, v30, v31
	v_lshl_add_u64 v[30:31], v[24:25], 0, s[8:9]
	v_readlane_b32 s3, v254, 20
	global_store_dword v[30:31], v34, off nt
	v_readlane_b32 s1, v253, 20
	v_lshl_add_u64 v[30:31], v[28:29], 0, s[2:3]
	v_readlane_b32 s2, v254, 21
	global_load_dwordx2 v[78:79], v[30:31], off
	v_readlane_b32 s3, v254, 22
	s_lshl_b32 s8, s1, 1
	v_readlane_b32 s1, v253, 22
	v_lshl_add_u64 v[30:31], v[28:29], 0, s[2:3]
	v_readlane_b32 s2, v254, 23
	global_load_dwordx2 v[80:81], v[30:31], off
	v_readlane_b32 s3, v254, 24
	s_nop 1
	v_lshl_add_u64 v[30:31], v[28:29], 0, s[2:3]
	v_readlane_b32 s2, v254, 25
	global_load_dwordx2 v[82:83], v[30:31], off
	v_readlane_b32 s3, v254, 26
	s_nop 1
	v_lshl_add_u64 v[30:31], v[28:29], 0, s[2:3]
	v_readlane_b32 s2, v254, 27
	global_load_dwordx2 v[84:85], v[30:31], off
	v_readlane_b32 s3, v254, 28
	s_nop 1
	v_lshl_add_u64 v[30:31], v[28:29], 0, s[2:3]
	v_readlane_b32 s2, v254, 29
	global_load_dwordx2 v[86:87], v[30:31], off
	v_readlane_b32 s3, v254, 30
	s_nop 1
	v_lshl_add_u64 v[30:31], v[28:29], 0, s[2:3]
	v_readlane_b32 s2, v254, 31
	global_load_dwordx2 v[88:89], v[30:31], off
	v_readlane_b32 s3, v254, 32
	s_nop 1
	v_lshl_add_u64 v[30:31], v[28:29], 0, s[2:3]
	v_readlane_b32 s2, v254, 33
	global_load_dwordx2 v[90:91], v[30:31], off
	v_readlane_b32 s3, v254, 34
	s_nop 1
	v_lshl_add_u64 v[30:31], v[28:29], 0, s[2:3]
	v_readlane_b32 s2, v254, 35
	global_load_dwordx2 v[92:93], v[30:31], off
	v_readlane_b32 s3, v254, 36
	s_nop 1
	v_lshl_add_u64 v[30:31], v[28:29], 0, s[2:3]
	v_readlane_b32 s2, v254, 37
	global_load_dwordx2 v[94:95], v[30:31], off
	v_readlane_b32 s3, v254, 38
	s_nop 1
	v_lshl_add_u64 v[30:31], v[28:29], 0, s[2:3]
	v_readlane_b32 s2, v254, 39
	global_load_dwordx2 v[96:97], v[30:31], off
	v_readlane_b32 s3, v254, 40
	s_nop 1
	v_lshl_add_u64 v[30:31], v[28:29], 0, s[2:3]
	v_readlane_b32 s2, v254, 41
	global_load_dwordx2 v[98:99], v[30:31], off
	v_readlane_b32 s3, v254, 42
	s_nop 1
	v_lshl_add_u64 v[30:31], v[28:29], 0, s[2:3]
	v_readlane_b32 s2, v254, 43
	global_load_dwordx2 v[100:101], v[30:31], off
	v_readlane_b32 s3, v254, 44
	s_nop 1
	v_lshl_add_u64 v[30:31], v[28:29], 0, s[2:3]
	v_readlane_b32 s2, v254, 45
	global_load_dwordx2 v[38:39], v[30:31], off
	v_readlane_b32 s3, v254, 46
	s_nop 1
	v_lshl_add_u64 v[30:31], v[28:29], 0, s[2:3]
	v_readlane_b32 s2, v254, 47
	global_load_dwordx2 v[36:37], v[30:31], off
	v_readlane_b32 s3, v254, 48
	s_nop 1
	v_lshl_add_u64 v[30:31], v[28:29], 0, s[2:3]
	v_readlane_b32 s2, v254, 49
	global_load_dwordx2 v[34:35], v[30:31], off
	v_readlane_b32 s3, v254, 50
	s_nop 1
	v_lshl_add_u64 v[30:31], v[28:29], 0, s[2:3]
	global_load_dwordx2 v[30:31], v[30:31], off
	ds_read_b128 v[48:51], v1 offset:128
	ds_read_b128 v[64:67], v1 offset:144
	ds_read_b128 v[68:71], v1 offset:160
	ds_read_b128 v[72:75], v1 offset:176
	s_waitcnt lgkmcnt(3)
	v_pk_mul_f32 v[102:103], v[26:27], v[48:49] op_sel_hi:[1,0]
	s_waitcnt vmcnt(15)
	v_pk_fma_f32 v[76:77], v[78:79], v[102:103], v[76:77]
	v_pk_mul_f32 v[104:105], v[78:79], v[102:103]
	v_pk_mul_f32 v[106:107], v[26:27], v[48:49] op_sel:[0,1]
	v_pk_fma_f32 v[46:47], v[46:47], v[62:63], v[76:77] neg_lo:[1,0,0] neg_hi:[1,0,0]
	s_waitcnt vmcnt(14)
	v_pk_mul_f32 v[108:109], v[80:81], v[106:107]
	v_pk_fma_f32 v[62:63], v[46:47], s[14:15], v[104:105] op_sel_hi:[1,0,1] neg_lo:[0,0,1] neg_hi:[0,0,1]
	v_pk_fma_f32 v[46:47], v[80:81], v[106:107], v[46:47]
	v_pk_mul_f32 v[110:111], v[26:27], v[50:51] op_sel_hi:[1,0]
	v_pk_fma_f32 v[44:45], v[44:45], v[60:61], v[46:47] neg_lo:[1,0,0] neg_hi:[1,0,0]
	v_mov_b32_e32 v48, v51
	v_pk_fma_f32 v[46:47], v[44:45], s[14:15], v[108:109] op_sel_hi:[1,0,1] neg_lo:[0,0,1] neg_hi:[0,0,1]
	s_waitcnt vmcnt(13)
	v_pk_fma_f32 v[44:45], v[82:83], v[110:111], v[44:45]
	v_pk_mul_f32 v[112:113], v[82:83], v[110:111]
	v_pk_mul_f32 v[114:115], v[26:27], v[48:49] op_sel_hi:[1,0]
	v_pk_fma_f32 v[42:43], v[42:43], v[56:57], v[44:45] neg_lo:[1,0,0] neg_hi:[1,0,0]
	v_cvt_pk_bf16_f32 v76, v62, v63
	v_lshl_add_u64 v[62:63], v[24:25], 0, s[8:9]
	s_lshl_b32 s8, s82, 1
	v_pk_fma_f32 v[44:45], v[42:43], s[14:15], v[112:113] op_sel_hi:[1,0,1] neg_lo:[0,0,1] neg_hi:[0,0,1]
	s_waitcnt vmcnt(12)
	v_pk_fma_f32 v[42:43], v[84:85], v[114:115], v[42:43]
	v_pk_mul_f32 v[116:117], v[84:85], v[114:115]
	s_waitcnt lgkmcnt(2)
	v_pk_mul_f32 v[118:119], v[26:27], v[64:65] op_sel_hi:[1,0]
	global_store_dword v[62:63], v76, off nt
	v_cvt_pk_bf16_f32 v60, v46, v47
	v_lshl_add_u64 v[46:47], v[24:25], 0, s[8:9]
	s_lshl_b32 s8, s1, 1
	v_pk_fma_f32 v[40:41], v[40:41], v[52:53], v[42:43] neg_lo:[1,0,0] neg_hi:[1,0,0]
	global_store_dword v[46:47], v60, off nt
	v_cvt_pk_bf16_f32 v46, v44, v45
	v_lshl_add_u64 v[44:45], v[24:25], 0, s[8:9]
	v_pk_fma_f32 v[42:43], v[40:41], s[14:15], v[116:117] op_sel_hi:[1,0,1] neg_lo:[0,0,1] neg_hi:[0,0,1]
	s_lshl_b32 s8, s80, 1
	s_waitcnt vmcnt(13)
	v_pk_fma_f32 v[40:41], v[86:87], v[118:119], v[40:41]
	v_pk_mul_f32 v[120:121], v[86:87], v[118:119]
	v_pk_mul_f32 v[64:65], v[26:27], v[64:65] op_sel:[0,1]
	global_store_dword v[44:45], v46, off nt
	v_cvt_pk_bf16_f32 v44, v42, v43
	v_lshl_add_u64 v[42:43], v[24:25], 0, s[8:9]
	v_pk_fma_f32 v[40:41], v[78:79], v[102:103], v[40:41] neg_lo:[1,0,0] neg_hi:[1,0,0]
	v_readlane_b32 s1, v253, 24
	global_store_dword v[42:43], v44, off nt
	v_pk_fma_f32 v[42:43], v[40:41], s[14:15], v[120:121] op_sel_hi:[1,0,1] neg_lo:[0,0,1] neg_hi:[0,0,1]
	s_lshl_b32 s8, s1, 1
	s_waitcnt vmcnt(14)
	v_pk_fma_f32 v[40:41], v[88:89], v[64:65], v[40:41]
	v_pk_mul_f32 v[122:123], v[88:89], v[64:65]
	v_pk_mul_f32 v[124:125], v[26:27], v[66:67] op_sel_hi:[1,0]
	v_cvt_pk_bf16_f32 v44, v42, v43
	v_lshl_add_u64 v[42:43], v[24:25], 0, s[8:9]
	v_pk_fma_f32 v[40:41], v[80:81], v[106:107], v[40:41] neg_lo:[1,0,0] neg_hi:[1,0,0]
	v_mov_b32_e32 v48, v67
	global_store_dword v[42:43], v44, off nt
	v_pk_fma_f32 v[42:43], v[40:41], s[14:15], v[122:123] op_sel_hi:[1,0,1] neg_lo:[0,0,1] neg_hi:[0,0,1]
	s_lshl_b32 s8, s79, 1
	s_waitcnt vmcnt(14)
	v_pk_fma_f32 v[40:41], v[90:91], v[124:125], v[40:41]
	v_pk_mul_f32 v[126:127], v[90:91], v[124:125]
	v_pk_mul_f32 v[66:67], v[26:27], v[48:49] op_sel_hi:[1,0]
	v_cvt_pk_bf16_f32 v44, v42, v43
	v_lshl_add_u64 v[42:43], v[24:25], 0, s[8:9]
	v_pk_fma_f32 v[40:41], v[82:83], v[110:111], v[40:41] neg_lo:[1,0,0] neg_hi:[1,0,0]
	global_store_dword v[42:43], v44, off nt
	v_pk_fma_f32 v[42:43], v[40:41], s[14:15], v[126:127] op_sel_hi:[1,0,1] neg_lo:[0,0,1] neg_hi:[0,0,1]
	s_lshl_b32 s8, s85, 1
	s_waitcnt vmcnt(14)
	v_pk_fma_f32 v[40:41], v[92:93], v[66:67], v[40:41]
	v_pk_mul_f32 v[128:129], v[92:93], v[66:67]
	s_waitcnt lgkmcnt(1)
	v_pk_mul_f32 v[130:131], v[26:27], v[68:69] op_sel_hi:[1,0]
	v_cvt_pk_bf16_f32 v44, v42, v43
	v_lshl_add_u64 v[42:43], v[24:25], 0, s[8:9]
	v_pk_fma_f32 v[40:41], v[84:85], v[114:115], v[40:41] neg_lo:[1,0,0] neg_hi:[1,0,0]
	v_readlane_b32 s1, v253, 25
	global_store_dword v[42:43], v44, off nt
	v_pk_fma_f32 v[42:43], v[40:41], s[14:15], v[128:129] op_sel_hi:[1,0,1] neg_lo:[0,0,1] neg_hi:[0,0,1]
	s_lshl_b32 s8, s1, 1
	s_waitcnt vmcnt(14)
	v_pk_fma_f32 v[40:41], v[94:95], v[130:131], v[40:41]
	v_pk_mul_f32 v[132:133], v[94:95], v[130:131]
	v_pk_mul_f32 v[68:69], v[26:27], v[68:69] op_sel:[0,1]
	v_cvt_pk_bf16_f32 v44, v42, v43
	v_lshl_add_u64 v[42:43], v[24:25], 0, s[8:9]
	v_pk_fma_f32 v[40:41], v[86:87], v[118:119], v[40:41] neg_lo:[1,0,0] neg_hi:[1,0,0]
	v_readlane_b32 s1, v253, 26
	global_store_dword v[42:43], v44, off nt
	v_pk_fma_f32 v[42:43], v[40:41], s[14:15], v[132:133] op_sel_hi:[1,0,1] neg_lo:[0,0,1] neg_hi:[0,0,1]
	s_lshl_b32 s8, s1, 1
	s_waitcnt vmcnt(14)
	v_pk_fma_f32 v[40:41], v[96:97], v[68:69], v[40:41]
	v_pk_mul_f32 v[134:135], v[96:97], v[68:69]
	v_pk_mul_f32 v[136:137], v[26:27], v[70:71] op_sel_hi:[1,0]
	v_cvt_pk_bf16_f32 v44, v42, v43
	v_lshl_add_u64 v[42:43], v[24:25], 0, s[8:9]
	v_pk_fma_f32 v[40:41], v[88:89], v[64:65], v[40:41] neg_lo:[1,0,0] neg_hi:[1,0,0]
	v_mov_b32_e32 v48, v71
	global_store_dword v[42:43], v44, off nt
	v_pk_fma_f32 v[42:43], v[40:41], s[14:15], v[134:135] op_sel_hi:[1,0,1] neg_lo:[0,0,1] neg_hi:[0,0,1]
	s_lshl_b32 s8, s84, 1
	s_waitcnt vmcnt(14)
	v_pk_fma_f32 v[40:41], v[98:99], v[136:137], v[40:41]
	v_pk_mul_f32 v[138:139], v[98:99], v[136:137]
	v_pk_mul_f32 v[70:71], v[26:27], v[48:49] op_sel_hi:[1,0]
	v_cvt_pk_bf16_f32 v44, v42, v43
	v_lshl_add_u64 v[42:43], v[24:25], 0, s[8:9]
	v_pk_fma_f32 v[40:41], v[90:91], v[124:125], v[40:41] neg_lo:[1,0,0] neg_hi:[1,0,0]
	v_readlane_b32 s1, v253, 28
	global_store_dword v[42:43], v44, off nt
	v_pk_fma_f32 v[42:43], v[40:41], s[14:15], v[138:139] op_sel_hi:[1,0,1] neg_lo:[0,0,1] neg_hi:[0,0,1]
	s_lshl_b32 s8, s1, 1
	s_waitcnt vmcnt(14)
	v_pk_fma_f32 v[40:41], v[100:101], v[70:71], v[40:41]
	v_pk_mul_f32 v[140:141], v[100:101], v[70:71]
	s_waitcnt lgkmcnt(0)
	v_pk_mul_f32 v[58:59], v[26:27], v[72:73] op_sel_hi:[1,0]
	v_cvt_pk_bf16_f32 v44, v42, v43
	v_lshl_add_u64 v[42:43], v[24:25], 0, s[8:9]
	v_pk_fma_f32 v[40:41], v[92:93], v[66:67], v[40:41] neg_lo:[1,0,0] neg_hi:[1,0,0]
	v_readlane_b32 s1, v253, 29
	global_store_dword v[42:43], v44, off nt
	v_pk_fma_f32 v[42:43], v[40:41], s[14:15], v[140:141] op_sel_hi:[1,0,1] neg_lo:[0,0,1] neg_hi:[0,0,1]
	s_lshl_b32 s8, s1, 1
	s_waitcnt vmcnt(14)
	v_pk_fma_f32 v[40:41], v[38:39], v[58:59], v[40:41]
	v_pk_mul_f32 v[142:143], v[38:39], v[58:59]
	v_pk_mul_f32 v[54:55], v[26:27], v[72:73] op_sel:[0,1]
	v_cvt_pk_bf16_f32 v44, v42, v43
	v_lshl_add_u64 v[42:43], v[24:25], 0, s[8:9]
	v_pk_fma_f32 v[40:41], v[94:95], v[130:131], v[40:41] neg_lo:[1,0,0] neg_hi:[1,0,0]
	v_readlane_b32 s1, v253, 30
	global_store_dword v[42:43], v44, off nt
	v_pk_fma_f32 v[42:43], v[40:41], s[14:15], v[142:143] op_sel_hi:[1,0,1] neg_lo:[0,0,1] neg_hi:[0,0,1]
	s_lshl_b32 s8, s1, 1
	s_waitcnt vmcnt(14)
	v_pk_fma_f32 v[40:41], v[36:37], v[54:55], v[40:41]
	v_pk_mul_f32 v[72:73], v[36:37], v[54:55]
	v_pk_mul_f32 v[50:51], v[26:27], v[74:75] op_sel_hi:[1,0]
	v_cvt_pk_bf16_f32 v44, v42, v43
	v_lshl_add_u64 v[42:43], v[24:25], 0, s[8:9]
	v_pk_fma_f32 v[40:41], v[96:97], v[68:69], v[40:41] neg_lo:[1,0,0] neg_hi:[1,0,0]
	v_readlane_b32 s1, v253, 31
	v_mov_b32_e32 v48, v75
	global_store_dword v[42:43], v44, off nt
	v_pk_fma_f32 v[42:43], v[40:41], s[14:15], v[72:73] op_sel_hi:[1,0,1] neg_lo:[0,0,1] neg_hi:[0,0,1]
	s_lshl_b32 s8, s1, 1
	s_waitcnt vmcnt(14)
	v_pk_fma_f32 v[40:41], v[34:35], v[50:51], v[40:41]
	v_pk_mul_f32 v[144:145], v[34:35], v[50:51]
	v_pk_mul_f32 v[48:49], v[26:27], v[48:49] op_sel_hi:[1,0]
	v_cvt_pk_bf16_f32 v44, v42, v43
	v_lshl_add_u64 v[42:43], v[24:25], 0, s[8:9]
	v_pk_fma_f32 v[40:41], v[98:99], v[136:137], v[40:41] neg_lo:[1,0,0] neg_hi:[1,0,0]
	global_store_dword v[42:43], v44, off nt
	v_pk_fma_f32 v[42:43], v[40:41], s[14:15], v[144:145] op_sel_hi:[1,0,1] neg_lo:[0,0,1] neg_hi:[0,0,1]
	v_readlane_b32 s1, v253, 33
	s_waitcnt vmcnt(14)
	v_pk_fma_f32 v[40:41], v[30:31], v[48:49], v[40:41]
	v_pk_mul_f32 v[74:75], v[30:31], v[48:49]
	s_lshl_b32 s8, s1, 1
	v_pk_fma_f32 v[52:53], v[100:101], v[70:71], v[40:41] neg_lo:[1,0,0] neg_hi:[1,0,0]
	v_readlane_b32 s1, v253, 34
	v_cvt_pk_bf16_f32 v44, v42, v43
	v_lshl_add_u64 v[42:43], v[24:25], 0, s[8:9]
	v_pk_fma_f32 v[40:41], v[52:53], s[14:15], v[74:75] op_sel_hi:[1,0,1] neg_lo:[0,0,1] neg_hi:[0,0,1]
	s_lshl_b32 s8, s1, 1
	global_store_dword v[42:43], v44, off nt
	v_cvt_pk_bf16_f32 v42, v40, v41
	v_lshl_add_u64 v[40:41], v[24:25], 0, s[8:9]
	global_store_dword v[40:41], v42, off nt
	v_lshl_add_u64 v[40:41], v[28:29], 0, s[42:43]
	global_load_dwordx2 v[56:57], v[40:41], off
	v_lshl_add_u64 v[40:41], v[28:29], 0, s[20:21]
	global_load_dwordx2 v[68:69], v[40:41], off
	v_lshl_add_u64 v[40:41], v[28:29], 0, s[16:17]
	global_load_dwordx2 v[70:71], v[40:41], off
	v_lshl_add_u64 v[40:41], v[28:29], 0, s[44:45]
	global_load_dwordx2 v[72:73], v[40:41], off
	v_lshl_add_u64 v[40:41], v[28:29], 0, s[18:19]
	global_load_dwordx2 v[74:75], v[40:41], off
	v_lshl_add_u64 v[40:41], v[28:29], 0, s[94:95]
	global_load_dwordx2 v[76:77], v[40:41], off
	v_lshl_add_u64 v[40:41], v[28:29], 0, s[92:93]
	global_load_dwordx2 v[78:79], v[40:41], off
	v_lshl_add_u64 v[40:41], v[28:29], 0, s[86:87]
	global_load_dwordx2 v[80:81], v[40:41], off
	v_lshl_add_u64 v[40:41], v[28:29], 0, s[74:75]
	global_load_dwordx2 v[82:83], v[40:41], off
	v_lshl_add_u64 v[40:41], v[28:29], 0, s[76:77]
	global_load_dwordx2 v[84:85], v[40:41], off
	v_lshl_add_u64 v[40:41], v[28:29], 0, s[72:73]
	global_load_dwordx2 v[86:87], v[40:41], off
	v_lshl_add_u64 v[40:41], v[28:29], 0, s[66:67]
	global_load_dwordx2 v[88:89], v[40:41], off
	v_lshl_add_u64 v[40:41], v[28:29], 0, s[88:89]
	global_load_dwordx2 v[90:91], v[40:41], off
	v_lshl_add_u64 v[40:41], v[28:29], 0, s[68:69]
	global_load_dwordx2 v[92:93], v[40:41], off
	v_lshl_add_u64 v[40:41], v[28:29], 0, s[22:23]
	global_load_dwordx2 v[94:95], v[40:41], off
	v_lshl_add_u64 v[40:41], v[28:29], 0, s[96:97]
	global_load_dwordx2 v[96:97], v[40:41], off
	ds_read_b128 v[40:43], v1 offset:192
	ds_read_b128 v[44:47], v1 offset:208
	ds_read_b128 v[60:63], v1 offset:224
	ds_read_b128 v[64:67], v1 offset:240
	s_lshl_b32 s8, s36, 1
	s_waitcnt lgkmcnt(3)
	v_pk_mul_f32 v[98:99], v[26:27], v[40:41] op_sel_hi:[1,0]
	v_pk_mul_f32 v[40:41], v[26:27], v[40:41] op_sel:[0,1]
	v_pk_mul_f32 v[104:105], v[26:27], v[42:43] op_sel_hi:[1,0]
	v_mov_b32_e32 v42, v43
	v_pk_mul_f32 v[42:43], v[26:27], v[42:43] op_sel_hi:[1,0]
	v_readlane_b32 s1, v253, 36
	s_waitcnt lgkmcnt(2)
	v_pk_mul_f32 v[110:111], v[26:27], v[44:45] op_sel_hi:[1,0]
	v_pk_mul_f32 v[44:45], v[26:27], v[44:45] op_sel:[0,1]
	v_pk_mul_f32 v[116:117], v[26:27], v[46:47] op_sel_hi:[1,0]
	v_mov_b32_e32 v46, v47
	v_pk_mul_f32 v[46:47], v[26:27], v[46:47] op_sel_hi:[1,0]
	s_waitcnt lgkmcnt(1)
	v_pk_mul_f32 v[122:123], v[26:27], v[60:61] op_sel_hi:[1,0]
	v_pk_mul_f32 v[60:61], v[26:27], v[60:61] op_sel:[0,1]
	v_pk_mul_f32 v[128:129], v[26:27], v[62:63] op_sel_hi:[1,0]
	v_mov_b32_e32 v62, v63
	v_pk_mul_f32 v[62:63], v[26:27], v[62:63] op_sel_hi:[1,0]
	s_waitcnt lgkmcnt(0)
	v_pk_mul_f32 v[134:135], v[26:27], v[64:65] op_sel_hi:[1,0]
	v_pk_mul_f32 v[64:65], v[26:27], v[64:65] op_sel:[0,1]
	v_pk_mul_f32 v[140:141], v[26:27], v[66:67] op_sel_hi:[1,0]
	v_mov_b32_e32 v66, v67
	v_pk_mul_f32 v[66:67], v[26:27], v[66:67] op_sel_hi:[1,0]
	s_waitcnt vmcnt(15)
	v_pk_fma_f32 v[52:53], v[56:57], v[98:99], v[52:53]
	v_pk_mul_f32 v[100:101], v[56:57], v[98:99]
	v_pk_fma_f32 v[38:39], v[38:39], v[58:59], v[52:53] neg_lo:[1,0,0] neg_hi:[1,0,0]
	s_waitcnt vmcnt(14)
	v_pk_mul_f32 v[102:103], v[68:69], v[40:41]
	v_pk_fma_f32 v[52:53], v[38:39], s[14:15], v[100:101] op_sel_hi:[1,0,1] neg_lo:[0,0,1] neg_hi:[0,0,1]
	v_pk_fma_f32 v[38:39], v[68:69], v[40:41], v[38:39]
	s_waitcnt vmcnt(13)
	v_pk_mul_f32 v[106:107], v[70:71], v[104:105]
	v_pk_fma_f32 v[36:37], v[36:37], v[54:55], v[38:39] neg_lo:[1,0,0] neg_hi:[1,0,0]
	v_cvt_pk_bf16_f32 v1, v52, v53
	v_lshl_add_u64 v[52:53], v[24:25], 0, s[8:9]
	v_pk_fma_f32 v[38:39], v[36:37], s[14:15], v[102:103] op_sel_hi:[1,0,1] neg_lo:[0,0,1] neg_hi:[0,0,1]
	v_pk_fma_f32 v[36:37], v[70:71], v[104:105], v[36:37]
	s_lshl_b32 s8, s81, 1
	v_pk_fma_f32 v[34:35], v[34:35], v[50:51], v[36:37] neg_lo:[1,0,0] neg_hi:[1,0,0]
	s_waitcnt vmcnt(12)
	v_pk_mul_f32 v[108:109], v[72:73], v[42:43]
	v_pk_fma_f32 v[36:37], v[34:35], s[14:15], v[106:107] op_sel_hi:[1,0,1] neg_lo:[0,0,1] neg_hi:[0,0,1]
	v_pk_fma_f32 v[34:35], v[72:73], v[42:43], v[34:35]
	global_store_dword v[52:53], v1, off nt
	v_cvt_pk_bf16_f32 v1, v38, v39
	v_lshl_add_u64 v[38:39], v[24:25], 0, s[8:9]
	s_lshl_b32 s8, s1, 1
	v_pk_fma_f32 v[30:31], v[30:31], v[48:49], v[34:35] neg_lo:[1,0,0] neg_hi:[1,0,0]
	v_readlane_b32 s1, v253, 37
	global_store_dword v[38:39], v1, off nt
	v_cvt_pk_bf16_f32 v1, v36, v37
	v_lshl_add_u64 v[36:37], v[24:25], 0, s[8:9]
	v_pk_fma_f32 v[34:35], v[30:31], s[14:15], v[108:109] op_sel_hi:[1,0,1] neg_lo:[0,0,1] neg_hi:[0,0,1]
	s_lshl_b32 s8, s1, 1
	s_waitcnt vmcnt(13)
	v_pk_fma_f32 v[30:31], v[74:75], v[110:111], v[30:31]
	v_pk_mul_f32 v[112:113], v[74:75], v[110:111]
	global_store_dword v[36:37], v1, off nt
	v_cvt_pk_bf16_f32 v1, v34, v35
	v_lshl_add_u64 v[34:35], v[24:25], 0, s[8:9]
	v_pk_fma_f32 v[30:31], v[56:57], v[98:99], v[30:31] neg_lo:[1,0,0] neg_hi:[1,0,0]
	v_readlane_b32 s1, v253, 38
	global_store_dword v[34:35], v1, off nt
	v_pk_fma_f32 v[34:35], v[30:31], s[14:15], v[112:113] op_sel_hi:[1,0,1] neg_lo:[0,0,1] neg_hi:[0,0,1]
	s_lshl_b32 s8, s1, 1
	s_waitcnt vmcnt(14)
	v_pk_fma_f32 v[30:31], v[76:77], v[44:45], v[30:31]
	v_pk_mul_f32 v[114:115], v[76:77], v[44:45]
	v_cvt_pk_bf16_f32 v1, v34, v35
	v_lshl_add_u64 v[34:35], v[24:25], 0, s[8:9]
	v_pk_fma_f32 v[30:31], v[68:69], v[40:41], v[30:31] neg_lo:[1,0,0] neg_hi:[1,0,0]
	v_readlane_b32 s1, v253, 41
	global_store_dword v[34:35], v1, off nt
	v_pk_fma_f32 v[34:35], v[30:31], s[14:15], v[114:115] op_sel_hi:[1,0,1] neg_lo:[0,0,1] neg_hi:[0,0,1]
	s_lshl_b32 s8, s1, 1
	s_waitcnt vmcnt(14)
	v_pk_fma_f32 v[30:31], v[78:79], v[116:117], v[30:31]
	v_pk_mul_f32 v[118:119], v[78:79], v[116:117]
	v_cvt_pk_bf16_f32 v1, v34, v35
	v_lshl_add_u64 v[34:35], v[24:25], 0, s[8:9]
	v_pk_fma_f32 v[30:31], v[70:71], v[104:105], v[30:31] neg_lo:[1,0,0] neg_hi:[1,0,0]
	global_store_dword v[34:35], v1, off nt
	v_pk_fma_f32 v[34:35], v[30:31], s[14:15], v[118:119] op_sel_hi:[1,0,1] neg_lo:[0,0,1] neg_hi:[0,0,1]
	s_lshl_b32 s8, s34, 1
	s_waitcnt vmcnt(14)
	v_pk_fma_f32 v[30:31], v[80:81], v[46:47], v[30:31]
	v_pk_mul_f32 v[120:121], v[80:81], v[46:47]
	v_cvt_pk_bf16_f32 v1, v34, v35
	v_lshl_add_u64 v[34:35], v[24:25], 0, s[8:9]
	v_pk_fma_f32 v[30:31], v[72:73], v[42:43], v[30:31] neg_lo:[1,0,0] neg_hi:[1,0,0]
	v_readlane_b32 s1, v253, 42
	global_store_dword v[34:35], v1, off nt
	v_pk_fma_f32 v[34:35], v[30:31], s[14:15], v[120:121] op_sel_hi:[1,0,1] neg_lo:[0,0,1] neg_hi:[0,0,1]
	s_lshl_b32 s8, s1, 1
	s_waitcnt vmcnt(14)
	v_pk_fma_f32 v[30:31], v[82:83], v[122:123], v[30:31]
	v_pk_mul_f32 v[124:125], v[82:83], v[122:123]
	v_cvt_pk_bf16_f32 v1, v34, v35
	v_lshl_add_u64 v[34:35], v[24:25], 0, s[8:9]
	v_pk_fma_f32 v[30:31], v[74:75], v[110:111], v[30:31] neg_lo:[1,0,0] neg_hi:[1,0,0]
	global_store_dword v[34:35], v1, off nt
	v_pk_fma_f32 v[34:35], v[30:31], s[14:15], v[124:125] op_sel_hi:[1,0,1] neg_lo:[0,0,1] neg_hi:[0,0,1]
	s_lshl_b32 s8, s35, 1
	s_waitcnt vmcnt(14)
	v_pk_fma_f32 v[30:31], v[84:85], v[60:61], v[30:31]
	v_pk_mul_f32 v[126:127], v[84:85], v[60:61]
	v_cvt_pk_bf16_f32 v1, v34, v35
	v_lshl_add_u64 v[34:35], v[24:25], 0, s[8:9]
	v_pk_fma_f32 v[30:31], v[76:77], v[44:45], v[30:31] neg_lo:[1,0,0] neg_hi:[1,0,0]
	global_store_dword v[34:35], v1, off nt
	v_pk_fma_f32 v[34:35], v[30:31], s[14:15], v[126:127] op_sel_hi:[1,0,1] neg_lo:[0,0,1] neg_hi:[0,0,1]
	s_lshl_b32 s8, s90, 1
	s_waitcnt vmcnt(14)
	v_pk_fma_f32 v[30:31], v[86:87], v[128:129], v[30:31]
	v_pk_mul_f32 v[130:131], v[86:87], v[128:129]
	v_cvt_pk_bf16_f32 v1, v34, v35
	v_lshl_add_u64 v[34:35], v[24:25], 0, s[8:9]
	v_pk_fma_f32 v[30:31], v[78:79], v[116:117], v[30:31] neg_lo:[1,0,0] neg_hi:[1,0,0]
	v_readlane_b32 s1, v253, 43
	global_store_dword v[34:35], v1, off nt
	v_pk_fma_f32 v[34:35], v[30:31], s[14:15], v[130:131] op_sel_hi:[1,0,1] neg_lo:[0,0,1] neg_hi:[0,0,1]
	s_lshl_b32 s8, s1, 1
	s_waitcnt vmcnt(14)
	v_pk_fma_f32 v[30:31], v[88:89], v[62:63], v[30:31]
	v_pk_mul_f32 v[132:133], v[88:89], v[62:63]
	v_cvt_pk_bf16_f32 v1, v34, v35
	v_lshl_add_u64 v[34:35], v[24:25], 0, s[8:9]
	v_pk_fma_f32 v[30:31], v[80:81], v[46:47], v[30:31] neg_lo:[1,0,0] neg_hi:[1,0,0]
	global_store_dword v[34:35], v1, off nt
	v_pk_fma_f32 v[34:35], v[30:31], s[14:15], v[132:133] op_sel_hi:[1,0,1] neg_lo:[0,0,1] neg_hi:[0,0,1]
	s_lshl_b32 s8, s83, 1
	s_waitcnt vmcnt(14)
	v_pk_fma_f32 v[30:31], v[90:91], v[134:135], v[30:31]
	v_pk_mul_f32 v[136:137], v[90:91], v[134:135]
	v_cvt_pk_bf16_f32 v1, v34, v35
	v_lshl_add_u64 v[34:35], v[24:25], 0, s[8:9]
	v_pk_fma_f32 v[30:31], v[82:83], v[122:123], v[30:31] neg_lo:[1,0,0] neg_hi:[1,0,0]
	global_store_dword v[34:35], v1, off nt
	v_pk_fma_f32 v[34:35], v[30:31], s[14:15], v[136:137] op_sel_hi:[1,0,1] neg_lo:[0,0,1] neg_hi:[0,0,1]
	s_lshl_b32 s8, s91, 1
	s_waitcnt vmcnt(14)
	v_pk_fma_f32 v[30:31], v[92:93], v[64:65], v[30:31]
	v_pk_mul_f32 v[138:139], v[92:93], v[64:65]
	v_cvt_pk_bf16_f32 v1, v34, v35
	v_lshl_add_u64 v[34:35], v[24:25], 0, s[8:9]
	v_pk_fma_f32 v[30:31], v[84:85], v[60:61], v[30:31] neg_lo:[1,0,0] neg_hi:[1,0,0]
	global_store_dword v[34:35], v1, off nt
	v_pk_fma_f32 v[34:35], v[30:31], s[14:15], v[138:139] op_sel_hi:[1,0,1] neg_lo:[0,0,1] neg_hi:[0,0,1]
	s_lshl_b32 s8, s64, 1
	s_waitcnt vmcnt(14)
	v_pk_fma_f32 v[30:31], v[94:95], v[140:141], v[30:31]
	v_pk_mul_f32 v[142:143], v[94:95], v[140:141]
	v_cvt_pk_bf16_f32 v1, v34, v35
	v_lshl_add_u64 v[34:35], v[24:25], 0, s[8:9]
	v_pk_fma_f32 v[30:31], v[86:87], v[128:129], v[30:31] neg_lo:[1,0,0] neg_hi:[1,0,0]
	global_store_dword v[34:35], v1, off nt
	v_pk_fma_f32 v[34:35], v[30:31], s[14:15], v[142:143] op_sel_hi:[1,0,1] neg_lo:[0,0,1] neg_hi:[0,0,1]
	s_lshl_b32 s8, s65, 1
	s_waitcnt vmcnt(14)
	v_pk_fma_f32 v[30:31], v[96:97], v[66:67], v[30:31]
	v_pk_mul_f32 v[144:145], v[96:97], v[66:67]
	v_cvt_pk_bf16_f32 v1, v34, v35
	v_lshl_add_u64 v[34:35], v[24:25], 0, s[8:9]
	v_pk_fma_f32 v[30:31], v[88:89], v[62:63], v[30:31] neg_lo:[1,0,0] neg_hi:[1,0,0]
	global_store_dword v[34:35], v1, off nt
	v_pk_fma_f32 v[30:31], v[30:31], s[14:15], v[144:145] op_sel_hi:[1,0,1] neg_lo:[0,0,1] neg_hi:[0,0,1]
	s_nop 0
	v_cvt_pk_bf16_f32 v163, v30, v31

.LBB0_256:
	s_mov_b32 s0, 0xfffe2000
	v_add_co_u32_e32 v34, vcc, s0, v32
	s_mov_b32 s0, 0xfffe4000
	s_nop 0
	v_addc_co_u32_e32 v35, vcc, -1, v33, vcc
	global_load_dwordx2 v[160:161], v[34:35], off
	v_add_co_u32_e32 v34, vcc, s0, v32
	s_mov_b32 s0, 0xfffe6000
	s_nop 0
	v_addc_co_u32_e32 v35, vcc, -1, v33, vcc
	global_load_dwordx2 v[146:147], v[34:35], off
	v_add_co_u32_e32 v34, vcc, s0, v32
	s_mov_b32 s0, 0xfffe8000
	s_nop 0
	v_addc_co_u32_e32 v35, vcc, -1, v33, vcc
	global_load_dwordx2 v[144:145], v[34:35], off
	v_add_co_u32_e32 v34, vcc, s0, v32
	s_mov_b32 s0, 0xfffea000
	s_nop 0
	v_addc_co_u32_e32 v35, vcc, -1, v33, vcc
	global_load_dwordx2 v[138:139], v[34:35], off
	v_add_co_u32_e32 v34, vcc, s0, v32
	s_mov_b32 s0, 0xfffec000
	s_nop 0
	v_addc_co_u32_e32 v35, vcc, -1, v33, vcc
	global_load_dwordx2 v[136:137], v[34:35], off
	v_add_co_u32_e32 v34, vcc, s0, v32
	s_mov_b32 s0, 0xfffee000
	s_nop 0
	v_addc_co_u32_e32 v35, vcc, -1, v33, vcc
	global_load_dwordx2 v[132:133], v[34:35], off
	v_add_co_u32_e32 v34, vcc, s0, v32
	s_mov_b32 s0, 0xffff0000
	s_nop 0
	v_addc_co_u32_e32 v35, vcc, -1, v33, vcc
	global_load_dwordx2 v[130:131], v[34:35], off
	v_add_co_u32_e32 v34, vcc, s0, v32
	s_mov_b32 s0, 0xffff2000
	s_nop 0
	v_addc_co_u32_e32 v35, vcc, -1, v33, vcc
	global_load_dwordx2 v[126:127], v[34:35], off
	v_add_co_u32_e32 v34, vcc, s0, v32
	s_mov_b32 s0, 0xffff4000
	s_nop 0
	v_addc_co_u32_e32 v35, vcc, -1, v33, vcc
	global_load_dwordx2 v[124:125], v[34:35], off
	v_add_co_u32_e32 v34, vcc, s0, v32
	s_mov_b32 s0, 0xffff6000
	s_nop 0
	v_addc_co_u32_e32 v35, vcc, -1, v33, vcc
	global_load_dwordx2 v[118:119], v[34:35], off
	v_add_co_u32_e32 v34, vcc, s0, v32
	s_movk_i32 s0, 0x8000
	s_nop 0
	v_addc_co_u32_e32 v35, vcc, -1, v33, vcc
	global_load_dwordx2 v[116:117], v[34:35], off
	v_add_co_u32_e32 v34, vcc, s0, v32
	s_movk_i32 s0, 0xa000
	s_nop 0
	v_addc_co_u32_e32 v35, vcc, -1, v33, vcc
	global_load_dwordx2 v[110:111], v[34:35], off
	v_add_co_u32_e32 v34, vcc, s0, v32
	s_movk_i32 s0, 0xc000
	s_nop 0
	v_addc_co_u32_e32 v35, vcc, -1, v33, vcc
	global_load_dwordx2 v[108:109], v[34:35], off
	v_add_co_u32_e32 v34, vcc, s0, v32
	s_movk_i32 s41, 0xe000
	s_nop 0
	v_addc_co_u32_e32 v35, vcc, -1, v33, vcc
	global_load_dwordx2 v[104:105], v[34:35], off
	v_add_co_u32_e32 v34, vcc, s41, v32
	v_mov_b32_e32 v1, s7
	s_nop 0
	v_addc_co_u32_e32 v35, vcc, -1, v33, vcc
	global_load_dwordx2 v[102:103], v[34:35], off
	global_load_dwordx2 v[98:99], v[32:33], off
	ds_read_b128 v[40:43], v1
	ds_read_b128 v[48:51], v1 offset:16
	ds_read_b128 v[56:59], v1 offset:32
	ds_read_b128 v[64:67], v1 offset:48
	s_min_u32 s41, s8, 15
	s_waitcnt lgkmcnt(3)
	v_pk_mul_f32 v[164:165], v[26:27], v[40:41] op_sel_hi:[1,0]
	s_add_i32 s41, s41, 1
	s_waitcnt vmcnt(15)
	v_pk_fma_f32 v[36:37], v[160:161], v[164:165], v[36:37]
	v_cvt_f32_ubyte0_e32 v1, s41
	v_pk_add_f32 v[114:115], v[36:37], v[114:115] neg_lo:[0,1] neg_hi:[0,1]
	v_div_scale_f32 v36, vcc, v1, v1, 1.0
	v_rcp_f32_e32 v37, v36
	v_pk_mul_f32 v[34:35], v[160:161], v[164:165]
	s_add_i32 s40, s8, 1
	s_mov_b32 s41, 0x17701000
	v_fma_f32 v160, -v36, v37, 1.0
	v_fmac_f32_e32 v37, v160, v37
	v_div_scale_f32 v160, vcc, 1.0, v1, 1.0
	v_mul_f32_e32 v161, v160, v37
	v_fma_f32 v164, -v36, v161, v160
	v_fmac_f32_e32 v161, v164, v37
	v_fma_f32 v36, -v36, v161, v160
	v_div_fmas_f32 v36, v36, v37, v161
	v_div_fixup_f32 v36, v36, v1, 1.0
	v_pk_fma_f32 v[36:37], v[36:37], v[114:115], v[34:35] op_sel_hi:[0,1,1] neg_lo:[0,0,1] neg_hi:[0,0,1]
	v_cvt_pk_bf16_f32 v1, v36, v37
	v_lshl_add_u64 v[36:37], v[30:31], 0, s[26:27]
	v_add_co_u32_e32 v160, vcc, s41, v36
	s_min_u32 s40, s40, 15
	v_pk_mul_f32 v[158:159], v[26:27], v[40:41] op_sel:[0,1]
	v_addc_co_u32_e32 v161, vcc, 0, v37, vcc
	s_add_i32 s40, s40, 1
	global_store_dword v[160:161], v1, off offset:-4096 nt
	s_waitcnt vmcnt(15)
	v_pk_fma_f32 v[114:115], v[146:147], v[158:159], v[114:115]
	v_cvt_f32_ubyte0_e32 v1, s40
	v_pk_add_f32 v[96:97], v[114:115], v[96:97] neg_lo:[0,1] neg_hi:[0,1]
	v_div_scale_f32 v114, s[40:41], v1, v1, 1.0
	v_rcp_f32_e32 v115, v114
	v_pk_mul_f32 v[38:39], v[146:147], v[158:159]
	s_add_i32 s39, s8, 2
	s_min_u32 s39, s39, 15
	v_fma_f32 v146, -v114, v115, 1.0
	v_fmac_f32_e32 v115, v146, v115
	v_div_scale_f32 v146, vcc, 1.0, v1, 1.0
	v_mul_f32_e32 v147, v146, v115
	v_fma_f32 v158, -v114, v147, v146
	v_fmac_f32_e32 v147, v158, v115
	v_fma_f32 v114, -v114, v147, v146
	v_div_fmas_f32 v114, v114, v115, v147
	v_div_fixup_f32 v114, v114, v1, 1.0
	v_pk_mul_f32 v[156:157], v[26:27], v[42:43] op_sel_hi:[1,0]
	v_pk_fma_f32 v[114:115], v[114:115], v[96:97], v[38:39] op_sel_hi:[0,1,1] neg_lo:[0,0,1] neg_hi:[0,0,1]
	v_cvt_pk_bf16_f32 v1, v114, v115
	s_add_i32 s39, s39, 1
	global_store_dword v[160:161], v1, off nt
	s_waitcnt vmcnt(15)
	v_pk_fma_f32 v[96:97], v[144:145], v[156:157], v[96:97]
	v_cvt_f32_ubyte0_e32 v1, s39
	v_pk_add_f32 v[94:95], v[96:97], v[94:95] neg_lo:[0,1] neg_hi:[0,1]
	v_div_scale_f32 v96, s[40:41], v1, v1, 1.0
	v_rcp_f32_e32 v97, v96
	v_pk_mul_f32 v[40:41], v[144:145], v[156:157]
	s_add_i32 s38, s8, 3
	s_mov_b32 s39, 0x17703000
	v_fma_f32 v114, -v96, v97, 1.0
	v_fmac_f32_e32 v97, v114, v97
	v_div_scale_f32 v114, vcc, 1.0, v1, 1.0
	v_mul_f32_e32 v115, v114, v97
	v_fma_f32 v144, -v96, v115, v114
	v_fmac_f32_e32 v115, v144, v97
	v_fma_f32 v96, -v96, v115, v114
	v_div_fmas_f32 v96, v96, v97, v115
	v_div_fixup_f32 v96, v96, v1, 1.0
	v_pk_fma_f32 v[96:97], v[96:97], v[94:95], v[40:41] op_sel_hi:[0,1,1] neg_lo:[0,0,1] neg_hi:[0,0,1]
	v_mov_b32_e32 v42, v43
	v_cvt_pk_bf16_f32 v1, v96, v97
	v_add_co_u32_e32 v96, vcc, s39, v36
	s_min_u32 s38, s38, 15
	v_pk_mul_f32 v[154:155], v[26:27], v[42:43] op_sel_hi:[1,0]
	v_addc_co_u32_e32 v97, vcc, 0, v37, vcc
	s_add_i32 s38, s38, 1
	global_store_dword v[96:97], v1, off offset:-4096 nt
	s_waitcnt vmcnt(15)
	v_pk_fma_f32 v[94:95], v[138:139], v[154:155], v[94:95]
	v_cvt_f32_ubyte0_e32 v1, s38
	v_pk_add_f32 v[92:93], v[94:95], v[92:93] neg_lo:[0,1] neg_hi:[0,1]
	v_div_scale_f32 v94, s[38:39], v1, v1, 1.0
	v_rcp_f32_e32 v95, v94
	v_pk_mul_f32 v[42:43], v[138:139], v[154:155]
	s_add_i32 s31, s8, 4
	s_min_u32 s31, s31, 15
	v_fma_f32 v114, -v94, v95, 1.0
	v_fmac_f32_e32 v95, v114, v95
	v_div_scale_f32 v114, vcc, 1.0, v1, 1.0
	v_mul_f32_e32 v115, v114, v95
	v_fma_f32 v138, -v94, v115, v114
	v_fmac_f32_e32 v115, v138, v95
	v_fma_f32 v94, -v94, v115, v114
	v_div_fmas_f32 v94, v94, v95, v115
	v_div_fixup_f32 v94, v94, v1, 1.0
	s_waitcnt lgkmcnt(2)
	v_pk_mul_f32 v[152:153], v[26:27], v[48:49] op_sel_hi:[1,0]
	v_pk_fma_f32 v[94:95], v[94:95], v[92:93], v[42:43] op_sel_hi:[0,1,1] neg_lo:[0,0,1] neg_hi:[0,0,1]
	v_cvt_pk_bf16_f32 v1, v94, v95
	s_add_i32 s31, s31, 1
	global_store_dword v[96:97], v1, off nt
	s_waitcnt vmcnt(15)
	v_pk_fma_f32 v[92:93], v[136:137], v[152:153], v[92:93]
	v_cvt_f32_ubyte0_e32 v1, s31
	v_pk_add_f32 v[90:91], v[92:93], v[90:91] neg_lo:[0,1] neg_hi:[0,1]
	v_div_scale_f32 v92, s[38:39], v1, v1, 1.0
	v_rcp_f32_e32 v93, v92
	v_pk_mul_f32 v[44:45], v[136:137], v[152:153]
	s_add_i32 s30, s8, 5
	s_mov_b32 s31, 0x17705000
	v_fma_f32 v94, -v92, v93, 1.0
	v_fmac_f32_e32 v93, v94, v93
	v_div_scale_f32 v94, vcc, 1.0, v1, 1.0
	v_mul_f32_e32 v95, v94, v93
	v_fma_f32 v96, -v92, v95, v94
	v_fmac_f32_e32 v95, v96, v93
	v_fma_f32 v92, -v92, v95, v94
	v_div_fmas_f32 v92, v92, v93, v95
	v_div_fixup_f32 v92, v92, v1, 1.0
	v_pk_fma_f32 v[92:93], v[92:93], v[90:91], v[44:45] op_sel_hi:[0,1,1] neg_lo:[0,0,1] neg_hi:[0,0,1]
	v_cvt_pk_bf16_f32 v1, v92, v93
	v_add_co_u32_e32 v92, vcc, s31, v36
	s_min_u32 s30, s30, 15
	v_pk_mul_f32 v[150:151], v[26:27], v[48:49] op_sel:[0,1]
	v_addc_co_u32_e32 v93, vcc, 0, v37, vcc
	s_add_i32 s30, s30, 1
	global_store_dword v[92:93], v1, off offset:-4096 nt
	s_waitcnt vmcnt(15)
	v_pk_fma_f32 v[90:91], v[132:133], v[150:151], v[90:91]
	v_cvt_f32_ubyte0_e32 v1, s30
	v_pk_add_f32 v[88:89], v[90:91], v[88:89] neg_lo:[0,1] neg_hi:[0,1]
	v_div_scale_f32 v90, s[30:31], v1, v1, 1.0
	v_rcp_f32_e32 v91, v90
	s_add_i32 s33, s8, 6
	v_pk_mul_f32 v[46:47], v[132:133], v[150:151]
	s_min_u32 s30, s33, 15
	v_fma_f32 v94, -v90, v91, 1.0
	v_fmac_f32_e32 v91, v94, v91
	v_div_scale_f32 v94, vcc, 1.0, v1, 1.0
	v_mul_f32_e32 v95, v94, v91
	v_fma_f32 v96, -v90, v95, v94
	v_fmac_f32_e32 v95, v96, v91
	v_fma_f32 v90, -v90, v95, v94
	v_div_fmas_f32 v90, v90, v91, v95
	v_div_fixup_f32 v90, v90, v1, 1.0
	v_pk_mul_f32 v[148:149], v[26:27], v[50:51] op_sel_hi:[1,0]
	v_pk_fma_f32 v[90:91], v[90:91], v[88:89], v[46:47] op_sel_hi:[0,1,1] neg_lo:[0,0,1] neg_hi:[0,0,1]
	v_cvt_pk_bf16_f32 v1, v90, v91
	s_add_i32 s30, s30, 1
	global_store_dword v[92:93], v1, off nt
	s_waitcnt vmcnt(15)
	v_pk_fma_f32 v[88:89], v[130:131], v[148:149], v[88:89]
	v_cvt_f32_ubyte0_e32 v1, s30
	v_pk_add_f32 v[86:87], v[88:89], v[86:87] neg_lo:[0,1] neg_hi:[0,1]
	v_div_scale_f32 v88, s[30:31], v1, v1, 1.0
	v_rcp_f32_e32 v89, v88
	v_pk_mul_f32 v[48:49], v[130:131], v[148:149]
	s_add_i32 s15, s8, 7
	s_mov_b32 s30, 0x17707000
	v_fma_f32 v90, -v88, v89, 1.0
	v_fmac_f32_e32 v89, v90, v89
	v_div_scale_f32 v90, vcc, 1.0, v1, 1.0
	v_mul_f32_e32 v91, v90, v89
	v_fma_f32 v92, -v88, v91, v90
	v_fmac_f32_e32 v91, v92, v89
	v_fma_f32 v88, -v88, v91, v90
	v_div_fmas_f32 v88, v88, v89, v91
	v_div_fixup_f32 v88, v88, v1, 1.0
	v_pk_fma_f32 v[88:89], v[88:89], v[86:87], v[48:49] op_sel_hi:[0,1,1] neg_lo:[0,0,1] neg_hi:[0,0,1]
	v_mov_b32_e32 v50, v51
	v_cvt_pk_bf16_f32 v1, v88, v89
	v_add_co_u32_e32 v88, vcc, s30, v36
	s_min_u32 s15, s15, 15
	v_pk_mul_f32 v[142:143], v[26:27], v[50:51] op_sel_hi:[1,0]
	v_addc_co_u32_e32 v89, vcc, 0, v37, vcc
	s_add_i32 s15, s15, 1
	global_store_dword v[88:89], v1, off offset:-4096 nt
	s_waitcnt vmcnt(15)
	v_pk_fma_f32 v[86:87], v[126:127], v[142:143], v[86:87]
	v_cvt_f32_ubyte0_e32 v1, s15
	v_pk_add_f32 v[84:85], v[86:87], v[84:85] neg_lo:[0,1] neg_hi:[0,1]
	v_div_scale_f32 v86, s[30:31], v1, v1, 1.0
	v_rcp_f32_e32 v87, v86
	s_add_i32 s13, s8, 8
	v_pk_mul_f32 v[50:51], v[126:127], v[142:143]
	s_min_u32 s13, s13, 15
	v_fma_f32 v90, -v86, v87, 1.0
	v_fmac_f32_e32 v87, v90, v87
	v_div_scale_f32 v90, vcc, 1.0, v1, 1.0
	v_mul_f32_e32 v91, v90, v87
	v_fma_f32 v92, -v86, v91, v90
	v_fmac_f32_e32 v91, v92, v87
	v_fma_f32 v86, -v86, v91, v90
	v_div_fmas_f32 v86, v86, v87, v91
	v_div_fixup_f32 v86, v86, v1, 1.0
	s_waitcnt lgkmcnt(1)
	v_pk_mul_f32 v[140:141], v[26:27], v[56:57] op_sel_hi:[1,0]
	v_pk_fma_f32 v[86:87], v[86:87], v[84:85], v[50:51] op_sel_hi:[0,1,1] neg_lo:[0,0,1] neg_hi:[0,0,1]
	v_cvt_pk_bf16_f32 v1, v86, v87
	s_add_i32 s13, s13, 1
	global_store_dword v[88:89], v1, off nt
	s_waitcnt vmcnt(15)
	v_pk_fma_f32 v[84:85], v[124:125], v[140:141], v[84:85]
	v_cvt_f32_ubyte0_e32 v1, s13
	v_pk_add_f32 v[82:83], v[84:85], v[82:83] neg_lo:[0,1] neg_hi:[0,1]
	v_div_scale_f32 v84, s[30:31], v1, v1, 1.0
	v_rcp_f32_e32 v85, v84
	v_pk_mul_f32 v[52:53], v[124:125], v[140:141]
	s_add_i32 s71, s8, 9
	s_mov_b32 s13, 0x17709000
	v_fma_f32 v86, -v84, v85, 1.0
	v_fmac_f32_e32 v85, v86, v85
	v_div_scale_f32 v86, vcc, 1.0, v1, 1.0
	v_mul_f32_e32 v87, v86, v85
	v_fma_f32 v88, -v84, v87, v86
	v_fmac_f32_e32 v87, v88, v85
	v_fma_f32 v84, -v84, v87, v86
	v_div_fmas_f32 v84, v84, v85, v87
	v_div_fixup_f32 v84, v84, v1, 1.0
	v_pk_fma_f32 v[84:85], v[84:85], v[82:83], v[52:53] op_sel_hi:[0,1,1] neg_lo:[0,0,1] neg_hi:[0,0,1]
	v_cvt_pk_bf16_f32 v1, v84, v85
	v_add_co_u32_e32 v84, vcc, s13, v36
	s_min_u32 s13, s71, 15
	v_pk_mul_f32 v[134:135], v[26:27], v[56:57] op_sel:[0,1]
	v_addc_co_u32_e32 v85, vcc, 0, v37, vcc
	s_add_i32 s13, s13, 1
	global_store_dword v[84:85], v1, off offset:-4096 nt
	s_waitcnt vmcnt(15)
	v_pk_fma_f32 v[82:83], v[118:119], v[134:135], v[82:83]
	v_cvt_f32_ubyte0_e32 v1, s13
	v_pk_add_f32 v[80:81], v[82:83], v[80:81] neg_lo:[0,1] neg_hi:[0,1]
	v_div_scale_f32 v82, s[30:31], v1, v1, 1.0
	v_rcp_f32_e32 v83, v82
	s_add_i32 s70, s8, 10
	v_pk_mul_f32 v[54:55], v[118:119], v[134:135]
	s_min_u32 s13, s70, 15
	v_fma_f32 v86, -v82, v83, 1.0
	v_fmac_f32_e32 v83, v86, v83
	v_div_scale_f32 v86, vcc, 1.0, v1, 1.0
	v_mul_f32_e32 v87, v86, v83
	v_fma_f32 v88, -v82, v87, v86
	v_fmac_f32_e32 v87, v88, v83
	v_fma_f32 v82, -v82, v87, v86
	v_div_fmas_f32 v82, v82, v83, v87
	v_div_fixup_f32 v82, v82, v1, 1.0
	v_pk_mul_f32 v[128:129], v[26:27], v[58:59] op_sel_hi:[1,0]
	v_pk_fma_f32 v[82:83], v[82:83], v[80:81], v[54:55] op_sel_hi:[0,1,1] neg_lo:[0,0,1] neg_hi:[0,0,1]
	v_cvt_pk_bf16_f32 v1, v82, v83
	s_add_i32 s13, s13, 1
	global_store_dword v[84:85], v1, off nt
	s_waitcnt vmcnt(15)
	v_pk_fma_f32 v[80:81], v[116:117], v[128:129], v[80:81]
	v_cvt_f32_ubyte0_e32 v1, s13
	v_pk_add_f32 v[78:79], v[80:81], v[78:79] neg_lo:[0,1] neg_hi:[0,1]
	v_div_scale_f32 v80, s[30:31], v1, v1, 1.0
	v_rcp_f32_e32 v81, v80
	v_pk_mul_f32 v[56:57], v[116:117], v[128:129]
	s_add_i32 s29, s8, 11
	s_mov_b32 s13, 0x1770b000
	v_fma_f32 v82, -v80, v81, 1.0
	v_fmac_f32_e32 v81, v82, v81
	v_div_scale_f32 v82, vcc, 1.0, v1, 1.0
	v_mul_f32_e32 v83, v82, v81
	v_fma_f32 v84, -v80, v83, v82
	v_fmac_f32_e32 v83, v84, v81
	v_fma_f32 v80, -v80, v83, v82
	v_div_fmas_f32 v80, v80, v81, v83
	v_div_fixup_f32 v80, v80, v1, 1.0
	v_pk_fma_f32 v[80:81], v[80:81], v[78:79], v[56:57] op_sel_hi:[0,1,1] neg_lo:[0,0,1] neg_hi:[0,0,1]
	v_mov_b32_e32 v58, v59
	v_cvt_pk_bf16_f32 v1, v80, v81
	v_add_co_u32_e32 v80, vcc, s13, v36
	s_min_u32 s13, s29, 15
	v_pk_mul_f32 v[122:123], v[26:27], v[58:59] op_sel_hi:[1,0]
	v_addc_co_u32_e32 v81, vcc, 0, v37, vcc
	s_add_i32 s13, s13, 1
	global_store_dword v[80:81], v1, off offset:-4096 nt
	s_waitcnt vmcnt(15)
	v_pk_fma_f32 v[78:79], v[110:111], v[122:123], v[78:79]
	v_cvt_f32_ubyte0_e32 v1, s13
	v_pk_add_f32 v[76:77], v[78:79], v[76:77] neg_lo:[0,1] neg_hi:[0,1]
	v_div_scale_f32 v78, s[30:31], v1, v1, 1.0
	v_rcp_f32_e32 v79, v78
	s_add_i32 s28, s8, 12
	v_pk_mul_f32 v[58:59], v[110:111], v[122:123]
	s_min_u32 s13, s28, 15
	v_fma_f32 v82, -v78, v79, 1.0
	v_fmac_f32_e32 v79, v82, v79
	v_div_scale_f32 v82, vcc, 1.0, v1, 1.0
	v_mul_f32_e32 v83, v82, v79
	v_fma_f32 v84, -v78, v83, v82
	v_fmac_f32_e32 v83, v84, v79
	v_fma_f32 v78, -v78, v83, v82
	v_div_fmas_f32 v78, v78, v79, v83
	v_div_fixup_f32 v78, v78, v1, 1.0
	s_waitcnt lgkmcnt(0)
	v_pk_mul_f32 v[120:121], v[26:27], v[64:65] op_sel_hi:[1,0]
	v_pk_fma_f32 v[78:79], v[78:79], v[76:77], v[58:59] op_sel_hi:[0,1,1] neg_lo:[0,0,1] neg_hi:[0,0,1]
	v_cvt_pk_bf16_f32 v1, v78, v79
	s_add_i32 s13, s13, 1
	global_store_dword v[80:81], v1, off nt
	s_waitcnt vmcnt(15)
	v_pk_fma_f32 v[76:77], v[108:109], v[120:121], v[76:77]
	v_cvt_f32_ubyte0_e32 v1, s13
	v_pk_add_f32 v[74:75], v[76:77], v[74:75] neg_lo:[0,1] neg_hi:[0,1]
	v_div_scale_f32 v76, s[28:29], v1, v1, 1.0
	v_rcp_f32_e32 v77, v76
	v_pk_mul_f32 v[60:61], v[108:109], v[120:121]
	s_add_i32 s1, s8, 13
	s_mov_b32 s13, 0x1770d000
	v_fma_f32 v78, -v76, v77, 1.0
	v_fmac_f32_e32 v77, v78, v77
	v_div_scale_f32 v78, vcc, 1.0, v1, 1.0
	v_mul_f32_e32 v79, v78, v77
	v_fma_f32 v80, -v76, v79, v78
	v_fmac_f32_e32 v79, v80, v77
	v_fma_f32 v76, -v76, v79, v78
	v_div_fmas_f32 v76, v76, v77, v79
	v_div_fixup_f32 v76, v76, v1, 1.0
	v_pk_fma_f32 v[76:77], v[76:77], v[74:75], v[60:61] op_sel_hi:[0,1,1] neg_lo:[0,0,1] neg_hi:[0,0,1]
	v_cvt_pk_bf16_f32 v1, v76, v77
	v_add_co_u32_e32 v76, vcc, s13, v36
	s_min_u32 s1, s1, 15
	v_pk_mul_f32 v[112:113], v[26:27], v[64:65] op_sel:[0,1]
	v_addc_co_u32_e32 v77, vcc, 0, v37, vcc
	s_add_i32 s1, s1, 1
	global_store_dword v[76:77], v1, off offset:-4096 nt
	s_waitcnt vmcnt(15)
	v_pk_fma_f32 v[74:75], v[104:105], v[112:113], v[74:75]
	v_cvt_f32_ubyte0_e32 v1, s1
	v_pk_add_f32 v[72:73], v[74:75], v[72:73] neg_lo:[0,1] neg_hi:[0,1]
	v_div_scale_f32 v74, s[28:29], v1, v1, 1.0
	v_rcp_f32_e32 v75, v74
	s_add_i32 s0, s8, 14
	v_pk_mul_f32 v[62:63], v[104:105], v[112:113]
	s_min_u32 s0, s0, 15
	v_fma_f32 v78, -v74, v75, 1.0
	v_fmac_f32_e32 v75, v78, v75
	v_div_scale_f32 v78, vcc, 1.0, v1, 1.0
	v_mul_f32_e32 v79, v78, v75
	v_fma_f32 v80, -v74, v79, v78
	v_fmac_f32_e32 v79, v80, v75
	v_fma_f32 v74, -v74, v79, v78
	v_div_fmas_f32 v74, v74, v75, v79
	v_div_fixup_f32 v74, v74, v1, 1.0
	v_pk_mul_f32 v[106:107], v[26:27], v[66:67] op_sel_hi:[1,0]
	v_pk_fma_f32 v[74:75], v[74:75], v[72:73], v[62:63] op_sel_hi:[0,1,1] neg_lo:[0,0,1] neg_hi:[0,0,1]
	v_cvt_pk_bf16_f32 v1, v74, v75
	s_add_i32 s0, s0, 1
	global_store_dword v[76:77], v1, off nt
	s_waitcnt vmcnt(15)
	v_pk_fma_f32 v[72:73], v[102:103], v[106:107], v[72:73]
	v_cvt_f32_ubyte0_e32 v1, s0
	v_pk_add_f32 v[70:71], v[72:73], v[70:71] neg_lo:[0,1] neg_hi:[0,1]
	v_div_scale_f32 v72, s[0:1], v1, v1, 1.0
	v_rcp_f32_e32 v73, v72
	v_pk_mul_f32 v[64:65], v[102:103], v[106:107]
	v_mov_b32_e32 v66, v67
	s_mov_b32 s0, 0x1770f000
	v_fma_f32 v74, -v72, v73, 1.0
	v_fmac_f32_e32 v73, v74, v73
	v_div_scale_f32 v74, vcc, 1.0, v1, 1.0
	v_mul_f32_e32 v75, v74, v73
	v_fma_f32 v76, -v72, v75, v74
	v_fmac_f32_e32 v75, v76, v73
	v_fma_f32 v72, -v72, v75, v74
	v_div_fmas_f32 v72, v72, v73, v75
	v_div_fixup_f32 v72, v72, v1, 1.0
	v_pk_fma_f32 v[72:73], v[72:73], v[70:71], v[64:65] op_sel_hi:[0,1,1] neg_lo:[0,0,1] neg_hi:[0,0,1]
	v_pk_mul_f32 v[100:101], v[26:27], v[66:67] op_sel_hi:[1,0]
	v_cvt_pk_bf16_f32 v1, v72, v73
	v_add_co_u32_e32 v72, vcc, s0, v36
	s_waitcnt vmcnt(14)
	v_pk_mul_f32 v[66:67], v[98:99], v[100:101]
	v_addc_co_u32_e32 v73, vcc, 0, v37, vcc
	v_pk_fma_f32 v[36:37], v[98:99], v[100:101], v[70:71]
	s_mov_b32 s0, 0x3d800000
	v_pk_add_f32 v[36:37], v[36:37], v[68:69] neg_lo:[0,1] neg_hi:[0,1]
	s_add_u32 s26, s26, 0x10000
	v_pk_fma_f32 v[68:69], v[36:37], s[0:1], v[66:67] op_sel_hi:[1,0,1] neg_lo:[0,0,1] neg_hi:[0,0,1]
	s_addc_u32 s27, s27, 0
	s_add_i32 s8, s8, 16
	s_add_i32 s7, s7, 64
	global_store_dword v[72:73], v1, off offset:-4096 nt
	v_cvt_pk_bf16_f32 v1, v68, v69
	global_store_dword v[72:73], v1, off nt
	v_lshl_add_u64 v[32:33], v[32:33], 0, s[10:11]
	s_cmp_eq_u32 s26, 0x40000
	v_mov_b64_e32 v[68:69], v[66:67]
	v_mov_b64_e32 v[70:71], v[64:65]
	v_mov_b64_e32 v[72:73], v[62:63]
	v_mov_b64_e32 v[74:75], v[60:61]
	v_mov_b64_e32 v[76:77], v[58:59]
	v_mov_b64_e32 v[78:79], v[56:57]
	v_mov_b64_e32 v[80:81], v[54:55]
	v_mov_b64_e32 v[82:83], v[52:53]
	v_mov_b64_e32 v[84:85], v[50:51]
	v_mov_b64_e32 v[86:87], v[48:49]
	v_mov_b64_e32 v[88:89], v[46:47]
	v_mov_b64_e32 v[90:91], v[44:45]
	v_mov_b64_e32 v[92:93], v[42:43]
	v_mov_b64_e32 v[94:95], v[40:41]
	v_mov_b64_e32 v[96:97], v[38:39]
	v_mov_b64_e32 v[114:115], v[34:35]
	s_cbranch_scc0 .LBB0_256

.LBB0_260:
	v_div_scale_f32 v1, s[2:3], s0, s0, 1.0
	v_rcp_f32_e32 v32, v1
	v_pk_add_f32 v[42:43], v[34:35], 0 op_sel_hi:[1,0]
	s_nop 0
	v_pk_add_f32 v[84:85], v[30:31], v[42:43]
	v_fma_f32 v33, -v1, v32, 1.0
	v_fmac_f32_e32 v32, v33, v32
	v_div_scale_f32 v33, vcc, 1.0, s0, 1.0
	v_mul_f32_e32 v36, v33, v32
	v_fma_f32 v37, -v1, v36, v33
	v_fmac_f32_e32 v36, v37, v32
	v_fma_f32 v1, -v1, v36, v33
	v_div_fmas_f32 v1, v1, v32, v36
	v_div_fixup_f32 v54, v1, s0, 1.0
	v_readlane_b32 s0, v251, 49
	v_readlane_b32 s1, v251, 50
	s_nop 1
	v_lshl_add_u64 v[32:33], v[28:29], 0, s[0:1]
	v_readlane_b32 s0, v252, 9
	v_readlane_b32 s1, v252, 10
	s_nop 1
	v_lshl_add_u64 v[36:37], v[28:29], 0, s[0:1]
	v_readlane_b32 s0, v252, 13
	v_readlane_b32 s1, v252, 14
	s_nop 1
	v_lshl_add_u64 v[38:39], v[28:29], 0, s[0:1]
	v_readlane_b32 s0, v252, 17
	v_readlane_b32 s1, v252, 18
	s_nop 1
	v_lshl_add_u64 v[40:41], v[28:29], 0, s[0:1]
	global_load_dwordx2 v[56:57], v[32:33], off
	global_load_dwordx2 v[58:59], v[36:37], off
	global_load_dwordx2 v[60:61], v[38:39], off
	global_load_dwordx2 v[62:63], v[40:41], off
	v_readlane_b32 s0, v252, 21
	v_readlane_b32 s1, v252, 22
	s_nop 1
	v_lshl_add_u64 v[32:33], v[28:29], 0, s[0:1]
	v_readlane_b32 s0, v252, 25
	v_readlane_b32 s1, v252, 26
	s_nop 1
	v_lshl_add_u64 v[36:37], v[28:29], 0, s[0:1]
	v_readlane_b32 s0, v252, 28
	v_readlane_b32 s1, v252, 29
	s_nop 1
	v_lshl_add_u64 v[38:39], v[28:29], 0, s[0:1]
	v_readlane_b32 s0, v252, 31
	v_readlane_b32 s1, v252, 32
	s_nop 1
	v_lshl_add_u64 v[40:41], v[28:29], 0, s[0:1]
	global_load_dwordx2 v[64:65], v[32:33], off
	global_load_dwordx2 v[66:67], v[36:37], off
	global_load_dwordx2 v[68:69], v[38:39], off
	global_load_dwordx2 v[70:71], v[40:41], off
	v_readlane_b32 s0, v252, 34
	v_readlane_b32 s1, v252, 35
	s_nop 1
	v_lshl_add_u64 v[32:33], v[28:29], 0, s[0:1]
	v_readlane_b32 s0, v252, 37
	v_readlane_b32 s1, v252, 38
	s_nop 1
	v_lshl_add_u64 v[36:37], v[28:29], 0, s[0:1]
	v_readlane_b32 s0, v252, 40
	v_readlane_b32 s1, v252, 41
	s_nop 1
	v_lshl_add_u64 v[38:39], v[28:29], 0, s[0:1]
	v_readlane_b32 s0, v252, 43
	v_readlane_b32 s1, v252, 44
	s_nop 1
	v_lshl_add_u64 v[40:41], v[28:29], 0, s[0:1]
	global_load_dwordx2 v[72:73], v[32:33], off
	global_load_dwordx2 v[74:75], v[36:37], off
	global_load_dwordx2 v[76:77], v[38:39], off
	global_load_dwordx2 v[78:79], v[40:41], off
	v_readlane_b32 s0, v251, 37
	v_readlane_b32 s1, v251, 38
	s_nop 1
	v_lshl_add_u64 v[32:33], v[28:29], 0, s[0:1]
	v_readlane_b32 s0, v254, 1
	global_load_dwordx2 v[80:81], v[32:33], off
	v_readlane_b32 s1, v254, 2
	s_nop 1
	v_lshl_add_u64 v[32:33], v[28:29], 0, s[0:1]
	v_readlane_b32 s0, v254, 3
	global_load_dwordx2 v[82:83], v[32:33], off
	v_readlane_b32 s1, v254, 4
	s_nop 1
	v_lshl_add_u64 v[32:33], v[28:29], 0, s[0:1]
	v_readlane_b32 s0, v254, 5
	global_load_dwordx2 v[36:37], v[32:33], off
	v_readlane_b32 s1, v254, 6
	s_nop 1
	v_lshl_add_u64 v[32:33], v[28:29], 0, s[0:1]
	global_load_dwordx2 v[32:33], v[32:33], off
	v_readlane_b32 s0, v252, 1
	s_nop 1
	v_mov_b32_e32 v1, s0
	ds_read_b128 v[38:41], v1
	v_readlane_b32 s0, v252, 3
	s_lshl_b32 s8, s0, 1
	v_readlane_b32 s0, v252, 7
	ds_read_b128 v[42:45], v1 offset:16
	ds_read_b128 v[46:49], v1 offset:32
	ds_read_b128 v[50:53], v1 offset:48
	s_waitcnt lgkmcnt(3)
	v_pk_mul_f32 v[86:87], v[26:27], v[38:39] op_sel_hi:[1,0]
	v_pk_mul_f32 v[88:89], v[26:27], v[38:39] op_sel:[0,1]
	s_waitcnt vmcnt(15)
	v_pk_fma_f32 v[84:85], v[56:57], v[86:87], v[84:85]
	v_pk_mul_f32 v[104:105], v[56:57], v[86:87]
	v_pk_add_f32 v[34:35], v[84:85], v[34:35] neg_lo:[0,1] neg_hi:[0,1]
	v_pk_mul_f32 v[90:91], v[26:27], v[40:41] op_sel_hi:[1,0]
	v_pk_fma_f32 v[54:55], v[54:55], v[34:35], v[104:105] op_sel_hi:[0,1,1] neg_lo:[0,0,1] neg_hi:[0,0,1]
	s_waitcnt vmcnt(14)
	v_pk_fma_f32 v[34:35], v[58:59], v[88:89], v[34:35]
	v_pk_mul_f32 v[106:107], v[58:59], v[88:89]
	v_pk_add_f32 v[30:31], v[34:35], v[30:31] neg_lo:[0,1] neg_hi:[0,1]
	v_mov_b32_e32 v38, v41
	v_cvt_pk_bf16_f32 v84, v54, v55
	v_lshl_add_u64 v[54:55], v[24:25], 0, s[8:9]
	v_pk_fma_f32 v[34:35], v[30:31], 0.5, v[106:107] op_sel_hi:[1,0,1] neg_lo:[0,0,1] neg_hi:[0,0,1]
	s_lshl_b32 s8, s0, 1
	s_waitcnt vmcnt(13)
	v_pk_fma_f32 v[30:31], v[60:61], v[90:91], v[30:31]
	v_pk_mul_f32 v[100:101], v[26:27], v[38:39] op_sel_hi:[1,0]
	v_pk_mul_f32 v[108:109], v[60:61], v[90:91]
	global_store_dword v[54:55], v84, off nt
	v_cvt_pk_bf16_f32 v54, v34, v35
	v_lshl_add_u64 v[34:35], v[24:25], 0, s[8:9]
	v_pk_fma_f32 v[30:31], v[56:57], v[86:87], v[30:31] neg_lo:[1,0,0] neg_hi:[1,0,0]
	v_readlane_b32 s0, v252, 11
	global_store_dword v[34:35], v54, off nt
	v_pk_fma_f32 v[34:35], v[30:31], 0.5, v[108:109] op_sel_hi:[1,0,1] neg_lo:[0,0,1] neg_hi:[0,0,1]
	s_lshl_b32 s8, s0, 1
	s_waitcnt vmcnt(14)
	v_pk_fma_f32 v[30:31], v[62:63], v[100:101], v[30:31]
	s_waitcnt lgkmcnt(2)
	v_pk_mul_f32 v[40:41], v[26:27], v[42:43] op_sel_hi:[1,0]
	v_pk_mul_f32 v[110:111], v[62:63], v[100:101]
	v_cvt_pk_bf16_f32 v54, v34, v35
	v_lshl_add_u64 v[34:35], v[24:25], 0, s[8:9]
	v_pk_fma_f32 v[30:31], v[58:59], v[88:89], v[30:31] neg_lo:[1,0,0] neg_hi:[1,0,0]
	v_readlane_b32 s0, v252, 15
	global_store_dword v[34:35], v54, off nt
	v_pk_fma_f32 v[34:35], v[30:31], 0.5, v[110:111] op_sel_hi:[1,0,1] neg_lo:[0,0,1] neg_hi:[0,0,1]
	s_lshl_b32 s8, s0, 1
	s_waitcnt vmcnt(14)
	v_pk_fma_f32 v[30:31], v[64:65], v[40:41], v[30:31]
	v_pk_mul_f32 v[92:93], v[26:27], v[42:43] op_sel:[0,1]
	v_pk_mul_f32 v[112:113], v[64:65], v[40:41]
	v_cvt_pk_bf16_f32 v54, v34, v35
	v_lshl_add_u64 v[34:35], v[24:25], 0, s[8:9]
	v_pk_fma_f32 v[30:31], v[60:61], v[90:91], v[30:31] neg_lo:[1,0,0] neg_hi:[1,0,0]
	v_readlane_b32 s0, v252, 19
	global_store_dword v[34:35], v54, off nt
	v_pk_fma_f32 v[34:35], v[30:31], 0.5, v[112:113] op_sel_hi:[1,0,1] neg_lo:[0,0,1] neg_hi:[0,0,1]
	s_lshl_b32 s8, s0, 1
	s_waitcnt vmcnt(14)
	v_pk_fma_f32 v[30:31], v[66:67], v[92:93], v[30:31]
	v_pk_mul_f32 v[94:95], v[26:27], v[44:45] op_sel_hi:[1,0]
	v_pk_mul_f32 v[114:115], v[66:67], v[92:93]
	v_cvt_pk_bf16_f32 v54, v34, v35
	v_lshl_add_u64 v[34:35], v[24:25], 0, s[8:9]
	v_pk_fma_f32 v[30:31], v[62:63], v[100:101], v[30:31] neg_lo:[1,0,0] neg_hi:[1,0,0]
	v_readlane_b32 s0, v252, 23
	v_mov_b32_e32 v42, v45
	global_store_dword v[34:35], v54, off nt
	v_pk_fma_f32 v[34:35], v[30:31], 0.5, v[114:115] op_sel_hi:[1,0,1] neg_lo:[0,0,1] neg_hi:[0,0,1]
	s_lshl_b32 s8, s0, 1
	s_waitcnt vmcnt(14)
	v_pk_fma_f32 v[30:31], v[68:69], v[94:95], v[30:31]
	v_pk_mul_f32 v[102:103], v[26:27], v[42:43] op_sel_hi:[1,0]
	v_pk_mul_f32 v[116:117], v[68:69], v[94:95]
	v_cvt_pk_bf16_f32 v54, v34, v35
	v_lshl_add_u64 v[34:35], v[24:25], 0, s[8:9]
	v_pk_fma_f32 v[30:31], v[64:65], v[40:41], v[30:31] neg_lo:[1,0,0] neg_hi:[1,0,0]
	v_readlane_b32 s0, v252, 27
	global_store_dword v[34:35], v54, off nt
	v_pk_fma_f32 v[34:35], v[30:31], 0.5, v[116:117] op_sel_hi:[1,0,1] neg_lo:[0,0,1] neg_hi:[0,0,1]
	s_lshl_b32 s8, s0, 1
	s_waitcnt vmcnt(14)
	v_pk_fma_f32 v[30:31], v[70:71], v[102:103], v[30:31]
	s_waitcnt lgkmcnt(1)
	v_pk_mul_f32 v[44:45], v[26:27], v[46:47] op_sel_hi:[1,0]
	v_pk_mul_f32 v[118:119], v[70:71], v[102:103]
	v_cvt_pk_bf16_f32 v40, v34, v35
	v_lshl_add_u64 v[34:35], v[24:25], 0, s[8:9]
	v_pk_fma_f32 v[30:31], v[66:67], v[92:93], v[30:31] neg_lo:[1,0,0] neg_hi:[1,0,0]
	v_readlane_b32 s0, v252, 30
	global_store_dword v[34:35], v40, off nt
	v_pk_fma_f32 v[34:35], v[30:31], 0.5, v[118:119] op_sel_hi:[1,0,1] neg_lo:[0,0,1] neg_hi:[0,0,1]
	s_lshl_b32 s8, s0, 1
	s_waitcnt vmcnt(14)
	v_pk_fma_f32 v[30:31], v[72:73], v[44:45], v[30:31]
	v_pk_mul_f32 v[46:47], v[26:27], v[46:47] op_sel:[0,1]
	v_pk_mul_f32 v[120:121], v[72:73], v[44:45]
	v_cvt_pk_bf16_f32 v40, v34, v35
	v_lshl_add_u64 v[34:35], v[24:25], 0, s[8:9]
	v_pk_fma_f32 v[30:31], v[68:69], v[94:95], v[30:31] neg_lo:[1,0,0] neg_hi:[1,0,0]
	v_readlane_b32 s0, v252, 33
	global_store_dword v[34:35], v40, off nt
	v_pk_fma_f32 v[34:35], v[30:31], 0.5, v[120:121] op_sel_hi:[1,0,1] neg_lo:[0,0,1] neg_hi:[0,0,1]
	s_lshl_b32 s8, s0, 1
	s_waitcnt vmcnt(14)
	v_pk_fma_f32 v[30:31], v[74:75], v[46:47], v[30:31]
	v_pk_mul_f32 v[96:97], v[26:27], v[48:49] op_sel_hi:[1,0]
	v_pk_mul_f32 v[122:123], v[74:75], v[46:47]
	v_cvt_pk_bf16_f32 v40, v34, v35
	v_lshl_add_u64 v[34:35], v[24:25], 0, s[8:9]
	v_pk_fma_f32 v[30:31], v[70:71], v[102:103], v[30:31] neg_lo:[1,0,0] neg_hi:[1,0,0]
	v_readlane_b32 s0, v252, 36
	v_mov_b32_e32 v48, v49
	global_store_dword v[34:35], v40, off nt
	v_pk_fma_f32 v[34:35], v[30:31], 0.5, v[122:123] op_sel_hi:[1,0,1] neg_lo:[0,0,1] neg_hi:[0,0,1]
	s_lshl_b32 s8, s0, 1
	s_waitcnt vmcnt(14)
	v_pk_fma_f32 v[30:31], v[76:77], v[96:97], v[30:31]
	v_pk_mul_f32 v[48:49], v[26:27], v[48:49] op_sel_hi:[1,0]
	v_pk_mul_f32 v[124:125], v[76:77], v[96:97]
	v_cvt_pk_bf16_f32 v40, v34, v35
	v_lshl_add_u64 v[34:35], v[24:25], 0, s[8:9]
	v_pk_fma_f32 v[30:31], v[72:73], v[44:45], v[30:31] neg_lo:[1,0,0] neg_hi:[1,0,0]
	v_readlane_b32 s0, v252, 39
	global_store_dword v[34:35], v40, off nt
	v_pk_fma_f32 v[34:35], v[30:31], 0.5, v[124:125] op_sel_hi:[1,0,1] neg_lo:[0,0,1] neg_hi:[0,0,1]
	s_lshl_b32 s8, s0, 1
	s_waitcnt vmcnt(14)
	v_pk_fma_f32 v[30:31], v[78:79], v[48:49], v[30:31]
	s_waitcnt lgkmcnt(0)
	v_pk_mul_f32 v[98:99], v[26:27], v[50:51] op_sel_hi:[1,0]
	v_pk_mul_f32 v[126:127], v[78:79], v[48:49]
	v_cvt_pk_bf16_f32 v40, v34, v35
	v_lshl_add_u64 v[34:35], v[24:25], 0, s[8:9]
	v_pk_fma_f32 v[30:31], v[74:75], v[46:47], v[30:31] neg_lo:[1,0,0] neg_hi:[1,0,0]
	v_readlane_b32 s0, v252, 42
	global_store_dword v[34:35], v40, off nt
	v_pk_fma_f32 v[34:35], v[30:31], 0.5, v[126:127] op_sel_hi:[1,0,1] neg_lo:[0,0,1] neg_hi:[0,0,1]
	s_lshl_b32 s8, s0, 1
	s_waitcnt vmcnt(14)
	v_pk_fma_f32 v[30:31], v[80:81], v[98:99], v[30:31]
	v_pk_mul_f32 v[128:129], v[80:81], v[98:99]
	v_pk_mul_f32 v[50:51], v[26:27], v[50:51] op_sel:[0,1]
	v_cvt_pk_bf16_f32 v40, v34, v35
	v_lshl_add_u64 v[34:35], v[24:25], 0, s[8:9]
	v_pk_fma_f32 v[30:31], v[76:77], v[96:97], v[30:31] neg_lo:[1,0,0] neg_hi:[1,0,0]
	v_readlane_b32 s0, v252, 45
	global_store_dword v[34:35], v40, off nt
	v_pk_fma_f32 v[34:35], v[30:31], 0.5, v[128:129] op_sel_hi:[1,0,1] neg_lo:[0,0,1] neg_hi:[0,0,1]
	s_lshl_b32 s8, s0, 1
	s_waitcnt vmcnt(14)
	v_pk_fma_f32 v[30:31], v[82:83], v[50:51], v[30:31]
	v_pk_mul_f32 v[130:131], v[82:83], v[50:51]
	v_pk_mul_f32 v[42:43], v[26:27], v[52:53] op_sel_hi:[1,0]
	v_cvt_pk_bf16_f32 v40, v34, v35
	v_lshl_add_u64 v[34:35], v[24:25], 0, s[8:9]
	v_pk_fma_f32 v[30:31], v[78:79], v[48:49], v[30:31] neg_lo:[1,0,0] neg_hi:[1,0,0]
	v_readlane_b32 s0, v252, 47
	v_mov_b32_e32 v38, v53
	global_store_dword v[34:35], v40, off nt
	v_pk_fma_f32 v[34:35], v[30:31], 0.5, v[130:131] op_sel_hi:[1,0,1] neg_lo:[0,0,1] neg_hi:[0,0,1]
	s_lshl_b32 s8, s0, 1
	s_waitcnt vmcnt(14)
	v_pk_fma_f32 v[30:31], v[36:37], v[42:43], v[30:31]
	v_pk_mul_f32 v[132:133], v[36:37], v[42:43]
	v_pk_mul_f32 v[38:39], v[26:27], v[38:39] op_sel_hi:[1,0]
	v_cvt_pk_bf16_f32 v40, v34, v35
	v_lshl_add_u64 v[34:35], v[24:25], 0, s[8:9]
	v_pk_fma_f32 v[30:31], v[80:81], v[98:99], v[30:31] neg_lo:[1,0,0] neg_hi:[1,0,0]
	global_store_dword v[34:35], v40, off nt
	v_pk_fma_f32 v[34:35], v[30:31], 0.5, v[132:133] op_sel_hi:[1,0,1] neg_lo:[0,0,1] neg_hi:[0,0,1]
	v_readlane_b32 s0, v252, 48
	s_waitcnt vmcnt(14)
	v_pk_fma_f32 v[30:31], v[32:33], v[38:39], v[30:31]
	v_pk_mul_f32 v[52:53], v[32:33], v[38:39]
	s_lshl_b32 s8, s0, 1
	v_pk_fma_f32 v[60:61], v[82:83], v[50:51], v[30:31] neg_lo:[1,0,0] neg_hi:[1,0,0]
	v_readlane_b32 s0, v252, 49
	v_cvt_pk_bf16_f32 v40, v34, v35
	v_lshl_add_u64 v[34:35], v[24:25], 0, s[8:9]
	v_pk_fma_f32 v[30:31], v[60:61], 0.5, v[52:53] op_sel_hi:[1,0,1] neg_lo:[0,0,1] neg_hi:[0,0,1]
	s_lshl_b32 s8, s0, 1
	v_readlane_b32 s0, v252, 51
	global_store_dword v[34:35], v40, off nt
	v_cvt_pk_bf16_f32 v34, v30, v31
	v_lshl_add_u64 v[30:31], v[24:25], 0, s[8:9]
	v_readlane_b32 s1, v252, 52
	global_store_dword v[30:31], v34, off nt
	s_nop 0
	v_lshl_add_u64 v[30:31], v[28:29], 0, s[0:1]
	v_readlane_b32 s0, v252, 54
	global_load_dwordx2 v[62:63], v[30:31], off
	v_readlane_b32 s1, v252, 55
	s_nop 1
	v_lshl_add_u64 v[30:31], v[28:29], 0, s[0:1]
	v_readlane_b32 s0, v252, 56
	global_load_dwordx2 v[64:65], v[30:31], off
	v_readlane_b32 s1, v252, 57
	s_nop 1
	v_lshl_add_u64 v[30:31], v[28:29], 0, s[0:1]
	v_readlane_b32 s0, v252, 59
	global_load_dwordx2 v[66:67], v[30:31], off
	v_readlane_b32 s1, v252, 60
	s_nop 1
	v_lshl_add_u64 v[30:31], v[28:29], 0, s[0:1]
	v_readlane_b32 s0, v252, 62
	global_load_dwordx2 v[68:69], v[30:31], off
	v_readlane_b32 s1, v252, 63
	s_nop 1
	v_lshl_add_u64 v[30:31], v[28:29], 0, s[0:1]
	v_readlane_b32 s0, v253, 1
	global_load_dwordx2 v[70:71], v[30:31], off
	v_readlane_b32 s1, v253, 2
	s_nop 1
	v_lshl_add_u64 v[30:31], v[28:29], 0, s[0:1]
	v_readlane_b32 s0, v253, 4
	global_load_dwordx2 v[72:73], v[30:31], off
	v_readlane_b32 s1, v253, 5
	s_nop 1
	v_lshl_add_u64 v[30:31], v[28:29], 0, s[0:1]
	v_readlane_b32 s0, v253, 7
	global_load_dwordx2 v[74:75], v[30:31], off
	v_readlane_b32 s1, v253, 8
	s_nop 1
	v_lshl_add_u64 v[30:31], v[28:29], 0, s[0:1]
	v_readlane_b32 s0, v253, 10
	global_load_dwordx2 v[76:77], v[30:31], off
	v_readlane_b32 s1, v253, 11
	s_nop 1
	v_lshl_add_u64 v[30:31], v[28:29], 0, s[0:1]
	v_readlane_b32 s0, v253, 13
	global_load_dwordx2 v[78:79], v[30:31], off
	v_readlane_b32 s1, v253, 14
	s_nop 1
	v_lshl_add_u64 v[30:31], v[28:29], 0, s[0:1]
	v_readlane_b32 s0, v254, 7
	global_load_dwordx2 v[80:81], v[30:31], off
	v_readlane_b32 s1, v254, 8
	s_nop 1
	v_lshl_add_u64 v[30:31], v[28:29], 0, s[0:1]
	v_readlane_b32 s0, v254, 9
	global_load_dwordx2 v[82:83], v[30:31], off
	v_readlane_b32 s1, v254, 10
	s_nop 1
	v_lshl_add_u64 v[30:31], v[28:29], 0, s[0:1]
	v_readlane_b32 s0, v254, 11
	global_load_dwordx2 v[84:85], v[30:31], off
	v_readlane_b32 s1, v254, 12
	s_nop 1
	v_lshl_add_u64 v[30:31], v[28:29], 0, s[0:1]
	v_readlane_b32 s0, v254, 13
	global_load_dwordx2 v[86:87], v[30:31], off
	v_readlane_b32 s1, v254, 14
	s_nop 1
	v_lshl_add_u64 v[30:31], v[28:29], 0, s[0:1]
	v_readlane_b32 s0, v254, 15
	global_load_dwordx2 v[88:89], v[30:31], off
	v_readlane_b32 s1, v254, 16
	s_nop 1
	v_lshl_add_u64 v[30:31], v[28:29], 0, s[0:1]
	v_readlane_b32 s0, v254, 17
	global_load_dwordx2 v[34:35], v[30:31], off
	v_readlane_b32 s1, v254, 18
	s_nop 1
	v_lshl_add_u64 v[30:31], v[28:29], 0, s[0:1]
	global_load_dwordx2 v[30:31], v[30:31], off
	ds_read_b128 v[44:47], v1 offset:64
	ds_read_b128 v[48:51], v1 offset:80
	ds_read_b128 v[52:55], v1 offset:96
	ds_read_b128 v[56:59], v1 offset:112
	v_readlane_b32 s0, v252, 50
	s_waitcnt lgkmcnt(3)
	v_pk_mul_f32 v[90:91], v[26:27], v[44:45] op_sel_hi:[1,0]
	v_pk_mul_f32 v[94:95], v[26:27], v[44:45] op_sel:[0,1]
	s_waitcnt vmcnt(15)
	v_pk_fma_f32 v[60:61], v[62:63], v[90:91], v[60:61]
	v_pk_mul_f32 v[92:93], v[62:63], v[90:91]
	v_pk_fma_f32 v[36:37], v[36:37], v[42:43], v[60:61] neg_lo:[1,0,0] neg_hi:[1,0,0]
	s_waitcnt vmcnt(14)
	v_pk_mul_f32 v[96:97], v[64:65], v[94:95]
	v_pk_fma_f32 v[42:43], v[36:37], 0.5, v[92:93] op_sel_hi:[1,0,1] neg_lo:[0,0,1] neg_hi:[0,0,1]
	v_pk_fma_f32 v[36:37], v[64:65], v[94:95], v[36:37]
	v_pk_mul_f32 v[98:99], v[26:27], v[46:47] op_sel_hi:[1,0]
	s_lshl_b32 s8, s0, 1
	v_pk_fma_f32 v[32:33], v[32:33], v[38:39], v[36:37] neg_lo:[1,0,0] neg_hi:[1,0,0]
	v_readlane_b32 s0, v252, 53
	v_mov_b32_e32 v40, v47
	v_cvt_pk_bf16_f32 v60, v42, v43
	v_lshl_add_u64 v[42:43], v[24:25], 0, s[8:9]
	v_pk_fma_f32 v[36:37], v[32:33], 0.5, v[96:97] op_sel_hi:[1,0,1] neg_lo:[0,0,1] neg_hi:[0,0,1]
	s_lshl_b32 s8, s0, 1
	s_waitcnt vmcnt(13)
	v_pk_fma_f32 v[32:33], v[66:67], v[98:99], v[32:33]
	v_pk_mul_f32 v[100:101], v[66:67], v[98:99]
	v_pk_mul_f32 v[46:47], v[26:27], v[40:41] op_sel_hi:[1,0]
	global_store_dword v[42:43], v60, off nt
	v_cvt_pk_bf16_f32 v38, v36, v37
	v_lshl_add_u64 v[36:37], v[24:25], 0, s[8:9]
	v_pk_fma_f32 v[32:33], v[62:63], v[90:91], v[32:33] neg_lo:[1,0,0] neg_hi:[1,0,0]
	global_store_dword v[36:37], v38, off nt
	v_pk_fma_f32 v[36:37], v[32:33], 0.5, v[100:101] op_sel_hi:[1,0,1] neg_lo:[0,0,1] neg_hi:[0,0,1]
	s_lshl_b32 s8, s5, 1
	s_waitcnt vmcnt(14)
	v_pk_fma_f32 v[32:33], v[68:69], v[46:47], v[32:33]
	v_pk_mul_f32 v[102:103], v[68:69], v[46:47]
	s_waitcnt lgkmcnt(2)
	v_pk_mul_f32 v[104:105], v[26:27], v[48:49] op_sel_hi:[1,0]
	v_cvt_pk_bf16_f32 v38, v36, v37
	v_lshl_add_u64 v[36:37], v[24:25], 0, s[8:9]
	v_pk_fma_f32 v[32:33], v[64:65], v[94:95], v[32:33] neg_lo:[1,0,0] neg_hi:[1,0,0]
	v_readlane_b32 s0, v252, 58
	global_store_dword v[36:37], v38, off nt
	v_pk_fma_f32 v[36:37], v[32:33], 0.5, v[102:103] op_sel_hi:[1,0,1] neg_lo:[0,0,1] neg_hi:[0,0,1]
	s_lshl_b32 s8, s0, 1
	s_waitcnt vmcnt(14)
	v_pk_fma_f32 v[32:33], v[70:71], v[104:105], v[32:33]
	v_pk_mul_f32 v[106:107], v[70:71], v[104:105]
	v_pk_mul_f32 v[48:49], v[26:27], v[48:49] op_sel:[0,1]
	v_cvt_pk_bf16_f32 v38, v36, v37
	v_lshl_add_u64 v[36:37], v[24:25], 0, s[8:9]
	v_pk_fma_f32 v[32:33], v[66:67], v[98:99], v[32:33] neg_lo:[1,0,0] neg_hi:[1,0,0]
	v_readlane_b32 s0, v252, 61
	global_store_dword v[36:37], v38, off nt
	v_pk_fma_f32 v[36:37], v[32:33], 0.5, v[106:107] op_sel_hi:[1,0,1] neg_lo:[0,0,1] neg_hi:[0,0,1]
	s_lshl_b32 s8, s0, 1
	s_waitcnt vmcnt(14)
	v_pk_fma_f32 v[32:33], v[72:73], v[48:49], v[32:33]
	v_pk_mul_f32 v[108:109], v[72:73], v[48:49]
	v_pk_mul_f32 v[110:111], v[26:27], v[50:51] op_sel_hi:[1,0]
	v_cvt_pk_bf16_f32 v38, v36, v37
	v_lshl_add_u64 v[36:37], v[24:25], 0, s[8:9]
	v_pk_fma_f32 v[32:33], v[68:69], v[46:47], v[32:33] neg_lo:[1,0,0] neg_hi:[1,0,0]
	v_readlane_b32 s0, v253, 0
	v_mov_b32_e32 v40, v51
	global_store_dword v[36:37], v38, off nt
	v_pk_fma_f32 v[36:37], v[32:33], 0.5, v[108:109] op_sel_hi:[1,0,1] neg_lo:[0,0,1] neg_hi:[0,0,1]
	s_lshl_b32 s8, s0, 1
	s_waitcnt vmcnt(14)
	v_pk_fma_f32 v[32:33], v[74:75], v[110:111], v[32:33]
	v_pk_mul_f32 v[112:113], v[74:75], v[110:111]
	v_pk_mul_f32 v[50:51], v[26:27], v[40:41] op_sel_hi:[1,0]
	v_cvt_pk_bf16_f32 v38, v36, v37
	v_lshl_add_u64 v[36:37], v[24:25], 0, s[8:9]
	v_pk_fma_f32 v[32:33], v[70:71], v[104:105], v[32:33] neg_lo:[1,0,0] neg_hi:[1,0,0]
	v_readlane_b32 s0, v253, 3
	global_store_dword v[36:37], v38, off nt
	v_pk_fma_f32 v[36:37], v[32:33], 0.5, v[112:113] op_sel_hi:[1,0,1] neg_lo:[0,0,1] neg_hi:[0,0,1]
	s_lshl_b32 s8, s0, 1
	s_waitcnt vmcnt(14)
	v_pk_fma_f32 v[32:33], v[76:77], v[50:51], v[32:33]
	v_pk_mul_f32 v[114:115], v[76:77], v[50:51]
	s_waitcnt lgkmcnt(1)
	v_pk_mul_f32 v[116:117], v[26:27], v[52:53] op_sel_hi:[1,0]
	v_cvt_pk_bf16_f32 v38, v36, v37
	v_lshl_add_u64 v[36:37], v[24:25], 0, s[8:9]
	v_pk_fma_f32 v[32:33], v[72:73], v[48:49], v[32:33] neg_lo:[1,0,0] neg_hi:[1,0,0]
	v_readlane_b32 s0, v253, 6
	global_store_dword v[36:37], v38, off nt
	v_pk_fma_f32 v[36:37], v[32:33], 0.5, v[114:115] op_sel_hi:[1,0,1] neg_lo:[0,0,1] neg_hi:[0,0,1]
	s_lshl_b32 s8, s0, 1
	s_waitcnt vmcnt(14)
	v_pk_fma_f32 v[32:33], v[78:79], v[116:117], v[32:33]
	v_pk_mul_f32 v[118:119], v[78:79], v[116:117]
	v_pk_mul_f32 v[52:53], v[26:27], v[52:53] op_sel:[0,1]
	v_cvt_pk_bf16_f32 v38, v36, v37
	v_lshl_add_u64 v[36:37], v[24:25], 0, s[8:9]
	v_pk_fma_f32 v[32:33], v[74:75], v[110:111], v[32:33] neg_lo:[1,0,0] neg_hi:[1,0,0]
	v_readlane_b32 s0, v253, 9
	global_store_dword v[36:37], v38, off nt
	v_pk_fma_f32 v[36:37], v[32:33], 0.5, v[118:119] op_sel_hi:[1,0,1] neg_lo:[0,0,1] neg_hi:[0,0,1]
	s_lshl_b32 s8, s0, 1
	s_waitcnt vmcnt(14)
	v_pk_fma_f32 v[32:33], v[80:81], v[52:53], v[32:33]
	v_pk_mul_f32 v[120:121], v[80:81], v[52:53]
	v_pk_mul_f32 v[122:123], v[26:27], v[54:55] op_sel_hi:[1,0]
	v_cvt_pk_bf16_f32 v38, v36, v37
	v_lshl_add_u64 v[36:37], v[24:25], 0, s[8:9]
	v_pk_fma_f32 v[32:33], v[76:77], v[50:51], v[32:33] neg_lo:[1,0,0] neg_hi:[1,0,0]
	v_readlane_b32 s0, v253, 12
	v_mov_b32_e32 v40, v55
	global_store_dword v[36:37], v38, off nt
	v_pk_fma_f32 v[36:37], v[32:33], 0.5, v[120:121] op_sel_hi:[1,0,1] neg_lo:[0,0,1] neg_hi:[0,0,1]
	s_lshl_b32 s8, s0, 1
	s_waitcnt vmcnt(14)
	v_pk_fma_f32 v[32:33], v[82:83], v[122:123], v[32:33]
	v_pk_mul_f32 v[124:125], v[82:83], v[122:123]
	v_pk_mul_f32 v[54:55], v[26:27], v[40:41] op_sel_hi:[1,0]
	v_cvt_pk_bf16_f32 v38, v36, v37
	v_lshl_add_u64 v[36:37], v[24:25], 0, s[8:9]
	v_pk_fma_f32 v[32:33], v[78:79], v[116:117], v[32:33] neg_lo:[1,0,0] neg_hi:[1,0,0]
	v_readlane_b32 s0, v253, 15
	global_store_dword v[36:37], v38, off nt
	v_pk_fma_f32 v[36:37], v[32:33], 0.5, v[124:125] op_sel_hi:[1,0,1] neg_lo:[0,0,1] neg_hi:[0,0,1]
	s_lshl_b32 s8, s0, 1
	s_waitcnt vmcnt(14)
	v_pk_fma_f32 v[32:33], v[84:85], v[54:55], v[32:33]
	v_pk_mul_f32 v[126:127], v[84:85], v[54:55]
	s_waitcnt lgkmcnt(0)
	v_pk_mul_f32 v[128:129], v[26:27], v[56:57] op_sel_hi:[1,0]
	v_cvt_pk_bf16_f32 v38, v36, v37
	v_lshl_add_u64 v[36:37], v[24:25], 0, s[8:9]
	v_pk_fma_f32 v[32:33], v[80:81], v[52:53], v[32:33] neg_lo:[1,0,0] neg_hi:[1,0,0]
	v_readlane_b32 s0, v253, 16
	global_store_dword v[36:37], v38, off nt
	v_pk_fma_f32 v[36:37], v[32:33], 0.5, v[126:127] op_sel_hi:[1,0,1] neg_lo:[0,0,1] neg_hi:[0,0,1]
	s_lshl_b32 s8, s0, 1
	s_waitcnt vmcnt(14)
	v_pk_fma_f32 v[32:33], v[86:87], v[128:129], v[32:33]
	v_pk_mul_f32 v[130:131], v[86:87], v[128:129]
	v_pk_mul_f32 v[56:57], v[26:27], v[56:57] op_sel:[0,1]
	v_cvt_pk_bf16_f32 v38, v36, v37
	v_lshl_add_u64 v[36:37], v[24:25], 0, s[8:9]
	v_pk_fma_f32 v[32:33], v[82:83], v[122:123], v[32:33] neg_lo:[1,0,0] neg_hi:[1,0,0]
	v_readlane_b32 s0, v253, 17
	global_store_dword v[36:37], v38, off nt
	v_pk_fma_f32 v[36:37], v[32:33], 0.5, v[130:131] op_sel_hi:[1,0,1] neg_lo:[0,0,1] neg_hi:[0,0,1]
	s_lshl_b32 s8, s0, 1
	s_waitcnt vmcnt(14)
	v_pk_fma_f32 v[32:33], v[88:89], v[56:57], v[32:33]
	v_pk_mul_f32 v[132:133], v[88:89], v[56:57]
	v_pk_mul_f32 v[44:45], v[26:27], v[58:59] op_sel_hi:[1,0]
	v_cvt_pk_bf16_f32 v38, v36, v37
	v_lshl_add_u64 v[36:37], v[24:25], 0, s[8:9]
	v_pk_fma_f32 v[32:33], v[84:85], v[54:55], v[32:33] neg_lo:[1,0,0] neg_hi:[1,0,0]
	v_readlane_b32 s0, v253, 18
	v_mov_b32_e32 v40, v59
	global_store_dword v[36:37], v38, off nt
	v_pk_fma_f32 v[36:37], v[32:33], 0.5, v[132:133] op_sel_hi:[1,0,1] neg_lo:[0,0,1] neg_hi:[0,0,1]
	s_lshl_b32 s8, s0, 1
	s_waitcnt vmcnt(14)
	v_pk_fma_f32 v[32:33], v[34:35], v[44:45], v[32:33]
	v_pk_mul_f32 v[134:135], v[34:35], v[44:45]
	v_pk_mul_f32 v[40:41], v[26:27], v[40:41] op_sel_hi:[1,0]
	v_cvt_pk_bf16_f32 v38, v36, v37
	v_lshl_add_u64 v[36:37], v[24:25], 0, s[8:9]
	v_pk_fma_f32 v[32:33], v[86:87], v[128:129], v[32:33] neg_lo:[1,0,0] neg_hi:[1,0,0]
	global_store_dword v[36:37], v38, off nt
	v_pk_fma_f32 v[36:37], v[32:33], 0.5, v[134:135] op_sel_hi:[1,0,1] neg_lo:[0,0,1] neg_hi:[0,0,1]
	v_readlane_b32 s0, v253, 19
	s_waitcnt vmcnt(14)
	v_pk_fma_f32 v[32:33], v[30:31], v[40:41], v[32:33]
	v_pk_mul_f32 v[58:59], v[30:31], v[40:41]
	s_lshl_b32 s8, s0, 1
	v_pk_fma_f32 v[62:63], v[88:89], v[56:57], v[32:33] neg_lo:[1,0,0] neg_hi:[1,0,0]
	v_cvt_pk_bf16_f32 v38, v36, v37
	v_lshl_add_u64 v[36:37], v[24:25], 0, s[8:9]
	v_pk_fma_f32 v[32:33], v[62:63], 0.5, v[58:59] op_sel_hi:[1,0,1] neg_lo:[0,0,1] neg_hi:[0,0,1]
	s_lshl_b32 s8, s4, 1
	v_readlane_b32 s0, v254, 19
	global_store_dword v[36:37], v38, off nt
	v_cvt_pk_bf16_f32 v36, v32, v33
	v_lshl_add_u64 v[32:33], v[24:25], 0, s[8:9]
	v_readlane_b32 s1, v254, 20
	global_store_dword v[32:33], v36, off nt
	s_nop 0
	v_lshl_add_u64 v[32:33], v[28:29], 0, s[0:1]
	v_readlane_b32 s0, v254, 21
	global_load_dwordx2 v[64:65], v[32:33], off
	v_readlane_b32 s1, v254, 22
	s_nop 1
	v_lshl_add_u64 v[32:33], v[28:29], 0, s[0:1]
	v_readlane_b32 s0, v254, 23
	global_load_dwordx2 v[66:67], v[32:33], off
	v_readlane_b32 s1, v254, 24
	s_nop 1
	v_lshl_add_u64 v[32:33], v[28:29], 0, s[0:1]
	v_readlane_b32 s0, v254, 25
	global_load_dwordx2 v[68:69], v[32:33], off
	v_readlane_b32 s1, v254, 26
	s_nop 1
	v_lshl_add_u64 v[32:33], v[28:29], 0, s[0:1]
	v_readlane_b32 s0, v254, 27
	global_load_dwordx2 v[70:71], v[32:33], off
	v_readlane_b32 s1, v254, 28
	s_nop 1
	v_lshl_add_u64 v[32:33], v[28:29], 0, s[0:1]
	v_readlane_b32 s0, v254, 29
	global_load_dwordx2 v[72:73], v[32:33], off
	v_readlane_b32 s1, v254, 30
	s_nop 1
	v_lshl_add_u64 v[32:33], v[28:29], 0, s[0:1]
	v_readlane_b32 s0, v254, 31
	global_load_dwordx2 v[74:75], v[32:33], off
	v_readlane_b32 s1, v254, 32
	s_nop 1
	v_lshl_add_u64 v[32:33], v[28:29], 0, s[0:1]
	v_readlane_b32 s0, v254, 33
	global_load_dwordx2 v[76:77], v[32:33], off
	v_readlane_b32 s1, v254, 34
	s_nop 1
	v_lshl_add_u64 v[32:33], v[28:29], 0, s[0:1]
	v_readlane_b32 s0, v254, 35
	global_load_dwordx2 v[78:79], v[32:33], off
	v_readlane_b32 s1, v254, 36
	s_nop 1
	v_lshl_add_u64 v[32:33], v[28:29], 0, s[0:1]
	v_readlane_b32 s0, v254, 37
	global_load_dwordx2 v[80:81], v[32:33], off
	v_readlane_b32 s1, v254, 38
	s_nop 1
	v_lshl_add_u64 v[32:33], v[28:29], 0, s[0:1]
	v_readlane_b32 s0, v254, 39
	global_load_dwordx2 v[82:83], v[32:33], off
	v_readlane_b32 s1, v254, 40
	s_nop 1
	v_lshl_add_u64 v[32:33], v[28:29], 0, s[0:1]
	v_readlane_b32 s0, v254, 41
	global_load_dwordx2 v[84:85], v[32:33], off
	v_readlane_b32 s1, v254, 42
	s_nop 1
	v_lshl_add_u64 v[32:33], v[28:29], 0, s[0:1]
	v_readlane_b32 s0, v254, 43
	global_load_dwordx2 v[86:87], v[32:33], off
	v_readlane_b32 s1, v254, 44
	s_nop 1
	v_lshl_add_u64 v[32:33], v[28:29], 0, s[0:1]
	v_readlane_b32 s0, v254, 45
	global_load_dwordx2 v[88:89], v[32:33], off
	v_readlane_b32 s1, v254, 46
	s_nop 1
	v_lshl_add_u64 v[32:33], v[28:29], 0, s[0:1]
	v_readlane_b32 s0, v254, 47
	global_load_dwordx2 v[90:91], v[32:33], off
	v_readlane_b32 s1, v254, 48
	s_nop 1
	v_lshl_add_u64 v[32:33], v[28:29], 0, s[0:1]
	global_load_dwordx2 v[36:37], v[32:33], off
	v_readlane_b32 s0, v254, 49
	v_readlane_b32 s1, v254, 50
	s_nop 1
	v_lshl_add_u64 v[32:33], v[28:29], 0, s[0:1]
	global_load_dwordx2 v[32:33], v[32:33], off
	ds_read_b128 v[46:49], v1 offset:128
	ds_read_b128 v[50:53], v1 offset:144
	ds_read_b128 v[54:57], v1 offset:160
	ds_read_b128 v[58:61], v1 offset:176
	v_readlane_b32 s0, v253, 20
	s_waitcnt lgkmcnt(3)
	v_pk_mul_f32 v[92:93], v[26:27], v[46:47] op_sel_hi:[1,0]
	v_pk_mul_f32 v[46:47], v[26:27], v[46:47] op_sel:[0,1]
	s_waitcnt vmcnt(15)
	v_pk_fma_f32 v[62:63], v[64:65], v[92:93], v[62:63]
	v_pk_mul_f32 v[94:95], v[64:65], v[92:93]
	v_pk_fma_f32 v[34:35], v[34:35], v[44:45], v[62:63] neg_lo:[1,0,0] neg_hi:[1,0,0]
	s_waitcnt vmcnt(14)
	v_pk_mul_f32 v[96:97], v[66:67], v[46:47]
	v_pk_fma_f32 v[44:45], v[34:35], 0.5, v[94:95] op_sel_hi:[1,0,1] neg_lo:[0,0,1] neg_hi:[0,0,1]
	v_pk_fma_f32 v[34:35], v[66:67], v[46:47], v[34:35]
	v_pk_mul_f32 v[98:99], v[26:27], v[48:49] op_sel_hi:[1,0]
	s_lshl_b32 s8, s0, 1
	v_pk_fma_f32 v[30:31], v[30:31], v[40:41], v[34:35] neg_lo:[1,0,0] neg_hi:[1,0,0]
	v_mov_b32_e32 v38, v49
	v_cvt_pk_bf16_f32 v62, v44, v45
	v_lshl_add_u64 v[44:45], v[24:25], 0, s[8:9]
	v_pk_fma_f32 v[34:35], v[30:31], 0.5, v[96:97] op_sel_hi:[1,0,1] neg_lo:[0,0,1] neg_hi:[0,0,1]
	s_lshl_b32 s8, s82, 1
	s_waitcnt vmcnt(13)
	v_pk_fma_f32 v[30:31], v[68:69], v[98:99], v[30:31]
	v_pk_mul_f32 v[100:101], v[68:69], v[98:99]
	v_pk_mul_f32 v[48:49], v[26:27], v[38:39] op_sel_hi:[1,0]
	global_store_dword v[44:45], v62, off nt
	v_cvt_pk_bf16_f32 v40, v34, v35
	v_lshl_add_u64 v[34:35], v[24:25], 0, s[8:9]
	v_pk_fma_f32 v[30:31], v[64:65], v[92:93], v[30:31] neg_lo:[1,0,0] neg_hi:[1,0,0]
	v_readlane_b32 s0, v253, 22
	global_store_dword v[34:35], v40, off nt
	v_pk_fma_f32 v[34:35], v[30:31], 0.5, v[100:101] op_sel_hi:[1,0,1] neg_lo:[0,0,1] neg_hi:[0,0,1]
	s_lshl_b32 s8, s0, 1
	s_waitcnt vmcnt(14)
	v_pk_fma_f32 v[30:31], v[70:71], v[48:49], v[30:31]
	v_pk_mul_f32 v[102:103], v[70:71], v[48:49]
	s_waitcnt lgkmcnt(2)
	v_pk_mul_f32 v[104:105], v[26:27], v[50:51] op_sel_hi:[1,0]
	v_cvt_pk_bf16_f32 v40, v34, v35
	v_lshl_add_u64 v[34:35], v[24:25], 0, s[8:9]
	v_pk_fma_f32 v[30:31], v[66:67], v[46:47], v[30:31] neg_lo:[1,0,0] neg_hi:[1,0,0]
	global_store_dword v[34:35], v40, off nt
	v_pk_fma_f32 v[34:35], v[30:31], 0.5, v[102:103] op_sel_hi:[1,0,1] neg_lo:[0,0,1] neg_hi:[0,0,1]
	s_lshl_b32 s8, s80, 1
	s_waitcnt vmcnt(14)
	v_pk_fma_f32 v[30:31], v[72:73], v[104:105], v[30:31]
	v_pk_mul_f32 v[106:107], v[72:73], v[104:105]
	v_pk_mul_f32 v[50:51], v[26:27], v[50:51] op_sel:[0,1]
	v_cvt_pk_bf16_f32 v40, v34, v35
	v_lshl_add_u64 v[34:35], v[24:25], 0, s[8:9]
	v_pk_fma_f32 v[30:31], v[68:69], v[98:99], v[30:31] neg_lo:[1,0,0] neg_hi:[1,0,0]
	v_readlane_b32 s0, v253, 24
	global_store_dword v[34:35], v40, off nt
	v_pk_fma_f32 v[34:35], v[30:31], 0.5, v[106:107] op_sel_hi:[1,0,1] neg_lo:[0,0,1] neg_hi:[0,0,1]
	s_lshl_b32 s8, s0, 1
	s_waitcnt vmcnt(14)
	v_pk_fma_f32 v[30:31], v[74:75], v[50:51], v[30:31]
	v_pk_mul_f32 v[108:109], v[74:75], v[50:51]
	v_pk_mul_f32 v[110:111], v[26:27], v[52:53] op_sel_hi:[1,0]
	v_cvt_pk_bf16_f32 v40, v34, v35
	v_lshl_add_u64 v[34:35], v[24:25], 0, s[8:9]
	v_pk_fma_f32 v[30:31], v[70:71], v[48:49], v[30:31] neg_lo:[1,0,0] neg_hi:[1,0,0]
	v_mov_b32_e32 v38, v53
	global_store_dword v[34:35], v40, off nt
	v_pk_fma_f32 v[34:35], v[30:31], 0.5, v[108:109] op_sel_hi:[1,0,1] neg_lo:[0,0,1] neg_hi:[0,0,1]
	s_lshl_b32 s8, s79, 1
	s_waitcnt vmcnt(14)
	v_pk_fma_f32 v[30:31], v[76:77], v[110:111], v[30:31]
	v_pk_mul_f32 v[112:113], v[76:77], v[110:111]
	v_pk_mul_f32 v[52:53], v[26:27], v[38:39] op_sel_hi:[1,0]
	v_cvt_pk_bf16_f32 v40, v34, v35
	v_lshl_add_u64 v[34:35], v[24:25], 0, s[8:9]
	v_pk_fma_f32 v[30:31], v[72:73], v[104:105], v[30:31] neg_lo:[1,0,0] neg_hi:[1,0,0]
	global_store_dword v[34:35], v40, off nt
	v_pk_fma_f32 v[34:35], v[30:31], 0.5, v[112:113] op_sel_hi:[1,0,1] neg_lo:[0,0,1] neg_hi:[0,0,1]
	s_lshl_b32 s8, s85, 1
	s_waitcnt vmcnt(14)
	v_pk_fma_f32 v[30:31], v[78:79], v[52:53], v[30:31]
	v_pk_mul_f32 v[114:115], v[78:79], v[52:53]
	s_waitcnt lgkmcnt(1)
	v_pk_mul_f32 v[116:117], v[26:27], v[54:55] op_sel_hi:[1,0]
	v_cvt_pk_bf16_f32 v40, v34, v35
	v_lshl_add_u64 v[34:35], v[24:25], 0, s[8:9]
	v_pk_fma_f32 v[30:31], v[74:75], v[50:51], v[30:31] neg_lo:[1,0,0] neg_hi:[1,0,0]
	v_readlane_b32 s0, v253, 25
	global_store_dword v[34:35], v40, off nt
	v_pk_fma_f32 v[34:35], v[30:31], 0.5, v[114:115] op_sel_hi:[1,0,1] neg_lo:[0,0,1] neg_hi:[0,0,1]
	s_lshl_b32 s8, s0, 1
	s_waitcnt vmcnt(14)
	v_pk_fma_f32 v[30:31], v[80:81], v[116:117], v[30:31]
	v_pk_mul_f32 v[118:119], v[80:81], v[116:117]
	v_pk_mul_f32 v[54:55], v[26:27], v[54:55] op_sel:[0,1]
	v_cvt_pk_bf16_f32 v40, v34, v35
	v_lshl_add_u64 v[34:35], v[24:25], 0, s[8:9]
	v_pk_fma_f32 v[30:31], v[76:77], v[110:111], v[30:31] neg_lo:[1,0,0] neg_hi:[1,0,0]
	v_readlane_b32 s0, v253, 26
	global_store_dword v[34:35], v40, off nt
	v_pk_fma_f32 v[34:35], v[30:31], 0.5, v[118:119] op_sel_hi:[1,0,1] neg_lo:[0,0,1] neg_hi:[0,0,1]
	s_lshl_b32 s8, s0, 1
	s_waitcnt vmcnt(14)
	v_pk_fma_f32 v[30:31], v[82:83], v[54:55], v[30:31]
	v_pk_mul_f32 v[120:121], v[82:83], v[54:55]
	v_pk_mul_f32 v[122:123], v[26:27], v[56:57] op_sel_hi:[1,0]
	v_cvt_pk_bf16_f32 v40, v34, v35
	v_lshl_add_u64 v[34:35], v[24:25], 0, s[8:9]
	v_pk_fma_f32 v[30:31], v[78:79], v[52:53], v[30:31] neg_lo:[1,0,0] neg_hi:[1,0,0]
	v_mov_b32_e32 v38, v57
	global_store_dword v[34:35], v40, off nt
	v_pk_fma_f32 v[34:35], v[30:31], 0.5, v[120:121] op_sel_hi:[1,0,1] neg_lo:[0,0,1] neg_hi:[0,0,1]
	s_lshl_b32 s8, s84, 1
	s_waitcnt vmcnt(14)
	v_pk_fma_f32 v[30:31], v[84:85], v[122:123], v[30:31]
	v_pk_mul_f32 v[124:125], v[84:85], v[122:123]
	v_pk_mul_f32 v[56:57], v[26:27], v[38:39] op_sel_hi:[1,0]
	v_cvt_pk_bf16_f32 v40, v34, v35
	v_lshl_add_u64 v[34:35], v[24:25], 0, s[8:9]
	v_pk_fma_f32 v[30:31], v[80:81], v[116:117], v[30:31] neg_lo:[1,0,0] neg_hi:[1,0,0]
	v_readlane_b32 s0, v253, 28
	global_store_dword v[34:35], v40, off nt
	v_pk_fma_f32 v[34:35], v[30:31], 0.5, v[124:125] op_sel_hi:[1,0,1] neg_lo:[0,0,1] neg_hi:[0,0,1]
	s_lshl_b32 s8, s0, 1
	s_waitcnt vmcnt(14)
	v_pk_fma_f32 v[30:31], v[86:87], v[56:57], v[30:31]
	v_pk_mul_f32 v[126:127], v[86:87], v[56:57]
	s_waitcnt lgkmcnt(0)
	v_pk_mul_f32 v[128:129], v[26:27], v[58:59] op_sel_hi:[1,0]
	v_cvt_pk_bf16_f32 v40, v34, v35
	v_lshl_add_u64 v[34:35], v[24:25], 0, s[8:9]
	v_pk_fma_f32 v[30:31], v[82:83], v[54:55], v[30:31] neg_lo:[1,0,0] neg_hi:[1,0,0]
	v_readlane_b32 s0, v253, 29
	global_store_dword v[34:35], v40, off nt
	v_pk_fma_f32 v[34:35], v[30:31], 0.5, v[126:127] op_sel_hi:[1,0,1] neg_lo:[0,0,1] neg_hi:[0,0,1]
	s_lshl_b32 s8, s0, 1
	s_waitcnt vmcnt(14)
	v_pk_fma_f32 v[30:31], v[88:89], v[128:129], v[30:31]
	v_pk_mul_f32 v[130:131], v[88:89], v[128:129]
	v_pk_mul_f32 v[58:59], v[26:27], v[58:59] op_sel:[0,1]
	v_cvt_pk_bf16_f32 v40, v34, v35
	v_lshl_add_u64 v[34:35], v[24:25], 0, s[8:9]
	v_pk_fma_f32 v[30:31], v[84:85], v[122:123], v[30:31] neg_lo:[1,0,0] neg_hi:[1,0,0]
	v_readlane_b32 s0, v253, 30
	global_store_dword v[34:35], v40, off nt
	v_pk_fma_f32 v[34:35], v[30:31], 0.5, v[130:131] op_sel_hi:[1,0,1] neg_lo:[0,0,1] neg_hi:[0,0,1]
	s_lshl_b32 s8, s0, 1
	s_waitcnt vmcnt(14)
	v_pk_fma_f32 v[30:31], v[90:91], v[58:59], v[30:31]
	v_pk_mul_f32 v[132:133], v[90:91], v[58:59]
	v_pk_mul_f32 v[42:43], v[26:27], v[60:61] op_sel_hi:[1,0]
	v_cvt_pk_bf16_f32 v40, v34, v35
	v_lshl_add_u64 v[34:35], v[24:25], 0, s[8:9]
	v_pk_fma_f32 v[30:31], v[86:87], v[56:57], v[30:31] neg_lo:[1,0,0] neg_hi:[1,0,0]
	v_readlane_b32 s0, v253, 31
	global_store_dword v[34:35], v40, off nt
	v_pk_fma_f32 v[34:35], v[30:31], 0.5, v[132:133] op_sel_hi:[1,0,1] neg_lo:[0,0,1] neg_hi:[0,0,1]
	s_lshl_b32 s8, s0, 1
	s_waitcnt vmcnt(14)
	v_pk_fma_f32 v[30:31], v[36:37], v[42:43], v[30:31]
	v_pk_mul_f32 v[134:135], v[36:37], v[42:43]
	v_mov_b32_e32 v38, v61
	v_cvt_pk_bf16_f32 v40, v34, v35
	v_lshl_add_u64 v[34:35], v[24:25], 0, s[8:9]
	v_pk_fma_f32 v[30:31], v[88:89], v[128:129], v[30:31] neg_lo:[1,0,0] neg_hi:[1,0,0]
	v_readlane_b32 s0, v253, 33
	v_pk_mul_f32 v[38:39], v[26:27], v[38:39] op_sel_hi:[1,0]
	global_store_dword v[34:35], v40, off nt
	v_pk_fma_f32 v[34:35], v[30:31], 0.5, v[134:135] op_sel_hi:[1,0,1] neg_lo:[0,0,1] neg_hi:[0,0,1]
	s_lshl_b32 s8, s0, 1
	v_cvt_pk_bf16_f32 v40, v34, v35
	v_lshl_add_u64 v[34:35], v[24:25], 0, s[8:9]
	s_waitcnt vmcnt(14)
	v_pk_fma_f32 v[30:31], v[32:33], v[38:39], v[30:31]
	v_pk_mul_f32 v[60:61], v[32:33], v[38:39]
	global_store_dword v[34:35], v40, off nt
	v_pk_fma_f32 v[34:35], v[90:91], v[58:59], v[30:31] neg_lo:[1,0,0] neg_hi:[1,0,0]
	v_readlane_b32 s0, v253, 34
	v_pk_fma_f32 v[30:31], v[34:35], 0.5, v[60:61] op_sel_hi:[1,0,1] neg_lo:[0,0,1] neg_hi:[0,0,1]
	s_lshl_b32 s8, s0, 1
	v_cvt_pk_bf16_f32 v40, v30, v31
	v_lshl_add_u64 v[30:31], v[24:25], 0, s[8:9]
	global_store_dword v[30:31], v40, off nt
	v_lshl_add_u64 v[30:31], v[28:29], 0, s[42:43]
	global_load_dwordx2 v[40:41], v[30:31], off
	v_lshl_add_u64 v[30:31], v[28:29], 0, s[20:21]
	global_load_dwordx2 v[56:57], v[30:31], off
	v_lshl_add_u64 v[30:31], v[28:29], 0, s[16:17]
	global_load_dwordx2 v[58:59], v[30:31], off
	v_lshl_add_u64 v[30:31], v[28:29], 0, s[44:45]
	global_load_dwordx2 v[60:61], v[30:31], off
	v_lshl_add_u64 v[30:31], v[28:29], 0, s[18:19]
	global_load_dwordx2 v[62:63], v[30:31], off
	v_lshl_add_u64 v[30:31], v[28:29], 0, s[94:95]
	global_load_dwordx2 v[64:65], v[30:31], off
	v_lshl_add_u64 v[30:31], v[28:29], 0, s[92:93]
	global_load_dwordx2 v[66:67], v[30:31], off
	v_lshl_add_u64 v[30:31], v[28:29], 0, s[86:87]
	global_load_dwordx2 v[68:69], v[30:31], off
	v_lshl_add_u64 v[30:31], v[28:29], 0, s[74:75]
	global_load_dwordx2 v[70:71], v[30:31], off
	v_lshl_add_u64 v[30:31], v[28:29], 0, s[76:77]
	global_load_dwordx2 v[72:73], v[30:31], off
	v_lshl_add_u64 v[30:31], v[28:29], 0, s[72:73]
	global_load_dwordx2 v[74:75], v[30:31], off
	v_lshl_add_u64 v[30:31], v[28:29], 0, s[66:67]
	global_load_dwordx2 v[76:77], v[30:31], off
	v_lshl_add_u64 v[30:31], v[28:29], 0, s[88:89]
	global_load_dwordx2 v[78:79], v[30:31], off
	v_lshl_add_u64 v[30:31], v[28:29], 0, s[68:69]
	global_load_dwordx2 v[80:81], v[30:31], off
	v_lshl_add_u64 v[30:31], v[28:29], 0, s[22:23]
	global_load_dwordx2 v[82:83], v[30:31], off
	v_lshl_add_u64 v[28:29], v[28:29], 0, s[96:97]
	global_load_dwordx2 v[84:85], v[28:29], off
	ds_read_b128 v[28:31], v1 offset:192
	ds_read_b128 v[44:47], v1 offset:208
	ds_read_b128 v[48:51], v1 offset:224
	ds_read_b128 v[52:55], v1 offset:240
	s_lshl_b32 s8, s36, 1
	s_waitcnt lgkmcnt(3)
	v_pk_mul_f32 v[86:87], v[26:27], v[28:29] op_sel_hi:[1,0]
	v_pk_mul_f32 v[28:29], v[26:27], v[28:29] op_sel:[0,1]
	v_pk_mul_f32 v[92:93], v[26:27], v[30:31] op_sel_hi:[1,0]
	v_mov_b32_e32 v30, v31
	v_pk_mul_f32 v[30:31], v[26:27], v[30:31] op_sel_hi:[1,0]
	v_readlane_b32 s0, v253, 36
	s_waitcnt lgkmcnt(2)
	v_pk_mul_f32 v[98:99], v[26:27], v[44:45] op_sel_hi:[1,0]
	v_pk_mul_f32 v[44:45], v[26:27], v[44:45] op_sel:[0,1]
	v_pk_mul_f32 v[104:105], v[26:27], v[46:47] op_sel_hi:[1,0]
	v_mov_b32_e32 v46, v47
	v_pk_mul_f32 v[46:47], v[26:27], v[46:47] op_sel_hi:[1,0]
	s_waitcnt lgkmcnt(1)
	v_pk_mul_f32 v[110:111], v[26:27], v[48:49] op_sel_hi:[1,0]
	v_pk_mul_f32 v[48:49], v[26:27], v[48:49] op_sel:[0,1]
	v_pk_mul_f32 v[116:117], v[26:27], v[50:51] op_sel_hi:[1,0]
	v_mov_b32_e32 v50, v51
	v_pk_mul_f32 v[50:51], v[26:27], v[50:51] op_sel_hi:[1,0]
	s_waitcnt lgkmcnt(0)
	v_pk_mul_f32 v[122:123], v[26:27], v[52:53] op_sel_hi:[1,0]
	v_pk_mul_f32 v[52:53], v[26:27], v[52:53] op_sel:[0,1]
	v_pk_mul_f32 v[128:129], v[26:27], v[54:55] op_sel_hi:[1,0]
	v_mov_b32_e32 v54, v55
	v_pk_mul_f32 v[26:27], v[26:27], v[54:55] op_sel_hi:[1,0]
	s_waitcnt vmcnt(15)
	v_pk_fma_f32 v[34:35], v[40:41], v[86:87], v[34:35]
	v_pk_mul_f32 v[88:89], v[40:41], v[86:87]
	v_pk_fma_f32 v[34:35], v[36:37], v[42:43], v[34:35] neg_lo:[1,0,0] neg_hi:[1,0,0]
	s_waitcnt vmcnt(14)
	v_pk_mul_f32 v[90:91], v[56:57], v[28:29]
	v_pk_fma_f32 v[36:37], v[34:35], 0.5, v[88:89] op_sel_hi:[1,0,1] neg_lo:[0,0,1] neg_hi:[0,0,1]
	v_pk_fma_f32 v[34:35], v[56:57], v[28:29], v[34:35]
	v_cvt_pk_bf16_f32 v1, v36, v37
	v_lshl_add_u64 v[36:37], v[24:25], 0, s[8:9]
	v_pk_fma_f32 v[32:33], v[32:33], v[38:39], v[34:35] neg_lo:[1,0,0] neg_hi:[1,0,0]
	s_lshl_b32 s8, s81, 1
	v_pk_fma_f32 v[34:35], v[32:33], 0.5, v[90:91] op_sel_hi:[1,0,1] neg_lo:[0,0,1] neg_hi:[0,0,1]
	s_waitcnt vmcnt(13)
	v_pk_fma_f32 v[32:33], v[58:59], v[92:93], v[32:33]
	v_pk_mul_f32 v[94:95], v[58:59], v[92:93]
	global_store_dword v[36:37], v1, off nt
	v_cvt_pk_bf16_f32 v1, v34, v35
	v_lshl_add_u64 v[34:35], v[24:25], 0, s[8:9]
	v_pk_fma_f32 v[32:33], v[40:41], v[86:87], v[32:33] neg_lo:[1,0,0] neg_hi:[1,0,0]
	global_store_dword v[34:35], v1, off nt
	v_pk_fma_f32 v[34:35], v[32:33], 0.5, v[94:95] op_sel_hi:[1,0,1] neg_lo:[0,0,1] neg_hi:[0,0,1]
	s_waitcnt vmcnt(14)
	v_pk_fma_f32 v[32:33], v[60:61], v[30:31], v[32:33]
	v_pk_mul_f32 v[96:97], v[60:61], v[30:31]
	s_lshl_b32 s8, s0, 1
	v_pk_fma_f32 v[28:29], v[56:57], v[28:29], v[32:33] neg_lo:[1,0,0] neg_hi:[1,0,0]
	v_readlane_b32 s0, v253, 37
	v_cvt_pk_bf16_f32 v1, v34, v35
	v_lshl_add_u64 v[34:35], v[24:25], 0, s[8:9]
	v_pk_fma_f32 v[32:33], v[28:29], 0.5, v[96:97] op_sel_hi:[1,0,1] neg_lo:[0,0,1] neg_hi:[0,0,1]
	s_lshl_b32 s8, s0, 1
	s_waitcnt vmcnt(13)
	v_pk_fma_f32 v[28:29], v[62:63], v[98:99], v[28:29]
	v_pk_mul_f32 v[100:101], v[62:63], v[98:99]
	global_store_dword v[34:35], v1, off nt
	v_cvt_pk_bf16_f32 v1, v32, v33
	v_lshl_add_u64 v[32:33], v[24:25], 0, s[8:9]
	v_pk_fma_f32 v[28:29], v[58:59], v[92:93], v[28:29] neg_lo:[1,0,0] neg_hi:[1,0,0]
	global_store_dword v[32:33], v1, off nt
	v_pk_fma_f32 v[32:33], v[28:29], 0.5, v[100:101] op_sel_hi:[1,0,1] neg_lo:[0,0,1] neg_hi:[0,0,1]
	v_readlane_b32 s0, v253, 38
	s_waitcnt vmcnt(14)
	v_pk_fma_f32 v[28:29], v[64:65], v[44:45], v[28:29]
	v_pk_mul_f32 v[102:103], v[64:65], v[44:45]
	s_lshl_b32 s8, s0, 1
	v_pk_fma_f32 v[28:29], v[60:61], v[30:31], v[28:29] neg_lo:[1,0,0] neg_hi:[1,0,0]
	v_readlane_b32 s0, v253, 41
	v_cvt_pk_bf16_f32 v1, v32, v33
	v_lshl_add_u64 v[32:33], v[24:25], 0, s[8:9]
	v_pk_fma_f32 v[30:31], v[28:29], 0.5, v[102:103] op_sel_hi:[1,0,1] neg_lo:[0,0,1] neg_hi:[0,0,1]
	s_lshl_b32 s8, s0, 1
	s_waitcnt vmcnt(13)
	v_pk_fma_f32 v[28:29], v[66:67], v[104:105], v[28:29]
	v_pk_mul_f32 v[106:107], v[66:67], v[104:105]
	global_store_dword v[32:33], v1, off nt
	v_cvt_pk_bf16_f32 v1, v30, v31
	v_lshl_add_u64 v[30:31], v[24:25], 0, s[8:9]
	v_pk_fma_f32 v[28:29], v[62:63], v[98:99], v[28:29] neg_lo:[1,0,0] neg_hi:[1,0,0]
	global_store_dword v[30:31], v1, off nt
	v_pk_fma_f32 v[30:31], v[28:29], 0.5, v[106:107] op_sel_hi:[1,0,1] neg_lo:[0,0,1] neg_hi:[0,0,1]
	s_lshl_b32 s8, s34, 1
	s_waitcnt vmcnt(14)
	v_pk_fma_f32 v[28:29], v[68:69], v[46:47], v[28:29]
	v_pk_mul_f32 v[108:109], v[68:69], v[46:47]
	v_cvt_pk_bf16_f32 v1, v30, v31
	v_lshl_add_u64 v[30:31], v[24:25], 0, s[8:9]
	v_pk_fma_f32 v[28:29], v[64:65], v[44:45], v[28:29] neg_lo:[1,0,0] neg_hi:[1,0,0]
	v_readlane_b32 s0, v253, 42
	global_store_dword v[30:31], v1, off nt
	v_pk_fma_f32 v[30:31], v[28:29], 0.5, v[108:109] op_sel_hi:[1,0,1] neg_lo:[0,0,1] neg_hi:[0,0,1]
	s_lshl_b32 s8, s0, 1
	s_waitcnt vmcnt(14)
	v_pk_fma_f32 v[28:29], v[70:71], v[110:111], v[28:29]
	v_pk_mul_f32 v[112:113], v[70:71], v[110:111]
	v_cvt_pk_bf16_f32 v1, v30, v31
	v_lshl_add_u64 v[30:31], v[24:25], 0, s[8:9]
	v_pk_fma_f32 v[28:29], v[66:67], v[104:105], v[28:29] neg_lo:[1,0,0] neg_hi:[1,0,0]
	global_store_dword v[30:31], v1, off nt
	v_pk_fma_f32 v[30:31], v[28:29], 0.5, v[112:113] op_sel_hi:[1,0,1] neg_lo:[0,0,1] neg_hi:[0,0,1]
	s_lshl_b32 s8, s35, 1
	s_waitcnt vmcnt(14)
	v_pk_fma_f32 v[28:29], v[72:73], v[48:49], v[28:29]
	v_pk_mul_f32 v[114:115], v[72:73], v[48:49]
	v_cvt_pk_bf16_f32 v1, v30, v31
	v_lshl_add_u64 v[30:31], v[24:25], 0, s[8:9]
	v_pk_fma_f32 v[28:29], v[68:69], v[46:47], v[28:29] neg_lo:[1,0,0] neg_hi:[1,0,0]
	global_store_dword v[30:31], v1, off nt
	v_pk_fma_f32 v[30:31], v[28:29], 0.5, v[114:115] op_sel_hi:[1,0,1] neg_lo:[0,0,1] neg_hi:[0,0,1]
	s_lshl_b32 s8, s90, 1
	s_waitcnt vmcnt(14)
	v_pk_fma_f32 v[28:29], v[74:75], v[116:117], v[28:29]
	v_pk_mul_f32 v[118:119], v[74:75], v[116:117]
	v_cvt_pk_bf16_f32 v1, v30, v31
	v_lshl_add_u64 v[30:31], v[24:25], 0, s[8:9]
	v_pk_fma_f32 v[28:29], v[70:71], v[110:111], v[28:29] neg_lo:[1,0,0] neg_hi:[1,0,0]
	v_readlane_b32 s0, v253, 43
	global_store_dword v[30:31], v1, off nt
	v_pk_fma_f32 v[30:31], v[28:29], 0.5, v[118:119] op_sel_hi:[1,0,1] neg_lo:[0,0,1] neg_hi:[0,0,1]
	s_lshl_b32 s8, s0, 1
	s_waitcnt vmcnt(14)
	v_pk_fma_f32 v[28:29], v[76:77], v[50:51], v[28:29]
	v_pk_mul_f32 v[120:121], v[76:77], v[50:51]
	v_cvt_pk_bf16_f32 v1, v30, v31
	v_lshl_add_u64 v[30:31], v[24:25], 0, s[8:9]
	v_pk_fma_f32 v[28:29], v[72:73], v[48:49], v[28:29] neg_lo:[1,0,0] neg_hi:[1,0,0]
	global_store_dword v[30:31], v1, off nt
	v_pk_fma_f32 v[30:31], v[28:29], 0.5, v[120:121] op_sel_hi:[1,0,1] neg_lo:[0,0,1] neg_hi:[0,0,1]
	s_lshl_b32 s8, s83, 1
	s_waitcnt vmcnt(14)
	v_pk_fma_f32 v[28:29], v[78:79], v[122:123], v[28:29]
	v_pk_mul_f32 v[124:125], v[78:79], v[122:123]
	v_cvt_pk_bf16_f32 v1, v30, v31
	v_lshl_add_u64 v[30:31], v[24:25], 0, s[8:9]
	v_pk_fma_f32 v[28:29], v[74:75], v[116:117], v[28:29] neg_lo:[1,0,0] neg_hi:[1,0,0]
	global_store_dword v[30:31], v1, off nt
	v_pk_fma_f32 v[30:31], v[28:29], 0.5, v[124:125] op_sel_hi:[1,0,1] neg_lo:[0,0,1] neg_hi:[0,0,1]
	s_lshl_b32 s8, s91, 1
	s_waitcnt vmcnt(14)
	v_pk_fma_f32 v[28:29], v[80:81], v[52:53], v[28:29]
	v_pk_mul_f32 v[126:127], v[80:81], v[52:53]
	v_cvt_pk_bf16_f32 v1, v30, v31
	v_lshl_add_u64 v[30:31], v[24:25], 0, s[8:9]
	v_pk_fma_f32 v[28:29], v[76:77], v[50:51], v[28:29] neg_lo:[1,0,0] neg_hi:[1,0,0]
	global_store_dword v[30:31], v1, off nt
	v_pk_fma_f32 v[30:31], v[28:29], 0.5, v[126:127] op_sel_hi:[1,0,1] neg_lo:[0,0,1] neg_hi:[0,0,1]
	s_lshl_b32 s8, s64, 1
	s_waitcnt vmcnt(14)
	v_pk_fma_f32 v[28:29], v[82:83], v[128:129], v[28:29]
	v_pk_mul_f32 v[130:131], v[82:83], v[128:129]
	v_cvt_pk_bf16_f32 v1, v30, v31
	v_lshl_add_u64 v[30:31], v[24:25], 0, s[8:9]
	v_pk_fma_f32 v[28:29], v[78:79], v[122:123], v[28:29] neg_lo:[1,0,0] neg_hi:[1,0,0]
	s_waitcnt vmcnt(13)
	v_pk_mul_f32 v[54:55], v[84:85], v[26:27]
	global_store_dword v[30:31], v1, off nt
	v_pk_fma_f32 v[30:31], v[28:29], 0.5, v[130:131] op_sel_hi:[1,0,1] neg_lo:[0,0,1] neg_hi:[0,0,1]
	s_lshl_b32 s8, s65, 1
	v_pk_fma_f32 v[26:27], v[84:85], v[26:27], v[28:29]
	v_cvt_pk_bf16_f32 v1, v30, v31
	v_lshl_add_u64 v[30:31], v[24:25], 0, s[8:9]
	v_pk_fma_f32 v[26:27], v[80:81], v[52:53], v[26:27] neg_lo:[1,0,0] neg_hi:[1,0,0]
	global_store_dword v[30:31], v1, off nt
	v_pk_fma_f32 v[26:27], v[26:27], 0.5, v[54:55] op_sel_hi:[1,0,1] neg_lo:[0,0,1] neg_hi:[0,0,1]
	s_nop 0
	v_cvt_pk_bf16_f32 v163, v26, v27
	s_cbranch_execz .LBB0_233
.LBB0_261:
	s_mov_b32 s7, s9
	v_lshl_add_u64 v[24:25], v[24:25], 0, s[6:7]
	global_store_dword v[24:25], v163, off nt
	s_branch .LBB0_233

.LBB0_365:
	v_readlane_b32 s0, v253, 20
	v_readlane_b32 s1, v253, 21
	v_readlane_b32 s18, v252, 3
	v_readlane_b32 s19, v252, 4
	v_lshl_add_u64 v[2:3], v[30:31], 0, s[0:1]
	v_readlane_b32 s0, v252, 31
	v_readlane_b32 s1, v252, 32
	flat_load_dword v34, v[2:3]
	v_readlane_b32 s10, v252, 11
	v_lshl_add_u64 v[2:3], v[30:31], 0, s[0:1]
	v_readlane_b32 s0, v252, 34
	v_readlane_b32 s1, v252, 35
	flat_load_dword v35, v[2:3]
	v_readlane_b32 s11, v252, 12
	v_lshl_add_u64 v[2:3], v[30:31], 0, s[0:1]
	v_readlane_b32 s0, v252, 37
	v_readlane_b32 s1, v252, 38
	flat_load_dword v38, v[2:3]
	v_readlane_b32 s8, v254, 31
	v_lshl_add_u64 v[2:3], v[30:31], 0, s[0:1]
	v_readlane_b32 s0, v252, 40
	v_readlane_b32 s1, v252, 41
	flat_load_dword v39, v[2:3]
	v_readlane_b32 s9, v254, 32
	v_lshl_add_u64 v[2:3], v[30:31], 0, s[0:1]
	v_readlane_b32 s0, v252, 43
	v_readlane_b32 s1, v252, 44
	flat_load_dword v42, v[2:3]
	s_mov_b64 s[96:97], -1
	v_lshl_add_u64 v[2:3], v[30:31], 0, s[0:1]
	v_readlane_b32 s0, v252, 51
	v_readlane_b32 s1, v252, 52
	flat_load_dword v43, v[2:3]
	s_waitcnt vmcnt(0) lgkmcnt(0)
	v_lshlrev_b32_e32 v96, 16, v34
	v_lshl_add_u64 v[2:3], v[30:31], 0, s[0:1]
	v_readlane_b32 s0, v253, 26
	v_readlane_b32 s1, v253, 27
	flat_load_dword v46, v[2:3]
	v_and_b32_e32 v97, 0xffff0000, v34
	v_lshl_add_u64 v[2:3], v[30:31], 0, s[0:1]
	v_readlane_b32 s0, v253, 31
	v_readlane_b32 s1, v253, 32
	flat_load_dword v47, v[2:3]
	v_lshlrev_b32_e32 v98, 16, v35
	v_lshl_add_u64 v[2:3], v[30:31], 0, s[0:1]
	v_readlane_b32 s0, v252, 54
	v_readlane_b32 s1, v252, 55
	flat_load_dword v50, v[2:3]
	v_and_b32_e32 v99, 0xffff0000, v35
	v_lshl_add_u64 v[2:3], v[30:31], 0, s[0:1]
	v_readlane_b32 s0, v254, 7
	v_readlane_b32 s1, v254, 8
	flat_load_dword v51, v[2:3]
	v_lshlrev_b32_e32 v100, 16, v38
	v_lshl_add_u64 v[2:3], v[30:31], 0, s[0:1]
	v_readlane_b32 s0, v253, 22
	v_readlane_b32 s1, v253, 23
	flat_load_dword v68, v[2:3]
	v_and_b32_e32 v101, 0xffff0000, v38
	v_lshl_add_u64 v[2:3], v[30:31], 0, s[0:1]
	v_readlane_b32 s0, v254, 13
	v_readlane_b32 s1, v254, 14
	flat_load_dword v69, v[2:3]
	v_lshlrev_b32_e32 v102, 16, v39
	v_lshl_add_u64 v[2:3], v[30:31], 0, s[0:1]
	v_readlane_b32 s0, v254, 15
	v_readlane_b32 s1, v254, 16
	flat_load_dword v72, v[2:3]
	v_and_b32_e32 v103, 0xffff0000, v39
	v_lshl_add_u64 v[2:3], v[30:31], 0, s[0:1]
	v_readlane_b32 s0, v254, 17
	v_readlane_b32 s1, v254, 18
	flat_load_dword v73, v[2:3]
	v_lshlrev_b32_e32 v104, 16, v42
	v_lshl_add_u64 v[2:3], v[30:31], 0, s[0:1]
	v_readlane_b32 s0, v253, 34
	v_readlane_b32 s1, v253, 35
	flat_load_dword v80, v[2:3]
	v_and_b32_e32 v105, 0xffff0000, v42
	v_lshl_add_u64 v[2:3], v[30:31], 0, s[0:1]
	flat_load_dword v81, v[2:3]
	v_pk_add_f32 v[2:3], v[66:67], 0 op_sel_hi:[1,0]
	v_readlane_b32 s0, v252, 23
	v_pk_add_f32 v[2:3], v[58:59], v[2:3]
	v_lshlrev_b32_e32 v106, 16, v43
	v_pk_add_f32 v[2:3], v[52:53], v[2:3]
	v_mov_b32_e32 v0, s0
	v_pk_add_f32 v[2:3], v[48:49], v[2:3]
	ds_read_b128 v[54:57], v0
	ds_read_b128 v[62:65], v0 offset:16
	ds_read_b128 v[76:79], v0 offset:32
	ds_read_b128 v[86:89], v0 offset:48
	v_pk_add_f32 v[2:3], v[44:45], v[2:3]
	s_waitcnt lgkmcnt(0)
	v_pk_mul_f32 v[82:83], v[28:29], v[54:55] op_sel_hi:[1,0]
	v_pk_add_f32 v[2:3], v[40:41], v[2:3]
	v_pk_mul_f32 v[90:91], v[28:29], v[54:55] op_sel:[0,1]
	v_pk_add_f32 v[2:3], v[36:37], v[2:3]
	v_pk_mul_f32 v[108:109], v[82:83], v[96:97]
	v_pk_add_f32 v[94:95], v[4:5], v[2:3]
	v_pk_mul_f32 v[92:93], v[28:29], v[56:57] op_sel_hi:[1,0]
	v_pk_fma_f32 v[94:95], v[82:83], v[96:97], v[94:95]
	v_pk_mul_f32 v[110:111], v[90:91], v[98:99]
	v_pk_add_f32 v[66:67], v[94:95], v[66:67] neg_lo:[0,1] neg_hi:[0,1]
	v_mov_b32_e32 v56, v57
	v_pk_fma_f32 v[94:95], v[6:7], v[66:67], v[108:109] neg_lo:[0,0,1] neg_hi:[0,0,1]
	v_pk_fma_f32 v[66:67], v[90:91], v[98:99], v[66:67]
	v_pk_mul_f32 v[112:113], v[92:93], v[100:101]
	v_pk_add_f32 v[58:59], v[66:67], v[58:59] neg_lo:[0,1] neg_hi:[0,1]
	v_pk_mul_f32 v[114:115], v[28:29], v[56:57] op_sel_hi:[1,0]
	v_pk_fma_f32 v[66:67], v[8:9], v[58:59], v[110:111] neg_lo:[0,0,1] neg_hi:[0,0,1]
	v_pk_fma_f32 v[58:59], v[92:93], v[100:101], v[58:59]
	v_pk_mul_f32 v[116:117], v[114:115], v[102:103]
	v_pk_add_f32 v[52:53], v[58:59], v[52:53] neg_lo:[0,1] neg_hi:[0,1]
	v_pk_mul_f32 v[118:119], v[28:29], v[62:63] op_sel_hi:[1,0]
	v_pk_fma_f32 v[58:59], v[10:11], v[52:53], v[112:113] neg_lo:[0,0,1] neg_hi:[0,0,1]
	v_pk_fma_f32 v[52:53], v[114:115], v[102:103], v[52:53]
	v_readlane_b32 s0, v252, 27
	v_pk_add_f32 v[48:49], v[52:53], v[48:49] neg_lo:[0,1] neg_hi:[0,1]
	v_and_b32_e32 v107, 0xffff0000, v43
	v_pk_fma_f32 v[52:53], v[12:13], v[48:49], v[116:117] neg_lo:[0,0,1] neg_hi:[0,0,1]
	v_pk_fma_f32 v[48:49], v[118:119], v[104:105], v[48:49]
	v_pk_mul_f32 v[120:121], v[118:119], v[104:105]
	v_pk_mul_f32 v[122:123], v[28:29], v[62:63] op_sel:[0,1]
	s_lshl_b32 s94, s0, 1
	v_readlane_b32 s0, v252, 30
	v_pk_add_f32 v[44:45], v[48:49], v[44:45] neg_lo:[0,1] neg_hi:[0,1]
	v_cvt_pk_bf16_f32 v108, v94, v95
	v_lshl_add_u64 v[94:95], v[26:27], 0, s[94:95]
	s_lshl_b32 s94, s0, 1
	v_readlane_b32 s0, v252, 33
	v_pk_fma_f32 v[48:49], v[14:15], v[44:45], v[120:121] neg_lo:[0,0,1] neg_hi:[0,0,1]
	v_pk_fma_f32 v[44:45], v[122:123], v[106:107], v[44:45]
	s_waitcnt vmcnt(0)
	v_lshlrev_b32_e32 v74, 16, v46
	v_and_b32_e32 v75, 0xffff0000, v46
	v_pk_mul_f32 v[124:125], v[122:123], v[106:107]
	v_pk_mul_f32 v[126:127], v[28:29], v[64:65] op_sel_hi:[1,0]
	global_store_dword v[94:95], v108, off nt
	v_cvt_pk_bf16_f32 v94, v66, v67
	v_lshl_add_u64 v[66:67], v[26:27], 0, s[94:95]
	s_lshl_b32 s94, s0, 1
	v_readlane_b32 s0, v252, 36
	v_pk_add_f32 v[40:41], v[44:45], v[40:41] neg_lo:[0,1] neg_hi:[0,1]
	v_mov_b32_e32 v56, v65
	global_store_dword v[66:67], v94, off nt
	v_cvt_pk_bf16_f32 v66, v58, v59
	v_lshl_add_u64 v[58:59], v[26:27], 0, s[94:95]
	s_lshl_b32 s94, s0, 1
	v_readlane_b32 s0, v252, 39
	v_pk_fma_f32 v[44:45], v[16:17], v[40:41], v[124:125] neg_lo:[0,0,1] neg_hi:[0,0,1]
	v_pk_fma_f32 v[40:41], v[126:127], v[74:75], v[40:41]
	v_lshlrev_b32_e32 v70, 16, v47
	v_and_b32_e32 v71, 0xffff0000, v47
	v_pk_mul_f32 v[128:129], v[126:127], v[74:75]
	v_pk_mul_f32 v[130:131], v[28:29], v[56:57] op_sel_hi:[1,0]
	global_store_dword v[58:59], v66, off nt
	v_cvt_pk_bf16_f32 v58, v52, v53
	v_lshl_add_u64 v[52:53], v[26:27], 0, s[94:95]
	s_lshl_b32 s94, s0, 1
	v_readlane_b32 s0, v252, 42
	v_pk_add_f32 v[36:37], v[40:41], v[36:37] neg_lo:[0,1] neg_hi:[0,1]
	global_store_dword v[52:53], v58, off nt
	v_cvt_pk_bf16_f32 v52, v48, v49
	v_lshl_add_u64 v[48:49], v[26:27], 0, s[94:95]
	s_lshl_b32 s94, s0, 1
	v_pk_fma_f32 v[40:41], v[18:19], v[36:37], v[128:129] neg_lo:[0,0,1] neg_hi:[0,0,1]
	v_readlane_b32 s0, v252, 45
	v_pk_fma_f32 v[36:37], v[130:131], v[70:71], v[36:37]
	v_pk_mul_f32 v[132:133], v[130:131], v[70:71]
	global_store_dword v[48:49], v52, off nt
	v_cvt_pk_bf16_f32 v48, v44, v45
	v_lshl_add_u64 v[44:45], v[26:27], 0, s[94:95]
	s_lshl_b32 s94, s0, 1
	v_pk_add_f32 v[4:5], v[36:37], v[4:5] neg_lo:[0,1] neg_hi:[0,1]
	s_mov_b32 s0, 0x3e000000
	v_lshlrev_b32_e32 v60, 16, v50
	v_and_b32_e32 v61, 0xffff0000, v50
	v_pk_mul_f32 v[84:85], v[28:29], v[76:77] op_sel_hi:[1,0]
	v_pk_fma_f32 v[36:37], v[4:5], s[0:1], v[132:133] op_sel_hi:[1,0,1] neg_lo:[0,0,1] neg_hi:[0,0,1]
	v_readlane_b32 s1, v252, 47
	global_store_dword v[44:45], v48, off nt
	v_cvt_pk_bf16_f32 v44, v40, v41
	v_lshl_add_u64 v[40:41], v[26:27], 0, s[94:95]
	s_lshl_b32 s94, s1, 1
	v_pk_fma_f32 v[4:5], v[84:85], v[60:61], v[4:5]
	v_pk_mul_f32 v[134:135], v[84:85], v[60:61]
	global_store_dword v[40:41], v44, off nt
	v_cvt_pk_bf16_f32 v40, v36, v37
	v_lshl_add_u64 v[36:37], v[26:27], 0, s[94:95]
	v_pk_fma_f32 v[4:5], v[82:83], v[96:97], v[4:5] neg_lo:[1,0,0] neg_hi:[1,0,0]
	v_lshlrev_b32_e32 v54, 16, v51
	v_and_b32_e32 v55, 0xffff0000, v51
	v_lshlrev_b32_e32 v34, 16, v80
	v_and_b32_e32 v35, 0xffff0000, v80
	v_lshlrev_b32_e32 v2, 16, v81
	v_and_b32_e32 v3, 0xffff0000, v81
	v_pk_mul_f32 v[80:81], v[28:29], v[76:77] op_sel:[0,1]
	global_store_dword v[36:37], v40, off nt
	v_pk_fma_f32 v[36:37], v[4:5], s[0:1], v[134:135] op_sel_hi:[1,0,1] neg_lo:[0,0,1] neg_hi:[0,0,1]
	v_readlane_b32 s1, v252, 48
	s_lshl_b32 s94, s1, 1
	v_pk_fma_f32 v[4:5], v[80:81], v[54:55], v[4:5]
	v_pk_mul_f32 v[136:137], v[80:81], v[54:55]
	v_cvt_pk_bf16_f32 v40, v36, v37
	v_lshl_add_u64 v[36:37], v[26:27], 0, s[94:95]
	v_pk_fma_f32 v[4:5], v[90:91], v[98:99], v[4:5] neg_lo:[1,0,0] neg_hi:[1,0,0]
	v_lshlrev_b32_e32 v50, 16, v68
	v_and_b32_e32 v51, 0xffff0000, v68
	v_pk_mul_f32 v[76:77], v[28:29], v[78:79] op_sel_hi:[1,0]
	global_store_dword v[36:37], v40, off nt
	v_pk_fma_f32 v[36:37], v[4:5], s[0:1], v[136:137] op_sel_hi:[1,0,1] neg_lo:[0,0,1] neg_hi:[0,0,1]
	v_readlane_b32 s1, v252, 49
	s_lshl_b32 s94, s1, 1
	v_pk_fma_f32 v[4:5], v[76:77], v[50:51], v[4:5]
	v_pk_mul_f32 v[138:139], v[76:77], v[50:51]
	v_mov_b32_e32 v56, v79
	v_cvt_pk_bf16_f32 v40, v36, v37
	v_lshl_add_u64 v[36:37], v[26:27], 0, s[94:95]
	v_pk_fma_f32 v[4:5], v[92:93], v[100:101], v[4:5] neg_lo:[1,0,0] neg_hi:[1,0,0]
	v_lshlrev_b32_e32 v46, 16, v69
	v_and_b32_e32 v47, 0xffff0000, v69
	v_lshlrev_b32_e32 v42, 16, v72
	v_and_b32_e32 v43, 0xffff0000, v72
	v_lshlrev_b32_e32 v38, 16, v73
	v_and_b32_e32 v39, 0xffff0000, v73
	v_pk_mul_f32 v[72:73], v[28:29], v[56:57] op_sel_hi:[1,0]
	global_store_dword v[36:37], v40, off nt
	v_pk_fma_f32 v[36:37], v[4:5], s[0:1], v[138:139] op_sel_hi:[1,0,1] neg_lo:[0,0,1] neg_hi:[0,0,1]
	v_readlane_b32 s1, v252, 50
	s_lshl_b32 s94, s1, 1
	v_pk_fma_f32 v[4:5], v[72:73], v[46:47], v[4:5]
	v_pk_mul_f32 v[78:79], v[72:73], v[46:47]
	v_cvt_pk_bf16_f32 v40, v36, v37
	v_lshl_add_u64 v[36:37], v[26:27], 0, s[94:95]
	v_pk_fma_f32 v[4:5], v[114:115], v[102:103], v[4:5] neg_lo:[1,0,0] neg_hi:[1,0,0]
	v_pk_mul_f32 v[68:69], v[28:29], v[86:87] op_sel_hi:[1,0]
	global_store_dword v[36:37], v40, off nt
	v_pk_fma_f32 v[36:37], v[4:5], s[0:1], v[78:79] op_sel_hi:[1,0,1] neg_lo:[0,0,1] neg_hi:[0,0,1]
	v_readlane_b32 s1, v252, 53
	s_lshl_b32 s94, s1, 1
	v_pk_fma_f32 v[4:5], v[68:69], v[42:43], v[4:5]
	v_pk_mul_f32 v[140:141], v[68:69], v[42:43]
	v_cvt_pk_bf16_f32 v40, v36, v37
	v_lshl_add_u64 v[36:37], v[26:27], 0, s[94:95]
	v_pk_fma_f32 v[4:5], v[118:119], v[104:105], v[4:5] neg_lo:[1,0,0] neg_hi:[1,0,0]
	v_pk_mul_f32 v[64:65], v[28:29], v[86:87] op_sel:[0,1]
	global_store_dword v[36:37], v40, off nt
	v_pk_fma_f32 v[36:37], v[4:5], s[0:1], v[140:141] op_sel_hi:[1,0,1] neg_lo:[0,0,1] neg_hi:[0,0,1]
	v_readlane_b32 s1, v252, 58
	s_lshl_b32 s94, s1, 1
	v_pk_fma_f32 v[4:5], v[64:65], v[38:39], v[4:5]
	v_pk_mul_f32 v[86:87], v[64:65], v[38:39]
	v_cvt_pk_bf16_f32 v40, v36, v37
	v_lshl_add_u64 v[36:37], v[26:27], 0, s[94:95]
	v_pk_fma_f32 v[4:5], v[122:123], v[106:107], v[4:5] neg_lo:[1,0,0] neg_hi:[1,0,0]
	v_pk_mul_f32 v[62:63], v[28:29], v[88:89] op_sel_hi:[1,0]
	global_store_dword v[36:37], v40, off nt
	v_pk_fma_f32 v[36:37], v[4:5], s[0:1], v[86:87] op_sel_hi:[1,0,1] neg_lo:[0,0,1] neg_hi:[0,0,1]
	v_readlane_b32 s1, v252, 61
	v_mov_b32_e32 v56, v89
	s_lshl_b32 s94, s1, 1
	v_pk_fma_f32 v[4:5], v[62:63], v[34:35], v[4:5]
	v_pk_mul_f32 v[142:143], v[62:63], v[34:35]
	v_pk_mul_f32 v[56:57], v[28:29], v[56:57] op_sel_hi:[1,0]
	v_cvt_pk_bf16_f32 v40, v36, v37
	v_lshl_add_u64 v[36:37], v[26:27], 0, s[94:95]
	v_pk_fma_f32 v[4:5], v[126:127], v[74:75], v[4:5] neg_lo:[1,0,0] neg_hi:[1,0,0]
	global_store_dword v[36:37], v40, off nt
	v_pk_fma_f32 v[36:37], v[4:5], s[0:1], v[142:143] op_sel_hi:[1,0,1] neg_lo:[0,0,1] neg_hi:[0,0,1]
	v_readlane_b32 s1, v253, 0
	v_pk_fma_f32 v[4:5], v[56:57], v[2:3], v[4:5]
	v_pk_mul_f32 v[88:89], v[56:57], v[2:3]
	s_lshl_b32 s94, s1, 1
	v_pk_fma_f32 v[108:109], v[130:131], v[70:71], v[4:5] neg_lo:[1,0,0] neg_hi:[1,0,0]
	v_cvt_pk_bf16_f32 v40, v36, v37
	v_lshl_add_u64 v[36:37], v[26:27], 0, s[94:95]
	v_pk_fma_f32 v[4:5], v[108:109], s[0:1], v[88:89] op_sel_hi:[1,0,1] neg_lo:[0,0,1] neg_hi:[0,0,1]
	global_store_dword v[36:37], v40, off nt
	v_cvt_pk_bf16_f32 v36, v4, v5
	v_lshl_add_u64 v[4:5], v[30:31], 0, s[18:19]
	v_readlane_b32 s18, v252, 1
	v_readlane_b32 s19, v252, 2
	flat_load_dword v37, v[4:5]
	ds_read_b128 v[86:89], v0 offset:64
	v_lshl_add_u64 v[4:5], v[30:31], 0, s[18:19]
	v_readlane_b32 s18, v252, 7
	v_readlane_b32 s19, v252, 8
	flat_load_dword v40, v[4:5]
	s_waitcnt lgkmcnt(0)
	v_pk_mul_f32 v[120:121], v[28:29], v[86:87] op_sel_hi:[1,0]
	v_lshl_add_u64 v[4:5], v[30:31], 0, s[18:19]
	flat_load_dword v41, v[4:5]
	v_lshl_add_u64 v[4:5], v[30:31], 0, s[10:11]
	v_readlane_b32 s10, v252, 15
	v_readlane_b32 s11, v252, 16
	flat_load_dword v44, v[4:5]
	v_readlane_b32 s1, v253, 3
	v_lshl_add_u64 v[4:5], v[30:31], 0, s[10:11]
	v_readlane_b32 s10, v252, 19
	v_readlane_b32 s11, v252, 20
	flat_load_dword v45, v[4:5]
	s_lshl_b32 s94, s1, 1
	v_lshl_add_u64 v[4:5], v[30:31], 0, s[10:11]
	flat_load_dword v48, v[4:5]
	v_lshl_add_u64 v[4:5], v[30:31], 0, s[8:9]
	v_readlane_b32 s8, v254, 35
	v_readlane_b32 s9, v254, 36
	flat_load_dword v49, v[4:5]
	v_pk_mul_f32 v[124:125], v[28:29], v[86:87] op_sel:[0,1]
	v_lshl_add_u64 v[4:5], v[30:31], 0, s[8:9]
	v_readlane_b32 s8, v253, 43
	v_readlane_b32 s9, v253, 44
	flat_load_dword v52, v[4:5]
	v_pk_mul_f32 v[128:129], v[28:29], v[88:89] op_sel_hi:[1,0]
	v_lshl_add_u64 v[4:5], v[30:31], 0, s[8:9]
	v_readlane_b32 s8, v254, 45
	v_readlane_b32 s9, v254, 46
	flat_load_dword v53, v[4:5]
	s_mov_b64 s[10:11], s[26:27]
	v_lshl_add_u64 v[4:5], v[30:31], 0, s[8:9]
	v_readlane_b32 s8, v254, 39
	v_readlane_b32 s9, v254, 40
	flat_load_dword v59, v[4:5]
	s_mov_b64 s[18:19], 0
	v_lshl_add_u64 v[4:5], v[30:31], 0, s[8:9]
	v_readlane_b32 s8, v254, 43
	v_readlane_b32 s9, v254, 44
	flat_load_dword v70, v[4:5]
	s_waitcnt vmcnt(0)
	v_lshlrev_b32_e32 v110, 16, v37
	v_lshl_add_u64 v[4:5], v[30:31], 0, s[8:9]
	flat_load_dword v71, v[4:5]
	v_readlane_b32 s8, v254, 47
	v_readlane_b32 s9, v254, 48
	v_and_b32_e32 v111, 0xffff0000, v37
	v_pk_fma_f32 v[108:109], v[120:121], v[110:111], v[108:109]
	v_lshl_add_u64 v[4:5], v[30:31], 0, s[8:9]
	v_readlane_b32 s8, v251, 63
	v_readlane_b32 s9, v252, 0
	flat_load_dword v74, v[4:5]
	v_lshlrev_b32_e32 v112, 16, v40
	v_lshl_add_u64 v[4:5], v[30:31], 0, s[8:9]
	v_readlane_b32 s8, v253, 45
	v_readlane_b32 s9, v253, 46
	flat_load_dword v75, v[4:5]
	v_and_b32_e32 v113, 0xffff0000, v40
	v_lshl_add_u64 v[4:5], v[30:31], 0, s[8:9]
	v_readlane_b32 s8, v251, 41
	v_readlane_b32 s9, v251, 42
	flat_load_dword v78, v[4:5]
	v_pk_mul_f32 v[122:123], v[120:121], v[110:111]
	v_lshl_add_u64 v[4:5], v[30:31], 0, s[8:9]
	flat_load_dword v79, v[4:5]
	v_pk_fma_f32 v[60:61], v[84:85], v[60:61], v[108:109] neg_lo:[1,0,0] neg_hi:[1,0,0]
	v_lshl_add_u64 v[4:5], v[26:27], 0, s[94:95]
	v_pk_fma_f32 v[84:85], v[60:61], s[0:1], v[122:123] op_sel_hi:[1,0,1] neg_lo:[0,0,1] neg_hi:[0,0,1]
	v_pk_fma_f32 v[60:61], v[124:125], v[112:113], v[60:61]
	global_store_dword v[4:5], v36, off nt
	s_waitcnt lgkmcnt(0)
	v_lshlrev_b32_e32 v114, 16, v41
	v_and_b32_e32 v115, 0xffff0000, v41
	v_pk_mul_f32 v[126:127], v[124:125], v[112:113]
	v_readlane_b32 s1, v253, 6
	v_pk_fma_f32 v[54:55], v[80:81], v[54:55], v[60:61] neg_lo:[1,0,0] neg_hi:[1,0,0]
	v_lshlrev_b32_e32 v94, 16, v52
	v_and_b32_e32 v95, 0xffff0000, v52
	v_lshlrev_b32_e32 v66, 16, v53
	v_and_b32_e32 v67, 0xffff0000, v53
	ds_read_b128 v[90:93], v0 offset:80
	ds_read_b128 v[100:103], v0 offset:96
	ds_read_b128 v[104:107], v0 offset:112
	v_pk_fma_f32 v[60:61], v[54:55], s[0:1], v[126:127] op_sel_hi:[1,0,1] neg_lo:[0,0,1] neg_hi:[0,0,1]
	v_pk_fma_f32 v[54:55], v[128:129], v[114:115], v[54:55]
	v_lshlrev_b32_e32 v116, 16, v44
	v_and_b32_e32 v117, 0xffff0000, v44
	v_pk_mul_f32 v[130:131], v[128:129], v[114:115]
	v_lshlrev_b32_e32 v52, 16, v70
	v_and_b32_e32 v53, 0xffff0000, v70
	v_mov_b32_e32 v70, v89
	s_lshl_b32 s94, s1, 1
	v_readlane_b32 s1, v253, 9
	v_pk_fma_f32 v[50:51], v[76:77], v[50:51], v[54:55] neg_lo:[1,0,0] neg_hi:[1,0,0]
	v_lshlrev_b32_e32 v118, 16, v45
	v_pk_fma_f32 v[54:55], v[50:51], s[0:1], v[130:131] op_sel_hi:[1,0,1] neg_lo:[0,0,1] neg_hi:[0,0,1]
	v_and_b32_e32 v119, 0xffff0000, v45
	s_waitcnt lgkmcnt(0)
	v_pk_mul_f32 v[136:137], v[28:29], v[90:91] op_sel_hi:[1,0]
	v_cvt_pk_bf16_f32 v108, v84, v85
	v_lshl_add_u64 v[84:85], v[26:27], 0, s[94:95]
	s_lshl_b32 s94, s1, 1
	v_readlane_b32 s1, v253, 12
	v_lshlrev_b32_e32 v98, 16, v48
	v_and_b32_e32 v99, 0xffff0000, v48
	v_pk_mul_f32 v[138:139], v[136:137], v[118:119]
	v_pk_mul_f32 v[140:141], v[28:29], v[90:91] op_sel:[0,1]
	global_store_dword v[84:85], v108, off nt
	v_cvt_pk_bf16_f32 v80, v60, v61
	v_lshl_add_u64 v[60:61], v[26:27], 0, s[94:95]
	s_lshl_b32 s94, s1, 1
	v_lshlrev_b32_e32 v96, 16, v49
	v_and_b32_e32 v97, 0xffff0000, v49
	v_pk_mul_f32 v[142:143], v[140:141], v[98:99]
	v_pk_mul_f32 v[144:145], v[28:29], v[92:93] op_sel_hi:[1,0]
	global_store_dword v[60:61], v80, off nt
	v_cvt_pk_bf16_f32 v60, v54, v55
	v_lshl_add_u64 v[54:55], v[26:27], 0, s[94:95]
	v_pk_mul_f32 v[146:147], v[144:145], v[96:97]
	global_store_dword v[54:55], v60, off nt
	v_lshlrev_b32_e32 v58, 16, v59
	v_and_b32_e32 v59, 0xffff0000, v59
	v_pk_mul_f32 v[90:91], v[28:29], v[100:101] op_sel:[0,1]
	v_pk_mul_f32 v[88:89], v[28:29], v[102:103] op_sel_hi:[1,0]
	v_pk_mul_f32 v[82:83], v[28:29], v[104:105] op_sel_hi:[1,0]
	v_pk_mul_f32 v[154:155], v[88:89], v[52:53]
	v_readlane_b32 s8, v251, 59
	s_waitcnt vmcnt(0)
	v_pk_mul_f32 v[132:133], v[28:29], v[70:71] op_sel_hi:[1,0]
	v_mov_b32_e32 v70, v93
	v_pk_fma_f32 v[50:51], v[132:133], v[116:117], v[50:51]
	v_pk_mul_f32 v[134:135], v[132:133], v[116:117]
	v_pk_fma_f32 v[46:47], v[72:73], v[46:47], v[50:51] neg_lo:[1,0,0] neg_hi:[1,0,0]
	v_pk_mul_f32 v[148:149], v[28:29], v[70:71] op_sel_hi:[1,0]
	v_pk_fma_f32 v[50:51], v[46:47], s[0:1], v[134:135] op_sel_hi:[1,0,1] neg_lo:[0,0,1] neg_hi:[0,0,1]
	v_pk_fma_f32 v[46:47], v[136:137], v[118:119], v[46:47]
	v_readlane_b32 s1, v251, 37
	v_pk_fma_f32 v[42:43], v[68:69], v[42:43], v[46:47] neg_lo:[1,0,0] neg_hi:[1,0,0]
	s_lshl_b32 s94, s1, 1
	v_pk_fma_f32 v[46:47], v[42:43], s[0:1], v[138:139] op_sel_hi:[1,0,1] neg_lo:[0,0,1] neg_hi:[0,0,1]
	v_pk_fma_f32 v[42:43], v[140:141], v[98:99], v[42:43]
	v_readlane_b32 s1, v253, 15
	v_pk_fma_f32 v[38:39], v[64:65], v[38:39], v[42:43] neg_lo:[1,0,0] neg_hi:[1,0,0]
	v_cvt_pk_bf16_f32 v54, v50, v51
	v_lshl_add_u64 v[50:51], v[26:27], 0, s[94:95]
	v_pk_fma_f32 v[42:43], v[38:39], s[0:1], v[142:143] op_sel_hi:[1,0,1] neg_lo:[0,0,1] neg_hi:[0,0,1]
	v_pk_fma_f32 v[38:39], v[144:145], v[96:97], v[38:39]
	s_lshl_b32 s94, s1, 1
	v_readlane_b32 s1, v253, 16
	v_pk_fma_f32 v[34:35], v[62:63], v[34:35], v[38:39] neg_lo:[1,0,0] neg_hi:[1,0,0]
	v_pk_mul_f32 v[150:151], v[148:149], v[94:95]
	v_pk_fma_f32 v[38:39], v[34:35], s[0:1], v[146:147] op_sel_hi:[1,0,1] neg_lo:[0,0,1] neg_hi:[0,0,1]
	v_pk_fma_f32 v[34:35], v[148:149], v[94:95], v[34:35]
	global_store_dword v[50:51], v54, off nt
	v_cvt_pk_bf16_f32 v50, v46, v47
	v_lshl_add_u64 v[46:47], v[26:27], 0, s[94:95]
	s_lshl_b32 s94, s1, 1
	v_readlane_b32 s1, v254, 1
	v_pk_fma_f32 v[2:3], v[56:57], v[2:3], v[34:35] neg_lo:[1,0,0] neg_hi:[1,0,0]
	v_pk_mul_f32 v[92:93], v[28:29], v[100:101] op_sel_hi:[1,0]
	global_store_dword v[46:47], v50, off nt
	v_cvt_pk_bf16_f32 v46, v42, v43
	v_lshl_add_u64 v[42:43], v[26:27], 0, s[94:95]
	s_lshl_b32 s94, s1, 1
	v_pk_fma_f32 v[34:35], v[2:3], s[0:1], v[150:151] op_sel_hi:[1,0,1] neg_lo:[0,0,1] neg_hi:[0,0,1]
	v_readlane_b32 s1, v254, 5
	global_store_dword v[42:43], v46, off nt
	v_cvt_pk_bf16_f32 v42, v38, v39
	v_lshl_add_u64 v[38:39], v[26:27], 0, s[94:95]
	s_lshl_b32 s94, s1, 1
	v_pk_fma_f32 v[2:3], v[92:93], v[66:67], v[2:3]
	v_pk_mul_f32 v[152:153], v[92:93], v[66:67]
	global_store_dword v[38:39], v42, off nt
	v_cvt_pk_bf16_f32 v38, v34, v35
	v_lshl_add_u64 v[34:35], v[26:27], 0, s[94:95]
	v_pk_fma_f32 v[2:3], v[120:121], v[110:111], v[2:3] neg_lo:[1,0,0] neg_hi:[1,0,0]
	global_store_dword v[34:35], v38, off nt
	v_pk_fma_f32 v[34:35], v[2:3], s[0:1], v[152:153] op_sel_hi:[1,0,1] neg_lo:[0,0,1] neg_hi:[0,0,1]
	v_readlane_b32 s1, v254, 3
	s_lshl_b32 s94, s1, 1
	v_pk_fma_f32 v[2:3], v[90:91], v[58:59], v[2:3]
	v_pk_mul_f32 v[100:101], v[90:91], v[58:59]
	v_cvt_pk_bf16_f32 v38, v34, v35
	v_lshl_add_u64 v[34:35], v[26:27], 0, s[94:95]
	v_pk_fma_f32 v[2:3], v[124:125], v[112:113], v[2:3] neg_lo:[1,0,0] neg_hi:[1,0,0]
	global_store_dword v[34:35], v38, off nt
	v_pk_fma_f32 v[34:35], v[2:3], s[0:1], v[100:101] op_sel_hi:[1,0,1] neg_lo:[0,0,1] neg_hi:[0,0,1]
	v_readlane_b32 s1, v253, 25
	s_lshl_b32 s94, s1, 1
	v_pk_fma_f32 v[2:3], v[88:89], v[52:53], v[2:3]
	v_mov_b32_e32 v70, v103
	v_cvt_pk_bf16_f32 v38, v34, v35
	v_lshl_add_u64 v[34:35], v[26:27], 0, s[94:95]
	v_pk_fma_f32 v[2:3], v[128:129], v[114:115], v[2:3] neg_lo:[1,0,0] neg_hi:[1,0,0]
	v_lshlrev_b32_e32 v48, 16, v71
	v_and_b32_e32 v49, 0xffff0000, v71
	v_pk_mul_f32 v[86:87], v[28:29], v[70:71] op_sel_hi:[1,0]
	global_store_dword v[34:35], v38, off nt
	v_pk_fma_f32 v[34:35], v[2:3], s[0:1], v[154:155] op_sel_hi:[1,0,1] neg_lo:[0,0,1] neg_hi:[0,0,1]
	v_readlane_b32 s1, v254, 49
	s_lshl_b32 s94, s1, 1
	v_pk_fma_f32 v[2:3], v[86:87], v[48:49], v[2:3]
	v_pk_mul_f32 v[102:103], v[86:87], v[48:49]
	v_cvt_pk_bf16_f32 v38, v34, v35
	v_lshl_add_u64 v[34:35], v[26:27], 0, s[94:95]
	v_pk_fma_f32 v[2:3], v[132:133], v[116:117], v[2:3] neg_lo:[1,0,0] neg_hi:[1,0,0]
	v_lshlrev_b32_e32 v44, 16, v74
	v_and_b32_e32 v45, 0xffff0000, v74
	global_store_dword v[34:35], v38, off nt
	v_pk_fma_f32 v[34:35], v[2:3], s[0:1], v[102:103] op_sel_hi:[1,0,1] neg_lo:[0,0,1] neg_hi:[0,0,1]
	v_readlane_b32 s1, v253, 19
	s_lshl_b32 s94, s1, 1
	v_pk_fma_f32 v[2:3], v[82:83], v[44:45], v[2:3]
	v_pk_mul_f32 v[156:157], v[82:83], v[44:45]
	v_cvt_pk_bf16_f32 v38, v34, v35
	v_lshl_add_u64 v[34:35], v[26:27], 0, s[94:95]
	v_pk_fma_f32 v[2:3], v[136:137], v[118:119], v[2:3] neg_lo:[1,0,0] neg_hi:[1,0,0]
	v_lshlrev_b32_e32 v40, 16, v75
	v_and_b32_e32 v41, 0xffff0000, v75
	v_lshlrev_b32_e32 v36, 16, v78
	v_and_b32_e32 v37, 0xffff0000, v78
	v_lshlrev_b32_e32 v4, 16, v79
	v_and_b32_e32 v5, 0xffff0000, v79
	v_pk_mul_f32 v[78:79], v[28:29], v[104:105] op_sel:[0,1]
	global_store_dword v[34:35], v38, off nt
	v_pk_fma_f32 v[34:35], v[2:3], s[0:1], v[156:157] op_sel_hi:[1,0,1] neg_lo:[0,0,1] neg_hi:[0,0,1]
	v_readlane_b32 s1, v253, 28
	s_lshl_b32 s94, s1, 1
	v_pk_fma_f32 v[2:3], v[78:79], v[40:41], v[2:3]
	v_pk_mul_f32 v[104:105], v[78:79], v[40:41]
	v_cvt_pk_bf16_f32 v38, v34, v35
	v_lshl_add_u64 v[34:35], v[26:27], 0, s[94:95]
	v_pk_fma_f32 v[2:3], v[140:141], v[98:99], v[2:3] neg_lo:[1,0,0] neg_hi:[1,0,0]
	v_pk_mul_f32 v[74:75], v[28:29], v[106:107] op_sel_hi:[1,0]
	global_store_dword v[34:35], v38, off nt
	v_pk_fma_f32 v[34:35], v[2:3], s[0:1], v[104:105] op_sel_hi:[1,0,1] neg_lo:[0,0,1] neg_hi:[0,0,1]
	v_readlane_b32 s1, v253, 24
	v_mov_b32_e32 v70, v107
	s_lshl_b32 s94, s1, 1
	v_pk_fma_f32 v[2:3], v[74:75], v[36:37], v[2:3]
	v_pk_mul_f32 v[158:159], v[74:75], v[36:37]
	v_pk_mul_f32 v[70:71], v[28:29], v[70:71] op_sel_hi:[1,0]
	v_cvt_pk_bf16_f32 v38, v34, v35
	v_lshl_add_u64 v[34:35], v[26:27], 0, s[94:95]
	v_pk_fma_f32 v[2:3], v[144:145], v[96:97], v[2:3] neg_lo:[1,0,0] neg_hi:[1,0,0]
	global_store_dword v[34:35], v38, off nt
	v_pk_fma_f32 v[34:35], v[2:3], s[0:1], v[158:159] op_sel_hi:[1,0,1] neg_lo:[0,0,1] neg_hi:[0,0,1]
	v_readlane_b32 s1, v253, 29
	v_pk_fma_f32 v[2:3], v[70:71], v[4:5], v[2:3]
	v_pk_mul_f32 v[106:107], v[70:71], v[4:5]
	s_lshl_b32 s94, s1, 1
	v_pk_fma_f32 v[112:113], v[148:149], v[94:95], v[2:3] neg_lo:[1,0,0] neg_hi:[1,0,0]
	v_cvt_pk_bf16_f32 v38, v34, v35
	v_lshl_add_u64 v[34:35], v[26:27], 0, s[94:95]
	v_pk_fma_f32 v[2:3], v[112:113], s[0:1], v[106:107] op_sel_hi:[1,0,1] neg_lo:[0,0,1] neg_hi:[0,0,1]
	v_readlane_b32 s9, v251, 60
	global_store_dword v[34:35], v38, off nt
	v_cvt_pk_bf16_f32 v34, v2, v3
	v_readlane_b32 s1, v254, 27
	v_lshl_add_u64 v[2:3], v[30:31], 0, s[8:9]
	v_readlane_b32 s8, v251, 61
	v_readlane_b32 s9, v251, 62
	flat_load_dword v35, v[2:3]
	s_lshl_b32 s94, s1, 1
	v_lshl_add_u64 v[2:3], v[30:31], 0, s[8:9]
	v_readlane_b32 s8, v251, 55
	flat_load_dword v38, v[2:3]
	v_lshl_add_u64 v[2:3], v[30:31], 0, s[62:63]
	v_readlane_b32 s9, v251, 56
	flat_load_dword v39, v[2:3]
	s_waitcnt vmcnt(0) lgkmcnt(0)
	v_lshlrev_b32_e32 v114, 16, v35
	v_lshl_add_u64 v[2:3], v[30:31], 0, s[8:9]
	v_readlane_b32 s8, v251, 57
	v_readlane_b32 s9, v251, 58
	flat_load_dword v42, v[2:3]
	v_lshlrev_b32_e32 v116, 16, v38
	v_lshl_add_u64 v[2:3], v[30:31], 0, s[8:9]
	flat_load_dword v43, v[2:3]
	v_lshl_add_u64 v[2:3], v[30:31], 0, s[20:21]
	flat_load_dword v46, v[2:3]
	v_lshl_add_u64 v[2:3], v[30:31], 0, s[58:59]
	flat_load_dword v47, v[2:3]
	v_lshl_add_u64 v[2:3], v[30:31], 0, s[22:23]
	flat_load_dword v50, v[2:3]
	v_lshl_add_u64 v[2:3], v[30:31], 0, s[54:55]
	flat_load_dword v51, v[2:3]
	v_lshl_add_u64 v[2:3], v[30:31], 0, s[88:89]
	flat_load_dword v55, v[2:3]
	v_lshl_add_u64 v[2:3], v[30:31], 0, s[68:69]
	flat_load_dword v60, v[2:3]
	v_lshl_add_u64 v[2:3], v[30:31], 0, s[92:93]
	flat_load_dword v61, v[2:3]
	v_lshl_add_u64 v[2:3], v[30:31], 0, s[14:15]
	flat_load_dword v62, v[2:3]
	v_lshl_add_u64 v[2:3], v[30:31], 0, s[12:13]
	flat_load_dword v63, v[2:3]
	v_lshl_add_u64 v[2:3], v[30:31], 0, s[42:43]
	flat_load_dword v64, v[2:3]
	v_lshl_add_u64 v[2:3], v[30:31], 0, s[36:37]
	flat_load_dword v65, v[2:3]
	v_and_b32_e32 v117, 0xffff0000, v38
	v_lshlrev_b32_e32 v118, 16, v39
	v_and_b32_e32 v119, 0xffff0000, v39
	v_and_b32_e32 v115, 0xffff0000, v35
	v_lshl_add_u64 v[2:3], v[26:27], 0, s[94:95]
	global_store_dword v[2:3], v34, off nt
	s_waitcnt vmcnt(0) lgkmcnt(0)
	v_lshlrev_b32_e32 v120, 16, v42
	v_and_b32_e32 v121, 0xffff0000, v42
	v_lshlrev_b32_e32 v122, 16, v43
	v_and_b32_e32 v123, 0xffff0000, v43
	v_lshlrev_b32_e32 v98, 16, v46
	v_and_b32_e32 v99, 0xffff0000, v46
	v_lshlrev_b32_e32 v96, 16, v47
	v_and_b32_e32 v97, 0xffff0000, v47
	v_lshlrev_b32_e32 v94, 16, v50
	v_and_b32_e32 v95, 0xffff0000, v50
	v_lshlrev_b32_e32 v56, 16, v51
	v_and_b32_e32 v57, 0xffff0000, v51
	v_lshlrev_b32_e32 v54, 16, v55
	v_and_b32_e32 v55, 0xffff0000, v55
	v_lshlrev_b32_e32 v50, 16, v60
	v_and_b32_e32 v51, 0xffff0000, v60
	v_lshlrev_b32_e32 v46, 16, v61
	v_and_b32_e32 v47, 0xffff0000, v61
	v_lshlrev_b32_e32 v42, 16, v62
	v_and_b32_e32 v43, 0xffff0000, v62
	v_lshlrev_b32_e32 v38, 16, v63
	v_and_b32_e32 v39, 0xffff0000, v63
	ds_read_b128 v[60:63], v0 offset:128
	ds_read_b128 v[100:103], v0 offset:144
	ds_read_b128 v[104:107], v0 offset:160
	ds_read_b128 v[108:111], v0 offset:176
	v_lshlrev_b32_e32 v34, 16, v64
	v_and_b32_e32 v35, 0xffff0000, v64
	s_waitcnt lgkmcnt(2)
	v_pk_mul_f32 v[140:141], v[28:29], v[100:101] op_sel_hi:[1,0]
	v_pk_mul_f32 v[124:125], v[28:29], v[60:61] op_sel_hi:[1,0]
	v_pk_mul_f32 v[128:129], v[28:29], v[60:61] op_sel:[0,1]
	v_pk_fma_f32 v[112:113], v[124:125], v[114:115], v[112:113]
	v_pk_mul_f32 v[126:127], v[124:125], v[114:115]
	v_pk_fma_f32 v[66:67], v[92:93], v[66:67], v[112:113] neg_lo:[1,0,0] neg_hi:[1,0,0]
	v_pk_mul_f32 v[130:131], v[128:129], v[116:117]
	v_pk_fma_f32 v[92:93], v[66:67], s[0:1], v[126:127] op_sel_hi:[1,0,1] neg_lo:[0,0,1] neg_hi:[0,0,1]
	v_pk_fma_f32 v[66:67], v[128:129], v[116:117], v[66:67]
	v_pk_mul_f32 v[132:133], v[28:29], v[62:63] op_sel_hi:[1,0]
	v_readlane_b32 s1, v254, 25
	v_pk_fma_f32 v[58:59], v[90:91], v[58:59], v[66:67] neg_lo:[1,0,0] neg_hi:[1,0,0]
	v_mov_b32_e32 v60, v63
	v_pk_fma_f32 v[66:67], v[58:59], s[0:1], v[130:131] op_sel_hi:[1,0,1] neg_lo:[0,0,1] neg_hi:[0,0,1]
	v_pk_fma_f32 v[58:59], v[132:133], v[118:119], v[58:59]
	v_pk_mul_f32 v[134:135], v[132:133], v[118:119]
	v_pk_mul_f32 v[136:137], v[28:29], v[60:61] op_sel_hi:[1,0]
	s_lshl_b32 s94, s1, 1
	v_readlane_b32 s1, v253, 33
	v_pk_fma_f32 v[52:53], v[88:89], v[52:53], v[58:59] neg_lo:[1,0,0] neg_hi:[1,0,0]
	v_pk_mul_f32 v[138:139], v[136:137], v[120:121]
	v_pk_fma_f32 v[58:59], v[52:53], s[0:1], v[134:135] op_sel_hi:[1,0,1] neg_lo:[0,0,1] neg_hi:[0,0,1]
	v_pk_fma_f32 v[52:53], v[136:137], v[120:121], v[52:53]
	v_cvt_pk_bf16_f32 v112, v92, v93
	v_lshl_add_u64 v[92:93], v[26:27], 0, s[94:95]
	s_lshl_b32 s94, s1, 1
	v_readlane_b32 s1, v251, 53
	v_pk_fma_f32 v[48:49], v[86:87], v[48:49], v[52:53] neg_lo:[1,0,0] neg_hi:[1,0,0]
	v_pk_mul_f32 v[142:143], v[140:141], v[122:123]
	v_pk_fma_f32 v[52:53], v[48:49], s[0:1], v[138:139] op_sel_hi:[1,0,1] neg_lo:[0,0,1] neg_hi:[0,0,1]
	v_pk_fma_f32 v[48:49], v[140:141], v[122:123], v[48:49]
	v_pk_mul_f32 v[100:101], v[28:29], v[100:101] op_sel:[0,1]
	global_store_dword v[92:93], v112, off nt
	v_cvt_pk_bf16_f32 v90, v66, v67
	v_lshl_add_u64 v[66:67], v[26:27], 0, s[94:95]
	s_lshl_b32 s94, s1, 1
	v_readlane_b32 s1, v251, 51
	v_pk_fma_f32 v[44:45], v[82:83], v[44:45], v[48:49] neg_lo:[1,0,0] neg_hi:[1,0,0]
	v_pk_mul_f32 v[144:145], v[100:101], v[98:99]
	v_pk_fma_f32 v[48:49], v[44:45], s[0:1], v[142:143] op_sel_hi:[1,0,1] neg_lo:[0,0,1] neg_hi:[0,0,1]
	v_pk_fma_f32 v[44:45], v[100:101], v[98:99], v[44:45]
	v_pk_mul_f32 v[146:147], v[28:29], v[102:103] op_sel_hi:[1,0]
	global_store_dword v[66:67], v90, off nt
	v_cvt_pk_bf16_f32 v66, v58, v59
	v_lshl_add_u64 v[58:59], v[26:27], 0, s[94:95]
	s_lshl_b32 s94, s1, 1
	v_readlane_b32 s1, v253, 17
	v_pk_fma_f32 v[40:41], v[78:79], v[40:41], v[44:45] neg_lo:[1,0,0] neg_hi:[1,0,0]
	v_mov_b32_e32 v60, v103
	v_pk_fma_f32 v[44:45], v[40:41], s[0:1], v[144:145] op_sel_hi:[1,0,1] neg_lo:[0,0,1] neg_hi:[0,0,1]
	v_pk_fma_f32 v[40:41], v[146:147], v[96:97], v[40:41]
	v_pk_mul_f32 v[148:149], v[146:147], v[96:97]
	v_pk_mul_f32 v[102:103], v[28:29], v[60:61] op_sel_hi:[1,0]
	global_store_dword v[58:59], v66, off nt
	v_cvt_pk_bf16_f32 v58, v52, v53
	v_lshl_add_u64 v[52:53], v[26:27], 0, s[94:95]
	s_lshl_b32 s94, s1, 1
	v_readlane_b32 s1, v254, 11
	v_pk_fma_f32 v[36:37], v[74:75], v[36:37], v[40:41] neg_lo:[1,0,0] neg_hi:[1,0,0]
	v_pk_mul_f32 v[150:151], v[102:103], v[94:95]
	v_pk_fma_f32 v[40:41], v[36:37], s[0:1], v[148:149] op_sel_hi:[1,0,1] neg_lo:[0,0,1] neg_hi:[0,0,1]
	v_pk_fma_f32 v[36:37], v[102:103], v[94:95], v[36:37]
	global_store_dword v[52:53], v58, off nt
	v_cvt_pk_bf16_f32 v52, v48, v49
	v_lshl_add_u64 v[48:49], v[26:27], 0, s[94:95]
	s_lshl_b32 s94, s1, 1
	v_readlane_b32 s1, v253, 30
	v_pk_fma_f32 v[4:5], v[70:71], v[4:5], v[36:37] neg_lo:[1,0,0] neg_hi:[1,0,0]
	s_waitcnt lgkmcnt(1)
	v_pk_mul_f32 v[84:85], v[28:29], v[104:105] op_sel_hi:[1,0]
	global_store_dword v[48:49], v52, off nt
	v_cvt_pk_bf16_f32 v48, v44, v45
	v_lshl_add_u64 v[44:45], v[26:27], 0, s[94:95]
	s_lshl_b32 s94, s1, 1
	v_pk_fma_f32 v[36:37], v[4:5], s[0:1], v[150:151] op_sel_hi:[1,0,1] neg_lo:[0,0,1] neg_hi:[0,0,1]
	v_readlane_b32 s1, v254, 9
	global_store_dword v[44:45], v48, off nt
	v_cvt_pk_bf16_f32 v44, v40, v41
	v_lshl_add_u64 v[40:41], v[26:27], 0, s[94:95]
	s_lshl_b32 s94, s1, 1
	v_pk_fma_f32 v[4:5], v[84:85], v[56:57], v[4:5]
	v_pk_mul_f32 v[152:153], v[84:85], v[56:57]
	v_pk_mul_f32 v[80:81], v[28:29], v[104:105] op_sel:[0,1]
	global_store_dword v[40:41], v44, off nt
	v_cvt_pk_bf16_f32 v40, v36, v37
	v_lshl_add_u64 v[36:37], v[26:27], 0, s[94:95]
	v_pk_fma_f32 v[4:5], v[124:125], v[114:115], v[4:5] neg_lo:[1,0,0] neg_hi:[1,0,0]
	global_store_dword v[36:37], v40, off nt
	v_pk_fma_f32 v[36:37], v[4:5], s[0:1], v[152:153] op_sel_hi:[1,0,1] neg_lo:[0,0,1] neg_hi:[0,0,1]
	s_lshl_b32 s94, s73, 1
	v_pk_fma_f32 v[4:5], v[80:81], v[54:55], v[4:5]
	v_pk_mul_f32 v[104:105], v[80:81], v[54:55]
	v_pk_mul_f32 v[76:77], v[28:29], v[106:107] op_sel_hi:[1,0]
	v_cvt_pk_bf16_f32 v40, v36, v37
	v_lshl_add_u64 v[36:37], v[26:27], 0, s[94:95]
	v_pk_fma_f32 v[4:5], v[128:129], v[116:117], v[4:5] neg_lo:[1,0,0] neg_hi:[1,0,0]
	global_store_dword v[36:37], v40, off nt
	v_pk_fma_f32 v[36:37], v[4:5], s[0:1], v[104:105] op_sel_hi:[1,0,1] neg_lo:[0,0,1] neg_hi:[0,0,1]
	s_lshl_b32 s94, s64, 1
	v_pk_fma_f32 v[4:5], v[76:77], v[50:51], v[4:5]
	v_pk_mul_f32 v[154:155], v[76:77], v[50:51]
	v_mov_b32_e32 v60, v107
	v_cvt_pk_bf16_f32 v40, v36, v37
	v_lshl_add_u64 v[36:37], v[26:27], 0, s[94:95]
	v_pk_fma_f32 v[4:5], v[132:133], v[118:119], v[4:5] neg_lo:[1,0,0] neg_hi:[1,0,0]
	v_pk_mul_f32 v[72:73], v[28:29], v[60:61] op_sel_hi:[1,0]
	global_store_dword v[36:37], v40, off nt
	v_pk_fma_f32 v[36:37], v[4:5], s[0:1], v[154:155] op_sel_hi:[1,0,1] neg_lo:[0,0,1] neg_hi:[0,0,1]
	v_readlane_b32 s1, v253, 41
	s_lshl_b32 s94, s1, 1
	v_pk_fma_f32 v[4:5], v[72:73], v[46:47], v[4:5]
	v_pk_mul_f32 v[106:107], v[72:73], v[46:47]
	v_cvt_pk_bf16_f32 v40, v36, v37
	v_lshl_add_u64 v[36:37], v[26:27], 0, s[94:95]
	v_pk_fma_f32 v[4:5], v[136:137], v[120:121], v[4:5] neg_lo:[1,0,0] neg_hi:[1,0,0]
	s_waitcnt lgkmcnt(0)
	v_pk_mul_f32 v[68:69], v[28:29], v[108:109] op_sel_hi:[1,0]
	global_store_dword v[36:37], v40, off nt
	v_pk_fma_f32 v[36:37], v[4:5], s[0:1], v[106:107] op_sel_hi:[1,0,1] neg_lo:[0,0,1] neg_hi:[0,0,1]
	v_readlane_b32 s1, v253, 36
	s_lshl_b32 s94, s1, 1
	v_pk_fma_f32 v[4:5], v[68:69], v[42:43], v[4:5]
	v_pk_mul_f32 v[156:157], v[68:69], v[42:43]
	v_cvt_pk_bf16_f32 v40, v36, v37
	v_lshl_add_u64 v[36:37], v[26:27], 0, s[94:95]
	v_pk_fma_f32 v[4:5], v[140:141], v[122:123], v[4:5] neg_lo:[1,0,0] neg_hi:[1,0,0]
	v_lshlrev_b32_e32 v2, 16, v65
	v_and_b32_e32 v3, 0xffff0000, v65
	v_pk_mul_f32 v[64:65], v[28:29], v[108:109] op_sel:[0,1]
	global_store_dword v[36:37], v40, off nt
	v_pk_fma_f32 v[36:37], v[4:5], s[0:1], v[156:157] op_sel_hi:[1,0,1] neg_lo:[0,0,1] neg_hi:[0,0,1]
	v_readlane_b32 s1, v253, 37
	s_lshl_b32 s94, s1, 1
	v_pk_fma_f32 v[4:5], v[64:65], v[38:39], v[4:5]
	v_pk_mul_f32 v[108:109], v[64:65], v[38:39]
	v_cvt_pk_bf16_f32 v40, v36, v37
	v_lshl_add_u64 v[36:37], v[26:27], 0, s[94:95]
	v_pk_fma_f32 v[4:5], v[100:101], v[98:99], v[4:5] neg_lo:[1,0,0] neg_hi:[1,0,0]
	v_pk_mul_f32 v[62:63], v[28:29], v[110:111] op_sel_hi:[1,0]
	global_store_dword v[36:37], v40, off nt
	v_pk_fma_f32 v[36:37], v[4:5], s[0:1], v[108:109] op_sel_hi:[1,0,1] neg_lo:[0,0,1] neg_hi:[0,0,1]
	v_readlane_b32 s1, v254, 21
	v_mov_b32_e32 v60, v111
	s_lshl_b32 s94, s1, 1
	v_pk_fma_f32 v[4:5], v[62:63], v[34:35], v[4:5]
	v_pk_mul_f32 v[158:159], v[62:63], v[34:35]
	v_pk_mul_f32 v[60:61], v[28:29], v[60:61] op_sel_hi:[1,0]
	v_cvt_pk_bf16_f32 v40, v36, v37
	v_lshl_add_u64 v[36:37], v[26:27], 0, s[94:95]
	v_pk_fma_f32 v[4:5], v[146:147], v[96:97], v[4:5] neg_lo:[1,0,0] neg_hi:[1,0,0]
	global_store_dword v[36:37], v40, off nt
	v_pk_fma_f32 v[36:37], v[4:5], s[0:1], v[158:159] op_sel_hi:[1,0,1] neg_lo:[0,0,1] neg_hi:[0,0,1]
	v_readlane_b32 s1, v253, 38
	v_pk_fma_f32 v[4:5], v[60:61], v[2:3], v[4:5]
	v_pk_mul_f32 v[110:111], v[60:61], v[2:3]
	s_lshl_b32 s94, s1, 1
	v_pk_fma_f32 v[52:53], v[102:103], v[94:95], v[4:5] neg_lo:[1,0,0] neg_hi:[1,0,0]
	v_cvt_pk_bf16_f32 v40, v36, v37
	v_lshl_add_u64 v[36:37], v[26:27], 0, s[94:95]
	v_pk_fma_f32 v[4:5], v[52:53], s[0:1], v[110:111] op_sel_hi:[1,0,1] neg_lo:[0,0,1] neg_hi:[0,0,1]
	global_store_dword v[36:37], v40, off nt
	v_cvt_pk_bf16_f32 v36, v4, v5
	v_lshl_add_u64 v[4:5], v[30:31], 0, s[44:45]
	flat_load_dword v37, v[4:5]
	v_lshl_add_u64 v[4:5], v[30:31], 0, s[40:41]
	flat_load_dword v40, v[4:5]
	v_lshl_add_u64 v[4:5], v[30:31], 0, s[46:47]
	flat_load_dword v41, v[4:5]
	v_lshl_add_u64 v[4:5], v[30:31], 0, s[10:11]
	flat_load_dword v44, v[4:5]
	v_lshl_add_u64 v[4:5], v[30:31], 0, s[52:53]
	flat_load_dword v45, v[4:5]
	v_lshl_add_u64 v[4:5], v[30:31], 0, s[38:39]
	flat_load_dword v48, v[4:5]
	v_lshl_add_u64 v[4:5], v[30:31], 0, s[90:91]
	flat_load_dword v49, v[4:5]
	v_lshl_add_u64 v[4:5], v[30:31], 0, s[78:79]
	flat_load_dword v82, v[4:5]
	v_lshl_add_u64 v[4:5], v[30:31], 0, s[50:51]
	flat_load_dword v83, v[4:5]
	v_lshl_add_u64 v[4:5], v[30:31], 0, s[56:57]
	flat_load_dword v86, v[4:5]
	v_lshl_add_u64 v[4:5], v[30:31], 0, s[34:35]
	flat_load_dword v87, v[4:5]
	v_lshl_add_u64 v[4:5], v[30:31], 0, s[6:7]
	flat_load_dword v88, v[4:5]
	v_lshl_add_u64 v[4:5], v[30:31], 0, s[74:75]
	flat_load_dword v89, v[4:5]
	v_lshl_add_u64 v[4:5], v[30:31], 0, s[4:5]
	flat_load_dword v90, v[4:5]
	v_lshl_add_u64 v[4:5], v[30:31], 0, s[24:25]
	flat_load_dword v91, v[4:5]
	v_lshl_add_u64 v[4:5], v[30:31], 0, s[60:61]
	flat_load_dword v92, v[4:5]
	v_readlane_b32 s1, v254, 19
	s_lshl_b32 s94, s1, 1
	v_lshl_add_u64 v[4:5], v[26:27], 0, s[94:95]
	global_store_dword v[4:5], v36, off nt
	s_waitcnt vmcnt(0) lgkmcnt(0)
	v_lshlrev_b32_e32 v58, 16, v37
	v_and_b32_e32 v59, 0xffff0000, v37
	v_lshlrev_b32_e32 v66, 16, v40
	v_and_b32_e32 v67, 0xffff0000, v40
	v_lshlrev_b32_e32 v70, 16, v41
	v_and_b32_e32 v71, 0xffff0000, v41
	v_lshlrev_b32_e32 v74, 16, v44
	v_and_b32_e32 v75, 0xffff0000, v44
	v_lshlrev_b32_e32 v78, 16, v45
	v_and_b32_e32 v79, 0xffff0000, v45
	v_lshlrev_b32_e32 v44, 16, v48
	v_and_b32_e32 v45, 0xffff0000, v48
	v_lshlrev_b32_e32 v36, 16, v49
	v_and_b32_e32 v37, 0xffff0000, v49
	v_lshlrev_b32_e32 v4, 16, v82
	v_and_b32_e32 v5, 0xffff0000, v82
	v_lshlrev_b32_e32 v82, 16, v83
	v_and_b32_e32 v83, 0xffff0000, v83
	v_lshlrev_b32_e32 v102, 16, v86
	v_and_b32_e32 v103, 0xffff0000, v86
	v_lshlrev_b32_e32 v104, 16, v87
	v_and_b32_e32 v105, 0xffff0000, v87
	v_lshlrev_b32_e32 v106, 16, v88
	v_and_b32_e32 v107, 0xffff0000, v88
	v_lshlrev_b32_e32 v108, 16, v89
	v_and_b32_e32 v109, 0xffff0000, v89
	ds_read_b128 v[86:89], v0 offset:192
	v_lshlrev_b32_e32 v110, 16, v90
	v_and_b32_e32 v111, 0xffff0000, v90
	v_lshlrev_b32_e32 v48, 16, v91
	v_and_b32_e32 v49, 0xffff0000, v91
	s_waitcnt lgkmcnt(0)
	v_pk_mul_f32 v[112:113], v[28:29], v[86:87] op_sel_hi:[1,0]
	v_lshlrev_b32_e32 v40, 16, v92
	v_pk_fma_f32 v[52:53], v[112:113], v[58:59], v[52:53]
	v_and_b32_e32 v41, 0xffff0000, v92
	ds_read_b128 v[90:93], v0 offset:208
	ds_read_b128 v[94:97], v0 offset:224
	ds_read_b128 v[98:101], v0 offset:240
	v_pk_mul_f32 v[114:115], v[112:113], v[58:59]
	v_pk_mul_f32 v[86:87], v[28:29], v[86:87] op_sel:[0,1]
	v_pk_fma_f32 v[52:53], v[84:85], v[56:57], v[52:53] neg_lo:[1,0,0] neg_hi:[1,0,0]
	v_pk_mul_f32 v[116:117], v[86:87], v[66:67]
	v_pk_fma_f32 v[56:57], v[52:53], s[0:1], v[114:115] op_sel_hi:[1,0,1] neg_lo:[0,0,1] neg_hi:[0,0,1]
	v_pk_fma_f32 v[52:53], v[86:87], v[66:67], v[52:53]
	v_pk_mul_f32 v[118:119], v[28:29], v[88:89] op_sel_hi:[1,0]
	v_mov_b32_e32 v0, v89
	v_readlane_b32 s1, v254, 23
	v_pk_fma_f32 v[52:53], v[80:81], v[54:55], v[52:53] neg_lo:[1,0,0] neg_hi:[1,0,0]
	v_pk_mul_f32 v[88:89], v[28:29], v[0:1] op_sel_hi:[1,0]
	s_waitcnt lgkmcnt(2)
	v_mov_b32_e32 v0, v93
	v_pk_fma_f32 v[54:55], v[52:53], s[0:1], v[116:117] op_sel_hi:[1,0,1] neg_lo:[0,0,1] neg_hi:[0,0,1]
	v_pk_fma_f32 v[52:53], v[118:119], v[70:71], v[52:53]
	v_pk_mul_f32 v[120:121], v[118:119], v[70:71]
	v_pk_mul_f32 v[130:131], v[28:29], v[92:93] op_sel_hi:[1,0]
	v_pk_mul_f32 v[92:93], v[28:29], v[0:1] op_sel_hi:[1,0]
	s_waitcnt lgkmcnt(1)
	v_mov_b32_e32 v0, v97
	s_lshl_b32 s94, s1, 1
	v_readlane_b32 s1, v254, 33
	v_pk_fma_f32 v[50:51], v[76:77], v[50:51], v[52:53] neg_lo:[1,0,0] neg_hi:[1,0,0]
	v_pk_mul_f32 v[142:143], v[28:29], v[96:97] op_sel_hi:[1,0]
	v_pk_mul_f32 v[96:97], v[28:29], v[0:1] op_sel_hi:[1,0]
	s_waitcnt lgkmcnt(0)
	v_mov_b32_e32 v0, v101
	v_pk_fma_f32 v[52:53], v[50:51], s[0:1], v[120:121] op_sel_hi:[1,0,1] neg_lo:[0,0,1] neg_hi:[0,0,1]
	v_pk_fma_f32 v[50:51], v[88:89], v[74:75], v[50:51]
	v_pk_mul_f32 v[122:123], v[88:89], v[74:75]
	v_pk_mul_f32 v[124:125], v[28:29], v[90:91] op_sel_hi:[1,0]
	v_pk_mul_f32 v[154:155], v[28:29], v[100:101] op_sel_hi:[1,0]
	v_pk_mul_f32 v[100:101], v[28:29], v[0:1] op_sel_hi:[1,0]
	v_cvt_pk_bf16_f32 v0, v56, v57
	v_lshl_add_u64 v[56:57], v[26:27], 0, s[94:95]
	s_lshl_b32 s94, s1, 1
	v_readlane_b32 s1, v254, 29
	v_pk_fma_f32 v[46:47], v[72:73], v[46:47], v[50:51] neg_lo:[1,0,0] neg_hi:[1,0,0]
	v_pk_mul_f32 v[126:127], v[124:125], v[78:79]
	v_pk_fma_f32 v[50:51], v[46:47], s[0:1], v[122:123] op_sel_hi:[1,0,1] neg_lo:[0,0,1] neg_hi:[0,0,1]
	v_pk_fma_f32 v[46:47], v[124:125], v[78:79], v[46:47]
	v_pk_mul_f32 v[90:91], v[28:29], v[90:91] op_sel:[0,1]
	global_store_dword v[56:57], v0, off nt
	v_cvt_pk_bf16_f32 v0, v54, v55
	v_lshl_add_u64 v[54:55], v[26:27], 0, s[94:95]
	s_lshl_b32 s94, s1, 1
	v_readlane_b32 s1, v253, 42
	v_pk_fma_f32 v[42:43], v[68:69], v[42:43], v[46:47] neg_lo:[1,0,0] neg_hi:[1,0,0]
	v_pk_mul_f32 v[128:129], v[90:91], v[44:45]
	v_pk_fma_f32 v[46:47], v[42:43], s[0:1], v[126:127] op_sel_hi:[1,0,1] neg_lo:[0,0,1] neg_hi:[0,0,1]
	v_pk_fma_f32 v[42:43], v[90:91], v[44:45], v[42:43]
	global_store_dword v[54:55], v0, off nt
	v_cvt_pk_bf16_f32 v0, v52, v53
	v_lshl_add_u64 v[52:53], v[26:27], 0, s[94:95]
	s_lshl_b32 s94, s1, 1
	v_readlane_b32 s1, v254, 37
	v_pk_fma_f32 v[38:39], v[64:65], v[38:39], v[42:43] neg_lo:[1,0,0] neg_hi:[1,0,0]
	v_pk_mul_f32 v[132:133], v[130:131], v[36:37]
	v_pk_fma_f32 v[42:43], v[38:39], s[0:1], v[128:129] op_sel_hi:[1,0,1] neg_lo:[0,0,1] neg_hi:[0,0,1]
	v_pk_fma_f32 v[38:39], v[130:131], v[36:37], v[38:39]
	global_store_dword v[52:53], v0, off nt
	v_pk_fma_f32 v[34:35], v[62:63], v[34:35], v[38:39] neg_lo:[1,0,0] neg_hi:[1,0,0]
	v_cvt_pk_bf16_f32 v0, v50, v51
	v_lshl_add_u64 v[50:51], v[26:27], 0, s[94:95]
	s_lshl_b32 s94, s1, 1
	v_pk_fma_f32 v[38:39], v[34:35], s[0:1], v[132:133] op_sel_hi:[1,0,1] neg_lo:[0,0,1] neg_hi:[0,0,1]
	v_pk_fma_f32 v[34:35], v[92:93], v[4:5], v[34:35]
	v_pk_mul_f32 v[134:135], v[92:93], v[4:5]
	global_store_dword v[50:51], v0, off nt
	v_cvt_pk_bf16_f32 v0, v46, v47
	v_lshl_add_u64 v[46:47], v[26:27], 0, s[94:95]
	s_lshl_b32 s94, s65, 1
	v_pk_fma_f32 v[2:3], v[60:61], v[2:3], v[34:35] neg_lo:[1,0,0] neg_hi:[1,0,0]
	v_pk_mul_f32 v[136:137], v[28:29], v[94:95] op_sel_hi:[1,0]
	global_store_dword v[46:47], v0, off nt
	v_cvt_pk_bf16_f32 v0, v42, v43
	v_lshl_add_u64 v[42:43], v[26:27], 0, s[94:95]
	s_lshl_b32 s94, s48, 1
	v_pk_fma_f32 v[34:35], v[2:3], s[0:1], v[134:135] op_sel_hi:[1,0,1] neg_lo:[0,0,1] neg_hi:[0,0,1]
	v_readlane_b32 s1, v253, 18
	global_store_dword v[42:43], v0, off nt
	v_cvt_pk_bf16_f32 v0, v38, v39
	v_lshl_add_u64 v[38:39], v[26:27], 0, s[94:95]
	s_lshl_b32 s94, s1, 1
	v_pk_fma_f32 v[2:3], v[136:137], v[82:83], v[2:3]
	v_pk_mul_f32 v[138:139], v[136:137], v[82:83]
	global_store_dword v[38:39], v0, off nt
	v_cvt_pk_bf16_f32 v0, v34, v35
	v_lshl_add_u64 v[34:35], v[26:27], 0, s[94:95]
	v_pk_fma_f32 v[2:3], v[112:113], v[58:59], v[2:3] neg_lo:[1,0,0] neg_hi:[1,0,0]
	v_pk_mul_f32 v[94:95], v[28:29], v[94:95] op_sel:[0,1]
	global_store_dword v[34:35], v0, off nt
	v_pk_fma_f32 v[34:35], v[2:3], s[0:1], v[138:139] op_sel_hi:[1,0,1] neg_lo:[0,0,1] neg_hi:[0,0,1]
	v_readlane_b32 s1, v254, 41
	s_lshl_b32 s94, s1, 1
	v_pk_fma_f32 v[2:3], v[94:95], v[102:103], v[2:3]
	v_pk_mul_f32 v[140:141], v[94:95], v[102:103]
	v_cvt_pk_bf16_f32 v0, v34, v35
	v_lshl_add_u64 v[34:35], v[26:27], 0, s[94:95]
	v_pk_fma_f32 v[2:3], v[86:87], v[66:67], v[2:3] neg_lo:[1,0,0] neg_hi:[1,0,0]
	global_store_dword v[34:35], v0, off nt
	v_pk_fma_f32 v[34:35], v[2:3], s[0:1], v[140:141] op_sel_hi:[1,0,1] neg_lo:[0,0,1] neg_hi:[0,0,1]
	s_lshl_b32 s94, s49, 1
	v_pk_fma_f32 v[2:3], v[142:143], v[104:105], v[2:3]
	v_pk_mul_f32 v[144:145], v[142:143], v[104:105]
	v_cvt_pk_bf16_f32 v0, v34, v35
	v_lshl_add_u64 v[34:35], v[26:27], 0, s[94:95]
	v_pk_fma_f32 v[2:3], v[118:119], v[70:71], v[2:3] neg_lo:[1,0,0] neg_hi:[1,0,0]
	global_store_dword v[34:35], v0, off nt
	v_pk_fma_f32 v[34:35], v[2:3], s[0:1], v[144:145] op_sel_hi:[1,0,1] neg_lo:[0,0,1] neg_hi:[0,0,1]
	s_lshl_b32 s94, s86, 1
	v_pk_fma_f32 v[2:3], v[96:97], v[106:107], v[2:3]
	v_pk_mul_f32 v[146:147], v[96:97], v[106:107]
	v_pk_mul_f32 v[148:149], v[28:29], v[98:99] op_sel_hi:[1,0]
	v_cvt_pk_bf16_f32 v0, v34, v35
	v_lshl_add_u64 v[34:35], v[26:27], 0, s[94:95]
	v_pk_fma_f32 v[2:3], v[88:89], v[74:75], v[2:3] neg_lo:[1,0,0] neg_hi:[1,0,0]
	global_store_dword v[34:35], v0, off nt
	v_pk_fma_f32 v[34:35], v[2:3], s[0:1], v[146:147] op_sel_hi:[1,0,1] neg_lo:[0,0,1] neg_hi:[0,0,1]
	s_lshl_b32 s94, s67, 1
	v_pk_fma_f32 v[2:3], v[148:149], v[108:109], v[2:3]
	v_pk_mul_f32 v[150:151], v[148:149], v[108:109]
	v_cvt_pk_bf16_f32 v0, v34, v35
	v_lshl_add_u64 v[34:35], v[26:27], 0, s[94:95]
	v_pk_fma_f32 v[2:3], v[124:125], v[78:79], v[2:3] neg_lo:[1,0,0] neg_hi:[1,0,0]
	v_pk_mul_f32 v[98:99], v[28:29], v[98:99] op_sel:[0,1]
	global_store_dword v[34:35], v0, off nt
	v_pk_fma_f32 v[34:35], v[2:3], s[0:1], v[150:151] op_sel_hi:[1,0,1] neg_lo:[0,0,1] neg_hi:[0,0,1]
	v_readlane_b32 s1, v253, 63
	s_lshl_b32 s94, s1, 1
	v_pk_fma_f32 v[2:3], v[98:99], v[110:111], v[2:3]
	v_pk_mul_f32 v[152:153], v[98:99], v[110:111]
	v_cvt_pk_bf16_f32 v0, v34, v35
	v_lshl_add_u64 v[34:35], v[26:27], 0, s[94:95]
	v_pk_fma_f32 v[2:3], v[90:91], v[44:45], v[2:3] neg_lo:[1,0,0] neg_hi:[1,0,0]
	global_store_dword v[34:35], v0, off nt
	v_pk_fma_f32 v[34:35], v[2:3], s[0:1], v[152:153] op_sel_hi:[1,0,1] neg_lo:[0,0,1] neg_hi:[0,0,1]
	v_readlane_b32 s1, v253, 61
	s_lshl_b32 s94, s1, 1
	v_pk_fma_f32 v[2:3], v[154:155], v[48:49], v[2:3]
	v_pk_mul_f32 v[156:157], v[154:155], v[48:49]
	v_cvt_pk_bf16_f32 v0, v34, v35
	v_lshl_add_u64 v[34:35], v[26:27], 0, s[94:95]
	v_pk_fma_f32 v[2:3], v[130:131], v[36:37], v[2:3] neg_lo:[1,0,0] neg_hi:[1,0,0]
	global_store_dword v[34:35], v0, off nt
	v_pk_fma_f32 v[34:35], v[2:3], s[0:1], v[156:157] op_sel_hi:[1,0,1] neg_lo:[0,0,1] neg_hi:[0,0,1]
	s_lshl_b32 s94, s66, 1
	v_pk_fma_f32 v[2:3], v[100:101], v[40:41], v[2:3]
	v_pk_mul_f32 v[158:159], v[100:101], v[40:41]
	v_cvt_pk_bf16_f32 v0, v34, v35
	v_lshl_add_u64 v[34:35], v[26:27], 0, s[94:95]
	v_pk_fma_f32 v[2:3], v[92:93], v[4:5], v[2:3] neg_lo:[1,0,0] neg_hi:[1,0,0]
	global_store_dword v[34:35], v0, off nt
	v_pk_fma_f32 v[2:3], v[2:3], s[0:1], v[158:159] op_sel_hi:[1,0,1] neg_lo:[0,0,1] neg_hi:[0,0,1]
	s_nop 0
	v_cvt_pk_bf16_f32 v162, v2, v3
	s_branch .LBB0_367

.LBB0_370:
	v_readlane_b32 s0, v253, 20
	v_readlane_b32 s1, v253, 21
	v_readlane_b32 s2, v252, 3
	v_readlane_b32 s3, v252, 4
	v_lshl_add_u64 v[2:3], v[30:31], 0, s[0:1]
	v_readlane_b32 s0, v252, 31
	v_readlane_b32 s1, v252, 32
	flat_load_dword v34, v[2:3]
	s_mov_b64 s[96:97], -1
	v_lshl_add_u64 v[2:3], v[30:31], 0, s[0:1]
	v_readlane_b32 s0, v252, 34
	v_readlane_b32 s1, v252, 35
	flat_load_dword v35, v[2:3]
	s_waitcnt vmcnt(0) lgkmcnt(0)
	v_lshlrev_b32_e32 v74, 16, v34
	v_lshl_add_u64 v[2:3], v[30:31], 0, s[0:1]
	v_readlane_b32 s0, v252, 37
	v_readlane_b32 s1, v252, 38
	flat_load_dword v38, v[2:3]
	v_and_b32_e32 v75, 0xffff0000, v34
	v_lshl_add_u64 v[2:3], v[30:31], 0, s[0:1]
	v_readlane_b32 s0, v252, 40
	v_readlane_b32 s1, v252, 41
	flat_load_dword v39, v[2:3]
	v_lshlrev_b32_e32 v76, 16, v35
	v_lshl_add_u64 v[2:3], v[30:31], 0, s[0:1]
	v_readlane_b32 s0, v252, 43
	v_readlane_b32 s1, v252, 44
	flat_load_dword v42, v[2:3]
	v_and_b32_e32 v77, 0xffff0000, v35
	v_lshl_add_u64 v[2:3], v[30:31], 0, s[0:1]
	v_readlane_b32 s0, v252, 51
	v_readlane_b32 s1, v252, 52
	flat_load_dword v43, v[2:3]
	s_waitcnt vmcnt(0) lgkmcnt(0)
	v_lshlrev_b32_e32 v78, 16, v38
	v_lshl_add_u64 v[2:3], v[30:31], 0, s[0:1]
	v_readlane_b32 s0, v253, 26
	v_readlane_b32 s1, v253, 27
	flat_load_dword v87, v[2:3]
	v_and_b32_e32 v79, 0xffff0000, v38
	v_lshl_add_u64 v[2:3], v[30:31], 0, s[0:1]
	v_readlane_b32 s0, v253, 31
	v_readlane_b32 s1, v253, 32
	flat_load_dword v89, v[2:3]
	v_lshlrev_b32_e32 v80, 16, v39
	v_lshl_add_u64 v[2:3], v[30:31], 0, s[0:1]
	v_readlane_b32 s0, v252, 54
	v_readlane_b32 s1, v252, 55
	flat_load_dword v91, v[2:3]
	v_and_b32_e32 v81, 0xffff0000, v39
	v_lshl_add_u64 v[2:3], v[30:31], 0, s[0:1]
	v_readlane_b32 s0, v254, 7
	v_readlane_b32 s1, v254, 8
	flat_load_dword v93, v[2:3]
	v_lshlrev_b32_e32 v82, 16, v42
	v_lshl_add_u64 v[2:3], v[30:31], 0, s[0:1]
	v_readlane_b32 s0, v253, 22
	v_readlane_b32 s1, v253, 23
	flat_load_dword v95, v[2:3]
	v_and_b32_e32 v83, 0xffff0000, v42
	v_lshl_add_u64 v[2:3], v[30:31], 0, s[0:1]
	v_readlane_b32 s0, v254, 13
	v_readlane_b32 s1, v254, 14
	flat_load_dword v97, v[2:3]
	v_lshlrev_b32_e32 v84, 16, v43
	v_lshl_add_u64 v[2:3], v[30:31], 0, s[0:1]
	v_readlane_b32 s0, v254, 15
	v_readlane_b32 s1, v254, 16
	flat_load_dword v98, v[2:3]
	v_and_b32_e32 v85, 0xffff0000, v43
	v_lshl_add_u64 v[2:3], v[30:31], 0, s[0:1]
	v_readlane_b32 s0, v254, 17
	v_readlane_b32 s1, v254, 18
	flat_load_dword v99, v[2:3]
	s_waitcnt vmcnt(0) lgkmcnt(0)
	v_lshlrev_b32_e32 v86, 16, v87
	v_lshl_add_u64 v[2:3], v[30:31], 0, s[0:1]
	v_readlane_b32 s0, v253, 34
	v_readlane_b32 s1, v253, 35
	flat_load_dword v100, v[2:3]
	v_and_b32_e32 v87, 0xffff0000, v87
	v_lshl_add_u64 v[2:3], v[30:31], 0, s[0:1]
	flat_load_dword v101, v[2:3]
	v_readlane_b32 s0, v252, 23
	v_pk_add_f32 v[2:3], v[44:45], 0 op_sel_hi:[1,0]
	v_lshlrev_b32_e32 v88, 16, v89
	v_mov_b32_e32 v0, s0
	v_pk_add_f32 v[2:3], v[40:41], v[2:3]
	ds_read_b128 v[46:49], v0
	ds_read_b128 v[50:53], v0 offset:16
	ds_read_b128 v[54:57], v0 offset:32
	ds_read_b128 v[58:61], v0 offset:48
	v_pk_add_f32 v[2:3], v[36:37], v[2:3]
	s_waitcnt lgkmcnt(0)
	v_pk_mul_f32 v[64:65], v[28:29], v[46:47] op_sel_hi:[1,0]
	v_pk_add_f32 v[62:63], v[4:5], v[2:3]
	v_pk_mul_f32 v[66:67], v[28:29], v[46:47] op_sel:[0,1]
	v_pk_fma_f32 v[62:63], v[64:65], v[74:75], v[62:63]
	v_mov_b32_e32 v2, v49
	v_pk_add_f32 v[44:45], v[62:63], v[44:45] neg_lo:[0,1] neg_hi:[0,1]
	v_pk_mul_f32 v[68:69], v[28:29], v[48:49] op_sel_hi:[1,0]
	v_pk_mul_f32 v[72:73], v[28:29], v[2:3] op_sel_hi:[1,0]
	v_readlane_b32 s0, v252, 27
	v_pk_mul_f32 v[102:103], v[68:69], v[78:79]
	s_lshl_b32 s94, s0, 1
	v_readlane_b32 s0, v252, 30
	v_pk_mul_f32 v[104:105], v[72:73], v[80:81]
	v_pk_mul_f32 v[70:71], v[28:29], v[50:51] op_sel_hi:[1,0]
	v_pk_mul_f32 v[108:109], v[28:29], v[50:51] op_sel:[0,1]
	v_lshlrev_b32_e32 v42, 16, v98
	v_and_b32_e32 v43, 0xffff0000, v98
	v_pk_mul_f32 v[106:107], v[70:71], v[82:83]
	v_pk_mul_f32 v[110:111], v[108:109], v[84:85]
	v_pk_mul_f32 v[112:113], v[28:29], v[52:53] op_sel_hi:[1,0]
	v_lshlrev_b32_e32 v38, 16, v99
	v_and_b32_e32 v39, 0xffff0000, v99
	v_pk_mul_f32 v[98:99], v[64:65], v[74:75]
	v_pk_mul_f32 v[114:115], v[112:113], v[86:87]
	v_pk_fma_f32 v[62:63], v[20:21], v[44:45], v[98:99] neg_lo:[0,0,1] neg_hi:[0,0,1]
	v_pk_fma_f32 v[44:45], v[66:67], v[76:77], v[44:45]
	v_cvt_pk_bf16_f32 v98, v62, v63
	v_lshl_add_u64 v[62:63], v[26:27], 0, s[94:95]
	v_pk_add_f32 v[40:41], v[44:45], v[40:41] neg_lo:[0,1] neg_hi:[0,1]
	s_lshl_b32 s94, s0, 1
	v_readlane_b32 s0, v252, 33
	global_store_dword v[62:63], v98, off nt
	v_mov_b32_e32 v46, v53
	v_and_b32_e32 v89, 0xffff0000, v89
	v_pk_mul_f32 v[116:117], v[28:29], v[46:47] op_sel_hi:[1,0]
	v_lshlrev_b32_e32 v90, 16, v91
	v_pk_mul_f32 v[118:119], v[116:117], v[88:89]
	v_and_b32_e32 v91, 0xffff0000, v91
	v_pk_mul_f32 v[120:121], v[28:29], v[54:55] op_sel_hi:[1,0]
	v_lshlrev_b32_e32 v92, 16, v93
	v_pk_mul_f32 v[122:123], v[120:121], v[90:91]
	v_and_b32_e32 v93, 0xffff0000, v93
	v_pk_mul_f32 v[54:55], v[28:29], v[54:55] op_sel:[0,1]
	v_lshlrev_b32_e32 v94, 16, v95
	v_pk_mul_f32 v[124:125], v[54:55], v[92:93]
	v_and_b32_e32 v95, 0xffff0000, v95
	v_pk_mul_f32 v[126:127], v[28:29], v[56:57] op_sel_hi:[1,0]
	v_mov_b32_e32 v46, v57
	v_pk_mul_f32 v[128:129], v[126:127], v[94:95]
	v_lshlrev_b32_e32 v96, 16, v97
	v_and_b32_e32 v97, 0xffff0000, v97
	v_pk_mul_f32 v[56:57], v[28:29], v[46:47] op_sel_hi:[1,0]
	v_pk_mul_f32 v[52:53], v[28:29], v[58:59] op_sel_hi:[1,0]
	v_pk_mul_f32 v[130:131], v[56:57], v[96:97]
	v_pk_mul_f32 v[132:133], v[52:53], v[42:43]
	v_pk_mul_f32 v[50:51], v[28:29], v[58:59] op_sel:[0,1]
	v_pk_mul_f32 v[48:49], v[28:29], v[60:61] op_sel_hi:[1,0]
	v_pk_mul_f32 v[58:59], v[50:51], v[38:39]
	v_mov_b32_e32 v46, v61
	v_pk_mul_f32 v[46:47], v[28:29], v[46:47] op_sel_hi:[1,0]
	s_waitcnt vmcnt(0)
	v_lshlrev_b32_e32 v34, 16, v100
	v_and_b32_e32 v35, 0xffff0000, v100
	v_pk_mul_f32 v[134:135], v[48:49], v[34:35]
	v_lshlrev_b32_e32 v2, 16, v101
	v_and_b32_e32 v3, 0xffff0000, v101
	v_pk_mul_f32 v[100:101], v[66:67], v[76:77]
	v_pk_mul_f32 v[60:61], v[46:47], v[2:3]
	v_pk_fma_f32 v[44:45], v[22:23], v[40:41], v[100:101] neg_lo:[0,0,1] neg_hi:[0,0,1]
	v_pk_fma_f32 v[40:41], v[68:69], v[78:79], v[40:41]
	v_cvt_pk_bf16_f32 v62, v44, v45
	v_lshl_add_u64 v[44:45], v[26:27], 0, s[94:95]
	v_pk_add_f32 v[36:37], v[40:41], v[36:37] neg_lo:[0,1] neg_hi:[0,1]
	s_lshl_b32 s94, s0, 1
	v_pk_fma_f32 v[40:41], v[24:25], v[36:37], v[102:103] neg_lo:[0,0,1] neg_hi:[0,0,1]
	v_pk_fma_f32 v[36:37], v[72:73], v[80:81], v[36:37]
	s_mov_b32 s0, 0x3e800000
	v_pk_add_f32 v[4:5], v[36:37], v[4:5] neg_lo:[0,1] neg_hi:[0,1]
	global_store_dword v[44:45], v62, off nt
	v_pk_fma_f32 v[36:37], v[4:5], s[0:1], v[104:105] op_sel_hi:[1,0,1] neg_lo:[0,0,1] neg_hi:[0,0,1]
	v_readlane_b32 s1, v252, 36
	v_cvt_pk_bf16_f32 v44, v40, v41
	v_lshl_add_u64 v[40:41], v[26:27], 0, s[94:95]
	s_lshl_b32 s94, s1, 1
	v_pk_fma_f32 v[4:5], v[70:71], v[82:83], v[4:5]
	global_store_dword v[40:41], v44, off nt
	v_cvt_pk_bf16_f32 v40, v36, v37
	v_lshl_add_u64 v[36:37], v[26:27], 0, s[94:95]
	v_pk_fma_f32 v[4:5], v[64:65], v[74:75], v[4:5] neg_lo:[1,0,0] neg_hi:[1,0,0]
	global_store_dword v[36:37], v40, off nt
	v_pk_fma_f32 v[36:37], v[4:5], s[0:1], v[106:107] op_sel_hi:[1,0,1] neg_lo:[0,0,1] neg_hi:[0,0,1]
	v_readlane_b32 s1, v252, 39
	s_lshl_b32 s94, s1, 1
	v_pk_fma_f32 v[4:5], v[108:109], v[84:85], v[4:5]
	v_cvt_pk_bf16_f32 v40, v36, v37
	v_lshl_add_u64 v[36:37], v[26:27], 0, s[94:95]
	v_pk_fma_f32 v[4:5], v[66:67], v[76:77], v[4:5] neg_lo:[1,0,0] neg_hi:[1,0,0]
	global_store_dword v[36:37], v40, off nt
	v_pk_fma_f32 v[36:37], v[4:5], s[0:1], v[110:111] op_sel_hi:[1,0,1] neg_lo:[0,0,1] neg_hi:[0,0,1]
	v_readlane_b32 s1, v252, 42
	s_lshl_b32 s94, s1, 1
	v_pk_fma_f32 v[4:5], v[112:113], v[86:87], v[4:5]
	v_cvt_pk_bf16_f32 v40, v36, v37
	v_lshl_add_u64 v[36:37], v[26:27], 0, s[94:95]
	v_pk_fma_f32 v[4:5], v[68:69], v[78:79], v[4:5] neg_lo:[1,0,0] neg_hi:[1,0,0]
	global_store_dword v[36:37], v40, off nt
	v_pk_fma_f32 v[36:37], v[4:5], s[0:1], v[114:115] op_sel_hi:[1,0,1] neg_lo:[0,0,1] neg_hi:[0,0,1]
	v_readlane_b32 s1, v252, 45
	s_lshl_b32 s94, s1, 1
	v_pk_fma_f32 v[4:5], v[116:117], v[88:89], v[4:5]
	v_cvt_pk_bf16_f32 v40, v36, v37
	v_lshl_add_u64 v[36:37], v[26:27], 0, s[94:95]
	v_pk_fma_f32 v[4:5], v[72:73], v[80:81], v[4:5] neg_lo:[1,0,0] neg_hi:[1,0,0]
	global_store_dword v[36:37], v40, off nt
	v_pk_fma_f32 v[36:37], v[4:5], s[0:1], v[118:119] op_sel_hi:[1,0,1] neg_lo:[0,0,1] neg_hi:[0,0,1]
	v_readlane_b32 s1, v252, 47
	s_lshl_b32 s94, s1, 1
	v_pk_fma_f32 v[4:5], v[120:121], v[90:91], v[4:5]
	v_cvt_pk_bf16_f32 v40, v36, v37
	v_lshl_add_u64 v[36:37], v[26:27], 0, s[94:95]
	v_pk_fma_f32 v[4:5], v[70:71], v[82:83], v[4:5] neg_lo:[1,0,0] neg_hi:[1,0,0]
	global_store_dword v[36:37], v40, off nt
	v_pk_fma_f32 v[36:37], v[4:5], s[0:1], v[122:123] op_sel_hi:[1,0,1] neg_lo:[0,0,1] neg_hi:[0,0,1]
	v_readlane_b32 s1, v252, 48
	s_lshl_b32 s94, s1, 1
	v_pk_fma_f32 v[4:5], v[54:55], v[92:93], v[4:5]
	v_cvt_pk_bf16_f32 v40, v36, v37
	v_lshl_add_u64 v[36:37], v[26:27], 0, s[94:95]
	v_pk_fma_f32 v[4:5], v[108:109], v[84:85], v[4:5] neg_lo:[1,0,0] neg_hi:[1,0,0]
	global_store_dword v[36:37], v40, off nt
	v_pk_fma_f32 v[36:37], v[4:5], s[0:1], v[124:125] op_sel_hi:[1,0,1] neg_lo:[0,0,1] neg_hi:[0,0,1]
	v_readlane_b32 s1, v252, 49
	s_lshl_b32 s94, s1, 1
	v_pk_fma_f32 v[4:5], v[126:127], v[94:95], v[4:5]
	v_cvt_pk_bf16_f32 v40, v36, v37
	v_lshl_add_u64 v[36:37], v[26:27], 0, s[94:95]
	v_pk_fma_f32 v[4:5], v[112:113], v[86:87], v[4:5] neg_lo:[1,0,0] neg_hi:[1,0,0]
	global_store_dword v[36:37], v40, off nt
	v_pk_fma_f32 v[36:37], v[4:5], s[0:1], v[128:129] op_sel_hi:[1,0,1] neg_lo:[0,0,1] neg_hi:[0,0,1]
	v_readlane_b32 s1, v252, 50
	s_lshl_b32 s94, s1, 1
	v_pk_fma_f32 v[4:5], v[56:57], v[96:97], v[4:5]
	v_cvt_pk_bf16_f32 v40, v36, v37
	v_lshl_add_u64 v[36:37], v[26:27], 0, s[94:95]
	v_pk_fma_f32 v[4:5], v[116:117], v[88:89], v[4:5] neg_lo:[1,0,0] neg_hi:[1,0,0]
	global_store_dword v[36:37], v40, off nt
	v_pk_fma_f32 v[36:37], v[4:5], s[0:1], v[130:131] op_sel_hi:[1,0,1] neg_lo:[0,0,1] neg_hi:[0,0,1]
	v_readlane_b32 s1, v252, 53
	s_lshl_b32 s94, s1, 1
	v_pk_fma_f32 v[4:5], v[52:53], v[42:43], v[4:5]
	v_cvt_pk_bf16_f32 v40, v36, v37
	v_lshl_add_u64 v[36:37], v[26:27], 0, s[94:95]
	v_pk_fma_f32 v[4:5], v[120:121], v[90:91], v[4:5] neg_lo:[1,0,0] neg_hi:[1,0,0]
	global_store_dword v[36:37], v40, off nt
	v_pk_fma_f32 v[36:37], v[4:5], s[0:1], v[132:133] op_sel_hi:[1,0,1] neg_lo:[0,0,1] neg_hi:[0,0,1]
	v_readlane_b32 s1, v252, 58
	s_lshl_b32 s94, s1, 1
	v_pk_fma_f32 v[4:5], v[50:51], v[38:39], v[4:5]
	v_cvt_pk_bf16_f32 v40, v36, v37
	v_lshl_add_u64 v[36:37], v[26:27], 0, s[94:95]
	v_pk_fma_f32 v[4:5], v[54:55], v[92:93], v[4:5] neg_lo:[1,0,0] neg_hi:[1,0,0]
	global_store_dword v[36:37], v40, off nt
	v_pk_fma_f32 v[36:37], v[4:5], s[0:1], v[58:59] op_sel_hi:[1,0,1] neg_lo:[0,0,1] neg_hi:[0,0,1]
	v_readlane_b32 s1, v252, 61
	s_lshl_b32 s94, s1, 1
	v_pk_fma_f32 v[4:5], v[48:49], v[34:35], v[4:5]
	v_cvt_pk_bf16_f32 v40, v36, v37
	v_lshl_add_u64 v[36:37], v[26:27], 0, s[94:95]
	v_pk_fma_f32 v[4:5], v[126:127], v[94:95], v[4:5] neg_lo:[1,0,0] neg_hi:[1,0,0]
	global_store_dword v[36:37], v40, off nt
	v_pk_fma_f32 v[36:37], v[4:5], s[0:1], v[134:135] op_sel_hi:[1,0,1] neg_lo:[0,0,1] neg_hi:[0,0,1]
	v_readlane_b32 s1, v253, 0
	v_pk_fma_f32 v[4:5], v[46:47], v[2:3], v[4:5]
	s_lshl_b32 s94, s1, 1
	v_pk_fma_f32 v[76:77], v[56:57], v[96:97], v[4:5] neg_lo:[1,0,0] neg_hi:[1,0,0]
	v_cvt_pk_bf16_f32 v40, v36, v37
	v_lshl_add_u64 v[36:37], v[26:27], 0, s[94:95]
	v_pk_fma_f32 v[4:5], v[76:77], s[0:1], v[60:61] op_sel_hi:[1,0,1] neg_lo:[0,0,1] neg_hi:[0,0,1]
	global_store_dword v[36:37], v40, off nt
	v_cvt_pk_bf16_f32 v36, v4, v5
	v_lshl_add_u64 v[4:5], v[30:31], 0, s[2:3]
	v_readlane_b32 s2, v252, 1
	v_readlane_b32 s3, v252, 2
	flat_load_dword v37, v[4:5]
	v_readlane_b32 s1, v253, 3
	v_lshl_add_u64 v[4:5], v[30:31], 0, s[2:3]
	v_readlane_b32 s2, v252, 7
	v_readlane_b32 s3, v252, 8
	flat_load_dword v40, v[4:5]
	s_lshl_b32 s94, s1, 1
	v_lshl_add_u64 v[4:5], v[30:31], 0, s[2:3]
	v_readlane_b32 s2, v252, 11
	v_readlane_b32 s3, v252, 12
	flat_load_dword v41, v[4:5]
	s_waitcnt vmcnt(0) lgkmcnt(0)
	v_lshlrev_b32_e32 v78, 16, v37
	v_lshl_add_u64 v[4:5], v[30:31], 0, s[2:3]
	v_readlane_b32 s2, v252, 15
	v_readlane_b32 s3, v252, 16
	flat_load_dword v44, v[4:5]
	v_and_b32_e32 v79, 0xffff0000, v37
	v_lshl_add_u64 v[4:5], v[30:31], 0, s[2:3]
	v_readlane_b32 s2, v252, 19
	v_readlane_b32 s3, v252, 20
	flat_load_dword v45, v[4:5]
	v_lshlrev_b32_e32 v80, 16, v40
	v_lshl_add_u64 v[4:5], v[30:31], 0, s[2:3]
	v_readlane_b32 s2, v254, 31
	v_readlane_b32 s3, v254, 32
	flat_load_dword v54, v[4:5]
	v_and_b32_e32 v81, 0xffff0000, v40
	v_lshl_add_u64 v[4:5], v[30:31], 0, s[2:3]
	v_readlane_b32 s2, v254, 35
	v_readlane_b32 s3, v254, 36
	flat_load_dword v55, v[4:5]
	v_lshlrev_b32_e32 v82, 16, v41
	v_lshl_add_u64 v[4:5], v[30:31], 0, s[2:3]
	v_readlane_b32 s2, v253, 43
	v_readlane_b32 s3, v253, 44
	flat_load_dword v56, v[4:5]
	v_and_b32_e32 v83, 0xffff0000, v41
	v_lshl_add_u64 v[4:5], v[30:31], 0, s[2:3]
	v_readlane_b32 s2, v254, 45
	v_readlane_b32 s3, v254, 46
	flat_load_dword v57, v[4:5]
	s_waitcnt vmcnt(0) lgkmcnt(0)
	v_lshlrev_b32_e32 v84, 16, v44
	v_lshl_add_u64 v[4:5], v[30:31], 0, s[2:3]
	v_readlane_b32 s2, v254, 39
	v_readlane_b32 s3, v254, 40
	flat_load_dword v58, v[4:5]
	v_and_b32_e32 v85, 0xffff0000, v44
	v_lshl_add_u64 v[4:5], v[30:31], 0, s[2:3]
	v_readlane_b32 s2, v254, 43
	v_readlane_b32 s3, v254, 44
	flat_load_dword v59, v[4:5]
	v_lshlrev_b32_e32 v88, 16, v54
	v_lshl_add_u64 v[4:5], v[30:31], 0, s[2:3]
	v_readlane_b32 s2, v254, 47
	v_readlane_b32 s3, v254, 48
	flat_load_dword v60, v[4:5]
	v_and_b32_e32 v89, 0xffff0000, v54
	v_lshl_add_u64 v[4:5], v[30:31], 0, s[2:3]
	v_readlane_b32 s2, v251, 63
	v_readlane_b32 s3, v252, 0
	flat_load_dword v61, v[4:5]
	v_lshlrev_b32_e32 v90, 16, v55
	v_lshl_add_u64 v[4:5], v[30:31], 0, s[2:3]
	v_readlane_b32 s2, v253, 45
	v_readlane_b32 s3, v253, 46
	flat_load_dword v68, v[4:5]
	v_and_b32_e32 v91, 0xffff0000, v55
	v_lshl_add_u64 v[4:5], v[30:31], 0, s[2:3]
	v_readlane_b32 s2, v251, 41
	v_readlane_b32 s3, v251, 42
	flat_load_dword v69, v[4:5]
	v_lshlrev_b32_e32 v92, 16, v56
	v_lshl_add_u64 v[4:5], v[30:31], 0, s[2:3]
	flat_load_dword v70, v[4:5]
	v_and_b32_e32 v93, 0xffff0000, v56
	v_lshlrev_b32_e32 v94, 16, v57
	v_and_b32_e32 v95, 0xffff0000, v57
	ds_read_b128 v[54:57], v0 offset:64
	v_lshl_add_u64 v[4:5], v[26:27], 0, s[94:95]
	global_store_dword v[4:5], v36, off nt
	v_lshlrev_b32_e32 v86, 16, v45
	v_and_b32_e32 v87, 0xffff0000, v45
	s_waitcnt lgkmcnt(0)
	v_pk_mul_f32 v[96:97], v[28:29], v[54:55] op_sel_hi:[1,0]
	v_pk_mul_f32 v[100:101], v[28:29], v[54:55] op_sel:[0,1]
	v_pk_fma_f32 v[76:77], v[96:97], v[78:79], v[76:77]
	v_pk_mul_f32 v[98:99], v[96:97], v[78:79]
	v_pk_fma_f32 v[42:43], v[52:53], v[42:43], v[76:77] neg_lo:[1,0,0] neg_hi:[1,0,0]
	v_pk_mul_f32 v[102:103], v[100:101], v[80:81]
	v_pk_fma_f32 v[52:53], v[42:43], s[0:1], v[98:99] op_sel_hi:[1,0,1] neg_lo:[0,0,1] neg_hi:[0,0,1]
	v_pk_fma_f32 v[42:43], v[100:101], v[80:81], v[42:43]
	v_pk_mul_f32 v[104:105], v[28:29], v[56:57] op_sel_hi:[1,0]
	v_readlane_b32 s1, v253, 6
	v_pk_fma_f32 v[38:39], v[50:51], v[38:39], v[42:43] neg_lo:[1,0,0] neg_hi:[1,0,0]
	v_mov_b32_e32 v54, v57
	v_pk_fma_f32 v[42:43], v[38:39], s[0:1], v[102:103] op_sel_hi:[1,0,1] neg_lo:[0,0,1] neg_hi:[0,0,1]
	v_pk_fma_f32 v[38:39], v[104:105], v[82:83], v[38:39]
	v_pk_mul_f32 v[106:107], v[104:105], v[82:83]
	v_pk_mul_f32 v[108:109], v[28:29], v[54:55] op_sel_hi:[1,0]
	s_lshl_b32 s94, s1, 1
	v_readlane_b32 s1, v253, 9
	v_pk_fma_f32 v[34:35], v[48:49], v[34:35], v[38:39] neg_lo:[1,0,0] neg_hi:[1,0,0]
	v_pk_mul_f32 v[110:111], v[108:109], v[84:85]
	v_pk_fma_f32 v[38:39], v[34:35], s[0:1], v[106:107] op_sel_hi:[1,0,1] neg_lo:[0,0,1] neg_hi:[0,0,1]
	v_pk_fma_f32 v[34:35], v[108:109], v[84:85], v[34:35]
	v_readlane_b32 s2, v251, 59
	v_pk_fma_f32 v[2:3], v[46:47], v[2:3], v[34:35] neg_lo:[1,0,0] neg_hi:[1,0,0]
	v_readlane_b32 s3, v251, 60
	s_waitcnt vmcnt(0)
	v_lshlrev_b32_e32 v66, 16, v58
	v_and_b32_e32 v67, 0xffff0000, v58
	v_lshlrev_b32_e32 v64, 16, v59
	v_and_b32_e32 v65, 0xffff0000, v59
	v_lshlrev_b32_e32 v62, 16, v60
	v_and_b32_e32 v63, 0xffff0000, v60
	v_lshlrev_b32_e32 v44, 16, v61
	v_and_b32_e32 v45, 0xffff0000, v61
	v_lshlrev_b32_e32 v40, 16, v68
	v_and_b32_e32 v41, 0xffff0000, v68
	v_lshlrev_b32_e32 v36, 16, v69
	v_and_b32_e32 v37, 0xffff0000, v69
	v_lshlrev_b32_e32 v4, 16, v70
	v_and_b32_e32 v5, 0xffff0000, v70
	ds_read_b128 v[58:61], v0 offset:80
	ds_read_b128 v[68:71], v0 offset:96
	ds_read_b128 v[72:75], v0 offset:112
	v_cvt_pk_bf16_f32 v76, v52, v53
	v_lshl_add_u64 v[52:53], v[26:27], 0, s[94:95]
	s_lshl_b32 s94, s1, 1
	v_readlane_b32 s1, v253, 12
	s_waitcnt lgkmcnt(2)
	v_pk_mul_f32 v[112:113], v[28:29], v[58:59] op_sel_hi:[1,0]
	global_store_dword v[52:53], v76, off nt
	v_cvt_pk_bf16_f32 v50, v42, v43
	v_lshl_add_u64 v[42:43], v[26:27], 0, s[94:95]
	s_lshl_b32 s94, s1, 1
	v_pk_fma_f32 v[34:35], v[2:3], s[0:1], v[110:111] op_sel_hi:[1,0,1] neg_lo:[0,0,1] neg_hi:[0,0,1]
	v_readlane_b32 s1, v251, 37
	global_store_dword v[42:43], v50, off nt
	v_cvt_pk_bf16_f32 v42, v38, v39
	v_lshl_add_u64 v[38:39], v[26:27], 0, s[94:95]
	s_lshl_b32 s94, s1, 1
	v_pk_fma_f32 v[2:3], v[112:113], v[86:87], v[2:3]
	v_pk_mul_f32 v[114:115], v[112:113], v[86:87]
	global_store_dword v[38:39], v42, off nt
	v_cvt_pk_bf16_f32 v38, v34, v35
	v_lshl_add_u64 v[34:35], v[26:27], 0, s[94:95]
	v_pk_fma_f32 v[2:3], v[96:97], v[78:79], v[2:3] neg_lo:[1,0,0] neg_hi:[1,0,0]
	v_pk_mul_f32 v[116:117], v[28:29], v[58:59] op_sel:[0,1]
	global_store_dword v[34:35], v38, off nt
	v_pk_fma_f32 v[34:35], v[2:3], s[0:1], v[114:115] op_sel_hi:[1,0,1] neg_lo:[0,0,1] neg_hi:[0,0,1]
	v_readlane_b32 s1, v253, 15
	s_lshl_b32 s94, s1, 1
	v_pk_fma_f32 v[2:3], v[116:117], v[88:89], v[2:3]
	v_pk_mul_f32 v[118:119], v[116:117], v[88:89]
	v_cvt_pk_bf16_f32 v38, v34, v35
	v_lshl_add_u64 v[34:35], v[26:27], 0, s[94:95]
	v_pk_fma_f32 v[2:3], v[100:101], v[80:81], v[2:3] neg_lo:[1,0,0] neg_hi:[1,0,0]
	v_pk_mul_f32 v[120:121], v[28:29], v[60:61] op_sel_hi:[1,0]
	global_store_dword v[34:35], v38, off nt
	v_pk_fma_f32 v[34:35], v[2:3], s[0:1], v[118:119] op_sel_hi:[1,0,1] neg_lo:[0,0,1] neg_hi:[0,0,1]
	v_readlane_b32 s1, v253, 16
	s_lshl_b32 s94, s1, 1
	v_pk_fma_f32 v[2:3], v[120:121], v[90:91], v[2:3]
	v_pk_mul_f32 v[122:123], v[120:121], v[90:91]
	v_mov_b32_e32 v54, v61
	v_cvt_pk_bf16_f32 v38, v34, v35
	v_lshl_add_u64 v[34:35], v[26:27], 0, s[94:95]
	v_pk_fma_f32 v[2:3], v[104:105], v[82:83], v[2:3] neg_lo:[1,0,0] neg_hi:[1,0,0]
	v_pk_mul_f32 v[124:125], v[28:29], v[54:55] op_sel_hi:[1,0]
	global_store_dword v[34:35], v38, off nt
	v_pk_fma_f32 v[34:35], v[2:3], s[0:1], v[122:123] op_sel_hi:[1,0,1] neg_lo:[0,0,1] neg_hi:[0,0,1]
	v_readlane_b32 s1, v254, 1
	s_lshl_b32 s94, s1, 1
	v_pk_fma_f32 v[2:3], v[124:125], v[92:93], v[2:3]
	v_pk_mul_f32 v[126:127], v[124:125], v[92:93]
	v_cvt_pk_bf16_f32 v38, v34, v35
	v_lshl_add_u64 v[34:35], v[26:27], 0, s[94:95]
	v_pk_fma_f32 v[2:3], v[108:109], v[84:85], v[2:3] neg_lo:[1,0,0] neg_hi:[1,0,0]
	s_waitcnt lgkmcnt(1)
	v_pk_mul_f32 v[128:129], v[28:29], v[68:69] op_sel_hi:[1,0]
	global_store_dword v[34:35], v38, off nt
	v_pk_fma_f32 v[34:35], v[2:3], s[0:1], v[126:127] op_sel_hi:[1,0,1] neg_lo:[0,0,1] neg_hi:[0,0,1]
	v_readlane_b32 s1, v254, 5
	s_lshl_b32 s94, s1, 1
	v_pk_fma_f32 v[2:3], v[128:129], v[94:95], v[2:3]
	v_pk_mul_f32 v[130:131], v[128:129], v[94:95]
	v_cvt_pk_bf16_f32 v38, v34, v35
	v_lshl_add_u64 v[34:35], v[26:27], 0, s[94:95]
	v_pk_fma_f32 v[2:3], v[112:113], v[86:87], v[2:3] neg_lo:[1,0,0] neg_hi:[1,0,0]
	v_pk_mul_f32 v[68:69], v[28:29], v[68:69] op_sel:[0,1]
	global_store_dword v[34:35], v38, off nt
	v_pk_fma_f32 v[34:35], v[2:3], s[0:1], v[130:131] op_sel_hi:[1,0,1] neg_lo:[0,0,1] neg_hi:[0,0,1]
	v_readlane_b32 s1, v254, 3
	s_lshl_b32 s94, s1, 1
	v_pk_fma_f32 v[2:3], v[68:69], v[66:67], v[2:3]
	v_pk_mul_f32 v[132:133], v[68:69], v[66:67]
	v_cvt_pk_bf16_f32 v38, v34, v35
	v_lshl_add_u64 v[34:35], v[26:27], 0, s[94:95]
	v_pk_fma_f32 v[2:3], v[116:117], v[88:89], v[2:3] neg_lo:[1,0,0] neg_hi:[1,0,0]
	v_pk_mul_f32 v[134:135], v[28:29], v[70:71] op_sel_hi:[1,0]
	global_store_dword v[34:35], v38, off nt
	v_pk_fma_f32 v[34:35], v[2:3], s[0:1], v[132:133] op_sel_hi:[1,0,1] neg_lo:[0,0,1] neg_hi:[0,0,1]
	v_readlane_b32 s1, v253, 25
	s_lshl_b32 s94, s1, 1
	v_pk_fma_f32 v[2:3], v[134:135], v[64:65], v[2:3]
	v_pk_mul_f32 v[136:137], v[134:135], v[64:65]
	v_mov_b32_e32 v54, v71
	v_cvt_pk_bf16_f32 v38, v34, v35
	v_lshl_add_u64 v[34:35], v[26:27], 0, s[94:95]
	v_pk_fma_f32 v[2:3], v[120:121], v[90:91], v[2:3] neg_lo:[1,0,0] neg_hi:[1,0,0]
	v_pk_mul_f32 v[70:71], v[28:29], v[54:55] op_sel_hi:[1,0]
	global_store_dword v[34:35], v38, off nt
	v_pk_fma_f32 v[34:35], v[2:3], s[0:1], v[136:137] op_sel_hi:[1,0,1] neg_lo:[0,0,1] neg_hi:[0,0,1]
	v_readlane_b32 s1, v254, 49
	s_lshl_b32 s94, s1, 1
	v_pk_fma_f32 v[2:3], v[70:71], v[62:63], v[2:3]
	v_pk_mul_f32 v[138:139], v[70:71], v[62:63]
	v_cvt_pk_bf16_f32 v38, v34, v35
	v_lshl_add_u64 v[34:35], v[26:27], 0, s[94:95]
	v_pk_fma_f32 v[2:3], v[124:125], v[92:93], v[2:3] neg_lo:[1,0,0] neg_hi:[1,0,0]
	s_waitcnt lgkmcnt(0)
	v_pk_mul_f32 v[60:61], v[28:29], v[72:73] op_sel_hi:[1,0]
	global_store_dword v[34:35], v38, off nt
	v_pk_fma_f32 v[34:35], v[2:3], s[0:1], v[138:139] op_sel_hi:[1,0,1] neg_lo:[0,0,1] neg_hi:[0,0,1]
	v_readlane_b32 s1, v253, 19
	s_lshl_b32 s94, s1, 1
	v_pk_fma_f32 v[2:3], v[60:61], v[44:45], v[2:3]
	v_pk_mul_f32 v[140:141], v[60:61], v[44:45]
	v_cvt_pk_bf16_f32 v38, v34, v35
	v_lshl_add_u64 v[34:35], v[26:27], 0, s[94:95]
	v_pk_fma_f32 v[2:3], v[128:129], v[94:95], v[2:3] neg_lo:[1,0,0] neg_hi:[1,0,0]
	v_pk_mul_f32 v[58:59], v[28:29], v[72:73] op_sel:[0,1]
	global_store_dword v[34:35], v38, off nt
	v_pk_fma_f32 v[34:35], v[2:3], s[0:1], v[140:141] op_sel_hi:[1,0,1] neg_lo:[0,0,1] neg_hi:[0,0,1]
	v_readlane_b32 s1, v253, 28
	s_lshl_b32 s94, s1, 1
	v_pk_fma_f32 v[2:3], v[58:59], v[40:41], v[2:3]
	v_pk_mul_f32 v[72:73], v[58:59], v[40:41]
	v_cvt_pk_bf16_f32 v38, v34, v35
	v_lshl_add_u64 v[34:35], v[26:27], 0, s[94:95]
	v_pk_fma_f32 v[2:3], v[68:69], v[66:67], v[2:3] neg_lo:[1,0,0] neg_hi:[1,0,0]
	v_pk_mul_f32 v[56:57], v[28:29], v[74:75] op_sel_hi:[1,0]
	global_store_dword v[34:35], v38, off nt
	v_pk_fma_f32 v[34:35], v[2:3], s[0:1], v[72:73] op_sel_hi:[1,0,1] neg_lo:[0,0,1] neg_hi:[0,0,1]
	v_readlane_b32 s1, v253, 24
	v_mov_b32_e32 v54, v75
	s_lshl_b32 s94, s1, 1
	v_pk_fma_f32 v[2:3], v[56:57], v[36:37], v[2:3]
	v_pk_mul_f32 v[142:143], v[56:57], v[36:37]
	v_pk_mul_f32 v[54:55], v[28:29], v[54:55] op_sel_hi:[1,0]
	v_cvt_pk_bf16_f32 v38, v34, v35
	v_lshl_add_u64 v[34:35], v[26:27], 0, s[94:95]
	v_pk_fma_f32 v[2:3], v[134:135], v[64:65], v[2:3] neg_lo:[1,0,0] neg_hi:[1,0,0]
	global_store_dword v[34:35], v38, off nt
	v_pk_fma_f32 v[34:35], v[2:3], s[0:1], v[142:143] op_sel_hi:[1,0,1] neg_lo:[0,0,1] neg_hi:[0,0,1]
	v_readlane_b32 s1, v253, 29
	v_pk_fma_f32 v[2:3], v[54:55], v[4:5], v[2:3]
	v_pk_mul_f32 v[74:75], v[54:55], v[4:5]
	s_lshl_b32 s94, s1, 1
	v_pk_fma_f32 v[76:77], v[70:71], v[62:63], v[2:3] neg_lo:[1,0,0] neg_hi:[1,0,0]
	v_cvt_pk_bf16_f32 v38, v34, v35
	v_lshl_add_u64 v[34:35], v[26:27], 0, s[94:95]
	v_pk_fma_f32 v[2:3], v[76:77], s[0:1], v[74:75] op_sel_hi:[1,0,1] neg_lo:[0,0,1] neg_hi:[0,0,1]
	global_store_dword v[34:35], v38, off nt
	v_cvt_pk_bf16_f32 v34, v2, v3
	v_lshl_add_u64 v[2:3], v[30:31], 0, s[2:3]
	v_readlane_b32 s2, v251, 61
	v_readlane_b32 s3, v251, 62
	flat_load_dword v35, v[2:3]
	v_readlane_b32 s1, v254, 27
	v_lshl_add_u64 v[2:3], v[30:31], 0, s[2:3]
	v_readlane_b32 s2, v251, 55
	flat_load_dword v38, v[2:3]
	v_lshl_add_u64 v[2:3], v[30:31], 0, s[62:63]
	v_readlane_b32 s3, v251, 56
	flat_load_dword v39, v[2:3]
	s_lshl_b32 s94, s1, 1
	v_lshl_add_u64 v[2:3], v[30:31], 0, s[2:3]
	v_readlane_b32 s2, v251, 57
	v_readlane_b32 s3, v251, 58
	flat_load_dword v42, v[2:3]
	s_waitcnt vmcnt(0) lgkmcnt(0)
	v_lshlrev_b32_e32 v74, 16, v35
	v_lshl_add_u64 v[2:3], v[30:31], 0, s[2:3]
	flat_load_dword v43, v[2:3]
	v_lshl_add_u64 v[2:3], v[30:31], 0, s[20:21]
	flat_load_dword v46, v[2:3]
	v_lshl_add_u64 v[2:3], v[30:31], 0, s[58:59]
	flat_load_dword v47, v[2:3]
	v_lshl_add_u64 v[2:3], v[30:31], 0, s[22:23]
	flat_load_dword v48, v[2:3]
	v_lshl_add_u64 v[2:3], v[30:31], 0, s[54:55]
	flat_load_dword v49, v[2:3]
	v_lshl_add_u64 v[2:3], v[30:31], 0, s[88:89]
	flat_load_dword v50, v[2:3]
	v_lshl_add_u64 v[2:3], v[30:31], 0, s[68:69]
	flat_load_dword v51, v[2:3]
	v_lshl_add_u64 v[2:3], v[30:31], 0, s[92:93]
	flat_load_dword v52, v[2:3]
	v_lshl_add_u64 v[2:3], v[30:31], 0, s[14:15]
	flat_load_dword v53, v[2:3]
	v_lshl_add_u64 v[2:3], v[30:31], 0, s[12:13]
	flat_load_dword v66, v[2:3]
	v_lshl_add_u64 v[2:3], v[30:31], 0, s[42:43]
	flat_load_dword v67, v[2:3]
	v_lshl_add_u64 v[2:3], v[30:31], 0, s[36:37]
	flat_load_dword v68, v[2:3]
	v_and_b32_e32 v75, 0xffff0000, v35
	v_lshlrev_b32_e32 v78, 16, v38
	v_and_b32_e32 v79, 0xffff0000, v38
	v_lshl_add_u64 v[2:3], v[26:27], 0, s[94:95]
	v_lshlrev_b32_e32 v80, 16, v39
	v_and_b32_e32 v81, 0xffff0000, v39
	global_store_dword v[2:3], v34, off nt
	v_lshlrev_b32_e32 v82, 16, v42
	v_and_b32_e32 v83, 0xffff0000, v42
	s_waitcnt vmcnt(0) lgkmcnt(0)
	v_lshlrev_b32_e32 v84, 16, v43
	v_and_b32_e32 v85, 0xffff0000, v43
	v_lshlrev_b32_e32 v86, 16, v46
	v_and_b32_e32 v87, 0xffff0000, v46
	v_lshlrev_b32_e32 v88, 16, v47
	v_and_b32_e32 v89, 0xffff0000, v47
	v_lshlrev_b32_e32 v90, 16, v48
	v_and_b32_e32 v91, 0xffff0000, v48
	v_lshlrev_b32_e32 v92, 16, v49
	v_and_b32_e32 v93, 0xffff0000, v49
	ds_read_b128 v[46:49], v0 offset:128
	v_lshlrev_b32_e32 v94, 16, v50
	v_and_b32_e32 v95, 0xffff0000, v50
	v_lshlrev_b32_e32 v64, 16, v51
	v_and_b32_e32 v65, 0xffff0000, v51
	s_waitcnt lgkmcnt(0)
	v_pk_mul_f32 v[96:97], v[28:29], v[46:47] op_sel_hi:[1,0]
	v_pk_mul_f32 v[100:101], v[28:29], v[46:47] op_sel:[0,1]
	v_pk_fma_f32 v[76:77], v[96:97], v[74:75], v[76:77]
	v_pk_mul_f32 v[98:99], v[96:97], v[74:75]
	v_pk_fma_f32 v[44:45], v[60:61], v[44:45], v[76:77] neg_lo:[1,0,0] neg_hi:[1,0,0]
	v_pk_mul_f32 v[102:103], v[100:101], v[78:79]
	v_pk_fma_f32 v[60:61], v[44:45], s[0:1], v[98:99] op_sel_hi:[1,0,1] neg_lo:[0,0,1] neg_hi:[0,0,1]
	v_pk_fma_f32 v[44:45], v[100:101], v[78:79], v[44:45]
	v_pk_mul_f32 v[104:105], v[28:29], v[48:49] op_sel_hi:[1,0]
	v_readlane_b32 s1, v254, 25
	v_pk_fma_f32 v[40:41], v[58:59], v[40:41], v[44:45] neg_lo:[1,0,0] neg_hi:[1,0,0]
	v_mov_b32_e32 v46, v49
	v_pk_fma_f32 v[44:45], v[40:41], s[0:1], v[102:103] op_sel_hi:[1,0,1] neg_lo:[0,0,1] neg_hi:[0,0,1]
	v_pk_fma_f32 v[40:41], v[104:105], v[80:81], v[40:41]
	v_lshlrev_b32_e32 v62, 16, v52
	v_and_b32_e32 v63, 0xffff0000, v52
	v_lshlrev_b32_e32 v42, 16, v53
	v_and_b32_e32 v43, 0xffff0000, v53
	v_lshlrev_b32_e32 v38, 16, v66
	v_and_b32_e32 v39, 0xffff0000, v66
	v_lshlrev_b32_e32 v34, 16, v67
	v_and_b32_e32 v35, 0xffff0000, v67
	v_lshlrev_b32_e32 v2, 16, v68
	v_and_b32_e32 v3, 0xffff0000, v68
	ds_read_b128 v[50:53], v0 offset:144
	ds_read_b128 v[66:69], v0 offset:160
	ds_read_b128 v[70:73], v0 offset:176
	v_pk_mul_f32 v[106:107], v[104:105], v[80:81]
	v_pk_mul_f32 v[108:109], v[28:29], v[46:47] op_sel_hi:[1,0]
	s_lshl_b32 s94, s1, 1
	v_readlane_b32 s1, v253, 33
	v_pk_fma_f32 v[36:37], v[56:57], v[36:37], v[40:41] neg_lo:[1,0,0] neg_hi:[1,0,0]
	v_pk_mul_f32 v[110:111], v[108:109], v[82:83]
	v_pk_fma_f32 v[40:41], v[36:37], s[0:1], v[106:107] op_sel_hi:[1,0,1] neg_lo:[0,0,1] neg_hi:[0,0,1]
	v_pk_fma_f32 v[36:37], v[108:109], v[82:83], v[36:37]
	v_cvt_pk_bf16_f32 v76, v60, v61
	v_lshl_add_u64 v[60:61], v[26:27], 0, s[94:95]
	s_lshl_b32 s94, s1, 1
	v_readlane_b32 s1, v251, 53
	v_pk_fma_f32 v[4:5], v[54:55], v[4:5], v[36:37] neg_lo:[1,0,0] neg_hi:[1,0,0]
	s_waitcnt lgkmcnt(2)
	v_pk_mul_f32 v[112:113], v[28:29], v[50:51] op_sel_hi:[1,0]
	global_store_dword v[60:61], v76, off nt
	v_cvt_pk_bf16_f32 v58, v44, v45
	v_lshl_add_u64 v[44:45], v[26:27], 0, s[94:95]
	s_lshl_b32 s94, s1, 1
	v_pk_fma_f32 v[36:37], v[4:5], s[0:1], v[110:111] op_sel_hi:[1,0,1] neg_lo:[0,0,1] neg_hi:[0,0,1]
	v_readlane_b32 s1, v251, 51
	global_store_dword v[44:45], v58, off nt
	v_cvt_pk_bf16_f32 v44, v40, v41
	v_lshl_add_u64 v[40:41], v[26:27], 0, s[94:95]
	s_lshl_b32 s94, s1, 1
	v_pk_fma_f32 v[4:5], v[112:113], v[84:85], v[4:5]
	v_pk_mul_f32 v[114:115], v[112:113], v[84:85]
	global_store_dword v[40:41], v44, off nt
	v_cvt_pk_bf16_f32 v40, v36, v37
	v_lshl_add_u64 v[36:37], v[26:27], 0, s[94:95]
	v_pk_fma_f32 v[4:5], v[96:97], v[74:75], v[4:5] neg_lo:[1,0,0] neg_hi:[1,0,0]
	v_pk_mul_f32 v[116:117], v[28:29], v[50:51] op_sel:[0,1]
	global_store_dword v[36:37], v40, off nt
	v_pk_fma_f32 v[36:37], v[4:5], s[0:1], v[114:115] op_sel_hi:[1,0,1] neg_lo:[0,0,1] neg_hi:[0,0,1]
	v_readlane_b32 s1, v253, 17
	s_lshl_b32 s94, s1, 1
	v_pk_fma_f32 v[4:5], v[116:117], v[86:87], v[4:5]
	v_pk_mul_f32 v[118:119], v[116:117], v[86:87]
	v_cvt_pk_bf16_f32 v40, v36, v37
	v_lshl_add_u64 v[36:37], v[26:27], 0, s[94:95]
	v_pk_fma_f32 v[4:5], v[100:101], v[78:79], v[4:5] neg_lo:[1,0,0] neg_hi:[1,0,0]
	v_pk_mul_f32 v[120:121], v[28:29], v[52:53] op_sel_hi:[1,0]
	global_store_dword v[36:37], v40, off nt
	v_pk_fma_f32 v[36:37], v[4:5], s[0:1], v[118:119] op_sel_hi:[1,0,1] neg_lo:[0,0,1] neg_hi:[0,0,1]
	v_readlane_b32 s1, v254, 11
	s_lshl_b32 s94, s1, 1
	v_pk_fma_f32 v[4:5], v[120:121], v[88:89], v[4:5]
	v_pk_mul_f32 v[122:123], v[120:121], v[88:89]
	v_mov_b32_e32 v46, v53
	v_cvt_pk_bf16_f32 v40, v36, v37
	v_lshl_add_u64 v[36:37], v[26:27], 0, s[94:95]
	v_pk_fma_f32 v[4:5], v[104:105], v[80:81], v[4:5] neg_lo:[1,0,0] neg_hi:[1,0,0]
	v_pk_mul_f32 v[124:125], v[28:29], v[46:47] op_sel_hi:[1,0]
	global_store_dword v[36:37], v40, off nt
	v_pk_fma_f32 v[36:37], v[4:5], s[0:1], v[122:123] op_sel_hi:[1,0,1] neg_lo:[0,0,1] neg_hi:[0,0,1]
	v_readlane_b32 s1, v253, 30
	s_lshl_b32 s94, s1, 1
	v_pk_fma_f32 v[4:5], v[124:125], v[90:91], v[4:5]
	v_pk_mul_f32 v[126:127], v[124:125], v[90:91]
	v_cvt_pk_bf16_f32 v40, v36, v37
	v_lshl_add_u64 v[36:37], v[26:27], 0, s[94:95]
	v_pk_fma_f32 v[4:5], v[108:109], v[82:83], v[4:5] neg_lo:[1,0,0] neg_hi:[1,0,0]
	s_waitcnt lgkmcnt(1)
	v_pk_mul_f32 v[128:129], v[28:29], v[66:67] op_sel_hi:[1,0]
	global_store_dword v[36:37], v40, off nt
	v_pk_fma_f32 v[36:37], v[4:5], s[0:1], v[126:127] op_sel_hi:[1,0,1] neg_lo:[0,0,1] neg_hi:[0,0,1]
	v_readlane_b32 s1, v254, 9
	s_lshl_b32 s94, s1, 1
	v_pk_fma_f32 v[4:5], v[128:129], v[92:93], v[4:5]
	v_pk_mul_f32 v[130:131], v[128:129], v[92:93]
	v_pk_mul_f32 v[66:67], v[28:29], v[66:67] op_sel:[0,1]
	v_cvt_pk_bf16_f32 v40, v36, v37
	v_lshl_add_u64 v[36:37], v[26:27], 0, s[94:95]
	v_pk_fma_f32 v[4:5], v[112:113], v[84:85], v[4:5] neg_lo:[1,0,0] neg_hi:[1,0,0]
	global_store_dword v[36:37], v40, off nt
	v_pk_fma_f32 v[36:37], v[4:5], s[0:1], v[130:131] op_sel_hi:[1,0,1] neg_lo:[0,0,1] neg_hi:[0,0,1]
	s_lshl_b32 s94, s73, 1
	v_pk_fma_f32 v[4:5], v[66:67], v[94:95], v[4:5]
	v_pk_mul_f32 v[132:133], v[66:67], v[94:95]
	v_pk_mul_f32 v[134:135], v[28:29], v[68:69] op_sel_hi:[1,0]
	v_cvt_pk_bf16_f32 v40, v36, v37
	v_lshl_add_u64 v[36:37], v[26:27], 0, s[94:95]
	v_pk_fma_f32 v[4:5], v[116:117], v[86:87], v[4:5] neg_lo:[1,0,0] neg_hi:[1,0,0]
	global_store_dword v[36:37], v40, off nt
	v_pk_fma_f32 v[36:37], v[4:5], s[0:1], v[132:133] op_sel_hi:[1,0,1] neg_lo:[0,0,1] neg_hi:[0,0,1]
	s_lshl_b32 s94, s64, 1
	v_pk_fma_f32 v[4:5], v[134:135], v[64:65], v[4:5]
	v_pk_mul_f32 v[136:137], v[134:135], v[64:65]
	v_mov_b32_e32 v46, v69
	v_cvt_pk_bf16_f32 v40, v36, v37
	v_lshl_add_u64 v[36:37], v[26:27], 0, s[94:95]
	v_pk_fma_f32 v[4:5], v[120:121], v[88:89], v[4:5] neg_lo:[1,0,0] neg_hi:[1,0,0]
	v_pk_mul_f32 v[68:69], v[28:29], v[46:47] op_sel_hi:[1,0]
	global_store_dword v[36:37], v40, off nt
	v_pk_fma_f32 v[36:37], v[4:5], s[0:1], v[136:137] op_sel_hi:[1,0,1] neg_lo:[0,0,1] neg_hi:[0,0,1]
	v_readlane_b32 s1, v253, 41
	s_lshl_b32 s94, s1, 1
	v_pk_fma_f32 v[4:5], v[68:69], v[62:63], v[4:5]
	v_pk_mul_f32 v[138:139], v[68:69], v[62:63]
	v_cvt_pk_bf16_f32 v40, v36, v37
	v_lshl_add_u64 v[36:37], v[26:27], 0, s[94:95]
	v_pk_fma_f32 v[4:5], v[124:125], v[90:91], v[4:5] neg_lo:[1,0,0] neg_hi:[1,0,0]
	s_waitcnt lgkmcnt(0)
	v_pk_mul_f32 v[52:53], v[28:29], v[70:71] op_sel_hi:[1,0]
	global_store_dword v[36:37], v40, off nt
	v_pk_fma_f32 v[36:37], v[4:5], s[0:1], v[138:139] op_sel_hi:[1,0,1] neg_lo:[0,0,1] neg_hi:[0,0,1]
	v_readlane_b32 s1, v253, 36
	s_lshl_b32 s94, s1, 1
	v_pk_fma_f32 v[4:5], v[52:53], v[42:43], v[4:5]
	v_pk_mul_f32 v[140:141], v[52:53], v[42:43]
	v_cvt_pk_bf16_f32 v40, v36, v37
	v_lshl_add_u64 v[36:37], v[26:27], 0, s[94:95]
	v_pk_fma_f32 v[4:5], v[128:129], v[92:93], v[4:5] neg_lo:[1,0,0] neg_hi:[1,0,0]
	v_pk_mul_f32 v[50:51], v[28:29], v[70:71] op_sel:[0,1]
	global_store_dword v[36:37], v40, off nt
	v_pk_fma_f32 v[36:37], v[4:5], s[0:1], v[140:141] op_sel_hi:[1,0,1] neg_lo:[0,0,1] neg_hi:[0,0,1]
	v_readlane_b32 s1, v253, 37
	s_lshl_b32 s94, s1, 1
	v_pk_fma_f32 v[4:5], v[50:51], v[38:39], v[4:5]
	v_pk_mul_f32 v[70:71], v[50:51], v[38:39]
	v_cvt_pk_bf16_f32 v40, v36, v37
	v_lshl_add_u64 v[36:37], v[26:27], 0, s[94:95]
	v_pk_fma_f32 v[4:5], v[66:67], v[94:95], v[4:5] neg_lo:[1,0,0] neg_hi:[1,0,0]
	v_pk_mul_f32 v[48:49], v[28:29], v[72:73] op_sel_hi:[1,0]
	global_store_dword v[36:37], v40, off nt
	v_pk_fma_f32 v[36:37], v[4:5], s[0:1], v[70:71] op_sel_hi:[1,0,1] neg_lo:[0,0,1] neg_hi:[0,0,1]
	v_readlane_b32 s1, v254, 21
	v_mov_b32_e32 v46, v73
	s_lshl_b32 s94, s1, 1
	v_pk_fma_f32 v[4:5], v[48:49], v[34:35], v[4:5]
	v_pk_mul_f32 v[142:143], v[48:49], v[34:35]
	v_pk_mul_f32 v[46:47], v[28:29], v[46:47] op_sel_hi:[1,0]
	v_cvt_pk_bf16_f32 v40, v36, v37
	v_lshl_add_u64 v[36:37], v[26:27], 0, s[94:95]
	v_pk_fma_f32 v[4:5], v[134:135], v[64:65], v[4:5] neg_lo:[1,0,0] neg_hi:[1,0,0]
	global_store_dword v[36:37], v40, off nt
	v_pk_fma_f32 v[36:37], v[4:5], s[0:1], v[142:143] op_sel_hi:[1,0,1] neg_lo:[0,0,1] neg_hi:[0,0,1]
	v_readlane_b32 s1, v253, 38
	v_pk_fma_f32 v[4:5], v[46:47], v[2:3], v[4:5]
	v_pk_mul_f32 v[72:73], v[46:47], v[2:3]
	s_lshl_b32 s94, s1, 1
	v_pk_fma_f32 v[44:45], v[68:69], v[62:63], v[4:5] neg_lo:[1,0,0] neg_hi:[1,0,0]
	v_cvt_pk_bf16_f32 v40, v36, v37
	v_lshl_add_u64 v[36:37], v[26:27], 0, s[94:95]
	v_pk_fma_f32 v[4:5], v[44:45], s[0:1], v[72:73] op_sel_hi:[1,0,1] neg_lo:[0,0,1] neg_hi:[0,0,1]
	global_store_dword v[36:37], v40, off nt
	v_cvt_pk_bf16_f32 v36, v4, v5
	v_lshl_add_u64 v[4:5], v[30:31], 0, s[44:45]
	flat_load_dword v37, v[4:5]
	v_lshl_add_u64 v[4:5], v[30:31], 0, s[40:41]
	flat_load_dword v40, v[4:5]
	v_lshl_add_u64 v[4:5], v[30:31], 0, s[46:47]
	flat_load_dword v41, v[4:5]
	v_lshl_add_u64 v[4:5], v[30:31], 0, s[10:11]
	flat_load_dword v54, v[4:5]
	v_lshl_add_u64 v[4:5], v[30:31], 0, s[52:53]
	flat_load_dword v55, v[4:5]
	v_lshl_add_u64 v[4:5], v[30:31], 0, s[38:39]
	flat_load_dword v56, v[4:5]
	v_lshl_add_u64 v[4:5], v[30:31], 0, s[90:91]
	flat_load_dword v57, v[4:5]
	v_lshl_add_u64 v[4:5], v[30:31], 0, s[78:79]
	flat_load_dword v58, v[4:5]
	v_lshl_add_u64 v[4:5], v[30:31], 0, s[50:51]
	flat_load_dword v59, v[4:5]
	v_lshl_add_u64 v[4:5], v[30:31], 0, s[56:57]
	flat_load_dword v60, v[4:5]
	v_lshl_add_u64 v[4:5], v[30:31], 0, s[34:35]
	flat_load_dword v61, v[4:5]
	v_lshl_add_u64 v[4:5], v[30:31], 0, s[6:7]
	flat_load_dword v62, v[4:5]
	v_lshl_add_u64 v[4:5], v[30:31], 0, s[74:75]
	flat_load_dword v63, v[4:5]
	v_lshl_add_u64 v[4:5], v[30:31], 0, s[4:5]
	flat_load_dword v64, v[4:5]
	v_lshl_add_u64 v[4:5], v[30:31], 0, s[24:25]
	flat_load_dword v65, v[4:5]
	v_lshl_add_u64 v[4:5], v[30:31], 0, s[60:61]
	flat_load_dword v66, v[4:5]
	v_readlane_b32 s1, v254, 19
	s_lshl_b32 s94, s1, 1
	v_lshl_add_u64 v[4:5], v[26:27], 0, s[94:95]
	global_store_dword v[4:5], v36, off nt
	s_waitcnt vmcnt(0) lgkmcnt(0)
	v_lshlrev_b32_e32 v70, 16, v37
	v_and_b32_e32 v71, 0xffff0000, v37
	v_lshlrev_b32_e32 v72, 16, v40
	v_and_b32_e32 v73, 0xffff0000, v40
	v_lshlrev_b32_e32 v74, 16, v41
	v_and_b32_e32 v75, 0xffff0000, v41
	v_lshlrev_b32_e32 v76, 16, v54
	v_and_b32_e32 v77, 0xffff0000, v54
	v_lshlrev_b32_e32 v78, 16, v55
	v_and_b32_e32 v79, 0xffff0000, v55
	v_lshlrev_b32_e32 v80, 16, v56
	v_and_b32_e32 v81, 0xffff0000, v56
	v_lshlrev_b32_e32 v82, 16, v57
	v_and_b32_e32 v83, 0xffff0000, v57
	ds_read_b128 v[54:57], v0 offset:192
	v_lshlrev_b32_e32 v84, 16, v58
	v_and_b32_e32 v85, 0xffff0000, v58
	v_lshlrev_b32_e32 v86, 16, v59
	v_and_b32_e32 v87, 0xffff0000, v59
	s_waitcnt lgkmcnt(0)
	v_pk_mul_f32 v[96:97], v[28:29], v[54:55] op_sel_hi:[1,0]
	v_lshlrev_b32_e32 v88, 16, v60
	v_pk_fma_f32 v[44:45], v[96:97], v[70:71], v[44:45]
	v_and_b32_e32 v89, 0xffff0000, v60
	v_lshlrev_b32_e32 v40, 16, v61
	v_and_b32_e32 v41, 0xffff0000, v61
	v_lshlrev_b32_e32 v4, 16, v62
	v_and_b32_e32 v5, 0xffff0000, v62
	v_lshlrev_b32_e32 v90, 16, v63
	v_and_b32_e32 v91, 0xffff0000, v63
	v_lshlrev_b32_e32 v92, 16, v64
	v_and_b32_e32 v93, 0xffff0000, v64
	v_lshlrev_b32_e32 v94, 16, v65
	v_and_b32_e32 v95, 0xffff0000, v65
	v_lshlrev_b32_e32 v36, 16, v66
	v_and_b32_e32 v37, 0xffff0000, v66
	ds_read_b128 v[58:61], v0 offset:208
	ds_read_b128 v[62:65], v0 offset:224
	ds_read_b128 v[66:69], v0 offset:240
	v_pk_mul_f32 v[98:99], v[96:97], v[70:71]
	v_pk_mul_f32 v[54:55], v[28:29], v[54:55] op_sel:[0,1]
	v_pk_fma_f32 v[42:43], v[52:53], v[42:43], v[44:45] neg_lo:[1,0,0] neg_hi:[1,0,0]
	v_pk_mul_f32 v[100:101], v[54:55], v[72:73]
	v_pk_fma_f32 v[44:45], v[42:43], s[0:1], v[98:99] op_sel_hi:[1,0,1] neg_lo:[0,0,1] neg_hi:[0,0,1]
	v_pk_fma_f32 v[42:43], v[54:55], v[72:73], v[42:43]
	v_pk_mul_f32 v[102:103], v[28:29], v[56:57] op_sel_hi:[1,0]
	v_mov_b32_e32 v0, v57
	v_readlane_b32 s1, v254, 23
	v_pk_fma_f32 v[38:39], v[50:51], v[38:39], v[42:43] neg_lo:[1,0,0] neg_hi:[1,0,0]
	v_pk_mul_f32 v[56:57], v[28:29], v[0:1] op_sel_hi:[1,0]
	s_waitcnt lgkmcnt(2)
	v_mov_b32_e32 v0, v61
	v_pk_fma_f32 v[42:43], v[38:39], s[0:1], v[100:101] op_sel_hi:[1,0,1] neg_lo:[0,0,1] neg_hi:[0,0,1]
	v_pk_fma_f32 v[38:39], v[102:103], v[74:75], v[38:39]
	v_pk_mul_f32 v[104:105], v[102:103], v[74:75]
	v_pk_mul_f32 v[114:115], v[28:29], v[60:61] op_sel_hi:[1,0]
	v_pk_mul_f32 v[60:61], v[28:29], v[0:1] op_sel_hi:[1,0]
	s_waitcnt lgkmcnt(1)
	v_mov_b32_e32 v0, v65
	s_lshl_b32 s94, s1, 1
	v_readlane_b32 s1, v254, 33
	v_pk_fma_f32 v[34:35], v[48:49], v[34:35], v[38:39] neg_lo:[1,0,0] neg_hi:[1,0,0]
	v_pk_mul_f32 v[126:127], v[28:29], v[64:65] op_sel_hi:[1,0]
	v_pk_mul_f32 v[64:65], v[28:29], v[0:1] op_sel_hi:[1,0]
	s_waitcnt lgkmcnt(0)
	v_mov_b32_e32 v0, v69
	v_pk_fma_f32 v[38:39], v[34:35], s[0:1], v[104:105] op_sel_hi:[1,0,1] neg_lo:[0,0,1] neg_hi:[0,0,1]
	v_pk_fma_f32 v[34:35], v[56:57], v[76:77], v[34:35]
	v_pk_mul_f32 v[106:107], v[56:57], v[76:77]
	v_pk_mul_f32 v[138:139], v[28:29], v[68:69] op_sel_hi:[1,0]
	v_pk_mul_f32 v[68:69], v[28:29], v[0:1] op_sel_hi:[1,0]
	v_cvt_pk_bf16_f32 v0, v44, v45
	v_lshl_add_u64 v[44:45], v[26:27], 0, s[94:95]
	s_lshl_b32 s94, s1, 1
	v_readlane_b32 s1, v254, 29
	v_pk_fma_f32 v[2:3], v[46:47], v[2:3], v[34:35] neg_lo:[1,0,0] neg_hi:[1,0,0]
	v_pk_mul_f32 v[108:109], v[28:29], v[58:59] op_sel_hi:[1,0]
	global_store_dword v[44:45], v0, off nt
	v_cvt_pk_bf16_f32 v0, v42, v43
	v_lshl_add_u64 v[42:43], v[26:27], 0, s[94:95]
	s_lshl_b32 s94, s1, 1
	v_pk_fma_f32 v[34:35], v[2:3], s[0:1], v[106:107] op_sel_hi:[1,0,1] neg_lo:[0,0,1] neg_hi:[0,0,1]
	v_readlane_b32 s1, v253, 42
	global_store_dword v[42:43], v0, off nt
	v_cvt_pk_bf16_f32 v0, v38, v39
	v_lshl_add_u64 v[38:39], v[26:27], 0, s[94:95]
	s_lshl_b32 s94, s1, 1
	v_pk_fma_f32 v[2:3], v[108:109], v[78:79], v[2:3]
	v_pk_mul_f32 v[110:111], v[108:109], v[78:79]
	global_store_dword v[38:39], v0, off nt
	v_cvt_pk_bf16_f32 v0, v34, v35
	v_lshl_add_u64 v[34:35], v[26:27], 0, s[94:95]
	v_pk_fma_f32 v[2:3], v[96:97], v[70:71], v[2:3] neg_lo:[1,0,0] neg_hi:[1,0,0]
	v_pk_mul_f32 v[58:59], v[28:29], v[58:59] op_sel:[0,1]
	global_store_dword v[34:35], v0, off nt
	v_pk_fma_f32 v[34:35], v[2:3], s[0:1], v[110:111] op_sel_hi:[1,0,1] neg_lo:[0,0,1] neg_hi:[0,0,1]
	v_readlane_b32 s1, v254, 37
	s_lshl_b32 s94, s1, 1
	v_pk_fma_f32 v[2:3], v[58:59], v[80:81], v[2:3]
	v_pk_mul_f32 v[112:113], v[58:59], v[80:81]
	v_cvt_pk_bf16_f32 v0, v34, v35
	v_lshl_add_u64 v[34:35], v[26:27], 0, s[94:95]
	v_pk_fma_f32 v[2:3], v[54:55], v[72:73], v[2:3] neg_lo:[1,0,0] neg_hi:[1,0,0]
	global_store_dword v[34:35], v0, off nt
	v_pk_fma_f32 v[34:35], v[2:3], s[0:1], v[112:113] op_sel_hi:[1,0,1] neg_lo:[0,0,1] neg_hi:[0,0,1]
	s_lshl_b32 s94, s65, 1
	v_pk_fma_f32 v[2:3], v[114:115], v[82:83], v[2:3]
	v_pk_mul_f32 v[116:117], v[114:115], v[82:83]
	v_cvt_pk_bf16_f32 v0, v34, v35
	v_lshl_add_u64 v[34:35], v[26:27], 0, s[94:95]
	v_pk_fma_f32 v[2:3], v[102:103], v[74:75], v[2:3] neg_lo:[1,0,0] neg_hi:[1,0,0]
	global_store_dword v[34:35], v0, off nt
	v_pk_fma_f32 v[34:35], v[2:3], s[0:1], v[116:117] op_sel_hi:[1,0,1] neg_lo:[0,0,1] neg_hi:[0,0,1]
	s_lshl_b32 s94, s48, 1
	v_pk_fma_f32 v[2:3], v[60:61], v[84:85], v[2:3]
	v_pk_mul_f32 v[118:119], v[60:61], v[84:85]
	v_cvt_pk_bf16_f32 v0, v34, v35
	v_lshl_add_u64 v[34:35], v[26:27], 0, s[94:95]
	v_pk_fma_f32 v[2:3], v[56:57], v[76:77], v[2:3] neg_lo:[1,0,0] neg_hi:[1,0,0]
	v_pk_mul_f32 v[120:121], v[28:29], v[62:63] op_sel_hi:[1,0]
	global_store_dword v[34:35], v0, off nt
	v_pk_fma_f32 v[34:35], v[2:3], s[0:1], v[118:119] op_sel_hi:[1,0,1] neg_lo:[0,0,1] neg_hi:[0,0,1]
	v_readlane_b32 s1, v253, 18
	s_lshl_b32 s94, s1, 1
	v_pk_fma_f32 v[2:3], v[120:121], v[86:87], v[2:3]
	v_pk_mul_f32 v[122:123], v[120:121], v[86:87]
	v_cvt_pk_bf16_f32 v0, v34, v35
	v_lshl_add_u64 v[34:35], v[26:27], 0, s[94:95]
	v_pk_fma_f32 v[2:3], v[108:109], v[78:79], v[2:3] neg_lo:[1,0,0] neg_hi:[1,0,0]
	v_pk_mul_f32 v[62:63], v[28:29], v[62:63] op_sel:[0,1]
	global_store_dword v[34:35], v0, off nt
	v_pk_fma_f32 v[34:35], v[2:3], s[0:1], v[122:123] op_sel_hi:[1,0,1] neg_lo:[0,0,1] neg_hi:[0,0,1]
	v_readlane_b32 s1, v254, 41
	s_lshl_b32 s94, s1, 1
	v_pk_fma_f32 v[2:3], v[62:63], v[88:89], v[2:3]
	v_pk_mul_f32 v[124:125], v[62:63], v[88:89]
	v_cvt_pk_bf16_f32 v0, v34, v35
	v_lshl_add_u64 v[34:35], v[26:27], 0, s[94:95]
	v_pk_fma_f32 v[2:3], v[58:59], v[80:81], v[2:3] neg_lo:[1,0,0] neg_hi:[1,0,0]
	global_store_dword v[34:35], v0, off nt
	v_pk_fma_f32 v[34:35], v[2:3], s[0:1], v[124:125] op_sel_hi:[1,0,1] neg_lo:[0,0,1] neg_hi:[0,0,1]
	s_lshl_b32 s94, s49, 1
	v_pk_fma_f32 v[2:3], v[126:127], v[40:41], v[2:3]
	v_pk_mul_f32 v[128:129], v[126:127], v[40:41]
	v_cvt_pk_bf16_f32 v0, v34, v35
	v_lshl_add_u64 v[34:35], v[26:27], 0, s[94:95]
	v_pk_fma_f32 v[2:3], v[114:115], v[82:83], v[2:3] neg_lo:[1,0,0] neg_hi:[1,0,0]
	global_store_dword v[34:35], v0, off nt
	v_pk_fma_f32 v[34:35], v[2:3], s[0:1], v[128:129] op_sel_hi:[1,0,1] neg_lo:[0,0,1] neg_hi:[0,0,1]
	s_lshl_b32 s94, s86, 1
	v_pk_fma_f32 v[2:3], v[64:65], v[4:5], v[2:3]
	v_pk_mul_f32 v[130:131], v[64:65], v[4:5]
	v_pk_mul_f32 v[132:133], v[28:29], v[66:67] op_sel_hi:[1,0]
	v_cvt_pk_bf16_f32 v0, v34, v35
	v_lshl_add_u64 v[34:35], v[26:27], 0, s[94:95]
	v_pk_fma_f32 v[2:3], v[60:61], v[84:85], v[2:3] neg_lo:[1,0,0] neg_hi:[1,0,0]
	global_store_dword v[34:35], v0, off nt
	v_pk_fma_f32 v[34:35], v[2:3], s[0:1], v[130:131] op_sel_hi:[1,0,1] neg_lo:[0,0,1] neg_hi:[0,0,1]
	s_lshl_b32 s94, s67, 1
	v_pk_fma_f32 v[2:3], v[132:133], v[90:91], v[2:3]
	v_pk_mul_f32 v[134:135], v[132:133], v[90:91]
	v_cvt_pk_bf16_f32 v0, v34, v35
	v_lshl_add_u64 v[34:35], v[26:27], 0, s[94:95]
	v_pk_fma_f32 v[2:3], v[120:121], v[86:87], v[2:3] neg_lo:[1,0,0] neg_hi:[1,0,0]
	v_pk_mul_f32 v[66:67], v[28:29], v[66:67] op_sel:[0,1]
	global_store_dword v[34:35], v0, off nt
	v_pk_fma_f32 v[34:35], v[2:3], s[0:1], v[134:135] op_sel_hi:[1,0,1] neg_lo:[0,0,1] neg_hi:[0,0,1]
	v_readlane_b32 s1, v253, 63
	s_lshl_b32 s94, s1, 1
	v_pk_fma_f32 v[2:3], v[66:67], v[92:93], v[2:3]
	v_pk_mul_f32 v[136:137], v[66:67], v[92:93]
	v_cvt_pk_bf16_f32 v0, v34, v35
	v_lshl_add_u64 v[34:35], v[26:27], 0, s[94:95]
	v_pk_fma_f32 v[2:3], v[62:63], v[88:89], v[2:3] neg_lo:[1,0,0] neg_hi:[1,0,0]
	global_store_dword v[34:35], v0, off nt
	v_pk_fma_f32 v[34:35], v[2:3], s[0:1], v[136:137] op_sel_hi:[1,0,1] neg_lo:[0,0,1] neg_hi:[0,0,1]
	v_readlane_b32 s1, v253, 61
	s_lshl_b32 s94, s1, 1
	v_pk_fma_f32 v[2:3], v[138:139], v[94:95], v[2:3]
	v_pk_mul_f32 v[140:141], v[138:139], v[94:95]
	v_cvt_pk_bf16_f32 v0, v34, v35
	v_lshl_add_u64 v[34:35], v[26:27], 0, s[94:95]
	v_pk_fma_f32 v[2:3], v[126:127], v[40:41], v[2:3] neg_lo:[1,0,0] neg_hi:[1,0,0]
	global_store_dword v[34:35], v0, off nt
	v_pk_fma_f32 v[34:35], v[2:3], s[0:1], v[140:141] op_sel_hi:[1,0,1] neg_lo:[0,0,1] neg_hi:[0,0,1]
	s_lshl_b32 s94, s66, 1
	v_pk_fma_f32 v[2:3], v[68:69], v[36:37], v[2:3]
	v_pk_mul_f32 v[142:143], v[68:69], v[36:37]
	v_cvt_pk_bf16_f32 v0, v34, v35
	v_lshl_add_u64 v[34:35], v[26:27], 0, s[94:95]
	v_pk_fma_f32 v[2:3], v[64:65], v[4:5], v[2:3] neg_lo:[1,0,0] neg_hi:[1,0,0]
	global_store_dword v[34:35], v0, off nt
	v_pk_fma_f32 v[2:3], v[2:3], s[0:1], v[142:143] op_sel_hi:[1,0,1] neg_lo:[0,0,1] neg_hi:[0,0,1]
	s_nop 0
	v_cvt_pk_bf16_f32 v162, v2, v3

.LBB0_382:
	v_lshl_add_u64 v[94:95], v[2:3], 0, s[16:17]
	s_mov_b32 s0, 0x30900000
	v_add_co_u32_e32 v32, vcc, s0, v94
	s_mov_b32 s0, 0x30901000
	s_nop 0
	v_addc_co_u32_e32 v33, vcc, 0, v95, vcc
	flat_load_dword v184, v[32:33]
	v_add_co_u32_e32 v32, vcc, s0, v94
	s_mov_b32 s0, 0x30902000
	s_nop 0
	v_addc_co_u32_e32 v33, vcc, 0, v95, vcc
	s_mov_b32 s1, 0x3090d000
	s_add_i32 s28, s19, 1
	s_min_u32 s28, s28, 15
	s_add_i32 s28, s28, 1
	s_add_i32 s29, s19, 2
	s_add_i32 s76, s19, 3
	s_add_i32 s77, s19, 4
	s_add_i32 s26, s19, 5
	s_min_u32 s26, s26, 15
	s_add_i32 s26, s26, 1
	s_add_i32 s27, s19, 6
	s_add_i32 s82, s19, 7
	s_add_i32 s87, s19, 8
	s_add_i32 s72, s19, 9
	s_add_i32 s81, s19, 10
	s_add_i32 s70, s19, 11
	s_add_i32 s71, s19, 12
	s_nop 1
	flat_load_dword v185, v[32:33]
	v_add_co_u32_e32 v32, vcc, s0, v94
	s_mov_b32 s0, 0x30903000
	s_nop 0
	v_addc_co_u32_e32 v33, vcc, 0, v95, vcc
	s_nop 1
	flat_load_dword v186, v[32:33]
	v_add_co_u32_e32 v32, vcc, s0, v94
	s_mov_b32 s0, 0x30904000
	s_nop 0
	v_addc_co_u32_e32 v33, vcc, 0, v95, vcc
	s_nop 1
	flat_load_dword v187, v[32:33]
	v_add_co_u32_e32 v32, vcc, s0, v94
	s_mov_b32 s0, 0x30905000
	s_nop 0
	v_addc_co_u32_e32 v33, vcc, 0, v95, vcc
	s_nop 1
	flat_load_dword v188, v[32:33]
	v_add_co_u32_e32 v32, vcc, s0, v94
	s_mov_b32 s0, 0x30906000
	s_nop 0
	v_addc_co_u32_e32 v33, vcc, 0, v95, vcc
	s_nop 1
	flat_load_dword v189, v[32:33]
	v_add_co_u32_e32 v32, vcc, s0, v94
	s_mov_b32 s0, 0x30907000
	s_nop 0
	v_addc_co_u32_e32 v33, vcc, 0, v95, vcc
	s_nop 1
	flat_load_dword v190, v[32:33]
	v_add_co_u32_e32 v32, vcc, s0, v94
	s_mov_b32 s0, 0x30908000
	s_nop 0
	v_addc_co_u32_e32 v33, vcc, 0, v95, vcc
	s_nop 1
	flat_load_dword v191, v[32:33]
	v_add_co_u32_e32 v32, vcc, s0, v94
	s_mov_b32 s0, 0x30909000
	s_nop 0
	v_addc_co_u32_e32 v33, vcc, 0, v95, vcc
	s_nop 1
	flat_load_dword v192, v[32:33]
	v_add_co_u32_e32 v32, vcc, s0, v94
	s_mov_b32 s0, 0x3090a000
	s_nop 0
	v_addc_co_u32_e32 v33, vcc, 0, v95, vcc
	s_nop 1
	flat_load_dword v193, v[32:33]
	v_add_co_u32_e32 v32, vcc, s0, v94
	s_mov_b32 s0, 0x3090b000
	s_nop 0
	v_addc_co_u32_e32 v33, vcc, 0, v95, vcc
	s_nop 1
	flat_load_dword v194, v[32:33]
	v_add_co_u32_e32 v32, vcc, s0, v94
	s_mov_b32 s0, 0x3090c000
	s_nop 0
	v_addc_co_u32_e32 v33, vcc, 0, v95, vcc
	s_nop 1
	flat_load_dword v195, v[32:33]
	v_add_co_u32_e32 v32, vcc, s0, v94
	s_add_i32 s0, s19, 13
	s_nop 0
	v_addc_co_u32_e32 v33, vcc, 0, v95, vcc
	s_min_u32 s0, s0, 15
	s_add_i32 s0, s0, 1
	s_nop 1
	flat_load_dword v196, v[32:33]
	v_add_co_u32_e32 v32, vcc, s1, v94
	s_add_i32 s1, s19, 14
	s_nop 0
	v_addc_co_u32_e32 v33, vcc, 0, v95, vcc
	s_mov_b32 vcc_lo, 0x3090e000
	s_nop 1
	flat_load_dword v197, v[32:33]
	v_add_co_u32_e32 v32, vcc, vcc_lo, v94
	s_nop 1
	v_addc_co_u32_e32 v33, vcc, 0, v95, vcc
	flat_load_dword v198, v[32:33]
	s_mov_b32 vcc_lo, 0x3090f000
	v_add_co_u32_e32 v32, vcc, vcc_lo, v94
	s_nop 1
	v_addc_co_u32_e32 v33, vcc, 0, v95, vcc
	flat_load_dword v199, v[32:33]
	s_min_u32 vcc_lo, s19, 15
	s_add_i32 vcc_lo, vcc_lo, 1
	s_nop 1
	s_waitcnt vmcnt(0) lgkmcnt(0)
	v_lshlrev_b32_e32 v154, 16, v184
	v_and_b32_e32 v155, 0xffff0000, v184
	v_lshlrev_b32_e32 v142, 16, v185
	v_and_b32_e32 v143, 0xffff0000, v185
	v_lshlrev_b32_e32 v146, 16, v186
	v_and_b32_e32 v147, 0xffff0000, v186
	v_lshlrev_b32_e32 v138, 16, v187
	v_and_b32_e32 v139, 0xffff0000, v187
	v_lshlrev_b32_e32 v140, 16, v188
	v_and_b32_e32 v141, 0xffff0000, v188
	v_lshlrev_b32_e32 v130, 16, v189
	v_and_b32_e32 v131, 0xffff0000, v189
	v_lshlrev_b32_e32 v132, 16, v190
	v_and_b32_e32 v133, 0xffff0000, v190
	v_lshlrev_b32_e32 v120, 16, v191
	v_and_b32_e32 v121, 0xffff0000, v191
	v_lshlrev_b32_e32 v122, 16, v192
	v_and_b32_e32 v123, 0xffff0000, v192
	v_lshlrev_b32_e32 v114, 16, v193
	v_and_b32_e32 v115, 0xffff0000, v193
	v_lshlrev_b32_e32 v116, 16, v194
	v_and_b32_e32 v117, 0xffff0000, v194
	v_lshlrev_b32_e32 v108, 16, v195
	v_and_b32_e32 v109, 0xffff0000, v195
	v_lshlrev_b32_e32 v110, 16, v196
	v_and_b32_e32 v111, 0xffff0000, v196
	v_lshlrev_b32_e32 v100, 16, v197
	v_and_b32_e32 v101, 0xffff0000, v197
	v_lshlrev_b32_e32 v102, 16, v198
	v_and_b32_e32 v103, 0xffff0000, v198
	v_lshlrev_b32_e32 v96, 16, v199
	v_and_b32_e32 v97, 0xffff0000, v199
	v_mov_b32_e32 v0, s18
	ds_read_b128 v[64:67], v0
	ds_read_b128 v[72:75], v0 offset:16
	ds_read_b128 v[80:83], v0 offset:32
	ds_read_b128 v[164:167], v0 offset:48
	s_waitcnt lgkmcnt(3)
	v_mov_b32_e32 v0, v67
	v_pk_mul_f32 v[152:153], v[28:29], v[0:1] op_sel_hi:[1,0]
	s_waitcnt lgkmcnt(2)
	v_mov_b32_e32 v0, v75
	v_pk_mul_f32 v[136:137], v[28:29], v[0:1] op_sel_hi:[1,0]
	s_waitcnt lgkmcnt(1)
	v_mov_b32_e32 v0, v83
	v_pk_mul_f32 v[168:169], v[28:29], v[64:65] op_sel_hi:[1,0]
	v_pk_mul_f32 v[118:119], v[28:29], v[0:1] op_sel_hi:[1,0]
	s_waitcnt lgkmcnt(0)
	v_mov_b32_e32 v0, v167
	v_pk_mul_f32 v[98:99], v[28:29], v[0:1] op_sel_hi:[1,0]
	v_pk_fma_f32 v[90:91], v[168:169], v[154:155], v[90:91]
	v_cvt_f32_ubyte0_e32 v0, vcc_lo
	v_pk_add_f32 v[90:91], v[90:91], v[124:125] neg_lo:[0,1] neg_hi:[0,1]
	v_div_scale_f32 v124, vcc, v0, v0, 1.0
	v_rcp_f32_e32 v125, v124
	v_pk_mul_f32 v[32:33], v[168:169], v[154:155]
	v_pk_mul_f32 v[158:159], v[28:29], v[64:65] op_sel:[0,1]
	v_pk_mul_f32 v[156:157], v[28:29], v[66:67] op_sel_hi:[1,0]
	v_fma_f32 v154, -v124, v125, 1.0
	v_fmac_f32_e32 v125, v154, v125
	v_div_scale_f32 v154, vcc, 1.0, v0, 1.0
	v_mul_f32_e32 v155, v154, v125
	v_fma_f32 v163, -v124, v155, v154
	v_fmac_f32_e32 v155, v163, v125
	v_fma_f32 v124, -v124, v155, v154
	v_div_fmas_f32 v124, v124, v125, v155
	v_div_fixup_f32 v0, v124, v0, 1.0
	v_pk_fma_f32 v[124:125], v[0:1], v[90:91], v[32:33] op_sel_hi:[0,1,1] neg_lo:[0,0,1] neg_hi:[0,0,1]
	s_mov_b32 vcc_lo, 0x17701000
	v_cvt_pk_bf16_f32 v0, v124, v125
	v_add_co_u32_e32 v124, vcc, vcc_lo, v94
	v_pk_fma_f32 v[90:91], v[158:159], v[142:143], v[90:91]
	s_nop 0
	v_addc_co_u32_e32 v125, vcc, 0, v95, vcc
	global_store_dword v[124:125], v0, off offset:-4096 nt
	v_cvt_f32_ubyte0_e32 v0, s28
	v_pk_add_f32 v[60:61], v[90:91], v[60:61] neg_lo:[0,1] neg_hi:[0,1]
	v_div_scale_f32 v90, vcc, v0, v0, 1.0
	v_rcp_f32_e32 v91, v90
	v_pk_mul_f32 v[62:63], v[158:159], v[142:143]
	s_min_u32 s28, s29, 15
	s_add_i32 s28, s28, 1
	v_fma_f32 v142, -v90, v91, 1.0
	v_fmac_f32_e32 v91, v142, v91
	v_div_scale_f32 v142, vcc, 1.0, v0, 1.0
	v_mul_f32_e32 v143, v142, v91
	v_fma_f32 v154, -v90, v143, v142
	v_fmac_f32_e32 v143, v154, v91
	v_fma_f32 v90, -v90, v143, v142
	v_div_fmas_f32 v90, v90, v91, v143
	v_div_fixup_f32 v0, v90, v0, 1.0
	v_pk_fma_f32 v[90:91], v[0:1], v[60:61], v[62:63] op_sel_hi:[0,1,1] neg_lo:[0,0,1] neg_hi:[0,0,1]
	v_cvt_pk_bf16_f32 v0, v90, v91
	global_store_dword v[124:125], v0, off nt
	v_pk_fma_f32 v[60:61], v[156:157], v[146:147], v[60:61]
	v_cvt_f32_ubyte0_e32 v0, s28
	v_pk_add_f32 v[58:59], v[60:61], v[58:59] neg_lo:[0,1] neg_hi:[0,1]
	v_div_scale_f32 v60, s[28:29], v0, v0, 1.0
	v_rcp_f32_e32 v61, v60
	v_pk_mul_f32 v[64:65], v[156:157], v[146:147]
	s_mov_b32 s28, 0x17703000
	v_pk_mul_f32 v[66:67], v[152:153], v[138:139]
	v_fma_f32 v90, -v60, v61, 1.0
	v_fmac_f32_e32 v61, v90, v61
	v_div_scale_f32 v90, vcc, 1.0, v0, 1.0
	v_mul_f32_e32 v91, v90, v61
	v_fma_f32 v124, -v60, v91, v90
	v_fmac_f32_e32 v91, v124, v61
	v_fma_f32 v60, -v60, v91, v90
	v_div_fmas_f32 v60, v60, v61, v91
	v_div_fixup_f32 v0, v60, v0, 1.0
	v_pk_fma_f32 v[60:61], v[0:1], v[58:59], v[64:65] op_sel_hi:[0,1,1] neg_lo:[0,0,1] neg_hi:[0,0,1]
	v_cvt_pk_bf16_f32 v0, v60, v61
	v_add_co_u32_e32 v60, vcc, s28, v94
	s_min_u32 s28, s76, 15
	s_nop 0
	v_addc_co_u32_e32 v61, vcc, 0, v95, vcc
	s_add_i32 s28, s28, 1
	global_store_dword v[60:61], v0, off offset:-4096 nt
	v_pk_fma_f32 v[58:59], v[152:153], v[138:139], v[58:59]
	v_cvt_f32_ubyte0_e32 v0, s28
	v_pk_add_f32 v[56:57], v[58:59], v[56:57] neg_lo:[0,1] neg_hi:[0,1]
	v_div_scale_f32 v58, s[28:29], v0, v0, 1.0
	v_rcp_f32_e32 v59, v58
	s_min_u32 s28, s77, 15
	v_pk_mul_f32 v[150:151], v[28:29], v[72:73] op_sel_hi:[1,0]
	s_add_i32 s28, s28, 1
	v_fma_f32 v90, -v58, v59, 1.0
	v_fmac_f32_e32 v59, v90, v59
	v_div_scale_f32 v90, vcc, 1.0, v0, 1.0
	v_mul_f32_e32 v91, v90, v59
	v_fma_f32 v124, -v58, v91, v90
	v_fmac_f32_e32 v91, v124, v59
	v_fma_f32 v58, -v58, v91, v90
	v_div_fmas_f32 v58, v58, v59, v91
	v_div_fixup_f32 v0, v58, v0, 1.0
	v_pk_fma_f32 v[58:59], v[0:1], v[56:57], v[66:67] op_sel_hi:[0,1,1] neg_lo:[0,0,1] neg_hi:[0,0,1]
	v_cvt_pk_bf16_f32 v0, v58, v59
	global_store_dword v[60:61], v0, off nt
	v_pk_fma_f32 v[56:57], v[150:151], v[140:141], v[56:57]
	v_cvt_f32_ubyte0_e32 v0, s28
	v_pk_add_f32 v[54:55], v[56:57], v[54:55] neg_lo:[0,1] neg_hi:[0,1]
	v_div_scale_f32 v56, s[28:29], v0, v0, 1.0
	v_rcp_f32_e32 v57, v56
	v_pk_mul_f32 v[68:69], v[150:151], v[140:141]
	s_mov_b32 s28, 0x17705000
	v_pk_mul_f32 v[148:149], v[28:29], v[72:73] op_sel:[0,1]
	v_fma_f32 v58, -v56, v57, 1.0
	v_fmac_f32_e32 v57, v58, v57
	v_div_scale_f32 v58, vcc, 1.0, v0, 1.0
	v_mul_f32_e32 v59, v58, v57
	v_fma_f32 v60, -v56, v59, v58
	v_fmac_f32_e32 v59, v60, v57
	v_fma_f32 v56, -v56, v59, v58
	v_div_fmas_f32 v56, v56, v57, v59
	v_div_fixup_f32 v0, v56, v0, 1.0
	v_pk_fma_f32 v[56:57], v[0:1], v[54:55], v[68:69] op_sel_hi:[0,1,1] neg_lo:[0,0,1] neg_hi:[0,0,1]
	v_cvt_pk_bf16_f32 v0, v56, v57
	v_add_co_u32_e32 v56, vcc, s28, v94
	v_pk_fma_f32 v[54:55], v[148:149], v[130:131], v[54:55]
	s_nop 0
	v_addc_co_u32_e32 v57, vcc, 0, v95, vcc
	global_store_dword v[56:57], v0, off offset:-4096 nt
	v_cvt_f32_ubyte0_e32 v0, s26
	v_pk_add_f32 v[50:51], v[54:55], v[50:51] neg_lo:[0,1] neg_hi:[0,1]
	v_div_scale_f32 v54, s[28:29], v0, v0, 1.0
	v_rcp_f32_e32 v55, v54
	v_pk_mul_f32 v[70:71], v[148:149], v[130:131]
	s_min_u32 s26, s27, 15
	v_pk_mul_f32 v[144:145], v[28:29], v[74:75] op_sel_hi:[1,0]
	v_fma_f32 v58, -v54, v55, 1.0
	v_fmac_f32_e32 v55, v58, v55
	v_div_scale_f32 v58, vcc, 1.0, v0, 1.0
	v_mul_f32_e32 v59, v58, v55
	v_fma_f32 v60, -v54, v59, v58
	v_fmac_f32_e32 v59, v60, v55
	v_fma_f32 v54, -v54, v59, v58
	v_div_fmas_f32 v54, v54, v55, v59
	v_div_fixup_f32 v0, v54, v0, 1.0
	v_pk_fma_f32 v[54:55], v[0:1], v[50:51], v[70:71] op_sel_hi:[0,1,1] neg_lo:[0,0,1] neg_hi:[0,0,1]
	v_cvt_pk_bf16_f32 v0, v54, v55
	s_add_i32 s26, s26, 1
	global_store_dword v[56:57], v0, off nt
	v_pk_fma_f32 v[50:51], v[144:145], v[132:133], v[50:51]
	v_cvt_f32_ubyte0_e32 v0, s26
	v_pk_add_f32 v[50:51], v[50:51], v[52:53] neg_lo:[0,1] neg_hi:[0,1]
	v_div_scale_f32 v52, s[26:27], v0, v0, 1.0
	v_rcp_f32_e32 v53, v52
	v_pk_mul_f32 v[72:73], v[144:145], v[132:133]
	s_mov_b32 s26, 0x17707000
	v_pk_mul_f32 v[74:75], v[136:137], v[120:121]
	v_fma_f32 v54, -v52, v53, 1.0
	v_fmac_f32_e32 v53, v54, v53
	v_div_scale_f32 v54, vcc, 1.0, v0, 1.0
	v_mul_f32_e32 v55, v54, v53
	v_fma_f32 v56, -v52, v55, v54
	v_fmac_f32_e32 v55, v56, v53
	v_fma_f32 v52, -v52, v55, v54
	v_div_fmas_f32 v52, v52, v53, v55
	v_div_fixup_f32 v0, v52, v0, 1.0
	v_pk_fma_f32 v[52:53], v[0:1], v[50:51], v[72:73] op_sel_hi:[0,1,1] neg_lo:[0,0,1] neg_hi:[0,0,1]
	v_cvt_pk_bf16_f32 v0, v52, v53
	v_add_co_u32_e32 v52, vcc, s26, v94
	s_min_u32 s26, s82, 15
	s_nop 0
	v_addc_co_u32_e32 v53, vcc, 0, v95, vcc
	s_add_i32 s26, s26, 1
	global_store_dword v[52:53], v0, off offset:-4096 nt
	v_pk_fma_f32 v[50:51], v[136:137], v[120:121], v[50:51]
	v_cvt_f32_ubyte0_e32 v0, s26
	v_pk_add_f32 v[48:49], v[50:51], v[48:49] neg_lo:[0,1] neg_hi:[0,1]
	v_div_scale_f32 v50, s[26:27], v0, v0, 1.0
	v_rcp_f32_e32 v51, v50
	s_min_u32 s26, s87, 15
	v_pk_mul_f32 v[134:135], v[28:29], v[80:81] op_sel_hi:[1,0]
	s_add_i32 s26, s26, 1
	v_fma_f32 v54, -v50, v51, 1.0
	v_fmac_f32_e32 v51, v54, v51
	v_div_scale_f32 v54, vcc, 1.0, v0, 1.0
	v_mul_f32_e32 v55, v54, v51
	v_fma_f32 v56, -v50, v55, v54
	v_fmac_f32_e32 v55, v56, v51
	v_fma_f32 v50, -v50, v55, v54
	v_div_fmas_f32 v50, v50, v51, v55
	v_div_fixup_f32 v0, v50, v0, 1.0
	v_pk_fma_f32 v[50:51], v[0:1], v[48:49], v[74:75] op_sel_hi:[0,1,1] neg_lo:[0,0,1] neg_hi:[0,0,1]
	v_cvt_pk_bf16_f32 v0, v50, v51
	global_store_dword v[52:53], v0, off nt
	v_pk_fma_f32 v[48:49], v[134:135], v[122:123], v[48:49]
	v_cvt_f32_ubyte0_e32 v0, s26
	v_pk_add_f32 v[46:47], v[48:49], v[46:47] neg_lo:[0,1] neg_hi:[0,1]
	v_div_scale_f32 v48, s[26:27], v0, v0, 1.0
	v_rcp_f32_e32 v49, v48
	v_pk_mul_f32 v[76:77], v[134:135], v[122:123]
	s_mov_b32 s26, 0x17709000
	v_pk_mul_f32 v[128:129], v[28:29], v[80:81] op_sel:[0,1]
	v_fma_f32 v50, -v48, v49, 1.0
	v_fmac_f32_e32 v49, v50, v49
	v_div_scale_f32 v50, vcc, 1.0, v0, 1.0
	v_mul_f32_e32 v51, v50, v49
	v_fma_f32 v52, -v48, v51, v50
	v_fmac_f32_e32 v51, v52, v49
	v_fma_f32 v48, -v48, v51, v50
	v_div_fmas_f32 v48, v48, v49, v51
	v_div_fixup_f32 v0, v48, v0, 1.0
	v_pk_fma_f32 v[48:49], v[0:1], v[46:47], v[76:77] op_sel_hi:[0,1,1] neg_lo:[0,0,1] neg_hi:[0,0,1]
	v_cvt_pk_bf16_f32 v0, v48, v49
	v_add_co_u32_e32 v48, vcc, s26, v94
	s_min_u32 s26, s72, 15
	s_nop 0
	v_addc_co_u32_e32 v49, vcc, 0, v95, vcc
	s_add_i32 s26, s26, 1
	global_store_dword v[48:49], v0, off offset:-4096 nt
	v_pk_fma_f32 v[46:47], v[128:129], v[114:115], v[46:47]
	v_cvt_f32_ubyte0_e32 v0, s26
	v_pk_add_f32 v[44:45], v[46:47], v[44:45] neg_lo:[0,1] neg_hi:[0,1]
	v_div_scale_f32 v46, s[26:27], v0, v0, 1.0
	v_rcp_f32_e32 v47, v46
	v_pk_mul_f32 v[78:79], v[128:129], v[114:115]
	s_min_u32 s26, s81, 15
	v_pk_mul_f32 v[126:127], v[28:29], v[82:83] op_sel_hi:[1,0]
	v_fma_f32 v50, -v46, v47, 1.0
	v_fmac_f32_e32 v47, v50, v47
	v_div_scale_f32 v50, vcc, 1.0, v0, 1.0
	v_mul_f32_e32 v51, v50, v47
	v_fma_f32 v52, -v46, v51, v50
	v_fmac_f32_e32 v51, v52, v47
	v_fma_f32 v46, -v46, v51, v50
	v_div_fmas_f32 v46, v46, v47, v51
	v_div_fixup_f32 v0, v46, v0, 1.0
	v_pk_fma_f32 v[46:47], v[0:1], v[44:45], v[78:79] op_sel_hi:[0,1,1] neg_lo:[0,0,1] neg_hi:[0,0,1]
	v_cvt_pk_bf16_f32 v0, v46, v47
	s_add_i32 s26, s26, 1
	global_store_dword v[48:49], v0, off nt
	v_pk_fma_f32 v[44:45], v[126:127], v[116:117], v[44:45]
	v_cvt_f32_ubyte0_e32 v0, s26
	v_pk_add_f32 v[42:43], v[44:45], v[42:43] neg_lo:[0,1] neg_hi:[0,1]
	v_div_scale_f32 v44, s[26:27], v0, v0, 1.0
	v_rcp_f32_e32 v45, v44
	v_pk_mul_f32 v[80:81], v[126:127], v[116:117]
	s_mov_b32 s26, 0x1770b000
	v_pk_mul_f32 v[82:83], v[118:119], v[108:109]
	v_fma_f32 v46, -v44, v45, 1.0
	v_fmac_f32_e32 v45, v46, v45
	v_div_scale_f32 v46, vcc, 1.0, v0, 1.0
	v_mul_f32_e32 v47, v46, v45
	v_fma_f32 v48, -v44, v47, v46
	v_fmac_f32_e32 v47, v48, v45
	v_fma_f32 v44, -v44, v47, v46
	v_div_fmas_f32 v44, v44, v45, v47
	v_div_fixup_f32 v0, v44, v0, 1.0
	v_pk_fma_f32 v[44:45], v[0:1], v[42:43], v[80:81] op_sel_hi:[0,1,1] neg_lo:[0,0,1] neg_hi:[0,0,1]
	v_cvt_pk_bf16_f32 v0, v44, v45
	v_add_co_u32_e32 v44, vcc, s26, v94
	s_min_u32 s26, s70, 15
	s_nop 0
	v_addc_co_u32_e32 v45, vcc, 0, v95, vcc
	s_add_i32 s26, s26, 1
	global_store_dword v[44:45], v0, off offset:-4096 nt
	v_pk_fma_f32 v[42:43], v[118:119], v[108:109], v[42:43]
	v_cvt_f32_ubyte0_e32 v0, s26
	v_pk_add_f32 v[40:41], v[42:43], v[40:41] neg_lo:[0,1] neg_hi:[0,1]
	v_div_scale_f32 v42, s[26:27], v0, v0, 1.0
	v_rcp_f32_e32 v43, v42
	s_min_u32 s26, s71, 15
	v_pk_mul_f32 v[112:113], v[28:29], v[164:165] op_sel_hi:[1,0]
	s_add_i32 s26, s26, 1
	v_fma_f32 v46, -v42, v43, 1.0
	v_fmac_f32_e32 v43, v46, v43
	v_div_scale_f32 v46, vcc, 1.0, v0, 1.0
	v_mul_f32_e32 v47, v46, v43
	v_fma_f32 v48, -v42, v47, v46
	v_fmac_f32_e32 v47, v48, v43
	v_fma_f32 v42, -v42, v47, v46
	v_div_fmas_f32 v42, v42, v43, v47
	v_div_fixup_f32 v0, v42, v0, 1.0
	v_pk_fma_f32 v[42:43], v[0:1], v[40:41], v[82:83] op_sel_hi:[0,1,1] neg_lo:[0,0,1] neg_hi:[0,0,1]
	v_cvt_pk_bf16_f32 v0, v42, v43
	global_store_dword v[44:45], v0, off nt
	v_pk_fma_f32 v[40:41], v[112:113], v[110:111], v[40:41]
	v_cvt_f32_ubyte0_e32 v0, s26
	v_pk_add_f32 v[38:39], v[40:41], v[38:39] neg_lo:[0,1] neg_hi:[0,1]
	v_div_scale_f32 v40, s[26:27], v0, v0, 1.0
	v_rcp_f32_e32 v41, v40
	v_pk_mul_f32 v[84:85], v[112:113], v[110:111]
	s_mov_b32 s26, 0x1770d000
	v_pk_mul_f32 v[106:107], v[28:29], v[164:165] op_sel:[0,1]
	v_fma_f32 v42, -v40, v41, 1.0
	v_fmac_f32_e32 v41, v42, v41
	v_div_scale_f32 v42, vcc, 1.0, v0, 1.0
	v_mul_f32_e32 v43, v42, v41
	v_fma_f32 v44, -v40, v43, v42
	v_fmac_f32_e32 v43, v44, v41
	v_fma_f32 v40, -v40, v43, v42
	v_div_fmas_f32 v40, v40, v41, v43
	v_div_fixup_f32 v0, v40, v0, 1.0
	v_pk_fma_f32 v[40:41], v[0:1], v[38:39], v[84:85] op_sel_hi:[0,1,1] neg_lo:[0,0,1] neg_hi:[0,0,1]
	v_cvt_pk_bf16_f32 v0, v40, v41
	v_add_co_u32_e32 v40, vcc, s26, v94
	v_pk_fma_f32 v[38:39], v[106:107], v[100:101], v[38:39]
	s_nop 0
	v_addc_co_u32_e32 v41, vcc, 0, v95, vcc
	global_store_dword v[40:41], v0, off offset:-4096 nt
	v_cvt_f32_ubyte0_e32 v0, s0
	v_pk_add_f32 v[36:37], v[38:39], v[36:37] neg_lo:[0,1] neg_hi:[0,1]
	v_div_scale_f32 v38, s[26:27], v0, v0, 1.0
	v_rcp_f32_e32 v39, v38
	v_pk_mul_f32 v[86:87], v[106:107], v[100:101]
	s_min_u32 s0, s1, 15
	v_pk_mul_f32 v[104:105], v[28:29], v[166:167] op_sel_hi:[1,0]
	v_fma_f32 v42, -v38, v39, 1.0
	v_fmac_f32_e32 v39, v42, v39
	v_div_scale_f32 v42, vcc, 1.0, v0, 1.0
	v_mul_f32_e32 v43, v42, v39
	v_fma_f32 v44, -v38, v43, v42
	v_fmac_f32_e32 v43, v44, v39
	v_fma_f32 v38, -v38, v43, v42
	v_div_fmas_f32 v38, v38, v39, v43
	v_div_fixup_f32 v0, v38, v0, 1.0
	v_pk_fma_f32 v[38:39], v[0:1], v[36:37], v[86:87] op_sel_hi:[0,1,1] neg_lo:[0,0,1] neg_hi:[0,0,1]
	v_cvt_pk_bf16_f32 v0, v38, v39
	s_add_i32 s0, s0, 1
	global_store_dword v[40:41], v0, off nt
	v_pk_fma_f32 v[36:37], v[104:105], v[102:103], v[36:37]
	v_cvt_f32_ubyte0_e32 v0, s0
	v_pk_add_f32 v[34:35], v[36:37], v[34:35] neg_lo:[0,1] neg_hi:[0,1]
	v_div_scale_f32 v36, s[0:1], v0, v0, 1.0
	v_rcp_f32_e32 v37, v36
	v_pk_mul_f32 v[88:89], v[104:105], v[102:103]
	s_mov_b32 s0, 0x1770f000
	v_pk_mul_f32 v[92:93], v[98:99], v[96:97]
	v_fma_f32 v38, -v36, v37, 1.0
	v_fmac_f32_e32 v37, v38, v37
	v_div_scale_f32 v38, vcc, 1.0, v0, 1.0
	v_mul_f32_e32 v39, v38, v37
	v_fma_f32 v40, -v36, v39, v38
	v_fmac_f32_e32 v39, v40, v37
	v_fma_f32 v36, -v36, v39, v38
	v_div_fmas_f32 v36, v36, v37, v39
	v_div_fixup_f32 v0, v36, v0, 1.0
	v_pk_fma_f32 v[36:37], v[0:1], v[34:35], v[88:89] op_sel_hi:[0,1,1] neg_lo:[0,0,1] neg_hi:[0,0,1]
	v_pk_fma_f32 v[34:35], v[98:99], v[96:97], v[34:35]
	v_cvt_pk_bf16_f32 v0, v36, v37
	v_add_co_u32_e32 v36, vcc, s0, v94
	v_pk_add_f32 v[90:91], v[34:35], v[4:5] neg_lo:[0,1] neg_hi:[0,1]
	s_mov_b32 s0, 0x3d800000
	s_add_u32 s16, s16, 0x10000
	v_addc_co_u32_e32 v37, vcc, 0, v95, vcc
	v_pk_fma_f32 v[4:5], v[90:91], s[0:1], v[92:93] op_sel_hi:[1,0,1] neg_lo:[0,0,1] neg_hi:[0,0,1]
	s_addc_u32 s17, s17, 0
	s_add_i32 s19, s19, 16
	s_add_i32 s18, s18, 64
	global_store_dword v[36:37], v0, off offset:-4096 nt
	v_cvt_pk_bf16_f32 v0, v4, v5
	global_store_dword v[36:37], v0, off nt
	s_cmp_eq_u32 s16, 0x40000
	v_mov_b64_e32 v[4:5], v[92:93]
	v_mov_b64_e32 v[34:35], v[88:89]
	v_mov_b64_e32 v[36:37], v[86:87]
	v_mov_b64_e32 v[38:39], v[84:85]
	v_mov_b64_e32 v[40:41], v[82:83]
	v_mov_b64_e32 v[42:43], v[80:81]
	v_mov_b64_e32 v[44:45], v[78:79]
	v_mov_b64_e32 v[46:47], v[76:77]
	v_mov_b64_e32 v[48:49], v[74:75]
	v_mov_b64_e32 v[52:53], v[72:73]
	v_mov_b64_e32 v[50:51], v[70:71]
	v_mov_b64_e32 v[54:55], v[68:69]
	v_mov_b64_e32 v[56:57], v[66:67]
	v_mov_b64_e32 v[58:59], v[64:65]
	v_mov_b64_e32 v[60:61], v[62:63]
	v_mov_b64_e32 v[124:125], v[32:33]
	s_cbranch_scc0 .LBB0_382

.LBB0_386:
	v_div_scale_f32 v0, s[2:3], s0, s0, 1.0
	v_rcp_f32_e32 v4, v0
	s_nop 0
	v_fma_f32 v5, -v0, v4, 1.0
	v_fmac_f32_e32 v4, v5, v4
	v_div_scale_f32 v5, vcc, 1.0, s0, 1.0
	v_mul_f32_e32 v34, v5, v4
	v_fma_f32 v35, -v0, v34, v5
	v_fmac_f32_e32 v34, v35, v4
	v_fma_f32 v0, -v0, v34, v5
	v_div_fmas_f32 v0, v0, v4, v34
	v_div_fixup_f32 v52, v0, s0, 1.0
	v_readlane_b32 s0, v253, 20
	v_readlane_b32 s1, v253, 21
	s_nop 1
	v_lshl_add_u64 v[4:5], v[30:31], 0, s[0:1]
	v_readlane_b32 s0, v252, 31
	v_readlane_b32 s1, v252, 32
	flat_load_dword v34, v[4:5]
	s_waitcnt vmcnt(0) lgkmcnt(0)
	v_lshlrev_b32_e32 v56, 16, v34
	v_lshl_add_u64 v[4:5], v[30:31], 0, s[0:1]
	v_readlane_b32 s0, v252, 34
	v_readlane_b32 s1, v252, 35
	flat_load_dword v35, v[4:5]
	v_and_b32_e32 v57, 0xffff0000, v34
	v_lshl_add_u64 v[4:5], v[30:31], 0, s[0:1]
	v_readlane_b32 s0, v252, 37
	v_readlane_b32 s1, v252, 38
	flat_load_dword v40, v[4:5]
	s_waitcnt vmcnt(0) lgkmcnt(0)
	v_lshlrev_b32_e32 v58, 16, v35
	v_lshl_add_u64 v[4:5], v[30:31], 0, s[0:1]
	v_readlane_b32 s0, v252, 40
	v_readlane_b32 s1, v252, 41
	flat_load_dword v41, v[4:5]
	v_and_b32_e32 v59, 0xffff0000, v35
	v_lshl_add_u64 v[4:5], v[30:31], 0, s[0:1]
	v_readlane_b32 s0, v252, 43
	v_readlane_b32 s1, v252, 44
	flat_load_dword v42, v[4:5]
	v_lshlrev_b32_e32 v60, 16, v40
	v_lshl_add_u64 v[4:5], v[30:31], 0, s[0:1]
	v_readlane_b32 s0, v252, 51
	v_readlane_b32 s1, v252, 52
	flat_load_dword v43, v[4:5]
	v_and_b32_e32 v61, 0xffff0000, v40
	v_lshl_add_u64 v[4:5], v[30:31], 0, s[0:1]
	v_readlane_b32 s0, v253, 26
	v_readlane_b32 s1, v253, 27
	flat_load_dword v44, v[4:5]
	s_waitcnt vmcnt(0) lgkmcnt(0)
	v_lshlrev_b32_e32 v62, 16, v41
	v_lshl_add_u64 v[4:5], v[30:31], 0, s[0:1]
	v_readlane_b32 s0, v253, 31
	v_readlane_b32 s1, v253, 32
	flat_load_dword v45, v[4:5]
	v_and_b32_e32 v63, 0xffff0000, v41
	v_lshl_add_u64 v[4:5], v[30:31], 0, s[0:1]
	v_readlane_b32 s0, v252, 54
	v_readlane_b32 s1, v252, 55
	flat_load_dword v46, v[4:5]
	v_lshlrev_b32_e32 v64, 16, v42
	v_lshl_add_u64 v[4:5], v[30:31], 0, s[0:1]
	v_readlane_b32 s0, v254, 7
	v_readlane_b32 s1, v254, 8
	flat_load_dword v47, v[4:5]
	v_and_b32_e32 v65, 0xffff0000, v42
	v_lshl_add_u64 v[4:5], v[30:31], 0, s[0:1]
	v_readlane_b32 s0, v253, 22
	v_readlane_b32 s1, v253, 23
	flat_load_dword v48, v[4:5]
	v_lshlrev_b32_e32 v66, 16, v43
	v_lshl_add_u64 v[4:5], v[30:31], 0, s[0:1]
	v_readlane_b32 s0, v254, 13
	v_readlane_b32 s1, v254, 14
	flat_load_dword v49, v[4:5]
	v_and_b32_e32 v67, 0xffff0000, v43
	v_lshl_add_u64 v[4:5], v[30:31], 0, s[0:1]
	v_readlane_b32 s0, v254, 15
	v_readlane_b32 s1, v254, 16
	flat_load_dword v50, v[4:5]
	v_lshlrev_b32_e32 v68, 16, v44
	v_lshl_add_u64 v[4:5], v[30:31], 0, s[0:1]
	v_readlane_b32 s0, v254, 17
	v_readlane_b32 s1, v254, 18
	flat_load_dword v51, v[4:5]
	v_and_b32_e32 v69, 0xffff0000, v44
	v_lshl_add_u64 v[4:5], v[30:31], 0, s[0:1]
	v_readlane_b32 s0, v253, 34
	v_readlane_b32 s1, v253, 35
	flat_load_dword v53, v[4:5]
	s_waitcnt vmcnt(0) lgkmcnt(0)
	v_lshlrev_b32_e32 v70, 16, v45
	v_lshl_add_u64 v[4:5], v[30:31], 0, s[0:1]
	flat_load_dword v84, v[4:5]
	v_readlane_b32 s0, v252, 23
	v_pk_add_f32 v[4:5], v[32:33], 0 op_sel_hi:[1,0]
	v_and_b32_e32 v71, 0xffff0000, v45
	v_mov_b32_e32 v0, s0
	ds_read_b128 v[36:39], v0
	v_pk_add_f32 v[54:55], v[2:3], v[4:5]
	v_readlane_b32 s0, v252, 27
	s_lshl_b32 s94, s0, 1
	v_readlane_b32 s0, v252, 30
	s_waitcnt lgkmcnt(0)
	v_pk_mul_f32 v[88:89], v[28:29], v[36:37] op_sel:[0,1]
	v_pk_mul_f32 v[92:93], v[28:29], v[38:39] op_sel_hi:[1,0]
	v_pk_mul_f32 v[90:91], v[88:89], v[58:59]
	v_lshlrev_b32_e32 v72, 16, v46
	v_and_b32_e32 v73, 0xffff0000, v46
	v_lshlrev_b32_e32 v74, 16, v47
	v_and_b32_e32 v75, 0xffff0000, v47
	v_lshlrev_b32_e32 v76, 16, v48
	v_and_b32_e32 v77, 0xffff0000, v48
	v_lshlrev_b32_e32 v78, 16, v49
	v_and_b32_e32 v79, 0xffff0000, v49
	v_pk_mul_f32 v[94:95], v[92:93], v[60:61]
	v_lshlrev_b32_e32 v80, 16, v50
	v_and_b32_e32 v81, 0xffff0000, v50
	v_lshlrev_b32_e32 v82, 16, v51
	v_and_b32_e32 v83, 0xffff0000, v51
	ds_read_b128 v[40:43], v0 offset:16
	ds_read_b128 v[44:47], v0 offset:32
	ds_read_b128 v[48:51], v0 offset:48
	v_lshlrev_b32_e32 v34, 16, v53
	v_and_b32_e32 v35, 0xffff0000, v53
	s_waitcnt lgkmcnt(0)
	v_pk_mul_f32 v[100:101], v[28:29], v[40:41] op_sel_hi:[1,0]
	v_pk_mul_f32 v[40:41], v[28:29], v[40:41] op_sel:[0,1]
	v_pk_mul_f32 v[102:103], v[100:101], v[64:65]
	v_pk_mul_f32 v[104:105], v[40:41], v[66:67]
	v_pk_mul_f32 v[106:107], v[28:29], v[42:43] op_sel_hi:[1,0]
	v_pk_mul_f32 v[112:113], v[28:29], v[44:45] op_sel_hi:[1,0]
	v_pk_mul_f32 v[108:109], v[106:107], v[68:69]
	v_pk_mul_f32 v[114:115], v[112:113], v[72:73]
	v_pk_mul_f32 v[44:45], v[28:29], v[44:45] op_sel:[0,1]
	v_pk_mul_f32 v[118:119], v[28:29], v[46:47] op_sel_hi:[1,0]
	v_pk_mul_f32 v[116:117], v[44:45], v[74:75]
	v_pk_mul_f32 v[120:121], v[118:119], v[76:77]
	v_pk_mul_f32 v[124:125], v[28:29], v[48:49] op_sel_hi:[1,0]
	v_pk_mul_f32 v[48:49], v[28:29], v[48:49] op_sel:[0,1]
	v_pk_mul_f32 v[126:127], v[124:125], v[80:81]
	v_pk_mul_f32 v[128:129], v[48:49], v[82:83]
	s_waitcnt vmcnt(0)
	v_lshlrev_b32_e32 v4, 16, v84
	v_and_b32_e32 v5, 0xffff0000, v84
	v_pk_mul_f32 v[84:85], v[28:29], v[36:37] op_sel_hi:[1,0]
	v_mov_b32_e32 v36, v39
	v_pk_fma_f32 v[54:55], v[84:85], v[56:57], v[54:55]
	v_pk_mul_f32 v[86:87], v[84:85], v[56:57]
	v_pk_add_f32 v[32:33], v[54:55], v[32:33] neg_lo:[0,1] neg_hi:[0,1]
	v_pk_mul_f32 v[96:97], v[28:29], v[36:37] op_sel_hi:[1,0]
	v_pk_fma_f32 v[52:53], v[52:53], v[32:33], v[86:87] op_sel_hi:[0,1,1] neg_lo:[0,0,1] neg_hi:[0,0,1]
	v_pk_fma_f32 v[32:33], v[88:89], v[58:59], v[32:33]
	v_cvt_pk_bf16_f32 v54, v52, v53
	v_lshl_add_u64 v[52:53], v[26:27], 0, s[94:95]
	v_pk_add_f32 v[2:3], v[32:33], v[2:3] neg_lo:[0,1] neg_hi:[0,1]
	s_lshl_b32 s94, s0, 1
	v_pk_fma_f32 v[32:33], v[2:3], 0.5, v[90:91] op_sel_hi:[1,0,1] neg_lo:[0,0,1] neg_hi:[0,0,1]
	v_pk_fma_f32 v[2:3], v[92:93], v[60:61], v[2:3]
	global_store_dword v[52:53], v54, off nt
	v_cvt_pk_bf16_f32 v52, v32, v33
	v_lshl_add_u64 v[32:33], v[26:27], 0, s[94:95]
	v_pk_fma_f32 v[2:3], v[84:85], v[56:57], v[2:3] neg_lo:[1,0,0] neg_hi:[1,0,0]
	v_readlane_b32 s0, v252, 33
	global_store_dword v[32:33], v52, off nt
	v_pk_fma_f32 v[32:33], v[2:3], 0.5, v[94:95] op_sel_hi:[1,0,1] neg_lo:[0,0,1] neg_hi:[0,0,1]
	s_lshl_b32 s94, s0, 1
	v_pk_fma_f32 v[2:3], v[96:97], v[62:63], v[2:3]
	v_pk_mul_f32 v[98:99], v[96:97], v[62:63]
	v_cvt_pk_bf16_f32 v52, v32, v33
	v_lshl_add_u64 v[32:33], v[26:27], 0, s[94:95]
	v_pk_fma_f32 v[2:3], v[88:89], v[58:59], v[2:3] neg_lo:[1,0,0] neg_hi:[1,0,0]
	v_readlane_b32 s0, v252, 36
	global_store_dword v[32:33], v52, off nt
	v_pk_fma_f32 v[32:33], v[2:3], 0.5, v[98:99] op_sel_hi:[1,0,1] neg_lo:[0,0,1] neg_hi:[0,0,1]
	s_lshl_b32 s94, s0, 1
	v_pk_fma_f32 v[2:3], v[100:101], v[64:65], v[2:3]
	v_cvt_pk_bf16_f32 v52, v32, v33
	v_lshl_add_u64 v[32:33], v[26:27], 0, s[94:95]
	v_pk_fma_f32 v[2:3], v[92:93], v[60:61], v[2:3] neg_lo:[1,0,0] neg_hi:[1,0,0]
	v_readlane_b32 s0, v252, 39
	global_store_dword v[32:33], v52, off nt
	v_pk_fma_f32 v[32:33], v[2:3], 0.5, v[102:103] op_sel_hi:[1,0,1] neg_lo:[0,0,1] neg_hi:[0,0,1]
	s_lshl_b32 s94, s0, 1
	v_pk_fma_f32 v[2:3], v[40:41], v[66:67], v[2:3]
	v_cvt_pk_bf16_f32 v52, v32, v33
	v_lshl_add_u64 v[32:33], v[26:27], 0, s[94:95]
	v_pk_fma_f32 v[2:3], v[96:97], v[62:63], v[2:3] neg_lo:[1,0,0] neg_hi:[1,0,0]
	v_readlane_b32 s0, v252, 42
	v_mov_b32_e32 v36, v43
	global_store_dword v[32:33], v52, off nt
	v_pk_fma_f32 v[32:33], v[2:3], 0.5, v[104:105] op_sel_hi:[1,0,1] neg_lo:[0,0,1] neg_hi:[0,0,1]
	s_lshl_b32 s94, s0, 1
	v_pk_fma_f32 v[2:3], v[106:107], v[68:69], v[2:3]
	v_pk_mul_f32 v[42:43], v[28:29], v[36:37] op_sel_hi:[1,0]
	v_cvt_pk_bf16_f32 v52, v32, v33
	v_lshl_add_u64 v[32:33], v[26:27], 0, s[94:95]
	v_pk_fma_f32 v[2:3], v[100:101], v[64:65], v[2:3] neg_lo:[1,0,0] neg_hi:[1,0,0]
	v_readlane_b32 s0, v252, 45
	global_store_dword v[32:33], v52, off nt
	v_pk_fma_f32 v[32:33], v[2:3], 0.5, v[108:109] op_sel_hi:[1,0,1] neg_lo:[0,0,1] neg_hi:[0,0,1]
	s_lshl_b32 s94, s0, 1
	v_pk_fma_f32 v[2:3], v[42:43], v[70:71], v[2:3]
	v_pk_mul_f32 v[110:111], v[42:43], v[70:71]
	v_cvt_pk_bf16_f32 v52, v32, v33
	v_lshl_add_u64 v[32:33], v[26:27], 0, s[94:95]
	v_pk_fma_f32 v[2:3], v[40:41], v[66:67], v[2:3] neg_lo:[1,0,0] neg_hi:[1,0,0]
	v_readlane_b32 s0, v252, 47
	global_store_dword v[32:33], v52, off nt
	v_pk_fma_f32 v[32:33], v[2:3], 0.5, v[110:111] op_sel_hi:[1,0,1] neg_lo:[0,0,1] neg_hi:[0,0,1]
	s_lshl_b32 s94, s0, 1
	v_pk_fma_f32 v[2:3], v[112:113], v[72:73], v[2:3]
	v_cvt_pk_bf16_f32 v40, v32, v33
	v_lshl_add_u64 v[32:33], v[26:27], 0, s[94:95]
	v_pk_fma_f32 v[2:3], v[106:107], v[68:69], v[2:3] neg_lo:[1,0,0] neg_hi:[1,0,0]
	v_readlane_b32 s0, v252, 48
	global_store_dword v[32:33], v40, off nt
	v_pk_fma_f32 v[32:33], v[2:3], 0.5, v[114:115] op_sel_hi:[1,0,1] neg_lo:[0,0,1] neg_hi:[0,0,1]
	s_lshl_b32 s94, s0, 1
	v_pk_fma_f32 v[2:3], v[44:45], v[74:75], v[2:3]
	v_cvt_pk_bf16_f32 v40, v32, v33
	v_lshl_add_u64 v[32:33], v[26:27], 0, s[94:95]
	v_pk_fma_f32 v[2:3], v[42:43], v[70:71], v[2:3] neg_lo:[1,0,0] neg_hi:[1,0,0]
	v_readlane_b32 s0, v252, 49
	v_mov_b32_e32 v36, v47
	global_store_dword v[32:33], v40, off nt
	v_pk_fma_f32 v[32:33], v[2:3], 0.5, v[116:117] op_sel_hi:[1,0,1] neg_lo:[0,0,1] neg_hi:[0,0,1]
	s_lshl_b32 s94, s0, 1
	v_pk_fma_f32 v[2:3], v[118:119], v[76:77], v[2:3]
	v_pk_mul_f32 v[46:47], v[28:29], v[36:37] op_sel_hi:[1,0]
	v_cvt_pk_bf16_f32 v40, v32, v33
	v_lshl_add_u64 v[32:33], v[26:27], 0, s[94:95]
	v_pk_fma_f32 v[2:3], v[112:113], v[72:73], v[2:3] neg_lo:[1,0,0] neg_hi:[1,0,0]
	v_readlane_b32 s0, v252, 50
	global_store_dword v[32:33], v40, off nt
	v_pk_fma_f32 v[32:33], v[2:3], 0.5, v[120:121] op_sel_hi:[1,0,1] neg_lo:[0,0,1] neg_hi:[0,0,1]
	s_lshl_b32 s94, s0, 1
	v_pk_fma_f32 v[2:3], v[46:47], v[78:79], v[2:3]
	v_pk_mul_f32 v[122:123], v[46:47], v[78:79]
	v_cvt_pk_bf16_f32 v40, v32, v33
	v_lshl_add_u64 v[32:33], v[26:27], 0, s[94:95]
	v_pk_fma_f32 v[2:3], v[44:45], v[74:75], v[2:3] neg_lo:[1,0,0] neg_hi:[1,0,0]
	v_readlane_b32 s0, v252, 53
	global_store_dword v[32:33], v40, off nt
	v_pk_fma_f32 v[32:33], v[2:3], 0.5, v[122:123] op_sel_hi:[1,0,1] neg_lo:[0,0,1] neg_hi:[0,0,1]
	s_lshl_b32 s94, s0, 1
	v_pk_fma_f32 v[2:3], v[124:125], v[80:81], v[2:3]
	v_cvt_pk_bf16_f32 v40, v32, v33
	v_lshl_add_u64 v[32:33], v[26:27], 0, s[94:95]
	v_pk_fma_f32 v[2:3], v[118:119], v[76:77], v[2:3] neg_lo:[1,0,0] neg_hi:[1,0,0]
	v_readlane_b32 s0, v252, 58
	global_store_dword v[32:33], v40, off nt
	v_pk_fma_f32 v[32:33], v[2:3], 0.5, v[126:127] op_sel_hi:[1,0,1] neg_lo:[0,0,1] neg_hi:[0,0,1]
	s_lshl_b32 s94, s0, 1
	v_pk_fma_f32 v[2:3], v[48:49], v[82:83], v[2:3]
	v_pk_mul_f32 v[38:39], v[28:29], v[50:51] op_sel_hi:[1,0]
	v_cvt_pk_bf16_f32 v40, v32, v33
	v_lshl_add_u64 v[32:33], v[26:27], 0, s[94:95]
	v_pk_fma_f32 v[2:3], v[46:47], v[78:79], v[2:3] neg_lo:[1,0,0] neg_hi:[1,0,0]
	v_readlane_b32 s0, v252, 61
	v_mov_b32_e32 v36, v51
	global_store_dword v[32:33], v40, off nt
	v_pk_fma_f32 v[32:33], v[2:3], 0.5, v[128:129] op_sel_hi:[1,0,1] neg_lo:[0,0,1] neg_hi:[0,0,1]
	s_lshl_b32 s94, s0, 1
	v_pk_fma_f32 v[2:3], v[38:39], v[34:35], v[2:3]
	v_pk_mul_f32 v[130:131], v[38:39], v[34:35]
	v_pk_mul_f32 v[36:37], v[28:29], v[36:37] op_sel_hi:[1,0]
	v_cvt_pk_bf16_f32 v40, v32, v33
	v_lshl_add_u64 v[32:33], v[26:27], 0, s[94:95]
	v_pk_fma_f32 v[2:3], v[124:125], v[80:81], v[2:3] neg_lo:[1,0,0] neg_hi:[1,0,0]
	global_store_dword v[32:33], v40, off nt
	v_pk_fma_f32 v[32:33], v[2:3], 0.5, v[130:131] op_sel_hi:[1,0,1] neg_lo:[0,0,1] neg_hi:[0,0,1]
	v_readlane_b32 s0, v253, 0
	v_pk_fma_f32 v[2:3], v[36:37], v[4:5], v[2:3]
	v_pk_mul_f32 v[50:51], v[36:37], v[4:5]
	s_lshl_b32 s94, s0, 1
	v_pk_fma_f32 v[60:61], v[48:49], v[82:83], v[2:3] neg_lo:[1,0,0] neg_hi:[1,0,0]
	v_readlane_b32 s0, v252, 3
	v_cvt_pk_bf16_f32 v40, v32, v33
	v_lshl_add_u64 v[32:33], v[26:27], 0, s[94:95]
	v_pk_fma_f32 v[2:3], v[60:61], 0.5, v[50:51] op_sel_hi:[1,0,1] neg_lo:[0,0,1] neg_hi:[0,0,1]
	v_readlane_b32 s1, v252, 4
	global_store_dword v[32:33], v40, off nt
	v_cvt_pk_bf16_f32 v32, v2, v3
	s_nop 0
	v_lshl_add_u64 v[2:3], v[30:31], 0, s[0:1]
	v_readlane_b32 s0, v252, 1
	v_readlane_b32 s1, v252, 2
	flat_load_dword v33, v[2:3]
	s_waitcnt vmcnt(0) lgkmcnt(0)
	v_lshlrev_b32_e32 v62, 16, v33
	v_lshl_add_u64 v[2:3], v[30:31], 0, s[0:1]
	v_readlane_b32 s0, v252, 7
	v_readlane_b32 s1, v252, 8
	flat_load_dword v40, v[2:3]
	v_and_b32_e32 v63, 0xffff0000, v33
	v_lshl_add_u64 v[2:3], v[30:31], 0, s[0:1]
	v_readlane_b32 s0, v252, 11
	v_readlane_b32 s1, v252, 12
	flat_load_dword v41, v[2:3]
	s_waitcnt vmcnt(0) lgkmcnt(0)
	v_lshlrev_b32_e32 v64, 16, v40
	v_lshl_add_u64 v[2:3], v[30:31], 0, s[0:1]
	v_readlane_b32 s0, v252, 15
	v_readlane_b32 s1, v252, 16
	flat_load_dword v42, v[2:3]
	v_and_b32_e32 v65, 0xffff0000, v40
	v_lshl_add_u64 v[2:3], v[30:31], 0, s[0:1]
	v_readlane_b32 s0, v252, 19
	v_readlane_b32 s1, v252, 20
	flat_load_dword v43, v[2:3]
	v_lshlrev_b32_e32 v66, 16, v41
	v_lshl_add_u64 v[2:3], v[30:31], 0, s[0:1]
	v_readlane_b32 s0, v254, 31
	v_readlane_b32 s1, v254, 32
	flat_load_dword v44, v[2:3]
	v_and_b32_e32 v67, 0xffff0000, v41
	v_lshl_add_u64 v[2:3], v[30:31], 0, s[0:1]
	v_readlane_b32 s0, v254, 35
	v_readlane_b32 s1, v254, 36
	flat_load_dword v45, v[2:3]
	s_waitcnt vmcnt(0) lgkmcnt(0)
	v_lshlrev_b32_e32 v68, 16, v42
	v_lshl_add_u64 v[2:3], v[30:31], 0, s[0:1]
	v_readlane_b32 s0, v253, 43
	v_readlane_b32 s1, v253, 44
	flat_load_dword v46, v[2:3]
	v_and_b32_e32 v69, 0xffff0000, v42
	v_lshl_add_u64 v[2:3], v[30:31], 0, s[0:1]
	v_readlane_b32 s0, v254, 45
	v_readlane_b32 s1, v254, 46
	flat_load_dword v47, v[2:3]
	v_lshlrev_b32_e32 v70, 16, v43
	v_lshl_add_u64 v[2:3], v[30:31], 0, s[0:1]
	v_readlane_b32 s0, v254, 39
	v_readlane_b32 s1, v254, 40
	flat_load_dword v48, v[2:3]
	v_and_b32_e32 v71, 0xffff0000, v43
	v_lshl_add_u64 v[2:3], v[30:31], 0, s[0:1]
	v_readlane_b32 s0, v254, 43
	v_readlane_b32 s1, v254, 44
	flat_load_dword v49, v[2:3]
	ds_read_b128 v[40:43], v0 offset:64
	v_lshl_add_u64 v[2:3], v[30:31], 0, s[0:1]
	v_readlane_b32 s0, v254, 47
	v_readlane_b32 s1, v254, 48
	flat_load_dword v50, v[2:3]
	s_waitcnt lgkmcnt(0)
	v_pk_mul_f32 v[86:87], v[28:29], v[40:41] op_sel_hi:[1,0]
	v_lshl_add_u64 v[2:3], v[30:31], 0, s[0:1]
	v_readlane_b32 s0, v251, 63
	v_readlane_b32 s1, v252, 0
	flat_load_dword v51, v[2:3]
	v_pk_fma_f32 v[60:61], v[86:87], v[62:63], v[60:61]
	v_lshl_add_u64 v[2:3], v[30:31], 0, s[0:1]
	v_readlane_b32 s0, v253, 45
	v_readlane_b32 s1, v253, 46
	flat_load_dword v52, v[2:3]
	v_pk_mul_f32 v[88:89], v[86:87], v[62:63]
	v_lshl_add_u64 v[2:3], v[30:31], 0, s[0:1]
	v_readlane_b32 s0, v251, 41
	v_readlane_b32 s1, v251, 42
	flat_load_dword v53, v[2:3]
	v_pk_mul_f32 v[90:91], v[28:29], v[40:41] op_sel:[0,1]
	v_lshl_add_u64 v[2:3], v[30:31], 0, s[0:1]
	flat_load_dword v54, v[2:3]
	v_readlane_b32 s0, v253, 3
	s_lshl_b32 s94, s0, 1
	v_pk_fma_f32 v[34:35], v[38:39], v[34:35], v[60:61] neg_lo:[1,0,0] neg_hi:[1,0,0]
	v_lshl_add_u64 v[2:3], v[26:27], 0, s[94:95]
	v_pk_fma_f32 v[38:39], v[34:35], 0.5, v[88:89] op_sel_hi:[1,0,1] neg_lo:[0,0,1] neg_hi:[0,0,1]
	v_readlane_b32 s0, v253, 6
	v_pk_fma_f32 v[34:35], v[90:91], v[64:65], v[34:35]
	global_store_dword v[2:3], v32, off nt
	v_pk_mul_f32 v[92:93], v[90:91], v[64:65]
	v_pk_mul_f32 v[94:95], v[28:29], v[42:43] op_sel_hi:[1,0]
	s_lshl_b32 s94, s0, 1
	v_pk_fma_f32 v[4:5], v[36:37], v[4:5], v[34:35] neg_lo:[1,0,0] neg_hi:[1,0,0]
	v_readlane_b32 s0, v253, 9
	v_lshlrev_b32_e32 v72, 16, v44
	v_and_b32_e32 v73, 0xffff0000, v44
	v_lshlrev_b32_e32 v74, 16, v45
	v_and_b32_e32 v75, 0xffff0000, v45
	v_mov_b32_e32 v40, v43
	v_pk_fma_f32 v[34:35], v[4:5], 0.5, v[92:93] op_sel_hi:[1,0,1] neg_lo:[0,0,1] neg_hi:[0,0,1]
	v_pk_fma_f32 v[4:5], v[94:95], v[66:67], v[4:5]
	v_pk_mul_f32 v[96:97], v[94:95], v[66:67]
	v_pk_mul_f32 v[98:99], v[28:29], v[40:41] op_sel_hi:[1,0]
	v_pk_fma_f32 v[4:5], v[86:87], v[62:63], v[4:5] neg_lo:[1,0,0] neg_hi:[1,0,0]
	v_pk_mul_f32 v[100:101], v[98:99], v[68:69]
	s_waitcnt vmcnt(0)
	v_lshlrev_b32_e32 v76, 16, v46
	v_and_b32_e32 v77, 0xffff0000, v46
	v_lshlrev_b32_e32 v78, 16, v47
	v_and_b32_e32 v79, 0xffff0000, v47
	v_lshlrev_b32_e32 v80, 16, v48
	v_and_b32_e32 v81, 0xffff0000, v48
	v_lshlrev_b32_e32 v82, 16, v49
	v_and_b32_e32 v83, 0xffff0000, v49
	v_lshlrev_b32_e32 v84, 16, v50
	v_and_b32_e32 v85, 0xffff0000, v50
	s_waitcnt lgkmcnt(0)
	v_lshlrev_b32_e32 v46, 16, v51
	v_and_b32_e32 v47, 0xffff0000, v51
	v_lshlrev_b32_e32 v44, 16, v52
	v_and_b32_e32 v45, 0xffff0000, v52
	v_lshlrev_b32_e32 v32, 16, v53
	v_and_b32_e32 v33, 0xffff0000, v53
	v_lshlrev_b32_e32 v2, 16, v54
	v_and_b32_e32 v3, 0xffff0000, v54
	ds_read_b128 v[48:51], v0 offset:80
	ds_read_b128 v[52:55], v0 offset:96
	ds_read_b128 v[56:59], v0 offset:112
	v_cvt_pk_bf16_f32 v60, v38, v39
	v_lshl_add_u64 v[38:39], v[26:27], 0, s[94:95]
	s_lshl_b32 s94, s0, 1
	global_store_dword v[38:39], v60, off nt
	v_cvt_pk_bf16_f32 v36, v34, v35
	v_lshl_add_u64 v[34:35], v[26:27], 0, s[94:95]
	v_readlane_b32 s0, v253, 12
	global_store_dword v[34:35], v36, off nt
	v_pk_fma_f32 v[34:35], v[4:5], 0.5, v[96:97] op_sel_hi:[1,0,1] neg_lo:[0,0,1] neg_hi:[0,0,1]
	s_lshl_b32 s94, s0, 1
	v_pk_fma_f32 v[4:5], v[98:99], v[68:69], v[4:5]
	s_waitcnt lgkmcnt(2)
	v_pk_mul_f32 v[102:103], v[28:29], v[48:49] op_sel_hi:[1,0]
	v_cvt_pk_bf16_f32 v36, v34, v35
	v_lshl_add_u64 v[34:35], v[26:27], 0, s[94:95]
	v_pk_fma_f32 v[4:5], v[90:91], v[64:65], v[4:5] neg_lo:[1,0,0] neg_hi:[1,0,0]
	v_readlane_b32 s0, v251, 37
	global_store_dword v[34:35], v36, off nt
	v_pk_fma_f32 v[34:35], v[4:5], 0.5, v[100:101] op_sel_hi:[1,0,1] neg_lo:[0,0,1] neg_hi:[0,0,1]
	s_lshl_b32 s94, s0, 1
	v_pk_fma_f32 v[4:5], v[102:103], v[70:71], v[4:5]
	v_pk_mul_f32 v[104:105], v[102:103], v[70:71]
	v_pk_mul_f32 v[48:49], v[28:29], v[48:49] op_sel:[0,1]
	v_cvt_pk_bf16_f32 v36, v34, v35
	v_lshl_add_u64 v[34:35], v[26:27], 0, s[94:95]
	v_pk_fma_f32 v[4:5], v[94:95], v[66:67], v[4:5] neg_lo:[1,0,0] neg_hi:[1,0,0]
	v_readlane_b32 s0, v253, 15
	global_store_dword v[34:35], v36, off nt
	v_pk_fma_f32 v[34:35], v[4:5], 0.5, v[104:105] op_sel_hi:[1,0,1] neg_lo:[0,0,1] neg_hi:[0,0,1]
	s_lshl_b32 s94, s0, 1
	v_pk_fma_f32 v[4:5], v[48:49], v[72:73], v[4:5]
	v_pk_mul_f32 v[106:107], v[48:49], v[72:73]
	v_pk_mul_f32 v[108:109], v[28:29], v[50:51] op_sel_hi:[1,0]
	v_cvt_pk_bf16_f32 v36, v34, v35
	v_lshl_add_u64 v[34:35], v[26:27], 0, s[94:95]
	v_pk_fma_f32 v[4:5], v[98:99], v[68:69], v[4:5] neg_lo:[1,0,0] neg_hi:[1,0,0]
	v_readlane_b32 s0, v253, 16
	v_mov_b32_e32 v40, v51
	global_store_dword v[34:35], v36, off nt
	v_pk_fma_f32 v[34:35], v[4:5], 0.5, v[106:107] op_sel_hi:[1,0,1] neg_lo:[0,0,1] neg_hi:[0,0,1]
	s_lshl_b32 s94, s0, 1
	v_pk_fma_f32 v[4:5], v[108:109], v[74:75], v[4:5]
	v_pk_mul_f32 v[110:111], v[108:109], v[74:75]
	v_pk_mul_f32 v[50:51], v[28:29], v[40:41] op_sel_hi:[1,0]
	v_cvt_pk_bf16_f32 v36, v34, v35
	v_lshl_add_u64 v[34:35], v[26:27], 0, s[94:95]
	v_pk_fma_f32 v[4:5], v[102:103], v[70:71], v[4:5] neg_lo:[1,0,0] neg_hi:[1,0,0]
	v_readlane_b32 s0, v254, 1
	global_store_dword v[34:35], v36, off nt
	v_pk_fma_f32 v[34:35], v[4:5], 0.5, v[110:111] op_sel_hi:[1,0,1] neg_lo:[0,0,1] neg_hi:[0,0,1]
	s_lshl_b32 s94, s0, 1
	v_pk_fma_f32 v[4:5], v[50:51], v[76:77], v[4:5]
	v_pk_mul_f32 v[112:113], v[50:51], v[76:77]
	s_waitcnt lgkmcnt(1)
	v_pk_mul_f32 v[114:115], v[28:29], v[52:53] op_sel_hi:[1,0]
	v_cvt_pk_bf16_f32 v36, v34, v35
	v_lshl_add_u64 v[34:35], v[26:27], 0, s[94:95]
	v_pk_fma_f32 v[4:5], v[48:49], v[72:73], v[4:5] neg_lo:[1,0,0] neg_hi:[1,0,0]
	v_readlane_b32 s0, v254, 5
	global_store_dword v[34:35], v36, off nt
	v_pk_fma_f32 v[34:35], v[4:5], 0.5, v[112:113] op_sel_hi:[1,0,1] neg_lo:[0,0,1] neg_hi:[0,0,1]
	s_lshl_b32 s94, s0, 1
	v_pk_fma_f32 v[4:5], v[114:115], v[78:79], v[4:5]
	v_pk_mul_f32 v[116:117], v[114:115], v[78:79]
	v_pk_mul_f32 v[52:53], v[28:29], v[52:53] op_sel:[0,1]
	v_cvt_pk_bf16_f32 v36, v34, v35
	v_lshl_add_u64 v[34:35], v[26:27], 0, s[94:95]
	v_pk_fma_f32 v[4:5], v[108:109], v[74:75], v[4:5] neg_lo:[1,0,0] neg_hi:[1,0,0]
	v_readlane_b32 s0, v254, 3
	global_store_dword v[34:35], v36, off nt
	v_pk_fma_f32 v[34:35], v[4:5], 0.5, v[116:117] op_sel_hi:[1,0,1] neg_lo:[0,0,1] neg_hi:[0,0,1]
	s_lshl_b32 s94, s0, 1
	v_pk_fma_f32 v[4:5], v[52:53], v[80:81], v[4:5]
	v_pk_mul_f32 v[118:119], v[52:53], v[80:81]
	v_pk_mul_f32 v[120:121], v[28:29], v[54:55] op_sel_hi:[1,0]
	v_cvt_pk_bf16_f32 v36, v34, v35
	v_lshl_add_u64 v[34:35], v[26:27], 0, s[94:95]
	v_pk_fma_f32 v[4:5], v[50:51], v[76:77], v[4:5] neg_lo:[1,0,0] neg_hi:[1,0,0]
	v_readlane_b32 s0, v253, 25
	v_mov_b32_e32 v40, v55
	global_store_dword v[34:35], v36, off nt
	v_pk_fma_f32 v[34:35], v[4:5], 0.5, v[118:119] op_sel_hi:[1,0,1] neg_lo:[0,0,1] neg_hi:[0,0,1]
	s_lshl_b32 s94, s0, 1
	v_pk_fma_f32 v[4:5], v[120:121], v[82:83], v[4:5]
	v_pk_mul_f32 v[122:123], v[120:121], v[82:83]
	v_pk_mul_f32 v[54:55], v[28:29], v[40:41] op_sel_hi:[1,0]
	v_cvt_pk_bf16_f32 v36, v34, v35
	v_lshl_add_u64 v[34:35], v[26:27], 0, s[94:95]
	v_pk_fma_f32 v[4:5], v[114:115], v[78:79], v[4:5] neg_lo:[1,0,0] neg_hi:[1,0,0]
	v_readlane_b32 s0, v254, 49
	global_store_dword v[34:35], v36, off nt
	v_pk_fma_f32 v[34:35], v[4:5], 0.5, v[122:123] op_sel_hi:[1,0,1] neg_lo:[0,0,1] neg_hi:[0,0,1]
	s_lshl_b32 s94, s0, 1
	v_pk_fma_f32 v[4:5], v[54:55], v[84:85], v[4:5]
	v_pk_mul_f32 v[124:125], v[54:55], v[84:85]
	s_waitcnt lgkmcnt(0)
	v_pk_mul_f32 v[126:127], v[28:29], v[56:57] op_sel_hi:[1,0]
	v_cvt_pk_bf16_f32 v36, v34, v35
	v_lshl_add_u64 v[34:35], v[26:27], 0, s[94:95]
	v_pk_fma_f32 v[4:5], v[52:53], v[80:81], v[4:5] neg_lo:[1,0,0] neg_hi:[1,0,0]
	v_readlane_b32 s0, v253, 19
	global_store_dword v[34:35], v36, off nt
	v_pk_fma_f32 v[34:35], v[4:5], 0.5, v[124:125] op_sel_hi:[1,0,1] neg_lo:[0,0,1] neg_hi:[0,0,1]
	s_lshl_b32 s94, s0, 1
	v_pk_fma_f32 v[4:5], v[126:127], v[46:47], v[4:5]
	v_pk_mul_f32 v[128:129], v[126:127], v[46:47]
	v_pk_mul_f32 v[56:57], v[28:29], v[56:57] op_sel:[0,1]
	v_cvt_pk_bf16_f32 v36, v34, v35
	v_lshl_add_u64 v[34:35], v[26:27], 0, s[94:95]
	v_pk_fma_f32 v[4:5], v[120:121], v[82:83], v[4:5] neg_lo:[1,0,0] neg_hi:[1,0,0]
	v_readlane_b32 s0, v253, 28
	global_store_dword v[34:35], v36, off nt
	v_pk_fma_f32 v[34:35], v[4:5], 0.5, v[128:129] op_sel_hi:[1,0,1] neg_lo:[0,0,1] neg_hi:[0,0,1]
	s_lshl_b32 s94, s0, 1
	v_pk_fma_f32 v[4:5], v[56:57], v[44:45], v[4:5]
	v_pk_mul_f32 v[130:131], v[56:57], v[44:45]
	v_pk_mul_f32 v[42:43], v[28:29], v[58:59] op_sel_hi:[1,0]
	v_cvt_pk_bf16_f32 v36, v34, v35
	v_lshl_add_u64 v[34:35], v[26:27], 0, s[94:95]
	v_pk_fma_f32 v[4:5], v[54:55], v[84:85], v[4:5] neg_lo:[1,0,0] neg_hi:[1,0,0]
	v_readlane_b32 s0, v253, 24
	v_mov_b32_e32 v40, v59
	global_store_dword v[34:35], v36, off nt
	v_pk_fma_f32 v[34:35], v[4:5], 0.5, v[130:131] op_sel_hi:[1,0,1] neg_lo:[0,0,1] neg_hi:[0,0,1]
	s_lshl_b32 s94, s0, 1
	v_pk_fma_f32 v[4:5], v[42:43], v[32:33], v[4:5]
	v_pk_mul_f32 v[132:133], v[42:43], v[32:33]
	v_pk_mul_f32 v[40:41], v[28:29], v[40:41] op_sel_hi:[1,0]
	v_cvt_pk_bf16_f32 v36, v34, v35
	v_lshl_add_u64 v[34:35], v[26:27], 0, s[94:95]
	v_pk_fma_f32 v[4:5], v[126:127], v[46:47], v[4:5] neg_lo:[1,0,0] neg_hi:[1,0,0]
	global_store_dword v[34:35], v36, off nt
	v_pk_fma_f32 v[34:35], v[4:5], 0.5, v[132:133] op_sel_hi:[1,0,1] neg_lo:[0,0,1] neg_hi:[0,0,1]
	v_readlane_b32 s0, v253, 29
	v_pk_fma_f32 v[4:5], v[40:41], v[2:3], v[4:5]
	v_pk_mul_f32 v[58:59], v[40:41], v[2:3]
	s_lshl_b32 s94, s0, 1
	v_pk_fma_f32 v[60:61], v[56:57], v[44:45], v[4:5] neg_lo:[1,0,0] neg_hi:[1,0,0]
	v_readlane_b32 s0, v251, 59
	v_cvt_pk_bf16_f32 v36, v34, v35
	v_lshl_add_u64 v[34:35], v[26:27], 0, s[94:95]
	v_pk_fma_f32 v[4:5], v[60:61], 0.5, v[58:59] op_sel_hi:[1,0,1] neg_lo:[0,0,1] neg_hi:[0,0,1]
	v_readlane_b32 s1, v251, 60
	global_store_dword v[34:35], v36, off nt
	v_cvt_pk_bf16_f32 v34, v4, v5
	s_nop 0
	v_lshl_add_u64 v[4:5], v[30:31], 0, s[0:1]
	v_readlane_b32 s0, v251, 61
	v_readlane_b32 s1, v251, 62
	flat_load_dword v35, v[4:5]
	s_waitcnt vmcnt(0) lgkmcnt(0)
	v_lshlrev_b32_e32 v62, 16, v35
	v_lshl_add_u64 v[4:5], v[30:31], 0, s[0:1]
	v_readlane_b32 s0, v251, 55
	flat_load_dword v36, v[4:5]
	v_lshl_add_u64 v[4:5], v[30:31], 0, s[62:63]
	v_readlane_b32 s1, v251, 56
	flat_load_dword v37, v[4:5]
	v_and_b32_e32 v63, 0xffff0000, v35
	v_lshl_add_u64 v[4:5], v[30:31], 0, s[0:1]
	v_readlane_b32 s0, v251, 57
	v_readlane_b32 s1, v251, 58
	flat_load_dword v38, v[4:5]
	s_waitcnt vmcnt(0) lgkmcnt(0)
	v_lshlrev_b32_e32 v64, 16, v36
	v_lshl_add_u64 v[4:5], v[30:31], 0, s[0:1]
	flat_load_dword v39, v[4:5]
	v_lshl_add_u64 v[4:5], v[30:31], 0, s[20:21]
	flat_load_dword v44, v[4:5]
	v_lshl_add_u64 v[4:5], v[30:31], 0, s[58:59]
	flat_load_dword v45, v[4:5]
	v_lshl_add_u64 v[4:5], v[30:31], 0, s[22:23]
	flat_load_dword v46, v[4:5]
	v_lshl_add_u64 v[4:5], v[30:31], 0, s[54:55]
	flat_load_dword v47, v[4:5]
	v_lshl_add_u64 v[4:5], v[30:31], 0, s[88:89]
	flat_load_dword v48, v[4:5]
	v_lshl_add_u64 v[4:5], v[30:31], 0, s[68:69]
	flat_load_dword v49, v[4:5]
	v_lshl_add_u64 v[4:5], v[30:31], 0, s[92:93]
	flat_load_dword v50, v[4:5]
	v_lshl_add_u64 v[4:5], v[30:31], 0, s[14:15]
	flat_load_dword v51, v[4:5]
	v_lshl_add_u64 v[4:5], v[30:31], 0, s[12:13]
	flat_load_dword v52, v[4:5]
	v_lshl_add_u64 v[4:5], v[30:31], 0, s[42:43]
	flat_load_dword v53, v[4:5]
	v_lshl_add_u64 v[4:5], v[30:31], 0, s[36:37]
	flat_load_dword v54, v[4:5]
	v_and_b32_e32 v65, 0xffff0000, v36
	v_lshlrev_b32_e32 v66, 16, v37
	v_and_b32_e32 v67, 0xffff0000, v37
	v_lshlrev_b32_e32 v68, 16, v38
	v_and_b32_e32 v69, 0xffff0000, v38
	v_readlane_b32 s0, v254, 27
	s_lshl_b32 s94, s0, 1
	v_lshl_add_u64 v[4:5], v[26:27], 0, s[94:95]
	v_readlane_b32 s0, v254, 25
	global_store_dword v[4:5], v34, off nt
	s_lshl_b32 s94, s0, 1
	v_readlane_b32 s0, v253, 33
	s_waitcnt vmcnt(0) lgkmcnt(0)
	v_lshlrev_b32_e32 v70, 16, v39
	v_and_b32_e32 v71, 0xffff0000, v39
	ds_read_b128 v[36:39], v0 offset:128
	v_lshlrev_b32_e32 v72, 16, v44
	v_and_b32_e32 v73, 0xffff0000, v44
	v_lshlrev_b32_e32 v74, 16, v45
	v_and_b32_e32 v75, 0xffff0000, v45
	s_waitcnt lgkmcnt(0)
	v_pk_mul_f32 v[86:87], v[28:29], v[36:37] op_sel_hi:[1,0]
	v_pk_mul_f32 v[90:91], v[28:29], v[36:37] op_sel:[0,1]
	v_pk_fma_f32 v[60:61], v[86:87], v[62:63], v[60:61]
	v_pk_mul_f32 v[88:89], v[86:87], v[62:63]
	v_pk_fma_f32 v[32:33], v[42:43], v[32:33], v[60:61] neg_lo:[1,0,0] neg_hi:[1,0,0]
	v_pk_mul_f32 v[92:93], v[90:91], v[64:65]
	v_pk_fma_f32 v[42:43], v[32:33], 0.5, v[88:89] op_sel_hi:[1,0,1] neg_lo:[0,0,1] neg_hi:[0,0,1]
	v_pk_fma_f32 v[32:33], v[90:91], v[64:65], v[32:33]
	v_pk_mul_f32 v[94:95], v[28:29], v[38:39] op_sel_hi:[1,0]
	v_pk_fma_f32 v[2:3], v[40:41], v[2:3], v[32:33] neg_lo:[1,0,0] neg_hi:[1,0,0]
	v_lshlrev_b32_e32 v76, 16, v46
	v_and_b32_e32 v77, 0xffff0000, v46
	v_lshlrev_b32_e32 v78, 16, v47
	v_and_b32_e32 v79, 0xffff0000, v47
	v_lshlrev_b32_e32 v80, 16, v48
	v_and_b32_e32 v81, 0xffff0000, v48
	v_lshlrev_b32_e32 v82, 16, v49
	v_and_b32_e32 v83, 0xffff0000, v49
	v_lshlrev_b32_e32 v84, 16, v50
	v_and_b32_e32 v85, 0xffff0000, v50
	v_lshlrev_b32_e32 v46, 16, v51
	v_and_b32_e32 v47, 0xffff0000, v51
	v_lshlrev_b32_e32 v44, 16, v52
	v_and_b32_e32 v45, 0xffff0000, v52
	v_lshlrev_b32_e32 v34, 16, v53
	v_and_b32_e32 v35, 0xffff0000, v53
	v_lshlrev_b32_e32 v4, 16, v54
	v_and_b32_e32 v5, 0xffff0000, v54
	ds_read_b128 v[48:51], v0 offset:144
	ds_read_b128 v[52:55], v0 offset:160
	ds_read_b128 v[56:59], v0 offset:176
	v_mov_b32_e32 v36, v39
	v_cvt_pk_bf16_f32 v60, v42, v43
	v_lshl_add_u64 v[42:43], v[26:27], 0, s[94:95]
	v_pk_fma_f32 v[32:33], v[2:3], 0.5, v[92:93] op_sel_hi:[1,0,1] neg_lo:[0,0,1] neg_hi:[0,0,1]
	s_lshl_b32 s94, s0, 1
	v_pk_fma_f32 v[2:3], v[94:95], v[66:67], v[2:3]
	v_pk_mul_f32 v[96:97], v[94:95], v[66:67]
	v_pk_mul_f32 v[98:99], v[28:29], v[36:37] op_sel_hi:[1,0]
	global_store_dword v[42:43], v60, off nt
	v_cvt_pk_bf16_f32 v40, v32, v33
	v_lshl_add_u64 v[32:33], v[26:27], 0, s[94:95]
	v_pk_fma_f32 v[2:3], v[86:87], v[62:63], v[2:3] neg_lo:[1,0,0] neg_hi:[1,0,0]
	v_readlane_b32 s0, v251, 53
	global_store_dword v[32:33], v40, off nt
	v_pk_fma_f32 v[32:33], v[2:3], 0.5, v[96:97] op_sel_hi:[1,0,1] neg_lo:[0,0,1] neg_hi:[0,0,1]
	s_lshl_b32 s94, s0, 1
	v_pk_fma_f32 v[2:3], v[98:99], v[68:69], v[2:3]
	v_pk_mul_f32 v[100:101], v[98:99], v[68:69]
	s_waitcnt lgkmcnt(2)
	v_pk_mul_f32 v[102:103], v[28:29], v[48:49] op_sel_hi:[1,0]
	v_cvt_pk_bf16_f32 v40, v32, v33
	v_lshl_add_u64 v[32:33], v[26:27], 0, s[94:95]
	v_pk_fma_f32 v[2:3], v[90:91], v[64:65], v[2:3] neg_lo:[1,0,0] neg_hi:[1,0,0]
	v_readlane_b32 s0, v251, 51
	global_store_dword v[32:33], v40, off nt
	v_pk_fma_f32 v[32:33], v[2:3], 0.5, v[100:101] op_sel_hi:[1,0,1] neg_lo:[0,0,1] neg_hi:[0,0,1]
	s_lshl_b32 s94, s0, 1
	v_pk_fma_f32 v[2:3], v[102:103], v[70:71], v[2:3]
	v_pk_mul_f32 v[104:105], v[102:103], v[70:71]
	v_pk_mul_f32 v[48:49], v[28:29], v[48:49] op_sel:[0,1]
	v_cvt_pk_bf16_f32 v40, v32, v33
	v_lshl_add_u64 v[32:33], v[26:27], 0, s[94:95]
	v_pk_fma_f32 v[2:3], v[94:95], v[66:67], v[2:3] neg_lo:[1,0,0] neg_hi:[1,0,0]
	v_readlane_b32 s0, v253, 17
	global_store_dword v[32:33], v40, off nt
	v_pk_fma_f32 v[32:33], v[2:3], 0.5, v[104:105] op_sel_hi:[1,0,1] neg_lo:[0,0,1] neg_hi:[0,0,1]
	s_lshl_b32 s94, s0, 1
	v_pk_fma_f32 v[2:3], v[48:49], v[72:73], v[2:3]
	v_pk_mul_f32 v[106:107], v[48:49], v[72:73]
	v_pk_mul_f32 v[108:109], v[28:29], v[50:51] op_sel_hi:[1,0]
	v_cvt_pk_bf16_f32 v40, v32, v33
	v_lshl_add_u64 v[32:33], v[26:27], 0, s[94:95]
	v_pk_fma_f32 v[2:3], v[98:99], v[68:69], v[2:3] neg_lo:[1,0,0] neg_hi:[1,0,0]
	v_readlane_b32 s0, v254, 11
	v_mov_b32_e32 v36, v51
	global_store_dword v[32:33], v40, off nt
	v_pk_fma_f32 v[32:33], v[2:3], 0.5, v[106:107] op_sel_hi:[1,0,1] neg_lo:[0,0,1] neg_hi:[0,0,1]
	s_lshl_b32 s94, s0, 1
	v_pk_fma_f32 v[2:3], v[108:109], v[74:75], v[2:3]
	v_pk_mul_f32 v[110:111], v[108:109], v[74:75]
	v_pk_mul_f32 v[50:51], v[28:29], v[36:37] op_sel_hi:[1,0]
	v_cvt_pk_bf16_f32 v40, v32, v33
	v_lshl_add_u64 v[32:33], v[26:27], 0, s[94:95]
	v_pk_fma_f32 v[2:3], v[102:103], v[70:71], v[2:3] neg_lo:[1,0,0] neg_hi:[1,0,0]
	v_readlane_b32 s0, v253, 30
	global_store_dword v[32:33], v40, off nt
	v_pk_fma_f32 v[32:33], v[2:3], 0.5, v[110:111] op_sel_hi:[1,0,1] neg_lo:[0,0,1] neg_hi:[0,0,1]
	s_lshl_b32 s94, s0, 1
	v_pk_fma_f32 v[2:3], v[50:51], v[76:77], v[2:3]
	v_pk_mul_f32 v[112:113], v[50:51], v[76:77]
	s_waitcnt lgkmcnt(1)
	v_pk_mul_f32 v[114:115], v[28:29], v[52:53] op_sel_hi:[1,0]
	v_cvt_pk_bf16_f32 v40, v32, v33
	v_lshl_add_u64 v[32:33], v[26:27], 0, s[94:95]
	v_pk_fma_f32 v[2:3], v[48:49], v[72:73], v[2:3] neg_lo:[1,0,0] neg_hi:[1,0,0]
	v_readlane_b32 s0, v254, 9
	global_store_dword v[32:33], v40, off nt
	v_pk_fma_f32 v[32:33], v[2:3], 0.5, v[112:113] op_sel_hi:[1,0,1] neg_lo:[0,0,1] neg_hi:[0,0,1]
	s_lshl_b32 s94, s0, 1
	v_pk_fma_f32 v[2:3], v[114:115], v[78:79], v[2:3]
	v_pk_mul_f32 v[116:117], v[114:115], v[78:79]
	v_pk_mul_f32 v[52:53], v[28:29], v[52:53] op_sel:[0,1]
	v_cvt_pk_bf16_f32 v40, v32, v33
	v_lshl_add_u64 v[32:33], v[26:27], 0, s[94:95]
	v_pk_fma_f32 v[2:3], v[108:109], v[74:75], v[2:3] neg_lo:[1,0,0] neg_hi:[1,0,0]
	global_store_dword v[32:33], v40, off nt
	v_pk_fma_f32 v[32:33], v[2:3], 0.5, v[116:117] op_sel_hi:[1,0,1] neg_lo:[0,0,1] neg_hi:[0,0,1]
	s_lshl_b32 s94, s73, 1
	v_pk_fma_f32 v[2:3], v[52:53], v[80:81], v[2:3]
	v_pk_mul_f32 v[118:119], v[52:53], v[80:81]
	v_pk_mul_f32 v[120:121], v[28:29], v[54:55] op_sel_hi:[1,0]
	v_cvt_pk_bf16_f32 v40, v32, v33
	v_lshl_add_u64 v[32:33], v[26:27], 0, s[94:95]
	v_pk_fma_f32 v[2:3], v[50:51], v[76:77], v[2:3] neg_lo:[1,0,0] neg_hi:[1,0,0]
	v_mov_b32_e32 v36, v55
	global_store_dword v[32:33], v40, off nt
	v_pk_fma_f32 v[32:33], v[2:3], 0.5, v[118:119] op_sel_hi:[1,0,1] neg_lo:[0,0,1] neg_hi:[0,0,1]
	s_lshl_b32 s94, s64, 1
	v_pk_fma_f32 v[2:3], v[120:121], v[82:83], v[2:3]
	v_pk_mul_f32 v[122:123], v[120:121], v[82:83]
	v_pk_mul_f32 v[54:55], v[28:29], v[36:37] op_sel_hi:[1,0]
	v_cvt_pk_bf16_f32 v40, v32, v33
	v_lshl_add_u64 v[32:33], v[26:27], 0, s[94:95]
	v_pk_fma_f32 v[2:3], v[114:115], v[78:79], v[2:3] neg_lo:[1,0,0] neg_hi:[1,0,0]
	v_readlane_b32 s0, v253, 41
	global_store_dword v[32:33], v40, off nt
	v_pk_fma_f32 v[32:33], v[2:3], 0.5, v[122:123] op_sel_hi:[1,0,1] neg_lo:[0,0,1] neg_hi:[0,0,1]
	s_lshl_b32 s94, s0, 1
	v_pk_fma_f32 v[2:3], v[54:55], v[84:85], v[2:3]
	v_pk_mul_f32 v[124:125], v[54:55], v[84:85]
	s_waitcnt lgkmcnt(0)
	v_pk_mul_f32 v[126:127], v[28:29], v[56:57] op_sel_hi:[1,0]
	v_cvt_pk_bf16_f32 v40, v32, v33
	v_lshl_add_u64 v[32:33], v[26:27], 0, s[94:95]
	v_pk_fma_f32 v[2:3], v[52:53], v[80:81], v[2:3] neg_lo:[1,0,0] neg_hi:[1,0,0]
	v_readlane_b32 s0, v253, 36
	global_store_dword v[32:33], v40, off nt
	v_pk_fma_f32 v[32:33], v[2:3], 0.5, v[124:125] op_sel_hi:[1,0,1] neg_lo:[0,0,1] neg_hi:[0,0,1]
	s_lshl_b32 s94, s0, 1
	v_pk_fma_f32 v[2:3], v[126:127], v[46:47], v[2:3]
	v_pk_mul_f32 v[128:129], v[126:127], v[46:47]
	v_pk_mul_f32 v[56:57], v[28:29], v[56:57] op_sel:[0,1]
	v_cvt_pk_bf16_f32 v40, v32, v33
	v_lshl_add_u64 v[32:33], v[26:27], 0, s[94:95]
	v_pk_fma_f32 v[2:3], v[120:121], v[82:83], v[2:3] neg_lo:[1,0,0] neg_hi:[1,0,0]
	v_readlane_b32 s0, v253, 37
	global_store_dword v[32:33], v40, off nt
	v_pk_fma_f32 v[32:33], v[2:3], 0.5, v[128:129] op_sel_hi:[1,0,1] neg_lo:[0,0,1] neg_hi:[0,0,1]
	s_lshl_b32 s94, s0, 1
	v_pk_fma_f32 v[2:3], v[56:57], v[44:45], v[2:3]
	v_pk_mul_f32 v[130:131], v[56:57], v[44:45]
	v_pk_mul_f32 v[38:39], v[28:29], v[58:59] op_sel_hi:[1,0]
	v_cvt_pk_bf16_f32 v40, v32, v33
	v_lshl_add_u64 v[32:33], v[26:27], 0, s[94:95]
	v_pk_fma_f32 v[2:3], v[54:55], v[84:85], v[2:3] neg_lo:[1,0,0] neg_hi:[1,0,0]
	v_readlane_b32 s0, v254, 21
	v_mov_b32_e32 v36, v59
	global_store_dword v[32:33], v40, off nt
	v_pk_fma_f32 v[32:33], v[2:3], 0.5, v[130:131] op_sel_hi:[1,0,1] neg_lo:[0,0,1] neg_hi:[0,0,1]
	s_lshl_b32 s94, s0, 1
	v_pk_fma_f32 v[2:3], v[38:39], v[34:35], v[2:3]
	v_pk_mul_f32 v[132:133], v[38:39], v[34:35]
	v_pk_mul_f32 v[36:37], v[28:29], v[36:37] op_sel_hi:[1,0]
	v_cvt_pk_bf16_f32 v40, v32, v33
	v_lshl_add_u64 v[32:33], v[26:27], 0, s[94:95]
	v_pk_fma_f32 v[2:3], v[126:127], v[46:47], v[2:3] neg_lo:[1,0,0] neg_hi:[1,0,0]
	global_store_dword v[32:33], v40, off nt
	v_pk_fma_f32 v[32:33], v[2:3], 0.5, v[132:133] op_sel_hi:[1,0,1] neg_lo:[0,0,1] neg_hi:[0,0,1]
	v_readlane_b32 s0, v253, 38
	v_pk_fma_f32 v[2:3], v[36:37], v[4:5], v[2:3]
	v_pk_mul_f32 v[58:59], v[36:37], v[4:5]
	s_lshl_b32 s94, s0, 1
	v_pk_fma_f32 v[56:57], v[56:57], v[44:45], v[2:3] neg_lo:[1,0,0] neg_hi:[1,0,0]
	v_cvt_pk_bf16_f32 v40, v32, v33
	v_lshl_add_u64 v[32:33], v[26:27], 0, s[94:95]
	v_pk_fma_f32 v[2:3], v[56:57], 0.5, v[58:59] op_sel_hi:[1,0,1] neg_lo:[0,0,1] neg_hi:[0,0,1]
	global_store_dword v[32:33], v40, off nt
	v_cvt_pk_bf16_f32 v32, v2, v3
	v_lshl_add_u64 v[2:3], v[30:31], 0, s[44:45]
	flat_load_dword v33, v[2:3]
	v_lshl_add_u64 v[2:3], v[30:31], 0, s[40:41]
	flat_load_dword v40, v[2:3]
	v_lshl_add_u64 v[2:3], v[30:31], 0, s[46:47]
	flat_load_dword v41, v[2:3]
	v_lshl_add_u64 v[2:3], v[30:31], 0, s[10:11]
	flat_load_dword v42, v[2:3]
	v_lshl_add_u64 v[2:3], v[30:31], 0, s[52:53]
	flat_load_dword v43, v[2:3]
	v_lshl_add_u64 v[2:3], v[30:31], 0, s[38:39]
	flat_load_dword v44, v[2:3]
	v_lshl_add_u64 v[2:3], v[30:31], 0, s[90:91]
	flat_load_dword v45, v[2:3]
	v_lshl_add_u64 v[2:3], v[30:31], 0, s[78:79]
	flat_load_dword v46, v[2:3]
	v_lshl_add_u64 v[2:3], v[30:31], 0, s[50:51]
	flat_load_dword v47, v[2:3]
	v_lshl_add_u64 v[2:3], v[30:31], 0, s[56:57]
	flat_load_dword v48, v[2:3]
	v_lshl_add_u64 v[2:3], v[30:31], 0, s[34:35]
	flat_load_dword v49, v[2:3]
	v_lshl_add_u64 v[2:3], v[30:31], 0, s[6:7]
	flat_load_dword v50, v[2:3]
	v_lshl_add_u64 v[2:3], v[30:31], 0, s[74:75]
	flat_load_dword v51, v[2:3]
	v_lshl_add_u64 v[2:3], v[30:31], 0, s[4:5]
	flat_load_dword v52, v[2:3]
	v_lshl_add_u64 v[2:3], v[30:31], 0, s[24:25]
	flat_load_dword v53, v[2:3]
	v_lshl_add_u64 v[2:3], v[30:31], 0, s[60:61]
	flat_load_dword v31, v[2:3]
	v_readlane_b32 s0, v254, 19
	s_lshl_b32 s94, s0, 1
	v_lshl_add_u64 v[2:3], v[26:27], 0, s[94:95]
	global_store_dword v[2:3], v32, off nt
	v_readlane_b32 s0, v254, 23
	s_lshl_b32 s94, s0, 1
	v_readlane_b32 s0, v254, 33
	s_waitcnt vmcnt(0) lgkmcnt(0)
	v_lshlrev_b32_e32 v58, 16, v33
	v_and_b32_e32 v59, 0xffff0000, v33
	v_lshlrev_b32_e32 v60, 16, v40
	v_and_b32_e32 v61, 0xffff0000, v40
	v_lshlrev_b32_e32 v62, 16, v41
	v_and_b32_e32 v63, 0xffff0000, v41
	v_lshlrev_b32_e32 v64, 16, v42
	v_and_b32_e32 v65, 0xffff0000, v42
	v_lshlrev_b32_e32 v66, 16, v43
	v_and_b32_e32 v67, 0xffff0000, v43
	ds_read_b128 v[40:43], v0 offset:192
	v_lshlrev_b32_e32 v68, 16, v44
	v_and_b32_e32 v69, 0xffff0000, v44
	v_lshlrev_b32_e32 v70, 16, v45
	v_and_b32_e32 v71, 0xffff0000, v45
	v_lshlrev_b32_e32 v72, 16, v46
	v_and_b32_e32 v73, 0xffff0000, v46
	v_lshlrev_b32_e32 v74, 16, v47
	v_and_b32_e32 v75, 0xffff0000, v47
	v_lshlrev_b32_e32 v76, 16, v48
	v_and_b32_e32 v77, 0xffff0000, v48
	v_lshlrev_b32_e32 v78, 16, v49
	v_and_b32_e32 v79, 0xffff0000, v49
	v_lshlrev_b32_e32 v80, 16, v50
	v_and_b32_e32 v81, 0xffff0000, v50
	v_lshlrev_b32_e32 v32, 16, v51
	v_and_b32_e32 v33, 0xffff0000, v51
	v_lshlrev_b32_e32 v2, 16, v52
	v_and_b32_e32 v3, 0xffff0000, v52
	v_lshlrev_b32_e32 v82, 16, v53
	v_and_b32_e32 v83, 0xffff0000, v53
	ds_read_b128 v[44:47], v0 offset:208
	ds_read_b128 v[48:51], v0 offset:224
	ds_read_b128 v[52:55], v0 offset:240
	s_waitcnt lgkmcnt(3)
	v_pk_mul_f32 v[84:85], v[28:29], v[40:41] op_sel_hi:[1,0]
	v_mov_b32_e32 v0, v43
	v_pk_fma_f32 v[56:57], v[84:85], v[58:59], v[56:57]
	v_pk_mul_f32 v[86:87], v[84:85], v[58:59]
	v_pk_mul_f32 v[40:41], v[28:29], v[40:41] op_sel:[0,1]
	v_pk_mul_f32 v[90:91], v[28:29], v[42:43] op_sel_hi:[1,0]
	v_pk_mul_f32 v[42:43], v[28:29], v[0:1] op_sel_hi:[1,0]
	s_waitcnt lgkmcnt(2)
	v_mov_b32_e32 v0, v47
	v_pk_fma_f32 v[34:35], v[38:39], v[34:35], v[56:57] neg_lo:[1,0,0] neg_hi:[1,0,0]
	v_pk_mul_f32 v[102:103], v[28:29], v[46:47] op_sel_hi:[1,0]
	v_pk_mul_f32 v[46:47], v[28:29], v[0:1] op_sel_hi:[1,0]
	s_waitcnt lgkmcnt(1)
	v_mov_b32_e32 v0, v51
	v_pk_fma_f32 v[38:39], v[34:35], 0.5, v[86:87] op_sel_hi:[1,0,1] neg_lo:[0,0,1] neg_hi:[0,0,1]
	v_pk_fma_f32 v[34:35], v[40:41], v[60:61], v[34:35]
	v_pk_mul_f32 v[88:89], v[40:41], v[60:61]
	v_pk_mul_f32 v[114:115], v[28:29], v[50:51] op_sel_hi:[1,0]
	v_pk_mul_f32 v[50:51], v[28:29], v[0:1] op_sel_hi:[1,0]
	s_waitcnt lgkmcnt(0)
	v_mov_b32_e32 v0, v55
	v_pk_fma_f32 v[4:5], v[36:37], v[4:5], v[34:35] neg_lo:[1,0,0] neg_hi:[1,0,0]
	v_pk_mul_f32 v[96:97], v[28:29], v[44:45] op_sel_hi:[1,0]
	v_pk_mul_f32 v[44:45], v[28:29], v[44:45] op_sel:[0,1]
	v_pk_mul_f32 v[108:109], v[28:29], v[48:49] op_sel_hi:[1,0]
	v_pk_mul_f32 v[48:49], v[28:29], v[48:49] op_sel:[0,1]
	v_pk_mul_f32 v[120:121], v[28:29], v[52:53] op_sel_hi:[1,0]
	v_pk_mul_f32 v[52:53], v[28:29], v[52:53] op_sel:[0,1]
	v_pk_mul_f32 v[126:127], v[28:29], v[54:55] op_sel_hi:[1,0]
	v_pk_mul_f32 v[28:29], v[28:29], v[0:1] op_sel_hi:[1,0]
	v_cvt_pk_bf16_f32 v0, v38, v39
	v_lshl_add_u64 v[38:39], v[26:27], 0, s[94:95]
	v_pk_fma_f32 v[34:35], v[4:5], 0.5, v[88:89] op_sel_hi:[1,0,1] neg_lo:[0,0,1] neg_hi:[0,0,1]
	s_lshl_b32 s94, s0, 1
	v_pk_fma_f32 v[4:5], v[90:91], v[62:63], v[4:5]
	v_pk_mul_f32 v[92:93], v[90:91], v[62:63]
	global_store_dword v[38:39], v0, off nt
	v_cvt_pk_bf16_f32 v0, v34, v35
	v_lshl_add_u64 v[34:35], v[26:27], 0, s[94:95]
	v_pk_fma_f32 v[4:5], v[84:85], v[58:59], v[4:5] neg_lo:[1,0,0] neg_hi:[1,0,0]
	v_readlane_b32 s0, v254, 29
	global_store_dword v[34:35], v0, off nt
	v_pk_fma_f32 v[34:35], v[4:5], 0.5, v[92:93] op_sel_hi:[1,0,1] neg_lo:[0,0,1] neg_hi:[0,0,1]
	s_lshl_b32 s94, s0, 1
	v_pk_fma_f32 v[4:5], v[42:43], v[64:65], v[4:5]
	v_pk_mul_f32 v[94:95], v[42:43], v[64:65]
	v_cvt_pk_bf16_f32 v0, v34, v35
	v_lshl_add_u64 v[34:35], v[26:27], 0, s[94:95]
	v_pk_fma_f32 v[4:5], v[40:41], v[60:61], v[4:5] neg_lo:[1,0,0] neg_hi:[1,0,0]
	v_readlane_b32 s0, v253, 42
	global_store_dword v[34:35], v0, off nt
	v_pk_fma_f32 v[34:35], v[4:5], 0.5, v[94:95] op_sel_hi:[1,0,1] neg_lo:[0,0,1] neg_hi:[0,0,1]
	s_lshl_b32 s94, s0, 1
	v_pk_fma_f32 v[4:5], v[96:97], v[66:67], v[4:5]
	v_pk_mul_f32 v[98:99], v[96:97], v[66:67]
	v_cvt_pk_bf16_f32 v0, v34, v35
	v_lshl_add_u64 v[34:35], v[26:27], 0, s[94:95]
	v_pk_fma_f32 v[4:5], v[90:91], v[62:63], v[4:5] neg_lo:[1,0,0] neg_hi:[1,0,0]
	v_readlane_b32 s0, v254, 37
	global_store_dword v[34:35], v0, off nt
	v_pk_fma_f32 v[34:35], v[4:5], 0.5, v[98:99] op_sel_hi:[1,0,1] neg_lo:[0,0,1] neg_hi:[0,0,1]
	s_lshl_b32 s94, s0, 1
	v_pk_fma_f32 v[4:5], v[44:45], v[68:69], v[4:5]
	v_pk_mul_f32 v[100:101], v[44:45], v[68:69]
	v_cvt_pk_bf16_f32 v0, v34, v35
	v_lshl_add_u64 v[34:35], v[26:27], 0, s[94:95]
	v_pk_fma_f32 v[4:5], v[42:43], v[64:65], v[4:5] neg_lo:[1,0,0] neg_hi:[1,0,0]
	global_store_dword v[34:35], v0, off nt
	v_pk_fma_f32 v[34:35], v[4:5], 0.5, v[100:101] op_sel_hi:[1,0,1] neg_lo:[0,0,1] neg_hi:[0,0,1]
	s_lshl_b32 s94, s65, 1
	v_pk_fma_f32 v[4:5], v[102:103], v[70:71], v[4:5]
	v_pk_mul_f32 v[104:105], v[102:103], v[70:71]
	v_cvt_pk_bf16_f32 v0, v34, v35
	v_lshl_add_u64 v[34:35], v[26:27], 0, s[94:95]
	v_pk_fma_f32 v[4:5], v[96:97], v[66:67], v[4:5] neg_lo:[1,0,0] neg_hi:[1,0,0]
	global_store_dword v[34:35], v0, off nt
	v_pk_fma_f32 v[34:35], v[4:5], 0.5, v[104:105] op_sel_hi:[1,0,1] neg_lo:[0,0,1] neg_hi:[0,0,1]
	s_lshl_b32 s94, s48, 1
	v_pk_fma_f32 v[4:5], v[46:47], v[72:73], v[4:5]
	v_pk_mul_f32 v[106:107], v[46:47], v[72:73]
	v_cvt_pk_bf16_f32 v0, v34, v35
	v_lshl_add_u64 v[34:35], v[26:27], 0, s[94:95]
	v_pk_fma_f32 v[4:5], v[44:45], v[68:69], v[4:5] neg_lo:[1,0,0] neg_hi:[1,0,0]
	v_readlane_b32 s0, v253, 18
	global_store_dword v[34:35], v0, off nt
	v_pk_fma_f32 v[34:35], v[4:5], 0.5, v[106:107] op_sel_hi:[1,0,1] neg_lo:[0,0,1] neg_hi:[0,0,1]
	s_lshl_b32 s94, s0, 1
	v_pk_fma_f32 v[4:5], v[108:109], v[74:75], v[4:5]
	v_pk_mul_f32 v[110:111], v[108:109], v[74:75]
	v_cvt_pk_bf16_f32 v0, v34, v35
	v_lshl_add_u64 v[34:35], v[26:27], 0, s[94:95]
	v_pk_fma_f32 v[4:5], v[102:103], v[70:71], v[4:5] neg_lo:[1,0,0] neg_hi:[1,0,0]
	v_readlane_b32 s0, v254, 41
	global_store_dword v[34:35], v0, off nt
	v_pk_fma_f32 v[34:35], v[4:5], 0.5, v[110:111] op_sel_hi:[1,0,1] neg_lo:[0,0,1] neg_hi:[0,0,1]
	s_lshl_b32 s94, s0, 1
	v_pk_fma_f32 v[4:5], v[48:49], v[76:77], v[4:5]
	v_pk_mul_f32 v[112:113], v[48:49], v[76:77]
	v_cvt_pk_bf16_f32 v0, v34, v35
	v_lshl_add_u64 v[34:35], v[26:27], 0, s[94:95]
	v_pk_fma_f32 v[4:5], v[46:47], v[72:73], v[4:5] neg_lo:[1,0,0] neg_hi:[1,0,0]
	global_store_dword v[34:35], v0, off nt
	v_pk_fma_f32 v[34:35], v[4:5], 0.5, v[112:113] op_sel_hi:[1,0,1] neg_lo:[0,0,1] neg_hi:[0,0,1]
	s_lshl_b32 s94, s49, 1
	v_pk_fma_f32 v[4:5], v[114:115], v[78:79], v[4:5]
	v_pk_mul_f32 v[116:117], v[114:115], v[78:79]
	v_cvt_pk_bf16_f32 v0, v34, v35
	v_lshl_add_u64 v[34:35], v[26:27], 0, s[94:95]
	v_pk_fma_f32 v[4:5], v[108:109], v[74:75], v[4:5] neg_lo:[1,0,0] neg_hi:[1,0,0]
	global_store_dword v[34:35], v0, off nt
	v_pk_fma_f32 v[34:35], v[4:5], 0.5, v[116:117] op_sel_hi:[1,0,1] neg_lo:[0,0,1] neg_hi:[0,0,1]
	s_lshl_b32 s94, s86, 1
	v_pk_fma_f32 v[4:5], v[50:51], v[80:81], v[4:5]
	v_pk_mul_f32 v[118:119], v[50:51], v[80:81]
	v_cvt_pk_bf16_f32 v0, v34, v35
	v_lshl_add_u64 v[34:35], v[26:27], 0, s[94:95]
	v_pk_fma_f32 v[4:5], v[48:49], v[76:77], v[4:5] neg_lo:[1,0,0] neg_hi:[1,0,0]
	global_store_dword v[34:35], v0, off nt
	v_pk_fma_f32 v[34:35], v[4:5], 0.5, v[118:119] op_sel_hi:[1,0,1] neg_lo:[0,0,1] neg_hi:[0,0,1]
	s_lshl_b32 s94, s67, 1
	v_pk_fma_f32 v[4:5], v[120:121], v[32:33], v[4:5]
	v_pk_mul_f32 v[122:123], v[120:121], v[32:33]
	v_cvt_pk_bf16_f32 v0, v34, v35
	v_lshl_add_u64 v[34:35], v[26:27], 0, s[94:95]
	v_pk_fma_f32 v[4:5], v[114:115], v[78:79], v[4:5] neg_lo:[1,0,0] neg_hi:[1,0,0]
	v_readlane_b32 s0, v253, 63
	global_store_dword v[34:35], v0, off nt
	v_pk_fma_f32 v[34:35], v[4:5], 0.5, v[122:123] op_sel_hi:[1,0,1] neg_lo:[0,0,1] neg_hi:[0,0,1]
	s_lshl_b32 s94, s0, 1
	v_pk_fma_f32 v[4:5], v[52:53], v[2:3], v[4:5]
	v_pk_mul_f32 v[124:125], v[52:53], v[2:3]
	v_cvt_pk_bf16_f32 v0, v34, v35
	v_lshl_add_u64 v[34:35], v[26:27], 0, s[94:95]
	v_pk_fma_f32 v[4:5], v[50:51], v[80:81], v[4:5] neg_lo:[1,0,0] neg_hi:[1,0,0]
	global_store_dword v[34:35], v0, off nt
	v_pk_fma_f32 v[34:35], v[4:5], 0.5, v[124:125] op_sel_hi:[1,0,1] neg_lo:[0,0,1] neg_hi:[0,0,1]
	v_readlane_b32 s0, v253, 61
	v_pk_fma_f32 v[4:5], v[126:127], v[82:83], v[4:5]
	v_lshlrev_b32_e32 v30, 16, v31
	v_and_b32_e32 v31, 0xffff0000, v31
	v_pk_mul_f32 v[128:129], v[126:127], v[82:83]
	s_lshl_b32 s94, s0, 1
	v_pk_fma_f32 v[4:5], v[120:121], v[32:33], v[4:5] neg_lo:[1,0,0] neg_hi:[1,0,0]
	v_cvt_pk_bf16_f32 v0, v34, v35
	v_lshl_add_u64 v[34:35], v[26:27], 0, s[94:95]
	v_pk_fma_f32 v[32:33], v[4:5], 0.5, v[128:129] op_sel_hi:[1,0,1] neg_lo:[0,0,1] neg_hi:[0,0,1]
	s_lshl_b32 s94, s66, 1
	v_pk_fma_f32 v[4:5], v[28:29], v[30:31], v[4:5]
	v_pk_mul_f32 v[54:55], v[28:29], v[30:31]
	global_store_dword v[34:35], v0, off nt
	v_cvt_pk_bf16_f32 v0, v32, v33
	v_lshl_add_u64 v[32:33], v[26:27], 0, s[94:95]
	v_pk_fma_f32 v[2:3], v[52:53], v[2:3], v[4:5] neg_lo:[1,0,0] neg_hi:[1,0,0]
	global_store_dword v[32:33], v0, off nt
	v_pk_fma_f32 v[2:3], v[2:3], 0.5, v[54:55] op_sel_hi:[1,0,1] neg_lo:[0,0,1] neg_hi:[0,0,1]
	s_nop 0
	v_cvt_pk_bf16_f32 v162, v2, v3
	s_cbranch_execz .LBB0_359
.LBB0_387:
	s_mov_b32 s81, s95
	v_lshl_add_u64 v[2:3], v[26:27], 0, s[80:81]
	global_store_dword v[2:3], v162, off nt
	s_branch .LBB0_359
